# GEMM unit seam: first two K-loop waits after an epilogue use vmcnt(24) once (flag in s32) so epilogue store drain overlaps the first phases; 12 K-loops
# baseline (speedup 1.0000x reference)
; #define PG8_STAGE(bufoff, gbase, voff) do { _Pragma("unroll") for (int _i = 0; _i < 2; ++_i) \
;         __builtin_amdgcn_global_load_lds((const unsigned*)((const char*)(gbase) + (voff)[_i]), (LAS unsigned*)(lds + (bufoff) + ldsw + _i * 8192), 16, 0, 0); } while (0)
; #define PG8_WAIT_V(n) asm volatile("s_waitcnt vmcnt(" #n ")" ::: "memory")
; #define PG8_BAR __builtin_amdgcn_s_barrier()
; template <class Epi>
; __device__ __forceinline__ void gemm_phase(LAS unsigned char* lds, const Gemm g, const StaticOrder& S, const Epi& E, const int wid) {
;     ...
;     for (int i = 0; i < 2; ++i) { int R, C; stage_rc(tid * 16 + i * 8192, R, C); const int Rb = Epi::PERM ? ((R & ~31) + perm32(R & 31)) : R;
;         voffA[i] = (unsigned)(R * lda + C) * 2u; voffB[i] = (unsigned)(Rb * K + C) * 2u; }
;     const size_t kstep = (size_t)(BK * 2);
;     const size_t hsA = (size_t)HALF * lda * 2, hsB = (size_t)HALF * K * 2;
;     const size_t tsA = 2 * hsA, tsB = 2 * hsB;
;     const unsigned ldsw = (unsigned)wid * 1024u;
;     const int aoff = lds_byte(wr * 64 + fr, fq * 8), boff = lds_byte(wc * 32 + fr, fq * 8);
;     ...
;     PG8_STAGE(PG8_SB(0, 0), cB, voffB); PG8_STAGE(PG8_SB(0, 1), cB + hsB, voffB); PG8_STAGE(PG8_SA(0, 0), cA, voffA); PG8_STAGE(PG8_SA(0, 1), cA + hsA, voffA);
;     if (wr == 1) PG8_BAR;
;     PG8_WAIT_V(2); PG8_BAR;
;     PG8_STAGE(PG8_SB(1, 0), cB + kstep, voffB); PG8_STAGE(PG8_SA(1, 0), cA + kstep, voffA); PG8_STAGE(PG8_SB(1, 1), cB + hsB + kstep, voffB);
;     PG8_WAIT_V(6); PG8_BAR;
.LBB0_181:
	s_add_u32 s8, s54, 0x500000
	s_addc_u32 s9, s55, 0
	s_add_u32 s10, s54, 0x700000
	s_mov_b64 s[14:15], 0x80
	s_addc_u32 s11, s55, 0
	s_add_i32 m0, s66, 0x18000
	v_lshl_add_u64 v[6:7], v[6:7], 0, s[14:15]
	global_load_lds_dwordx4 v[6:7], off
	v_lshl_add_u64 v[4:5], v[4:5], 0, s[14:15]
	s_add_i32 m0, s66, 0x1a000
	s_add_i32 s76, s66, 0x8000
	s_add_i32 s77, s66, 0xa000
	global_load_lds_dwordx4 v[4:5], off
	v_lshl_add_u64 v[0:1], v[0:1], 0, s[14:15]
	s_mov_b32 m0, s76
	s_add_u32 s16, s34, 0x40080
	global_load_lds_dwordx4 v[0:1], off
	v_lshl_add_u64 v[0:1], v[2:3], 0, s[14:15]
	s_mov_b32 m0, s77
	s_addc_u32 s17, s35, 0
	global_load_lds_dwordx4 v[0:1], off
	s_add_i32 m0, s66, 0x1c000
	v_lshl_add_u64 v[0:1], s[16:17], 0, v[138:139]
	global_load_lds_dwordx4 v[0:1], off
	v_lshl_add_u64 v[0:1], s[16:17], 0, v[142:143]
	s_add_i32 m0, s66, 0x1e000
	s_sext_i32_i8 s93, s0
	global_load_lds_dwordx4 v[0:1], off
	s_waitcnt vmcnt(8)
	s_barrier
	v_and_b32_e32 v0, 15, v8
	v_ashrrev_i32_e32 v1, 6, v8
	v_and_b32_e32 v2, 48, v8
	v_readlane_b32 s0, v254, 3
	v_lshl_or_b32 v0, v0, 6, v2
	v_lshlrev_b32_e32 v3, 2, v8
	v_lshl_add_u32 v2, v1, 10, s0
	v_readlane_b32 s0, v254, 5
	v_and_b32_e32 v3, 32, v3
	v_bitop3_b32 v2, v0, v2, v3 bitop3:0xde
	v_add_lshl_u32 v1, v1, s0, 10
	v_bitop3_b32 v170, v0, v1, v3 bitop3:0xde
	v_lshlrev_b32_e32 v0, 14, v12
	v_and_b32_e32 v0, 0xffff8000, v0
	v_lshl_add_u32 v0, v13, 11, v0
	v_and_b32_e32 v1, 1, v12
	v_lshl_or_b32 v0, v1, 6, v0
	v_lshl_add_u32 v146, v14, 1, v0
	v_lshlrev_b32_e32 v0, 14, v9
	v_and_b32_e32 v0, 0xffff8000, v0
	s_waitcnt vmcnt(6)
	s_mov_b32 s32, 0
	s_cmpk_lt_u32 s3, 0x100
	v_lshl_add_u32 v0, v10, 11, v0
	v_and_b32_e32 v1, 1, v9
	s_cselect_b64 s[16:17], -1, 0
	s_lshl_b32 s0, s33, 4
	v_lshl_or_b32 v0, v1, 6, v0
	s_add_i32 s81, 0, 0x10000
	s_add_i32 s82, 0, 0x14000
	s_and_b32 s78, s0, 0x3fffffc0
	s_ashr_i32 s79, s56, 31
	s_mov_b32 s80, s56
	v_mov_b32_e32 v147, v145
	v_lshl_add_u32 v148, v11, 1, v0
	v_mov_b32_e32 v149, v145
	v_mov_b64_e32 v[150:151], 0x800
	v_mov_b64_e32 v[152:153], 0x7ff
	v_add_u32_e32 v171, s81, v170
	v_add_u32_e32 v172, s82, v170
	v_add_u32_e32 v173, 0, v2
	v_mov_b32_e32 v174, 0x358637bd
	s_mov_b64 s[18:19], 0x90000
	s_mov_b32 s83, 0x90000
	s_mov_b64 s[20:21], 0xa0000
	s_mov_b32 s90, 0xa0000
	s_mov_b64 s[22:23], 0xb0000
	s_mov_b32 s91, 0xb0000
	v_mov_b32_e32 v175, 0x3d800000
	v_mov_b32_e32 v176, 0x4000
	s_mov_b32 s92, 0
	s_barrier
	s_branch .LBB0_184

; #define PG8_STAGE(bufoff, gbase, voff) do { _Pragma("unroll") for (int _i = 0; _i < 2; ++_i) \
;         __builtin_amdgcn_global_load_lds((const unsigned*)((const char*)(gbase) + (voff)[_i]), (LAS unsigned*)(lds + (bufoff) + ldsw + _i * 8192), 16, 0, 0); } while (0)
; #define PG8_LDA(dst, b, h) do { _Pragma("unroll") for (int m = 0; m < 4; ++m) _Pragma("unroll") for (int k = 0; k < 2; ++k) dst[m][k] = *(const LAS bf16x8*)(lds + PG8_SA(b, h) + aoff + m * 2048 + k * 1024); } while (0)
; #define PG8_LDB(dst, b, h) do { _Pragma("unroll") for (int n = 0; n < 2; ++n) _Pragma("unroll") for (int k = 0; k < 2; ++k) dst[n][k] = *(const LAS bf16x8*)(lds + PG8_SB(b, h) + boff + n * 2048 + k * 1024); } while (0)
; #define PG8_MMA(ai, bj, At, Bt) do { __builtin_amdgcn_s_setprio(1); _Pragma("unroll") for (int m = 0; m < 4; ++m) _Pragma("unroll") for (int n = 0; n < 2; ++n) _Pragma("unroll") for (int k = 0; k < 2; ++k) \
;         acc[ai][bj][m][n] = __builtin_amdgcn_mfma_f32_16x16x32_bf16(Bt[n][k], At[m][k], acc[ai][bj][m][n], 0, 0, 0); __builtin_amdgcn_s_setprio(0); } while (0)
; #define PG8_WAIT_V(n) asm volatile("s_waitcnt vmcnt(" #n ")" ::: "memory")
; #define PG8_WAIT_L(n) asm volatile("s_waitcnt lgkmcnt(" #n ")" ::: "memory")
; #define PG8_BAR __builtin_amdgcn_s_barrier()
; #define PG8_SCHED __builtin_amdgcn_sched_barrier(0)
; template <class Epi>
; __device__ __forceinline__ void gemm_phase(LAS unsigned char* lds, const Gemm g, const StaticOrder& S, const Epi& E, const int wid) {
;     ...
;             PG8_LDB(B0, 0, 0); PG8_LDB(B1, 0, 1); PG8_SCHED; PG8_LDA(At, 0, 0); PG8_STAGE(PG8_SA(1, 1), a1 + hsA, voffA);
;             PG8_WAIT_V(8); PG8_WAIT_L(0); PG8_BAR; PG8_MMA(0, 0, At, B0); PG8_MMA(0, 1, At, B1); PG8_BAR; PG8_SCHED;
;             PG8_LDA(At, 0, 1); PG8_STAGE(PG8_SB(0, 0), b2, voffB); PG8_STAGE(PG8_SB(0, 1), b2 + hsB, voffB); PG8_STAGE(PG8_SA(0, 0), a2, voffA);
;             PG8_WAIT_V(8); PG8_WAIT_L(0); PG8_BAR; PG8_MMA(1, 0, At, B0); PG8_MMA(1, 1, At, B1); PG8_BAR; PG8_SCHED;
.LBB0_191:
	ds_read_b128 v[128:131], v171
	ds_read_b128 v[132:135], v171 offset:1024
	ds_read_b128 v[154:157], v171 offset:2048
	ds_read_b128 v[158:161], v171 offset:3072
	ds_read_b128 v[162:165], v172
	ds_read_b128 v[166:169], v172 offset:1024
	ds_read_b128 v[178:181], v172 offset:2048
	ds_read_b128 v[182:185], v172 offset:3072
	s_add_u32 s47, s34, 0xfffc0080
	s_addc_u32 s50, s35, -1
	s_cmp_eq_u32 s97, 12
	s_cselect_b32 s63, s27, s50
	s_cselect_b32 s62, s89, s47
	s_cselect_b32 s51, s25, s96
	s_cselect_b32 s50, s94, s95
	v_lshl_add_u64 v[218:219], s[34:35], 0, v[148:149]
	s_add_i32 m0, s66, 0xc000
	ds_read_b128 v[186:189], v173
	ds_read_b128 v[190:193], v173 offset:1024
	ds_read_b128 v[194:197], v173 offset:2048
	ds_read_b128 v[198:201], v173 offset:3072
	ds_read_b128 v[202:205], v173 offset:4096
	ds_read_b128 v[206:209], v173 offset:5120
	ds_read_b128 v[210:213], v173 offset:6144
	ds_read_b128 v[214:217], v173 offset:7168
	global_load_lds_dwordx4 v[218:219], off
	v_lshl_add_u64 v[218:219], s[34:35], 0, v[146:147]
	s_add_i32 m0, s66, 0xe000
	s_nop 0
	global_load_lds_dwordx4 v[218:219], off
	s_cmp_lg_u32 s32, 0
	s_cbranch_scc1 .Lkw0a_b
	s_waitcnt vmcnt(8)
	s_branch .Lkw0a_d
.Lkw0a_b:
	s_waitcnt vmcnt(24)
.Lkw0a_d:
	s_waitcnt lgkmcnt(0)
	s_barrier
	s_setprio 1
	s_waitcnt lgkmcnt(0)
	v_mfma_f32_16x16x32_bf16 v[124:127], v[128:131], v[186:189], v[124:127]
	v_mfma_f32_16x16x32_bf16 v[120:123], v[154:157], v[186:189], v[120:123]
	v_mfma_f32_16x16x32_bf16 v[116:119], v[128:131], v[194:197], v[116:119]
	v_mfma_f32_16x16x32_bf16 v[104:107], v[154:157], v[194:197], v[104:107]
	v_mfma_f32_16x16x32_bf16 v[92:95], v[128:131], v[202:205], v[92:95]
	v_mfma_f32_16x16x32_bf16 v[88:91], v[154:157], v[202:205], v[88:91]
	v_mfma_f32_16x16x32_bf16 v[84:87], v[128:131], v[210:213], v[84:87]
	v_mfma_f32_16x16x32_bf16 v[68:71], v[154:157], v[210:213], v[68:71]
	v_mfma_f32_16x16x32_bf16 v[124:127], v[132:135], v[190:193], v[124:127]
	v_mfma_f32_16x16x32_bf16 v[120:123], v[158:161], v[190:193], v[120:123]
	v_mfma_f32_16x16x32_bf16 v[116:119], v[132:135], v[198:201], v[116:119]
	v_mfma_f32_16x16x32_bf16 v[104:107], v[158:161], v[198:201], v[104:107]
	v_mfma_f32_16x16x32_bf16 v[92:95], v[132:135], v[206:209], v[92:95]
	v_mfma_f32_16x16x32_bf16 v[88:91], v[158:161], v[206:209], v[88:91]
	v_mfma_f32_16x16x32_bf16 v[84:87], v[132:135], v[214:217], v[84:87]
	v_mfma_f32_16x16x32_bf16 v[68:71], v[158:161], v[214:217], v[68:71]
	s_setprio 0
	s_setprio 1
	v_mfma_f32_16x16x32_bf16 v[112:115], v[162:165], v[186:189], v[112:115]
	v_mfma_f32_16x16x32_bf16 v[108:111], v[178:181], v[186:189], v[108:111]
	v_mfma_f32_16x16x32_bf16 v[100:103], v[162:165], v[194:197], v[100:103]
	v_mfma_f32_16x16x32_bf16 v[96:99], v[178:181], v[194:197], v[96:99]
	v_mfma_f32_16x16x32_bf16 v[80:83], v[162:165], v[202:205], v[80:83]
	v_mfma_f32_16x16x32_bf16 v[76:79], v[178:181], v[202:205], v[76:79]
	v_mfma_f32_16x16x32_bf16 v[72:75], v[162:165], v[210:213], v[72:75]
	v_mfma_f32_16x16x32_bf16 v[64:67], v[178:181], v[210:213], v[64:67]
	v_mfma_f32_16x16x32_bf16 v[112:115], v[166:169], v[190:193], v[112:115]
	v_mfma_f32_16x16x32_bf16 v[108:111], v[182:185], v[190:193], v[108:111]
	v_mfma_f32_16x16x32_bf16 v[100:103], v[166:169], v[198:201], v[100:103]
	v_mfma_f32_16x16x32_bf16 v[96:99], v[182:185], v[198:201], v[96:99]
	v_mfma_f32_16x16x32_bf16 v[80:83], v[166:169], v[206:209], v[80:83]
	v_mfma_f32_16x16x32_bf16 v[76:79], v[182:185], v[206:209], v[76:79]
	v_mfma_f32_16x16x32_bf16 v[72:75], v[166:169], v[214:217], v[72:75]
	v_mfma_f32_16x16x32_bf16 v[64:67], v[182:185], v[214:217], v[64:67]
	s_setprio 0
	s_barrier
	s_add_i32 s47, s81, s68
	v_lshl_add_u64 v[218:219], s[50:51], 0, v[138:139]
	s_mov_b32 m0, s47
	ds_read_b128 v[186:189], v173 offset:16384
	ds_read_b128 v[190:193], v173 offset:17408
	ds_read_b128 v[194:197], v173 offset:18432
	ds_read_b128 v[198:201], v173 offset:19456
	ds_read_b128 v[202:205], v173 offset:20480
	ds_read_b128 v[206:209], v173 offset:21504
	ds_read_b128 v[210:213], v173 offset:22528
	ds_read_b128 v[214:217], v173 offset:23552
	global_load_lds_dwordx4 v[218:219], off
	s_add_i32 m0, s47, 0x2000
	s_add_u32 s70, s50, 0x40000
	v_lshl_add_u64 v[220:221], s[50:51], 0, v[142:143]
	s_addc_u32 s71, s51, 0
	s_add_i32 s47, s82, s68
	global_load_lds_dwordx4 v[220:221], off
	v_lshl_add_u64 v[222:223], s[70:71], 0, v[138:139]
	s_mov_b32 m0, s47
	v_lshl_add_u64 v[224:225], s[62:63], 0, v[140:141]
	global_load_lds_dwordx4 v[222:223], off
	v_lshl_add_u64 v[222:223], s[70:71], 0, v[142:143]
	s_add_i32 m0, s47, 0x2000
	s_nop 0
	global_load_lds_dwordx4 v[222:223], off
	v_lshl_add_u64 v[222:223], s[62:63], 0, v[136:137]
	s_mov_b32 m0, s66
	s_nop 0
	global_load_lds_dwordx4 v[222:223], off
	s_mov_b32 m0, s67
	s_nop 0
	global_load_lds_dwordx4 v[224:225], off
	s_cmp_lg_u32 s32, 0
	s_cbranch_scc1 .Lkw0b_b
	s_waitcnt vmcnt(8)
	s_branch .Lkw0b_d

; #define PG8_STAGE(bufoff, gbase, voff) do { _Pragma("unroll") for (int _i = 0; _i < 2; ++_i) \
;         __builtin_amdgcn_global_load_lds((const unsigned*)((const char*)(gbase) + (voff)[_i]), (LAS unsigned*)(lds + (bufoff) + ldsw + _i * 8192), 16, 0, 0); } while (0)
; #define PG8_LDA(dst, b, h) do { _Pragma("unroll") for (int m = 0; m < 4; ++m) _Pragma("unroll") for (int k = 0; k < 2; ++k) dst[m][k] = *(const LAS bf16x8*)(lds + PG8_SA(b, h) + aoff + m * 2048 + k * 1024); } while (0)
; #define PG8_LDB(dst, b, h) do { _Pragma("unroll") for (int n = 0; n < 2; ++n) _Pragma("unroll") for (int k = 0; k < 2; ++k) dst[n][k] = *(const LAS bf16x8*)(lds + PG8_SB(b, h) + boff + n * 2048 + k * 1024); } while (0)
; #define PG8_MMA(ai, bj, At, Bt) do { __builtin_amdgcn_s_setprio(1); _Pragma("unroll") for (int m = 0; m < 4; ++m) _Pragma("unroll") for (int n = 0; n < 2; ++n) _Pragma("unroll") for (int k = 0; k < 2; ++k) \
;         acc[ai][bj][m][n] = __builtin_amdgcn_mfma_f32_16x16x32_bf16(Bt[n][k], At[m][k], acc[ai][bj][m][n], 0, 0, 0); __builtin_amdgcn_s_setprio(0); } while (0)
; #define PG8_WAIT_V(n) asm volatile("s_waitcnt vmcnt(" #n ")" ::: "memory")
; #define PG8_WAIT_L(n) asm volatile("s_waitcnt lgkmcnt(" #n ")" ::: "memory")
; #define PG8_BAR __builtin_amdgcn_s_barrier()
; #define PG8_SCHED __builtin_amdgcn_sched_barrier(0)
; template <class Epi>
; __device__ __forceinline__ void gemm_phase(LAS unsigned char* lds, const Gemm g, const StaticOrder& S, const Epi& E, const int wid) {
;     ...
;             PG8_WAIT_V(8); PG8_WAIT_L(0); PG8_BAR; PG8_MMA(1, 0, At, B0); PG8_MMA(1, 1, At, B1); PG8_BAR; PG8_SCHED;
;             PG8_LDB(B0, 1, 0); PG8_LDB(B1, 1, 1); PG8_SCHED; PG8_LDA(At, 1, 0); PG8_STAGE(PG8_SA(0, 1), a2 + hsA, voffA);
;             PG8_WAIT_V(8); PG8_WAIT_L(0); PG8_BAR; PG8_MMA(0, 0, At, B0); PG8_MMA(0, 1, At, B1); PG8_BAR; PG8_SCHED;
.Lkw0b_d:
	s_mov_b32 s32, 0
	s_waitcnt lgkmcnt(0)
	s_barrier
	s_setprio 1
	s_waitcnt lgkmcnt(0)
	v_mfma_f32_16x16x32_bf16 v[60:63], v[128:131], v[186:189], v[60:63]
	v_mfma_f32_16x16x32_bf16 v[56:59], v[154:157], v[186:189], v[56:59]
	v_mfma_f32_16x16x32_bf16 v[44:47], v[128:131], v[194:197], v[44:47]
	v_mfma_f32_16x16x32_bf16 v[40:43], v[154:157], v[194:197], v[40:43]
	v_mfma_f32_16x16x32_bf16 v[28:31], v[128:131], v[202:205], v[28:31]
	v_mfma_f32_16x16x32_bf16 v[24:27], v[154:157], v[202:205], v[24:27]
	v_mfma_f32_16x16x32_bf16 v[12:15], v[128:131], v[210:213], v[12:15]
	v_mfma_f32_16x16x32_bf16 v[8:11], v[154:157], v[210:213], v[8:11]
	v_mfma_f32_16x16x32_bf16 v[60:63], v[132:135], v[190:193], v[60:63]
	v_mfma_f32_16x16x32_bf16 v[56:59], v[158:161], v[190:193], v[56:59]
	v_mfma_f32_16x16x32_bf16 v[44:47], v[132:135], v[198:201], v[44:47]
	v_mfma_f32_16x16x32_bf16 v[40:43], v[158:161], v[198:201], v[40:43]
	v_mfma_f32_16x16x32_bf16 v[28:31], v[132:135], v[206:209], v[28:31]
	v_mfma_f32_16x16x32_bf16 v[24:27], v[158:161], v[206:209], v[24:27]
	v_mfma_f32_16x16x32_bf16 v[12:15], v[132:135], v[214:217], v[12:15]
	v_mfma_f32_16x16x32_bf16 v[8:11], v[158:161], v[214:217], v[8:11]
	s_setprio 0
	s_setprio 1
	v_mfma_f32_16x16x32_bf16 v[52:55], v[162:165], v[186:189], v[52:55]
	v_mfma_f32_16x16x32_bf16 v[48:51], v[178:181], v[186:189], v[48:51]
	v_mfma_f32_16x16x32_bf16 v[36:39], v[162:165], v[194:197], v[36:39]
	v_mfma_f32_16x16x32_bf16 v[32:35], v[178:181], v[194:197], v[32:35]
	v_mfma_f32_16x16x32_bf16 v[20:23], v[162:165], v[202:205], v[20:23]
	v_mfma_f32_16x16x32_bf16 v[16:19], v[178:181], v[202:205], v[16:19]
	v_mfma_f32_16x16x32_bf16 v[4:7], v[162:165], v[210:213], v[4:7]
	v_mfma_f32_16x16x32_bf16 v[0:3], v[178:181], v[210:213], v[0:3]
	v_mfma_f32_16x16x32_bf16 v[52:55], v[166:169], v[190:193], v[52:55]
	v_mfma_f32_16x16x32_bf16 v[48:51], v[182:185], v[190:193], v[48:51]
	v_mfma_f32_16x16x32_bf16 v[36:39], v[166:169], v[198:201], v[36:39]
	v_mfma_f32_16x16x32_bf16 v[32:35], v[182:185], v[198:201], v[32:35]
	v_mfma_f32_16x16x32_bf16 v[20:23], v[166:169], v[206:209], v[20:23]
	v_mfma_f32_16x16x32_bf16 v[16:19], v[182:185], v[206:209], v[16:19]
	v_mfma_f32_16x16x32_bf16 v[4:7], v[166:169], v[214:217], v[4:7]
	v_mfma_f32_16x16x32_bf16 v[0:3], v[182:185], v[214:217], v[0:3]
	s_setprio 0
	s_barrier
	s_add_i32 s47, 0, 0x18000
	v_add_u32_e32 v144, s47, v170
	s_add_i32 s70, 0, 0x1c000
	ds_read_b128 v[128:131], v144
	ds_read_b128 v[132:135], v144 offset:1024
	ds_read_b128 v[154:157], v144 offset:2048
	ds_read_b128 v[158:161], v144 offset:3072
	v_add_u32_e32 v144, s70, v170
	ds_read_b128 v[162:165], v144
	ds_read_b128 v[166:169], v144 offset:1024
	ds_read_b128 v[178:181], v144 offset:2048
	ds_read_b128 v[182:185], v144 offset:3072
	s_add_u32 s62, s62, 0x40000
	s_addc_u32 s63, s63, 0
	s_mov_b32 m0, s74
	v_lshl_add_u64 v[226:227], s[62:63], 0, v[136:137]
	ds_read_b128 v[186:189], v173 offset:32768
	ds_read_b128 v[190:193], v173 offset:33792
	ds_read_b128 v[194:197], v173 offset:34816
	ds_read_b128 v[198:201], v173 offset:35840
	ds_read_b128 v[202:205], v173 offset:36864
	ds_read_b128 v[206:209], v173 offset:37888
	ds_read_b128 v[210:213], v173 offset:38912
	ds_read_b128 v[214:217], v173 offset:39936
	global_load_lds_dwordx4 v[226:227], off
	v_lshl_add_u64 v[226:227], s[62:63], 0, v[140:141]
	s_mov_b32 m0, s75
	s_nop 0
	global_load_lds_dwordx4 v[226:227], off
	s_waitcnt vmcnt(8)
	s_waitcnt lgkmcnt(0)
	s_barrier
	s_setprio 1
	s_waitcnt lgkmcnt(0)
	v_mfma_f32_16x16x32_bf16 v[124:127], v[128:131], v[186:189], v[124:127]
	v_mfma_f32_16x16x32_bf16 v[120:123], v[154:157], v[186:189], v[120:123]
	v_mfma_f32_16x16x32_bf16 v[116:119], v[128:131], v[194:197], v[116:119]
	v_mfma_f32_16x16x32_bf16 v[104:107], v[154:157], v[194:197], v[104:107]
	v_mfma_f32_16x16x32_bf16 v[92:95], v[128:131], v[202:205], v[92:95]
	v_mfma_f32_16x16x32_bf16 v[88:91], v[154:157], v[202:205], v[88:91]
	v_mfma_f32_16x16x32_bf16 v[84:87], v[128:131], v[210:213], v[84:87]
	v_mfma_f32_16x16x32_bf16 v[68:71], v[154:157], v[210:213], v[68:71]
	v_mfma_f32_16x16x32_bf16 v[124:127], v[132:135], v[190:193], v[124:127]
	v_mfma_f32_16x16x32_bf16 v[120:123], v[158:161], v[190:193], v[120:123]
	v_mfma_f32_16x16x32_bf16 v[116:119], v[132:135], v[198:201], v[116:119]
	v_mfma_f32_16x16x32_bf16 v[104:107], v[158:161], v[198:201], v[104:107]
	v_mfma_f32_16x16x32_bf16 v[92:95], v[132:135], v[206:209], v[92:95]
	v_mfma_f32_16x16x32_bf16 v[88:91], v[158:161], v[206:209], v[88:91]
	v_mfma_f32_16x16x32_bf16 v[84:87], v[132:135], v[214:217], v[84:87]
	v_mfma_f32_16x16x32_bf16 v[68:71], v[158:161], v[214:217], v[68:71]
	s_setprio 0
	s_setprio 1
	v_mfma_f32_16x16x32_bf16 v[112:115], v[162:165], v[186:189], v[112:115]
	v_mfma_f32_16x16x32_bf16 v[108:111], v[178:181], v[186:189], v[108:111]
	v_mfma_f32_16x16x32_bf16 v[100:103], v[162:165], v[194:197], v[100:103]
	v_mfma_f32_16x16x32_bf16 v[96:99], v[178:181], v[194:197], v[96:99]
	v_mfma_f32_16x16x32_bf16 v[80:83], v[162:165], v[202:205], v[80:83]
	v_mfma_f32_16x16x32_bf16 v[76:79], v[178:181], v[202:205], v[76:79]
	v_mfma_f32_16x16x32_bf16 v[72:75], v[162:165], v[210:213], v[72:75]
	v_mfma_f32_16x16x32_bf16 v[64:67], v[178:181], v[210:213], v[64:67]
	v_mfma_f32_16x16x32_bf16 v[112:115], v[166:169], v[190:193], v[112:115]
	v_mfma_f32_16x16x32_bf16 v[108:111], v[182:185], v[190:193], v[108:111]
	v_mfma_f32_16x16x32_bf16 v[100:103], v[166:169], v[198:201], v[100:103]
	v_mfma_f32_16x16x32_bf16 v[96:99], v[182:185], v[198:201], v[96:99]
	v_mfma_f32_16x16x32_bf16 v[80:83], v[166:169], v[206:209], v[80:83]
	v_mfma_f32_16x16x32_bf16 v[76:79], v[182:185], v[206:209], v[76:79]
	v_mfma_f32_16x16x32_bf16 v[72:75], v[166:169], v[214:217], v[72:75]
	v_mfma_f32_16x16x32_bf16 v[64:67], v[182:185], v[214:217], v[64:67]
	s_setprio 0
	s_barrier
; #define PG8_STAGE(bufoff, gbase, voff) do { _Pragma("unroll") for (int _i = 0; _i < 2; ++_i) \
;         __builtin_amdgcn_global_load_lds((const unsigned*)((const char*)(gbase) + (voff)[_i]), (LAS unsigned*)(lds + (bufoff) + ldsw + _i * 8192), 16, 0, 0); } while (0)
; #define PG8_LDA(dst, b, h) do { _Pragma("unroll") for (int m = 0; m < 4; ++m) _Pragma("unroll") for (int k = 0; k < 2; ++k) dst[m][k] = *(const LAS bf16x8*)(lds + PG8_SA(b, h) + aoff + m * 2048 + k * 1024); } while (0)
; #define PG8_MMA(ai, bj, At, Bt) do { __builtin_amdgcn_s_setprio(1); _Pragma("unroll") for (int m = 0; m < 4; ++m) _Pragma("unroll") for (int n = 0; n < 2; ++n) _Pragma("unroll") for (int k = 0; k < 2; ++k) \
;         acc[ai][bj][m][n] = __builtin_amdgcn_mfma_f32_16x16x32_bf16(Bt[n][k], At[m][k], acc[ai][bj][m][n], 0, 0, 0); __builtin_amdgcn_s_setprio(0); } while (0)
; #define PG8_WAIT_V(n) asm volatile("s_waitcnt vmcnt(" #n ")" ::: "memory")
; #define PG8_WAIT_L(n) asm volatile("s_waitcnt lgkmcnt(" #n ")" ::: "memory")
; #define PG8_BAR __builtin_amdgcn_s_barrier()
; #define PG8_SCHED __builtin_amdgcn_sched_barrier(0)
; template <class Epi>
; __device__ __forceinline__ void gemm_phase(LAS unsigned char* lds, const Gemm g, const StaticOrder& S, const Epi& E, const int wid) {
;     ...
;             PG8_LDA(At, 1, 1); PG8_STAGE(PG8_SB(1, 0), b3, voffB); PG8_STAGE(PG8_SB(1, 1), b3 + hsB, voffB); PG8_STAGE(PG8_SA(1, 0), a3, voffA);
;             PG8_WAIT_V(8); PG8_WAIT_L(0); PG8_BAR; PG8_MMA(1, 0, At, B0); PG8_MMA(1, 1, At, B1); PG8_BAR; PG8_SCHED;
;         }
;         if (wr == 0) PG8_BAR;
;         E(acc, cur, wid);
;         if (!has_next) break;
	s_add_i32 s47, s47, s68
	v_lshl_add_u64 v[218:219], v[218:219], 0, s[14:15]
	s_mov_b32 m0, s47
	ds_read_b128 v[186:189], v173 offset:49152
	ds_read_b128 v[190:193], v173 offset:50176
	ds_read_b128 v[194:197], v173 offset:51200
	ds_read_b128 v[198:201], v173 offset:52224
	ds_read_b128 v[202:205], v173 offset:53248
	ds_read_b128 v[206:209], v173 offset:54272
	ds_read_b128 v[210:213], v173 offset:55296
	ds_read_b128 v[214:217], v173 offset:56320
	global_load_lds_dwordx4 v[218:219], off
	s_add_i32 m0, s47, 0x2000
	s_add_u32 s50, s50, 0x40080
	v_lshl_add_u64 v[218:219], v[220:221], 0, s[14:15]
	s_addc_u32 s51, s51, 0
	s_add_i32 s47, s70, s68
	global_load_lds_dwordx4 v[218:219], off
	v_lshl_add_u64 v[218:219], s[50:51], 0, v[138:139]
	s_mov_b32 m0, s47
	s_nop 0
	global_load_lds_dwordx4 v[218:219], off
	v_lshl_add_u64 v[218:219], s[50:51], 0, v[142:143]
	s_add_i32 m0, s47, 0x2000
	s_nop 0
	global_load_lds_dwordx4 v[218:219], off
	v_lshl_add_u64 v[218:219], v[222:223], 0, s[14:15]
	s_mov_b32 m0, s76
	s_nop 0
	global_load_lds_dwordx4 v[218:219], off
	v_lshl_add_u64 v[218:219], v[224:225], 0, s[14:15]
	s_mov_b32 m0, s77
	s_nop 0
	global_load_lds_dwordx4 v[218:219], off
	s_waitcnt vmcnt(8)
	s_waitcnt lgkmcnt(0)
	s_barrier
	s_setprio 1
	s_waitcnt lgkmcnt(0)
	v_mfma_f32_16x16x32_bf16 v[60:63], v[128:131], v[186:189], v[60:63]
	v_mfma_f32_16x16x32_bf16 v[56:59], v[154:157], v[186:189], v[56:59]
	v_mfma_f32_16x16x32_bf16 v[44:47], v[128:131], v[194:197], v[44:47]
	v_mfma_f32_16x16x32_bf16 v[40:43], v[154:157], v[194:197], v[40:43]
	v_mfma_f32_16x16x32_bf16 v[28:31], v[128:131], v[202:205], v[28:31]
	v_mfma_f32_16x16x32_bf16 v[24:27], v[154:157], v[202:205], v[24:27]
	v_mfma_f32_16x16x32_bf16 v[12:15], v[128:131], v[210:213], v[12:15]
	v_mfma_f32_16x16x32_bf16 v[8:11], v[154:157], v[210:213], v[8:11]
	v_mfma_f32_16x16x32_bf16 v[60:63], v[132:135], v[190:193], v[60:63]
	v_mfma_f32_16x16x32_bf16 v[56:59], v[158:161], v[190:193], v[56:59]
	v_mfma_f32_16x16x32_bf16 v[44:47], v[132:135], v[198:201], v[44:47]
	v_mfma_f32_16x16x32_bf16 v[40:43], v[158:161], v[198:201], v[40:43]
	v_mfma_f32_16x16x32_bf16 v[28:31], v[132:135], v[206:209], v[28:31]
	v_mfma_f32_16x16x32_bf16 v[24:27], v[158:161], v[206:209], v[24:27]
	v_mfma_f32_16x16x32_bf16 v[12:15], v[132:135], v[214:217], v[12:15]
	v_mfma_f32_16x16x32_bf16 v[8:11], v[158:161], v[214:217], v[8:11]
	s_setprio 0
	s_setprio 1
	v_mfma_f32_16x16x32_bf16 v[52:55], v[162:165], v[186:189], v[52:55]
	v_mfma_f32_16x16x32_bf16 v[48:51], v[178:181], v[186:189], v[48:51]
	v_mfma_f32_16x16x32_bf16 v[36:39], v[162:165], v[194:197], v[36:39]
	v_mfma_f32_16x16x32_bf16 v[32:35], v[178:181], v[194:197], v[32:35]
	v_mfma_f32_16x16x32_bf16 v[20:23], v[162:165], v[202:205], v[20:23]
	v_mfma_f32_16x16x32_bf16 v[16:19], v[178:181], v[202:205], v[16:19]
	v_mfma_f32_16x16x32_bf16 v[4:7], v[162:165], v[210:213], v[4:7]
	v_mfma_f32_16x16x32_bf16 v[0:3], v[178:181], v[210:213], v[0:3]
	v_mfma_f32_16x16x32_bf16 v[52:55], v[166:169], v[190:193], v[52:55]
	v_mfma_f32_16x16x32_bf16 v[48:51], v[182:185], v[190:193], v[48:51]
	v_mfma_f32_16x16x32_bf16 v[36:39], v[166:169], v[198:201], v[36:39]
	v_mfma_f32_16x16x32_bf16 v[32:35], v[182:185], v[198:201], v[32:35]
	v_mfma_f32_16x16x32_bf16 v[20:23], v[166:169], v[206:209], v[20:23]
	v_mfma_f32_16x16x32_bf16 v[16:19], v[182:185], v[206:209], v[16:19]
	v_mfma_f32_16x16x32_bf16 v[4:7], v[166:169], v[214:217], v[4:7]
	v_mfma_f32_16x16x32_bf16 v[0:3], v[182:185], v[214:217], v[0:3]
	s_setprio 0
	s_barrier
	s_add_i32 s97, s97, 2
	s_add_u32 s95, s95, 0x100
	s_addc_u32 s96, s96, 0
	s_add_u32 s34, s34, 0x100
	s_addc_u32 s35, s35, 0
	s_cmp_gt_u32 s97, 13
	s_cbranch_scc0 .LBB0_191
	s_mov_b32 s32, 1
	s_and_b64 vcc, exec, s[16:17]
	s_cbranch_vccz .LBB0_194
	s_barrier

; #define PG8_STAGE(bufoff, gbase, voff) do { _Pragma("unroll") for (int _i = 0; _i < 2; ++_i) \
;         __builtin_amdgcn_global_load_lds((const unsigned*)((const char*)(gbase) + (voff)[_i]), (LAS unsigned*)(lds + (bufoff) + ldsw + _i * 8192), 16, 0, 0); } while (0)
; #define PG8_WAIT_V(n) asm volatile("s_waitcnt vmcnt(" #n ")" ::: "memory")
; #define PG8_BAR __builtin_amdgcn_s_barrier()
; template <class Epi>
; __device__ __forceinline__ void gemm_phase(LAS unsigned char* lds, const Gemm g, const StaticOrder& S, const Epi& E, const int wid) {
;     ...
;     for (int i = 0; i < 2; ++i) { int R, C; stage_rc(tid * 16 + i * 8192, R, C); const int Rb = Epi::PERM ? ((R & ~31) + perm32(R & 31)) : R;
;         voffA[i] = (unsigned)(R * lda + C) * 2u; voffB[i] = (unsigned)(Rb * K + C) * 2u; }
;     const size_t kstep = (size_t)(BK * 2);
;     const size_t hsA = (size_t)HALF * lda * 2, hsB = (size_t)HALF * K * 2;
;     const size_t tsA = 2 * hsA, tsB = 2 * hsB;
;     const unsigned ldsw = (unsigned)wid * 1024u;
;     const int aoff = lds_byte(wr * 64 + fr, fq * 8), boff = lds_byte(wc * 32 + fr, fq * 8);
;     ...
;     PG8_STAGE(PG8_SB(0, 0), cB, voffB); PG8_STAGE(PG8_SB(0, 1), cB + hsB, voffB); PG8_STAGE(PG8_SA(0, 0), cA, voffA); PG8_STAGE(PG8_SA(0, 1), cA + hsA, voffA);
;     if (wr == 1) PG8_BAR;
;     PG8_WAIT_V(2); PG8_BAR;
;     PG8_STAGE(PG8_SB(1, 0), cB + kstep, voffB); PG8_STAGE(PG8_SA(1, 0), cA + kstep, voffA); PG8_STAGE(PG8_SB(1, 1), cB + hsB + kstep, voffB);
;     PG8_WAIT_V(6); PG8_BAR;
.LBB0_321:
	s_mov_b64 s[6:7], 0x80
	s_add_i32 m0, s23, 0x18000
	v_lshl_add_u64 v[6:7], v[6:7], 0, s[6:7]
	global_load_lds_dwordx4 v[6:7], off
	v_lshl_add_u64 v[4:5], v[4:5], 0, s[6:7]
	s_add_i32 m0, s23, 0x1a000
	s_add_i32 s64, s23, 0x8000
	s_add_i32 s65, s23, 0xa000
	global_load_lds_dwordx4 v[4:5], off
	v_lshl_add_u64 v[0:1], v[0:1], 0, s[6:7]
	s_mov_b32 m0, s64
	s_add_u32 s0, s24, 0x40080
	global_load_lds_dwordx4 v[0:1], off
	v_lshl_add_u64 v[0:1], v[2:3], 0, s[6:7]
	s_mov_b32 m0, s65
	s_addc_u32 s1, s25, 0
	global_load_lds_dwordx4 v[0:1], off
	s_add_i32 m0, s23, 0x1c000
	v_lshl_add_u64 v[0:1], s[0:1], 0, v[170:171]
	global_load_lds_dwordx4 v[0:1], off
	v_lshl_add_u64 v[0:1], s[0:1], 0, v[174:175]
	s_add_i32 m0, s23, 0x1e000
	v_and_b32_e32 v2, 48, v8
	global_load_lds_dwordx4 v[0:1], off
	s_waitcnt vmcnt(8)
	s_barrier
	v_and_b32_e32 v0, 15, v8
	v_ashrrev_i32_e32 v1, 6, v8
	v_readlane_b32 s0, v254, 3
	v_lshl_or_b32 v0, v0, 6, v2
	v_lshlrev_b32_e32 v3, 2, v8
	v_lshl_add_u32 v2, v1, 10, s0
	v_readlane_b32 s0, v254, 5
	v_and_b32_e32 v3, 32, v3
	v_bitop3_b32 v2, v0, v2, v3 bitop3:0xde
	v_add_lshl_u32 v1, v1, s0, 10
	v_bitop3_b32 v194, v0, v1, v3 bitop3:0xde
	v_lshlrev_b32_e32 v0, 14, v12
	v_and_b32_e32 v0, 0xffff8000, v0
	v_lshl_add_u32 v0, v13, 11, v0
	v_and_b32_e32 v1, 1, v12
	v_lshl_or_b32 v0, v1, 6, v0
	v_lshl_add_u32 v176, v14, 1, v0
	v_lshlrev_b32_e32 v0, 14, v9
	v_and_b32_e32 v0, 0xffff8000, v0
	s_waitcnt vmcnt(6)
	s_mov_b32 s32, 0
	s_cmpk_lt_u32 s3, 0x100
	v_lshl_add_u32 v0, v10, 11, v0
	v_and_b32_e32 v1, 1, v9
	s_cselect_b64 s[8:9], -1, 0
	s_lshl_b32 s0, s33, 4
	v_lshl_or_b32 v0, v1, 6, v0
	s_add_i32 s76, 0, 0x10000
	s_add_i32 s77, 0, 0x14000
	s_and_b32 s66, s0, 0x3fffffc0
	s_ashr_i32 s67, s56, 31
	s_mov_b32 s74, s56
	s_ashr_i32 s75, s2, 31
	v_mov_b32_e32 v177, v171
	v_lshl_add_u32 v178, v11, 1, v0
	v_mov_b32_e32 v179, v171
	v_mov_b64_e32 v[180:181], 0x400
	v_mov_b64_e32 v[182:183], 0x3ff
	v_add_u32_e32 v195, s76, v194
	v_add_u32_e32 v196, s77, v194
	v_add_u32_e32 v197, 0, v2
	v_mov_b32_e32 v198, 0x358637bd
	s_barrier
	s_branch .LBB0_324

; #define PG8_STAGE(bufoff, gbase, voff) do { _Pragma("unroll") for (int _i = 0; _i < 2; ++_i) \
;         __builtin_amdgcn_global_load_lds((const unsigned*)((const char*)(gbase) + (voff)[_i]), (LAS unsigned*)(lds + (bufoff) + ldsw + _i * 8192), 16, 0, 0); } while (0)
; #define PG8_LDA(dst, b, h) do { _Pragma("unroll") for (int m = 0; m < 4; ++m) _Pragma("unroll") for (int k = 0; k < 2; ++k) dst[m][k] = *(const LAS bf16x8*)(lds + PG8_SA(b, h) + aoff + m * 2048 + k * 1024); } while (0)
; #define PG8_LDB(dst, b, h) do { _Pragma("unroll") for (int n = 0; n < 2; ++n) _Pragma("unroll") for (int k = 0; k < 2; ++k) dst[n][k] = *(const LAS bf16x8*)(lds + PG8_SB(b, h) + boff + n * 2048 + k * 1024); } while (0)
; #define PG8_MMA(ai, bj, At, Bt) do { __builtin_amdgcn_s_setprio(1); _Pragma("unroll") for (int m = 0; m < 4; ++m) _Pragma("unroll") for (int n = 0; n < 2; ++n) _Pragma("unroll") for (int k = 0; k < 2; ++k) \
;         acc[ai][bj][m][n] = __builtin_amdgcn_mfma_f32_16x16x32_bf16(Bt[n][k], At[m][k], acc[ai][bj][m][n], 0, 0, 0); __builtin_amdgcn_s_setprio(0); } while (0)
; #define PG8_WAIT_V(n) asm volatile("s_waitcnt vmcnt(" #n ")" ::: "memory")
; #define PG8_WAIT_L(n) asm volatile("s_waitcnt lgkmcnt(" #n ")" ::: "memory")
; #define PG8_BAR __builtin_amdgcn_s_barrier()
; #define PG8_SCHED __builtin_amdgcn_sched_barrier(0)
; template <class Epi>
; __device__ __forceinline__ void gemm_phase(LAS unsigned char* lds, const Gemm g, const StaticOrder& S, const Epi& E, const int wid) {
;     ...
;             PG8_LDB(B0, 0, 0); PG8_LDB(B1, 0, 1); PG8_SCHED; PG8_LDA(At, 0, 0); PG8_STAGE(PG8_SA(1, 1), a1 + hsA, voffA);
;             PG8_WAIT_V(8); PG8_WAIT_L(0); PG8_BAR; PG8_MMA(0, 0, At, B0); PG8_MMA(0, 1, At, B1); PG8_BAR; PG8_SCHED;
.LBB0_331:
	ds_read_b128 v[48:51], v195
	ds_read_b128 v[56:59], v195 offset:1024
	ds_read_b128 v[64:67], v195 offset:2048
	ds_read_b128 v[68:71], v195 offset:3072
	ds_read_b128 v[144:147], v196
	ds_read_b128 v[148:151], v196 offset:1024
	ds_read_b128 v[152:155], v196 offset:2048
	ds_read_b128 v[156:159], v196 offset:3072
	s_add_u32 s26, s24, 0xfffc0080
	s_addc_u32 s27, s25, -1
	s_cmp_eq_u32 s81, 12
	s_cselect_b32 s29, s15, s27
	s_cselect_b32 s28, s21, s26
	s_cselect_b32 s27, s11, s80
	s_cselect_b32 s26, s78, s79
	v_lshl_add_u64 v[192:193], s[24:25], 0, v[178:179]
	s_add_i32 m0, s23, 0xc000
	ds_read_b128 v[160:163], v197
	ds_read_b128 v[164:167], v197 offset:1024
	ds_read_b128 v[184:187], v197 offset:2048
	ds_read_b128 v[188:191], v197 offset:3072
	ds_read_b128 v[200:203], v197 offset:4096
	ds_read_b128 v[204:207], v197 offset:5120
	ds_read_b128 v[208:211], v197 offset:6144
	ds_read_b128 v[212:215], v197 offset:7168
	global_load_lds_dwordx4 v[192:193], off
	v_lshl_add_u64 v[192:193], s[24:25], 0, v[176:177]
	s_add_i32 m0, s23, 0xe000
	s_nop 0
	global_load_lds_dwordx4 v[192:193], off
	s_cmp_lg_u32 s32, 0
	s_cbranch_scc1 .Lkw1a_b
	s_waitcnt vmcnt(8)
	s_branch .Lkw1a_d

; #define PG8_STAGE(bufoff, gbase, voff) do { _Pragma("unroll") for (int _i = 0; _i < 2; ++_i) \
;         __builtin_amdgcn_global_load_lds((const unsigned*)((const char*)(gbase) + (voff)[_i]), (LAS unsigned*)(lds + (bufoff) + ldsw + _i * 8192), 16, 0, 0); } while (0)
; #define PG8_LDA(dst, b, h) do { _Pragma("unroll") for (int m = 0; m < 4; ++m) _Pragma("unroll") for (int k = 0; k < 2; ++k) dst[m][k] = *(const LAS bf16x8*)(lds + PG8_SA(b, h) + aoff + m * 2048 + k * 1024); } while (0)
; #define PG8_LDB(dst, b, h) do { _Pragma("unroll") for (int n = 0; n < 2; ++n) _Pragma("unroll") for (int k = 0; k < 2; ++k) dst[n][k] = *(const LAS bf16x8*)(lds + PG8_SB(b, h) + boff + n * 2048 + k * 1024); } while (0)
; #define PG8_MMA(ai, bj, At, Bt) do { __builtin_amdgcn_s_setprio(1); _Pragma("unroll") for (int m = 0; m < 4; ++m) _Pragma("unroll") for (int n = 0; n < 2; ++n) _Pragma("unroll") for (int k = 0; k < 2; ++k) \
;         acc[ai][bj][m][n] = __builtin_amdgcn_mfma_f32_16x16x32_bf16(Bt[n][k], At[m][k], acc[ai][bj][m][n], 0, 0, 0); __builtin_amdgcn_s_setprio(0); } while (0)
; #define PG8_WAIT_V(n) asm volatile("s_waitcnt vmcnt(" #n ")" ::: "memory")
; #define PG8_WAIT_L(n) asm volatile("s_waitcnt lgkmcnt(" #n ")" ::: "memory")
; #define PG8_BAR __builtin_amdgcn_s_barrier()
; #define PG8_SCHED __builtin_amdgcn_sched_barrier(0)
; template <class Epi>
; __device__ __forceinline__ void gemm_phase(LAS unsigned char* lds, const Gemm g, const StaticOrder& S, const Epi& E, const int wid) {
;     ...
;             PG8_LDB(B0, 0, 0); PG8_LDB(B1, 0, 1); PG8_SCHED; PG8_LDA(At, 0, 0); PG8_STAGE(PG8_SA(1, 1), a1 + hsA, voffA);
;             PG8_WAIT_V(8); PG8_WAIT_L(0); PG8_BAR; PG8_MMA(0, 0, At, B0); PG8_MMA(0, 1, At, B1); PG8_BAR; PG8_SCHED;
;             PG8_LDA(At, 0, 1); PG8_STAGE(PG8_SB(0, 0), b2, voffB); PG8_STAGE(PG8_SB(0, 1), b2 + hsB, voffB); PG8_STAGE(PG8_SA(0, 0), a2, voffA);
.Lkw1a_d:
	s_waitcnt lgkmcnt(0)
	s_barrier
	s_setprio 1
	s_waitcnt lgkmcnt(0)
	v_mfma_f32_16x16x32_bf16 v[140:143], v[48:51], v[160:163], v[140:143]
	v_mfma_f32_16x16x32_bf16 v[136:139], v[64:67], v[160:163], v[136:139]
	v_mfma_f32_16x16x32_bf16 v[124:127], v[48:51], v[184:187], v[124:127]
	v_mfma_f32_16x16x32_bf16 v[120:123], v[64:67], v[184:187], v[120:123]
	v_mfma_f32_16x16x32_bf16 v[108:111], v[48:51], v[200:203], v[108:111]
	v_mfma_f32_16x16x32_bf16 v[104:107], v[64:67], v[200:203], v[104:107]
	v_mfma_f32_16x16x32_bf16 v[92:95], v[48:51], v[208:211], v[92:95]
	v_mfma_f32_16x16x32_bf16 v[88:91], v[64:67], v[208:211], v[88:91]
	v_mfma_f32_16x16x32_bf16 v[140:143], v[56:59], v[164:167], v[140:143]
	v_mfma_f32_16x16x32_bf16 v[136:139], v[68:71], v[164:167], v[136:139]
	v_mfma_f32_16x16x32_bf16 v[124:127], v[56:59], v[188:191], v[124:127]
	v_mfma_f32_16x16x32_bf16 v[120:123], v[68:71], v[188:191], v[120:123]
	v_mfma_f32_16x16x32_bf16 v[108:111], v[56:59], v[204:207], v[108:111]
	v_mfma_f32_16x16x32_bf16 v[104:107], v[68:71], v[204:207], v[104:107]
	v_mfma_f32_16x16x32_bf16 v[92:95], v[56:59], v[212:215], v[92:95]
	v_mfma_f32_16x16x32_bf16 v[88:91], v[68:71], v[212:215], v[88:91]
	s_setprio 0
	s_setprio 1
	v_mfma_f32_16x16x32_bf16 v[132:135], v[144:147], v[160:163], v[132:135]
	v_mfma_f32_16x16x32_bf16 v[128:131], v[152:155], v[160:163], v[128:131]
	v_mfma_f32_16x16x32_bf16 v[116:119], v[144:147], v[184:187], v[116:119]
	v_mfma_f32_16x16x32_bf16 v[112:115], v[152:155], v[184:187], v[112:115]
	v_mfma_f32_16x16x32_bf16 v[100:103], v[144:147], v[200:203], v[100:103]
	v_mfma_f32_16x16x32_bf16 v[96:99], v[152:155], v[200:203], v[96:99]
	v_mfma_f32_16x16x32_bf16 v[84:87], v[144:147], v[208:211], v[84:87]
	v_mfma_f32_16x16x32_bf16 v[80:83], v[152:155], v[208:211], v[80:83]
	v_mfma_f32_16x16x32_bf16 v[132:135], v[148:151], v[164:167], v[132:135]
	v_mfma_f32_16x16x32_bf16 v[128:131], v[156:159], v[164:167], v[128:131]
	v_mfma_f32_16x16x32_bf16 v[116:119], v[148:151], v[188:191], v[116:119]
	v_mfma_f32_16x16x32_bf16 v[112:115], v[156:159], v[188:191], v[112:115]
	v_mfma_f32_16x16x32_bf16 v[100:103], v[148:151], v[204:207], v[100:103]
	v_mfma_f32_16x16x32_bf16 v[96:99], v[156:159], v[204:207], v[96:99]
	v_mfma_f32_16x16x32_bf16 v[84:87], v[148:151], v[212:215], v[84:87]
	v_mfma_f32_16x16x32_bf16 v[80:83], v[156:159], v[212:215], v[80:83]
	s_setprio 0
	s_barrier
	s_add_i32 s47, s76, s68
	v_lshl_add_u64 v[192:193], s[26:27], 0, v[170:171]
	s_mov_b32 m0, s47
	ds_read_b128 v[160:163], v197 offset:16384
	ds_read_b128 v[164:167], v197 offset:17408
	ds_read_b128 v[184:187], v197 offset:18432
	ds_read_b128 v[188:191], v197 offset:19456
	ds_read_b128 v[200:203], v197 offset:20480
	ds_read_b128 v[204:207], v197 offset:21504
	ds_read_b128 v[208:211], v197 offset:22528
	ds_read_b128 v[212:215], v197 offset:23552
	global_load_lds_dwordx4 v[192:193], off
	s_add_i32 m0, s47, 0x2000
	s_add_u32 s50, s26, 0x40000
	v_lshl_add_u64 v[216:217], s[26:27], 0, v[174:175]
	s_addc_u32 s51, s27, 0
	s_add_i32 s47, s77, s68
	global_load_lds_dwordx4 v[216:217], off
	v_lshl_add_u64 v[218:219], s[50:51], 0, v[170:171]
	s_mov_b32 m0, s47
	v_lshl_add_u64 v[220:221], s[28:29], 0, v[172:173]
	global_load_lds_dwordx4 v[218:219], off
	v_lshl_add_u64 v[218:219], s[50:51], 0, v[174:175]
	s_add_i32 m0, s47, 0x2000
	s_nop 0
	global_load_lds_dwordx4 v[218:219], off
	v_lshl_add_u64 v[218:219], s[28:29], 0, v[168:169]
	s_mov_b32 m0, s23
	s_nop 0
	global_load_lds_dwordx4 v[218:219], off
	s_mov_b32 m0, s34
	s_nop 0
	global_load_lds_dwordx4 v[220:221], off
	s_cmp_lg_u32 s32, 0
	s_cbranch_scc1 .Lkw1b_b
	s_waitcnt vmcnt(8)
	s_branch .Lkw1b_d

; #define PG8_STAGE(bufoff, gbase, voff) do { _Pragma("unroll") for (int _i = 0; _i < 2; ++_i) \
;         __builtin_amdgcn_global_load_lds((const unsigned*)((const char*)(gbase) + (voff)[_i]), (LAS unsigned*)(lds + (bufoff) + ldsw + _i * 8192), 16, 0, 0); } while (0)
; #define PG8_LDA(dst, b, h) do { _Pragma("unroll") for (int m = 0; m < 4; ++m) _Pragma("unroll") for (int k = 0; k < 2; ++k) dst[m][k] = *(const LAS bf16x8*)(lds + PG8_SA(b, h) + aoff + m * 2048 + k * 1024); } while (0)
; #define PG8_LDB(dst, b, h) do { _Pragma("unroll") for (int n = 0; n < 2; ++n) _Pragma("unroll") for (int k = 0; k < 2; ++k) dst[n][k] = *(const LAS bf16x8*)(lds + PG8_SB(b, h) + boff + n * 2048 + k * 1024); } while (0)
; #define PG8_MMA(ai, bj, At, Bt) do { __builtin_amdgcn_s_setprio(1); _Pragma("unroll") for (int m = 0; m < 4; ++m) _Pragma("unroll") for (int n = 0; n < 2; ++n) _Pragma("unroll") for (int k = 0; k < 2; ++k) \
;         acc[ai][bj][m][n] = __builtin_amdgcn_mfma_f32_16x16x32_bf16(Bt[n][k], At[m][k], acc[ai][bj][m][n], 0, 0, 0); __builtin_amdgcn_s_setprio(0); } while (0)
; #define PG8_WAIT_V(n) asm volatile("s_waitcnt vmcnt(" #n ")" ::: "memory")
; #define PG8_WAIT_L(n) asm volatile("s_waitcnt lgkmcnt(" #n ")" ::: "memory")
; #define PG8_BAR __builtin_amdgcn_s_barrier()
; #define PG8_SCHED __builtin_amdgcn_sched_barrier(0)
; template <class Epi>
; __device__ __forceinline__ void gemm_phase(LAS unsigned char* lds, const Gemm g, const StaticOrder& S, const Epi& E, const int wid) {
;     ...
;             PG8_WAIT_V(8); PG8_WAIT_L(0); PG8_BAR; PG8_MMA(1, 0, At, B0); PG8_MMA(1, 1, At, B1); PG8_BAR; PG8_SCHED;
;             PG8_LDB(B0, 1, 0); PG8_LDB(B1, 1, 1); PG8_SCHED; PG8_LDA(At, 1, 0); PG8_STAGE(PG8_SA(0, 1), a2 + hsA, voffA);
;             PG8_WAIT_V(8); PG8_WAIT_L(0); PG8_BAR; PG8_MMA(0, 0, At, B0); PG8_MMA(0, 1, At, B1); PG8_BAR; PG8_SCHED;
.Lkw1b_d:
	s_mov_b32 s32, 0
	s_waitcnt lgkmcnt(0)
	s_barrier
	s_setprio 1
	s_waitcnt lgkmcnt(0)
	v_mfma_f32_16x16x32_bf16 v[76:79], v[48:51], v[160:163], v[76:79]
	v_mfma_f32_16x16x32_bf16 v[72:75], v[64:67], v[160:163], v[72:75]
	v_mfma_f32_16x16x32_bf16 v[44:47], v[48:51], v[184:187], v[44:47]
	v_mfma_f32_16x16x32_bf16 v[40:43], v[64:67], v[184:187], v[40:43]
	v_mfma_f32_16x16x32_bf16 v[28:31], v[48:51], v[200:203], v[28:31]
	v_mfma_f32_16x16x32_bf16 v[24:27], v[64:67], v[200:203], v[24:27]
	v_mfma_f32_16x16x32_bf16 v[12:15], v[48:51], v[208:211], v[12:15]
	v_mfma_f32_16x16x32_bf16 v[8:11], v[64:67], v[208:211], v[8:11]
	v_mfma_f32_16x16x32_bf16 v[76:79], v[56:59], v[164:167], v[76:79]
	v_mfma_f32_16x16x32_bf16 v[72:75], v[68:71], v[164:167], v[72:75]
	v_mfma_f32_16x16x32_bf16 v[44:47], v[56:59], v[188:191], v[44:47]
	v_mfma_f32_16x16x32_bf16 v[40:43], v[68:71], v[188:191], v[40:43]
	v_mfma_f32_16x16x32_bf16 v[28:31], v[56:59], v[204:207], v[28:31]
	v_mfma_f32_16x16x32_bf16 v[24:27], v[68:71], v[204:207], v[24:27]
	v_mfma_f32_16x16x32_bf16 v[12:15], v[56:59], v[212:215], v[12:15]
	v_mfma_f32_16x16x32_bf16 v[8:11], v[68:71], v[212:215], v[8:11]
	s_setprio 0
	s_setprio 1
	v_mfma_f32_16x16x32_bf16 v[52:55], v[152:155], v[160:163], v[52:55]
	v_mfma_f32_16x16x32_bf16 v[36:39], v[144:147], v[184:187], v[36:39]
	v_mfma_f32_16x16x32_bf16 v[32:35], v[152:155], v[184:187], v[32:35]
	v_mfma_f32_16x16x32_bf16 v[20:23], v[144:147], v[200:203], v[20:23]
	v_mfma_f32_16x16x32_bf16 v[16:19], v[152:155], v[200:203], v[16:19]
	v_mfma_f32_16x16x32_bf16 v[4:7], v[144:147], v[208:211], v[4:7]
	v_mfma_f32_16x16x32_bf16 v[0:3], v[152:155], v[208:211], v[0:3]
	v_mfma_f32_16x16x32_bf16 v[48:51], v[144:147], v[160:163], v[60:63]
	v_mfma_f32_16x16x32_bf16 v[52:55], v[156:159], v[164:167], v[52:55]
	v_mfma_f32_16x16x32_bf16 v[36:39], v[148:151], v[188:191], v[36:39]
	v_mfma_f32_16x16x32_bf16 v[32:35], v[156:159], v[188:191], v[32:35]
	v_mfma_f32_16x16x32_bf16 v[20:23], v[148:151], v[204:207], v[20:23]
	v_mfma_f32_16x16x32_bf16 v[16:19], v[156:159], v[204:207], v[16:19]
	v_mfma_f32_16x16x32_bf16 v[4:7], v[148:151], v[212:215], v[4:7]
	v_mfma_f32_16x16x32_bf16 v[0:3], v[156:159], v[212:215], v[0:3]
	v_mfma_f32_16x16x32_bf16 v[48:51], v[148:151], v[164:167], v[48:51]
	s_setprio 0
	s_barrier
	s_add_i32 s47, 0, 0x18000
	s_add_i32 s50, 0, 0x1c000
	v_add_u32_e32 v68, s47, v194
	v_add_u32_e32 v156, s50, v194
	ds_read_b128 v[56:59], v68
	ds_read_b128 v[60:63], v68 offset:1024
	ds_read_b128 v[64:67], v68 offset:2048
	ds_read_b128 v[68:71], v68 offset:3072
	ds_read_b128 v[144:147], v156
	ds_read_b128 v[148:151], v156 offset:1024
	ds_read_b128 v[152:155], v156 offset:2048
	ds_read_b128 v[156:159], v156 offset:3072
	s_add_u32 s28, s28, 0x40000
	s_addc_u32 s29, s29, 0
	s_mov_b32 m0, s35
	v_lshl_add_u64 v[222:223], s[28:29], 0, v[168:169]
	ds_read_b128 v[160:163], v197 offset:32768
	ds_read_b128 v[164:167], v197 offset:33792
	ds_read_b128 v[184:187], v197 offset:34816
	ds_read_b128 v[188:191], v197 offset:35840
	ds_read_b128 v[200:203], v197 offset:36864
	ds_read_b128 v[204:207], v197 offset:37888
	ds_read_b128 v[208:211], v197 offset:38912
	ds_read_b128 v[212:215], v197 offset:39936
	global_load_lds_dwordx4 v[222:223], off
	v_lshl_add_u64 v[222:223], s[28:29], 0, v[172:173]
	s_mov_b32 m0, s62
	s_nop 0
	global_load_lds_dwordx4 v[222:223], off
	s_waitcnt vmcnt(8)
	s_waitcnt lgkmcnt(0)
	s_barrier
	s_setprio 1
	s_waitcnt lgkmcnt(0)
	v_mfma_f32_16x16x32_bf16 v[140:143], v[56:59], v[160:163], v[140:143]
	v_mfma_f32_16x16x32_bf16 v[136:139], v[64:67], v[160:163], v[136:139]
	v_mfma_f32_16x16x32_bf16 v[124:127], v[56:59], v[184:187], v[124:127]
	v_mfma_f32_16x16x32_bf16 v[120:123], v[64:67], v[184:187], v[120:123]
	v_mfma_f32_16x16x32_bf16 v[108:111], v[56:59], v[200:203], v[108:111]
	v_mfma_f32_16x16x32_bf16 v[104:107], v[64:67], v[200:203], v[104:107]
	v_mfma_f32_16x16x32_bf16 v[92:95], v[56:59], v[208:211], v[92:95]
	v_mfma_f32_16x16x32_bf16 v[88:91], v[64:67], v[208:211], v[88:91]
	v_mfma_f32_16x16x32_bf16 v[140:143], v[60:63], v[164:167], v[140:143]
	v_mfma_f32_16x16x32_bf16 v[136:139], v[68:71], v[164:167], v[136:139]
	v_mfma_f32_16x16x32_bf16 v[124:127], v[60:63], v[188:191], v[124:127]
	v_mfma_f32_16x16x32_bf16 v[120:123], v[68:71], v[188:191], v[120:123]
	v_mfma_f32_16x16x32_bf16 v[108:111], v[60:63], v[204:207], v[108:111]
	v_mfma_f32_16x16x32_bf16 v[104:107], v[68:71], v[204:207], v[104:107]
	v_mfma_f32_16x16x32_bf16 v[92:95], v[60:63], v[212:215], v[92:95]
	v_mfma_f32_16x16x32_bf16 v[88:91], v[68:71], v[212:215], v[88:91]
	s_setprio 0
	s_setprio 1
	v_mfma_f32_16x16x32_bf16 v[132:135], v[144:147], v[160:163], v[132:135]
	v_mfma_f32_16x16x32_bf16 v[128:131], v[152:155], v[160:163], v[128:131]
	v_mfma_f32_16x16x32_bf16 v[116:119], v[144:147], v[184:187], v[116:119]
	v_mfma_f32_16x16x32_bf16 v[112:115], v[152:155], v[184:187], v[112:115]
	v_mfma_f32_16x16x32_bf16 v[100:103], v[144:147], v[200:203], v[100:103]
	v_mfma_f32_16x16x32_bf16 v[96:99], v[152:155], v[200:203], v[96:99]
	v_mfma_f32_16x16x32_bf16 v[84:87], v[144:147], v[208:211], v[84:87]
	v_mfma_f32_16x16x32_bf16 v[80:83], v[152:155], v[208:211], v[80:83]
	v_mfma_f32_16x16x32_bf16 v[132:135], v[148:151], v[164:167], v[132:135]
	v_mfma_f32_16x16x32_bf16 v[128:131], v[156:159], v[164:167], v[128:131]
	v_mfma_f32_16x16x32_bf16 v[116:119], v[148:151], v[188:191], v[116:119]
	v_mfma_f32_16x16x32_bf16 v[112:115], v[156:159], v[188:191], v[112:115]
	v_mfma_f32_16x16x32_bf16 v[100:103], v[148:151], v[204:207], v[100:103]
	v_mfma_f32_16x16x32_bf16 v[96:99], v[156:159], v[204:207], v[96:99]
	v_mfma_f32_16x16x32_bf16 v[84:87], v[148:151], v[212:215], v[84:87]
	v_mfma_f32_16x16x32_bf16 v[80:83], v[156:159], v[212:215], v[80:83]
	s_setprio 0
	s_barrier
; #define PG8_STAGE(bufoff, gbase, voff) do { _Pragma("unroll") for (int _i = 0; _i < 2; ++_i) \
;         __builtin_amdgcn_global_load_lds((const unsigned*)((const char*)(gbase) + (voff)[_i]), (LAS unsigned*)(lds + (bufoff) + ldsw + _i * 8192), 16, 0, 0); } while (0)
; #define PG8_LDA(dst, b, h) do { _Pragma("unroll") for (int m = 0; m < 4; ++m) _Pragma("unroll") for (int k = 0; k < 2; ++k) dst[m][k] = *(const LAS bf16x8*)(lds + PG8_SA(b, h) + aoff + m * 2048 + k * 1024); } while (0)
; #define PG8_MMA(ai, bj, At, Bt) do { __builtin_amdgcn_s_setprio(1); _Pragma("unroll") for (int m = 0; m < 4; ++m) _Pragma("unroll") for (int n = 0; n < 2; ++n) _Pragma("unroll") for (int k = 0; k < 2; ++k) \
;         acc[ai][bj][m][n] = __builtin_amdgcn_mfma_f32_16x16x32_bf16(Bt[n][k], At[m][k], acc[ai][bj][m][n], 0, 0, 0); __builtin_amdgcn_s_setprio(0); } while (0)
; #define PG8_WAIT_V(n) asm volatile("s_waitcnt vmcnt(" #n ")" ::: "memory")
; #define PG8_WAIT_L(n) asm volatile("s_waitcnt lgkmcnt(" #n ")" ::: "memory")
; #define PG8_BAR __builtin_amdgcn_s_barrier()
; #define PG8_SCHED __builtin_amdgcn_sched_barrier(0)
; template <class Epi>
; __device__ __forceinline__ void gemm_phase(LAS unsigned char* lds, const Gemm g, const StaticOrder& S, const Epi& E, const int wid) {
;     ...
;             PG8_LDA(At, 1, 1); PG8_STAGE(PG8_SB(1, 0), b3, voffB); PG8_STAGE(PG8_SB(1, 1), b3 + hsB, voffB); PG8_STAGE(PG8_SA(1, 0), a3, voffA);
;             PG8_WAIT_V(8); PG8_WAIT_L(0); PG8_BAR; PG8_MMA(1, 0, At, B0); PG8_MMA(1, 1, At, B1); PG8_BAR; PG8_SCHED;
;         }
;         if (wr == 0) PG8_BAR;
;         E(acc, cur, wid);
;         if (!has_next) break;
	s_add_i32 s28, s47, s68
	v_lshl_add_u64 v[192:193], v[192:193], 0, s[6:7]
	s_mov_b32 m0, s28
	ds_read_b128 v[160:163], v197 offset:49152
	ds_read_b128 v[164:167], v197 offset:50176
	ds_read_b128 v[184:187], v197 offset:51200
	ds_read_b128 v[188:191], v197 offset:52224
	ds_read_b128 v[200:203], v197 offset:53248
	ds_read_b128 v[204:207], v197 offset:54272
	ds_read_b128 v[208:211], v197 offset:55296
	ds_read_b128 v[212:215], v197 offset:56320
	global_load_lds_dwordx4 v[192:193], off
	s_add_i32 m0, s28, 0x2000
	s_add_u32 s26, s26, 0x40080
	v_lshl_add_u64 v[192:193], v[216:217], 0, s[6:7]
	s_addc_u32 s27, s27, 0
	s_add_i32 s28, s50, s68
	global_load_lds_dwordx4 v[192:193], off
	v_lshl_add_u64 v[192:193], s[26:27], 0, v[170:171]
	s_mov_b32 m0, s28
	s_nop 0
	global_load_lds_dwordx4 v[192:193], off
	v_lshl_add_u64 v[192:193], s[26:27], 0, v[174:175]
	s_add_i32 m0, s28, 0x2000
	s_nop 0
	global_load_lds_dwordx4 v[192:193], off
	v_lshl_add_u64 v[192:193], v[218:219], 0, s[6:7]
	s_mov_b32 m0, s64
	s_nop 0
	global_load_lds_dwordx4 v[192:193], off
	v_lshl_add_u64 v[192:193], v[220:221], 0, s[6:7]
	s_mov_b32 m0, s65
	s_nop 0
	global_load_lds_dwordx4 v[192:193], off
	s_waitcnt vmcnt(8)
	s_waitcnt lgkmcnt(0)
	s_barrier
	s_setprio 1
	s_waitcnt lgkmcnt(0)
	v_mfma_f32_16x16x32_bf16 v[76:79], v[56:59], v[160:163], v[76:79]
	v_mfma_f32_16x16x32_bf16 v[72:75], v[64:67], v[160:163], v[72:75]
	v_mfma_f32_16x16x32_bf16 v[44:47], v[56:59], v[184:187], v[44:47]
	v_mfma_f32_16x16x32_bf16 v[40:43], v[64:67], v[184:187], v[40:43]
	v_mfma_f32_16x16x32_bf16 v[28:31], v[56:59], v[200:203], v[28:31]
	v_mfma_f32_16x16x32_bf16 v[24:27], v[64:67], v[200:203], v[24:27]
	v_mfma_f32_16x16x32_bf16 v[12:15], v[56:59], v[208:211], v[12:15]
	v_mfma_f32_16x16x32_bf16 v[8:11], v[64:67], v[208:211], v[8:11]
	v_mfma_f32_16x16x32_bf16 v[76:79], v[60:63], v[164:167], v[76:79]
	v_mfma_f32_16x16x32_bf16 v[72:75], v[68:71], v[164:167], v[72:75]
	v_mfma_f32_16x16x32_bf16 v[44:47], v[60:63], v[188:191], v[44:47]
	v_mfma_f32_16x16x32_bf16 v[40:43], v[68:71], v[188:191], v[40:43]
	v_mfma_f32_16x16x32_bf16 v[28:31], v[60:63], v[204:207], v[28:31]
	v_mfma_f32_16x16x32_bf16 v[24:27], v[68:71], v[204:207], v[24:27]
	v_mfma_f32_16x16x32_bf16 v[12:15], v[60:63], v[212:215], v[12:15]
	v_mfma_f32_16x16x32_bf16 v[8:11], v[68:71], v[212:215], v[8:11]
	s_setprio 0
	s_setprio 1
	v_mfma_f32_16x16x32_bf16 v[48:51], v[144:147], v[160:163], v[48:51]
	v_mfma_f32_16x16x32_bf16 v[60:63], v[148:151], v[164:167], v[48:51]
	v_mfma_f32_16x16x32_bf16 v[48:51], v[152:155], v[160:163], v[52:55]
	v_mfma_f32_16x16x32_bf16 v[36:39], v[144:147], v[184:187], v[36:39]
	v_mfma_f32_16x16x32_bf16 v[32:35], v[152:155], v[184:187], v[32:35]
	v_mfma_f32_16x16x32_bf16 v[20:23], v[144:147], v[200:203], v[20:23]
	v_mfma_f32_16x16x32_bf16 v[16:19], v[152:155], v[200:203], v[16:19]
	v_mfma_f32_16x16x32_bf16 v[4:7], v[144:147], v[208:211], v[4:7]
	v_mfma_f32_16x16x32_bf16 v[0:3], v[152:155], v[208:211], v[0:3]
	v_mfma_f32_16x16x32_bf16 v[52:55], v[156:159], v[164:167], v[48:51]
	v_mfma_f32_16x16x32_bf16 v[36:39], v[148:151], v[188:191], v[36:39]
	v_mfma_f32_16x16x32_bf16 v[32:35], v[156:159], v[188:191], v[32:35]
	v_mfma_f32_16x16x32_bf16 v[20:23], v[148:151], v[204:207], v[20:23]
	v_mfma_f32_16x16x32_bf16 v[16:19], v[156:159], v[204:207], v[16:19]
	v_mfma_f32_16x16x32_bf16 v[4:7], v[148:151], v[212:215], v[4:7]
	v_mfma_f32_16x16x32_bf16 v[0:3], v[156:159], v[212:215], v[0:3]
	s_setprio 0
	s_barrier
	s_add_i32 s81, s81, 2
	s_add_u32 s79, s79, 0x100
	s_addc_u32 s80, s80, 0
	s_add_u32 s24, s24, 0x100
	s_addc_u32 s25, s25, 0
	s_cmp_gt_u32 s81, 13
	s_cbranch_scc0 .LBB0_331
	s_mov_b32 s32, 1
	s_and_b64 vcc, exec, s[8:9]
	s_cbranch_vccz .LBB0_334
	s_barrier

; #define PG8_STAGE(bufoff, gbase, voff) do { _Pragma("unroll") for (int _i = 0; _i < 2; ++_i) \
;         __builtin_amdgcn_global_load_lds((const unsigned*)((const char*)(gbase) + (voff)[_i]), (LAS unsigned*)(lds + (bufoff) + ldsw + _i * 8192), 16, 0, 0); } while (0)
; #define PG8_WAIT_V(n) asm volatile("s_waitcnt vmcnt(" #n ")" ::: "memory")
; #define PG8_BAR __builtin_amdgcn_s_barrier()
; template <class Epi>
; __device__ __forceinline__ void gemm_phase(LAS unsigned char* lds, const Gemm g, const StaticOrder& S, const Epi& E, const int wid) {
;     ...
;     for (int i = 0; i < 2; ++i) { int R, C; stage_rc(tid * 16 + i * 8192, R, C); const int Rb = Epi::PERM ? ((R & ~31) + perm32(R & 31)) : R;
;         voffA[i] = (unsigned)(R * lda + C) * 2u; voffB[i] = (unsigned)(Rb * K + C) * 2u; }
;     const size_t kstep = (size_t)(BK * 2);
;     const size_t hsA = (size_t)HALF * lda * 2, hsB = (size_t)HALF * K * 2;
;     const size_t tsA = 2 * hsA, tsB = 2 * hsB;
;     const unsigned ldsw = (unsigned)wid * 1024u;
;     const int aoff = lds_byte(wr * 64 + fr, fq * 8), boff = lds_byte(wc * 32 + fr, fq * 8);
;     ...
;     PG8_STAGE(PG8_SB(0, 0), cB, voffB); PG8_STAGE(PG8_SB(0, 1), cB + hsB, voffB); PG8_STAGE(PG8_SA(0, 0), cA, voffA); PG8_STAGE(PG8_SA(0, 1), cA + hsA, voffA);
;     if (wr == 1) PG8_BAR;
;     PG8_WAIT_V(2); PG8_BAR;
;     PG8_STAGE(PG8_SB(1, 0), cB + kstep, voffB); PG8_STAGE(PG8_SA(1, 0), cA + kstep, voffA); PG8_STAGE(PG8_SB(1, 1), cB + hsB + kstep, voffB);
;     PG8_WAIT_V(6); PG8_BAR;
.LBB0_391:
	s_mov_b64 s[8:9], 0x80
	s_add_i32 m0, s25, 0x18000
	v_lshl_add_u64 v[6:7], v[6:7], 0, s[8:9]
	global_load_lds_dwordx4 v[6:7], off
	v_lshl_add_u64 v[4:5], v[4:5], 0, s[8:9]
	s_add_i32 m0, s25, 0x1a000
	s_add_i32 s64, s25, 0x8000
	s_add_i32 s65, s25, 0xa000
	global_load_lds_dwordx4 v[4:5], off
	v_lshl_add_u64 v[0:1], v[0:1], 0, s[8:9]
	s_mov_b32 m0, s64
	s_add_u32 s4, s26, 0x80080
	global_load_lds_dwordx4 v[0:1], off
	v_lshl_add_u64 v[0:1], v[2:3], 0, s[8:9]
	s_mov_b32 m0, s65
	s_addc_u32 s5, s27, 0
	global_load_lds_dwordx4 v[0:1], off
	s_add_i32 m0, s25, 0x1c000
	v_lshl_add_u64 v[0:1], s[4:5], 0, v[194:195]
	global_load_lds_dwordx4 v[0:1], off
	v_lshl_add_u64 v[0:1], s[4:5], 0, v[198:199]
	s_add_i32 m0, s25, 0x1e000
	v_and_b32_e32 v2, 48, v8
	global_load_lds_dwordx4 v[0:1], off
	s_waitcnt vmcnt(8)
	s_barrier
	v_and_b32_e32 v0, 15, v8
	v_ashrrev_i32_e32 v1, 6, v8
	v_readlane_b32 s1, v254, 3
	v_lshl_or_b32 v0, v0, 6, v2
	v_lshlrev_b32_e32 v3, 2, v8
	v_lshl_add_u32 v2, v1, 10, s1
	v_readlane_b32 s1, v254, 5
	v_and_b32_e32 v3, 32, v3
	v_bitop3_b32 v2, v0, v2, v3 bitop3:0xde
	v_add_lshl_u32 v1, v1, s1, 10
	v_bitop3_b32 v245, v0, v1, v3 bitop3:0xde
	v_lshlrev_b32_e32 v0, 15, v12
	v_and_b32_e32 v0, 0xffff0000, v0
	v_lshl_add_u32 v0, v13, 12, v0
	v_and_b32_e32 v1, 1, v12
	v_lshl_or_b32 v0, v1, 6, v0
	v_lshl_add_u32 v200, v14, 1, v0
	v_lshlrev_b32_e32 v0, 15, v9
	v_and_b32_e32 v0, 0xffff0000, v0
	s_waitcnt vmcnt(6)
	s_mov_b32 s32, 0
	s_cmpk_lt_u32 s3, 0x100
	v_lshl_add_u32 v0, v10, 12, v0
	v_and_b32_e32 v1, 1, v9
	s_cselect_b64 s[10:11], -1, 0
	s_lshl_b32 s1, s33, 4
	v_lshl_or_b32 v0, v1, 6, v0
	s_add_i32 s76, 0, 0x10000
	s_add_i32 s77, 0, 0x14000
	s_and_b32 s66, s1, 0x3fffffc0
	s_ashr_i32 s67, s56, 31
	s_mov_b32 s74, s56
	s_ashr_i32 s75, s2, 31
	v_mov_b32_e32 v201, v195
	v_lshl_add_u32 v202, v11, 1, v0
	v_mov_b32_e32 v203, v195
	v_mov_b64_e32 v[204:205], 0x200
	v_mov_b64_e32 v[206:207], 0x1ff
	v_add_u32_e32 v246, s76, v245
	v_add_u32_e32 v247, s77, v245
	v_add_u32_e32 v248, 0, v2
	v_mbcnt_hi_u32_b32 v249, -1, v244
	s_barrier
	s_branch .LBB0_394

; #define PG8_STAGE(bufoff, gbase, voff) do { _Pragma("unroll") for (int _i = 0; _i < 2; ++_i) \
;         __builtin_amdgcn_global_load_lds((const unsigned*)((const char*)(gbase) + (voff)[_i]), (LAS unsigned*)(lds + (bufoff) + ldsw + _i * 8192), 16, 0, 0); } while (0)
; #define PG8_LDA(dst, b, h) do { _Pragma("unroll") for (int m = 0; m < 4; ++m) _Pragma("unroll") for (int k = 0; k < 2; ++k) dst[m][k] = *(const LAS bf16x8*)(lds + PG8_SA(b, h) + aoff + m * 2048 + k * 1024); } while (0)
; #define PG8_LDB(dst, b, h) do { _Pragma("unroll") for (int n = 0; n < 2; ++n) _Pragma("unroll") for (int k = 0; k < 2; ++k) dst[n][k] = *(const LAS bf16x8*)(lds + PG8_SB(b, h) + boff + n * 2048 + k * 1024); } while (0)
; #define PG8_MMA(ai, bj, At, Bt) do { __builtin_amdgcn_s_setprio(1); _Pragma("unroll") for (int m = 0; m < 4; ++m) _Pragma("unroll") for (int n = 0; n < 2; ++n) _Pragma("unroll") for (int k = 0; k < 2; ++k) \
;         acc[ai][bj][m][n] = __builtin_amdgcn_mfma_f32_16x16x32_bf16(Bt[n][k], At[m][k], acc[ai][bj][m][n], 0, 0, 0); __builtin_amdgcn_s_setprio(0); } while (0)
; #define PG8_WAIT_V(n) asm volatile("s_waitcnt vmcnt(" #n ")" ::: "memory")
; #define PG8_WAIT_L(n) asm volatile("s_waitcnt lgkmcnt(" #n ")" ::: "memory")
; #define PG8_BAR __builtin_amdgcn_s_barrier()
; #define PG8_SCHED __builtin_amdgcn_sched_barrier(0)
; template <class Epi>
; __device__ __forceinline__ void gemm_phase(LAS unsigned char* lds, const Gemm g, const StaticOrder& S, const Epi& E, const int wid) {
;     ...
;             PG8_LDB(B0, 0, 0); PG8_LDB(B1, 0, 1); PG8_SCHED; PG8_LDA(At, 0, 0); PG8_STAGE(PG8_SA(1, 1), a1 + hsA, voffA);
;             PG8_WAIT_V(8); PG8_WAIT_L(0); PG8_BAR; PG8_MMA(0, 0, At, B0); PG8_MMA(0, 1, At, B1); PG8_BAR; PG8_SCHED;
.LBB0_401:
	ds_read_b128 v[120:123], v246
	ds_read_b128 v[124:127], v246 offset:1024
	ds_read_b128 v[132:135], v246 offset:2048
	ds_read_b128 v[136:139], v246 offset:3072
	ds_read_b128 v[144:147], v247
	ds_read_b128 v[148:151], v247 offset:1024
	ds_read_b128 v[152:155], v247 offset:2048
	ds_read_b128 v[156:159], v247 offset:3072
	s_add_u32 s28, s26, 0xfff80080
	s_addc_u32 s29, s27, -1
	s_cmp_eq_u32 s81, 28
	s_cselect_b32 s31, s1, s29
	s_cselect_b32 s30, s19, s28
	s_cselect_b32 s29, s17, s80
	s_cselect_b32 s28, s78, s79
	v_lshl_add_u64 v[208:209], s[26:27], 0, v[202:203]
	s_add_i32 m0, s25, 0xc000
	ds_read_b128 v[160:163], v248
	ds_read_b128 v[164:167], v248 offset:1024
	ds_read_b128 v[168:171], v248 offset:2048
	ds_read_b128 v[172:175], v248 offset:3072
	ds_read_b128 v[176:179], v248 offset:4096
	ds_read_b128 v[180:183], v248 offset:5120
	ds_read_b128 v[184:187], v248 offset:6144
	ds_read_b128 v[188:191], v248 offset:7168
	global_load_lds_dwordx4 v[208:209], off
	v_lshl_add_u64 v[208:209], s[26:27], 0, v[200:201]
	s_add_i32 m0, s25, 0xe000
	s_nop 0
	global_load_lds_dwordx4 v[208:209], off
	s_cmp_lg_u32 s32, 0
	s_cbranch_scc1 .Lkw2a_b
	s_waitcnt vmcnt(8)
	s_branch .Lkw2a_d

; #define PG8_STAGE(bufoff, gbase, voff) do { _Pragma("unroll") for (int _i = 0; _i < 2; ++_i) \
;         __builtin_amdgcn_global_load_lds((const unsigned*)((const char*)(gbase) + (voff)[_i]), (LAS unsigned*)(lds + (bufoff) + ldsw + _i * 8192), 16, 0, 0); } while (0)
; #define PG8_LDA(dst, b, h) do { _Pragma("unroll") for (int m = 0; m < 4; ++m) _Pragma("unroll") for (int k = 0; k < 2; ++k) dst[m][k] = *(const LAS bf16x8*)(lds + PG8_SA(b, h) + aoff + m * 2048 + k * 1024); } while (0)
; #define PG8_LDB(dst, b, h) do { _Pragma("unroll") for (int n = 0; n < 2; ++n) _Pragma("unroll") for (int k = 0; k < 2; ++k) dst[n][k] = *(const LAS bf16x8*)(lds + PG8_SB(b, h) + boff + n * 2048 + k * 1024); } while (0)
; #define PG8_MMA(ai, bj, At, Bt) do { __builtin_amdgcn_s_setprio(1); _Pragma("unroll") for (int m = 0; m < 4; ++m) _Pragma("unroll") for (int n = 0; n < 2; ++n) _Pragma("unroll") for (int k = 0; k < 2; ++k) \
;         acc[ai][bj][m][n] = __builtin_amdgcn_mfma_f32_16x16x32_bf16(Bt[n][k], At[m][k], acc[ai][bj][m][n], 0, 0, 0); __builtin_amdgcn_s_setprio(0); } while (0)
; #define PG8_WAIT_V(n) asm volatile("s_waitcnt vmcnt(" #n ")" ::: "memory")
; #define PG8_WAIT_L(n) asm volatile("s_waitcnt lgkmcnt(" #n ")" ::: "memory")
; #define PG8_BAR __builtin_amdgcn_s_barrier()
; #define PG8_SCHED __builtin_amdgcn_sched_barrier(0)
; template <class Epi>
; __device__ __forceinline__ void gemm_phase(LAS unsigned char* lds, const Gemm g, const StaticOrder& S, const Epi& E, const int wid) {
;     ...
;             PG8_LDB(B0, 0, 0); PG8_LDB(B1, 0, 1); PG8_SCHED; PG8_LDA(At, 0, 0); PG8_STAGE(PG8_SA(1, 1), a1 + hsA, voffA);
;             PG8_WAIT_V(8); PG8_WAIT_L(0); PG8_BAR; PG8_MMA(0, 0, At, B0); PG8_MMA(0, 1, At, B1); PG8_BAR; PG8_SCHED;
;             PG8_LDA(At, 0, 1); PG8_STAGE(PG8_SB(0, 0), b2, voffB); PG8_STAGE(PG8_SB(0, 1), b2 + hsB, voffB); PG8_STAGE(PG8_SA(0, 0), a2, voffA);
.Lkw2a_d:
	s_waitcnt lgkmcnt(0)
	s_barrier
	s_setprio 1
	s_waitcnt lgkmcnt(0)
	v_mfma_f32_16x16x32_bf16 v[140:143], v[120:123], v[160:163], v[140:143]
	v_mfma_f32_16x16x32_bf16 v[128:131], v[132:135], v[160:163], v[128:131]
	v_mfma_f32_16x16x32_bf16 v[108:111], v[120:123], v[168:171], v[108:111]
	v_mfma_f32_16x16x32_bf16 v[104:107], v[132:135], v[168:171], v[104:107]
	v_mfma_f32_16x16x32_bf16 v[92:95], v[120:123], v[176:179], v[92:95]
	v_mfma_f32_16x16x32_bf16 v[88:91], v[132:135], v[176:179], v[88:91]
	v_mfma_f32_16x16x32_bf16 v[76:79], v[120:123], v[184:187], v[76:79]
	v_mfma_f32_16x16x32_bf16 v[72:75], v[132:135], v[184:187], v[72:75]
	v_mfma_f32_16x16x32_bf16 v[140:143], v[124:127], v[164:167], v[140:143]
	v_mfma_f32_16x16x32_bf16 v[128:131], v[136:139], v[164:167], v[128:131]
	v_mfma_f32_16x16x32_bf16 v[108:111], v[124:127], v[172:175], v[108:111]
	v_mfma_f32_16x16x32_bf16 v[104:107], v[136:139], v[172:175], v[104:107]
	v_mfma_f32_16x16x32_bf16 v[92:95], v[124:127], v[180:183], v[92:95]
	v_mfma_f32_16x16x32_bf16 v[88:91], v[136:139], v[180:183], v[88:91]
	v_mfma_f32_16x16x32_bf16 v[76:79], v[124:127], v[188:191], v[76:79]
	v_mfma_f32_16x16x32_bf16 v[72:75], v[136:139], v[188:191], v[72:75]
	s_setprio 0
	s_setprio 1
	v_mfma_f32_16x16x32_bf16 v[116:119], v[144:147], v[160:163], v[116:119]
	v_mfma_f32_16x16x32_bf16 v[112:115], v[152:155], v[160:163], v[112:115]
	v_mfma_f32_16x16x32_bf16 v[100:103], v[144:147], v[168:171], v[100:103]
	v_mfma_f32_16x16x32_bf16 v[96:99], v[152:155], v[168:171], v[96:99]
	v_mfma_f32_16x16x32_bf16 v[84:87], v[144:147], v[176:179], v[84:87]
	v_mfma_f32_16x16x32_bf16 v[80:83], v[152:155], v[176:179], v[80:83]
	v_mfma_f32_16x16x32_bf16 v[68:71], v[144:147], v[184:187], v[68:71]
	v_mfma_f32_16x16x32_bf16 v[64:67], v[152:155], v[184:187], v[64:67]
	v_mfma_f32_16x16x32_bf16 v[116:119], v[148:151], v[164:167], v[116:119]
	v_mfma_f32_16x16x32_bf16 v[112:115], v[156:159], v[164:167], v[112:115]
	v_mfma_f32_16x16x32_bf16 v[100:103], v[148:151], v[172:175], v[100:103]
	v_mfma_f32_16x16x32_bf16 v[96:99], v[156:159], v[172:175], v[96:99]
	v_mfma_f32_16x16x32_bf16 v[84:87], v[148:151], v[180:183], v[84:87]
	v_mfma_f32_16x16x32_bf16 v[80:83], v[156:159], v[180:183], v[80:83]
	v_mfma_f32_16x16x32_bf16 v[68:71], v[148:151], v[188:191], v[68:71]
	v_mfma_f32_16x16x32_bf16 v[64:67], v[156:159], v[188:191], v[64:67]
	s_setprio 0
	s_barrier
	s_add_i32 s47, s76, s68
	v_lshl_add_u64 v[208:209], s[28:29], 0, v[194:195]
	s_mov_b32 m0, s47
	ds_read_b128 v[160:163], v248 offset:16384
	ds_read_b128 v[164:167], v248 offset:17408
	ds_read_b128 v[168:171], v248 offset:18432
	ds_read_b128 v[172:175], v248 offset:19456
	ds_read_b128 v[176:179], v248 offset:20480
	ds_read_b128 v[180:183], v248 offset:21504
	ds_read_b128 v[184:187], v248 offset:22528
	ds_read_b128 v[188:191], v248 offset:23552
	global_load_lds_dwordx4 v[208:209], off
	s_add_i32 m0, s47, 0x2000
	s_add_u32 s50, s28, 0x80000
	v_lshl_add_u64 v[210:211], s[28:29], 0, v[198:199]
	s_addc_u32 s51, s29, 0
	s_add_i32 s47, s77, s68
	global_load_lds_dwordx4 v[210:211], off
	v_lshl_add_u64 v[212:213], s[50:51], 0, v[194:195]
	s_mov_b32 m0, s47
	v_lshl_add_u64 v[214:215], s[30:31], 0, v[196:197]
	global_load_lds_dwordx4 v[212:213], off
	v_lshl_add_u64 v[212:213], s[50:51], 0, v[198:199]
	s_add_i32 m0, s47, 0x2000
	s_nop 0
	global_load_lds_dwordx4 v[212:213], off
	v_lshl_add_u64 v[212:213], s[30:31], 0, v[192:193]
	s_mov_b32 m0, s25
	s_nop 0
	global_load_lds_dwordx4 v[212:213], off
	s_mov_b32 m0, s60
	s_nop 0
	global_load_lds_dwordx4 v[214:215], off
	s_cmp_lg_u32 s32, 0
	s_cbranch_scc1 .Lkw2b_b
	s_waitcnt vmcnt(8)
	s_branch .Lkw2b_d

; #define PG8_STAGE(bufoff, gbase, voff) do { _Pragma("unroll") for (int _i = 0; _i < 2; ++_i) \
;         __builtin_amdgcn_global_load_lds((const unsigned*)((const char*)(gbase) + (voff)[_i]), (LAS unsigned*)(lds + (bufoff) + ldsw + _i * 8192), 16, 0, 0); } while (0)
; #define PG8_LDA(dst, b, h) do { _Pragma("unroll") for (int m = 0; m < 4; ++m) _Pragma("unroll") for (int k = 0; k < 2; ++k) dst[m][k] = *(const LAS bf16x8*)(lds + PG8_SA(b, h) + aoff + m * 2048 + k * 1024); } while (0)
; #define PG8_LDB(dst, b, h) do { _Pragma("unroll") for (int n = 0; n < 2; ++n) _Pragma("unroll") for (int k = 0; k < 2; ++k) dst[n][k] = *(const LAS bf16x8*)(lds + PG8_SB(b, h) + boff + n * 2048 + k * 1024); } while (0)
; #define PG8_MMA(ai, bj, At, Bt) do { __builtin_amdgcn_s_setprio(1); _Pragma("unroll") for (int m = 0; m < 4; ++m) _Pragma("unroll") for (int n = 0; n < 2; ++n) _Pragma("unroll") for (int k = 0; k < 2; ++k) \
;         acc[ai][bj][m][n] = __builtin_amdgcn_mfma_f32_16x16x32_bf16(Bt[n][k], At[m][k], acc[ai][bj][m][n], 0, 0, 0); __builtin_amdgcn_s_setprio(0); } while (0)
; #define PG8_WAIT_V(n) asm volatile("s_waitcnt vmcnt(" #n ")" ::: "memory")
; #define PG8_WAIT_L(n) asm volatile("s_waitcnt lgkmcnt(" #n ")" ::: "memory")
; #define PG8_BAR __builtin_amdgcn_s_barrier()
; #define PG8_SCHED __builtin_amdgcn_sched_barrier(0)
; template <class Epi>
; __device__ __forceinline__ void gemm_phase(LAS unsigned char* lds, const Gemm g, const StaticOrder& S, const Epi& E, const int wid) {
;     ...
;             PG8_WAIT_V(8); PG8_WAIT_L(0); PG8_BAR; PG8_MMA(1, 0, At, B0); PG8_MMA(1, 1, At, B1); PG8_BAR; PG8_SCHED;
;             PG8_LDB(B0, 1, 0); PG8_LDB(B1, 1, 1); PG8_SCHED; PG8_LDA(At, 1, 0); PG8_STAGE(PG8_SA(0, 1), a2 + hsA, voffA);
;             PG8_WAIT_V(8); PG8_WAIT_L(0); PG8_BAR; PG8_MMA(0, 0, At, B0); PG8_MMA(0, 1, At, B1); PG8_BAR; PG8_SCHED;
.Lkw2b_d:
	s_mov_b32 s32, 0
	s_waitcnt lgkmcnt(0)
	s_barrier
	s_setprio 1
	s_waitcnt lgkmcnt(0)
	v_mfma_f32_16x16x32_bf16 v[60:63], v[120:123], v[160:163], v[60:63]
	v_mfma_f32_16x16x32_bf16 v[56:59], v[132:135], v[160:163], v[56:59]
	v_mfma_f32_16x16x32_bf16 v[44:47], v[120:123], v[168:171], v[44:47]
	v_mfma_f32_16x16x32_bf16 v[40:43], v[132:135], v[168:171], v[40:43]
	v_mfma_f32_16x16x32_bf16 v[28:31], v[120:123], v[176:179], v[28:31]
	v_mfma_f32_16x16x32_bf16 v[24:27], v[132:135], v[176:179], v[24:27]
	v_mfma_f32_16x16x32_bf16 v[12:15], v[120:123], v[184:187], v[12:15]
	v_mfma_f32_16x16x32_bf16 v[8:11], v[132:135], v[184:187], v[8:11]
	v_mfma_f32_16x16x32_bf16 v[60:63], v[124:127], v[164:167], v[60:63]
	v_mfma_f32_16x16x32_bf16 v[56:59], v[136:139], v[164:167], v[56:59]
	v_mfma_f32_16x16x32_bf16 v[44:47], v[124:127], v[172:175], v[44:47]
	v_mfma_f32_16x16x32_bf16 v[40:43], v[136:139], v[172:175], v[40:43]
	v_mfma_f32_16x16x32_bf16 v[28:31], v[124:127], v[180:183], v[28:31]
	v_mfma_f32_16x16x32_bf16 v[24:27], v[136:139], v[180:183], v[24:27]
	v_mfma_f32_16x16x32_bf16 v[12:15], v[124:127], v[188:191], v[12:15]
	v_mfma_f32_16x16x32_bf16 v[8:11], v[136:139], v[188:191], v[8:11]
	s_setprio 0
	s_setprio 1
	v_mfma_f32_16x16x32_bf16 v[52:55], v[144:147], v[160:163], v[52:55]
	v_mfma_f32_16x16x32_bf16 v[48:51], v[152:155], v[160:163], v[48:51]
	v_mfma_f32_16x16x32_bf16 v[36:39], v[144:147], v[168:171], v[36:39]
	v_mfma_f32_16x16x32_bf16 v[32:35], v[152:155], v[168:171], v[32:35]
	v_mfma_f32_16x16x32_bf16 v[20:23], v[144:147], v[176:179], v[20:23]
	v_mfma_f32_16x16x32_bf16 v[16:19], v[152:155], v[176:179], v[16:19]
	v_mfma_f32_16x16x32_bf16 v[4:7], v[144:147], v[184:187], v[4:7]
	v_mfma_f32_16x16x32_bf16 v[0:3], v[152:155], v[184:187], v[0:3]
	v_mfma_f32_16x16x32_bf16 v[52:55], v[148:151], v[164:167], v[52:55]
	v_mfma_f32_16x16x32_bf16 v[48:51], v[156:159], v[164:167], v[48:51]
	v_mfma_f32_16x16x32_bf16 v[36:39], v[148:151], v[172:175], v[36:39]
	v_mfma_f32_16x16x32_bf16 v[32:35], v[156:159], v[172:175], v[32:35]
	v_mfma_f32_16x16x32_bf16 v[20:23], v[148:151], v[180:183], v[20:23]
	v_mfma_f32_16x16x32_bf16 v[16:19], v[156:159], v[180:183], v[16:19]
	v_mfma_f32_16x16x32_bf16 v[4:7], v[148:151], v[188:191], v[4:7]
	v_mfma_f32_16x16x32_bf16 v[0:3], v[156:159], v[188:191], v[0:3]
	s_setprio 0
	s_barrier
	s_add_i32 s47, 0, 0x18000
	s_add_i32 s50, 0, 0x1c000
	v_add_u32_e32 v136, s47, v245
	v_add_u32_e32 v156, s50, v245
	ds_read_b128 v[120:123], v136
	ds_read_b128 v[124:127], v136 offset:1024
	ds_read_b128 v[132:135], v136 offset:2048
	ds_read_b128 v[136:139], v136 offset:3072
	ds_read_b128 v[144:147], v156
	ds_read_b128 v[148:151], v156 offset:1024
	ds_read_b128 v[152:155], v156 offset:2048
	ds_read_b128 v[156:159], v156 offset:3072
	s_add_u32 s30, s30, 0x80000
	s_addc_u32 s31, s31, 0
	s_mov_b32 m0, s61
	v_lshl_add_u64 v[216:217], s[30:31], 0, v[192:193]
	ds_read_b128 v[160:163], v248 offset:32768
	ds_read_b128 v[164:167], v248 offset:33792
	ds_read_b128 v[168:171], v248 offset:34816
	ds_read_b128 v[172:175], v248 offset:35840
	ds_read_b128 v[176:179], v248 offset:36864
	ds_read_b128 v[180:183], v248 offset:37888
	ds_read_b128 v[184:187], v248 offset:38912
	ds_read_b128 v[188:191], v248 offset:39936
	global_load_lds_dwordx4 v[216:217], off
	v_lshl_add_u64 v[216:217], s[30:31], 0, v[196:197]
	s_mov_b32 m0, s62
	s_nop 0
	global_load_lds_dwordx4 v[216:217], off
	s_waitcnt vmcnt(8)
	s_waitcnt lgkmcnt(0)
	s_barrier
	s_setprio 1
	s_waitcnt lgkmcnt(0)
	v_mfma_f32_16x16x32_bf16 v[140:143], v[120:123], v[160:163], v[140:143]
	v_mfma_f32_16x16x32_bf16 v[128:131], v[132:135], v[160:163], v[128:131]
	v_mfma_f32_16x16x32_bf16 v[108:111], v[120:123], v[168:171], v[108:111]
	v_mfma_f32_16x16x32_bf16 v[104:107], v[132:135], v[168:171], v[104:107]
	v_mfma_f32_16x16x32_bf16 v[92:95], v[120:123], v[176:179], v[92:95]
	v_mfma_f32_16x16x32_bf16 v[88:91], v[132:135], v[176:179], v[88:91]
	v_mfma_f32_16x16x32_bf16 v[76:79], v[120:123], v[184:187], v[76:79]
	v_mfma_f32_16x16x32_bf16 v[72:75], v[132:135], v[184:187], v[72:75]
	v_mfma_f32_16x16x32_bf16 v[140:143], v[124:127], v[164:167], v[140:143]
	v_mfma_f32_16x16x32_bf16 v[128:131], v[136:139], v[164:167], v[128:131]
	v_mfma_f32_16x16x32_bf16 v[108:111], v[124:127], v[172:175], v[108:111]
	v_mfma_f32_16x16x32_bf16 v[104:107], v[136:139], v[172:175], v[104:107]
	v_mfma_f32_16x16x32_bf16 v[92:95], v[124:127], v[180:183], v[92:95]
	v_mfma_f32_16x16x32_bf16 v[88:91], v[136:139], v[180:183], v[88:91]
	v_mfma_f32_16x16x32_bf16 v[76:79], v[124:127], v[188:191], v[76:79]
	v_mfma_f32_16x16x32_bf16 v[72:75], v[136:139], v[188:191], v[72:75]
	s_setprio 0
	s_setprio 1
	v_mfma_f32_16x16x32_bf16 v[116:119], v[144:147], v[160:163], v[116:119]
	v_mfma_f32_16x16x32_bf16 v[112:115], v[152:155], v[160:163], v[112:115]
	v_mfma_f32_16x16x32_bf16 v[100:103], v[144:147], v[168:171], v[100:103]
	v_mfma_f32_16x16x32_bf16 v[96:99], v[152:155], v[168:171], v[96:99]
	v_mfma_f32_16x16x32_bf16 v[84:87], v[144:147], v[176:179], v[84:87]
	v_mfma_f32_16x16x32_bf16 v[80:83], v[152:155], v[176:179], v[80:83]
	v_mfma_f32_16x16x32_bf16 v[68:71], v[144:147], v[184:187], v[68:71]
	v_mfma_f32_16x16x32_bf16 v[64:67], v[152:155], v[184:187], v[64:67]
	v_mfma_f32_16x16x32_bf16 v[116:119], v[148:151], v[164:167], v[116:119]
	v_mfma_f32_16x16x32_bf16 v[112:115], v[156:159], v[164:167], v[112:115]
	v_mfma_f32_16x16x32_bf16 v[100:103], v[148:151], v[172:175], v[100:103]
	v_mfma_f32_16x16x32_bf16 v[96:99], v[156:159], v[172:175], v[96:99]
	v_mfma_f32_16x16x32_bf16 v[84:87], v[148:151], v[180:183], v[84:87]
	v_mfma_f32_16x16x32_bf16 v[80:83], v[156:159], v[180:183], v[80:83]
	v_mfma_f32_16x16x32_bf16 v[68:71], v[148:151], v[188:191], v[68:71]
	v_mfma_f32_16x16x32_bf16 v[64:67], v[156:159], v[188:191], v[64:67]
	s_setprio 0
	s_barrier
; #define PG8_STAGE(bufoff, gbase, voff) do { _Pragma("unroll") for (int _i = 0; _i < 2; ++_i) \
;         __builtin_amdgcn_global_load_lds((const unsigned*)((const char*)(gbase) + (voff)[_i]), (LAS unsigned*)(lds + (bufoff) + ldsw + _i * 8192), 16, 0, 0); } while (0)
; #define PG8_LDA(dst, b, h) do { _Pragma("unroll") for (int m = 0; m < 4; ++m) _Pragma("unroll") for (int k = 0; k < 2; ++k) dst[m][k] = *(const LAS bf16x8*)(lds + PG8_SA(b, h) + aoff + m * 2048 + k * 1024); } while (0)
; #define PG8_MMA(ai, bj, At, Bt) do { __builtin_amdgcn_s_setprio(1); _Pragma("unroll") for (int m = 0; m < 4; ++m) _Pragma("unroll") for (int n = 0; n < 2; ++n) _Pragma("unroll") for (int k = 0; k < 2; ++k) \
;         acc[ai][bj][m][n] = __builtin_amdgcn_mfma_f32_16x16x32_bf16(Bt[n][k], At[m][k], acc[ai][bj][m][n], 0, 0, 0); __builtin_amdgcn_s_setprio(0); } while (0)
; #define PG8_WAIT_V(n) asm volatile("s_waitcnt vmcnt(" #n ")" ::: "memory")
; #define PG8_WAIT_L(n) asm volatile("s_waitcnt lgkmcnt(" #n ")" ::: "memory")
; #define PG8_BAR __builtin_amdgcn_s_barrier()
; #define PG8_SCHED __builtin_amdgcn_sched_barrier(0)
; template <class Epi>
; __device__ __forceinline__ void gemm_phase(LAS unsigned char* lds, const Gemm g, const StaticOrder& S, const Epi& E, const int wid) {
;     ...
;             PG8_LDA(At, 1, 1); PG8_STAGE(PG8_SB(1, 0), b3, voffB); PG8_STAGE(PG8_SB(1, 1), b3 + hsB, voffB); PG8_STAGE(PG8_SA(1, 0), a3, voffA);
;             PG8_WAIT_V(8); PG8_WAIT_L(0); PG8_BAR; PG8_MMA(1, 0, At, B0); PG8_MMA(1, 1, At, B1); PG8_BAR; PG8_SCHED;
;         }
;         if (wr == 0) PG8_BAR;
;         E(acc, cur, wid);
;         if (!has_next) break;
	s_add_i32 s30, s47, s68
	v_lshl_add_u64 v[208:209], v[208:209], 0, s[8:9]
	s_mov_b32 m0, s30
	ds_read_b128 v[160:163], v248 offset:49152
	ds_read_b128 v[164:167], v248 offset:50176
	ds_read_b128 v[168:171], v248 offset:51200
	ds_read_b128 v[172:175], v248 offset:52224
	ds_read_b128 v[176:179], v248 offset:53248
	ds_read_b128 v[180:183], v248 offset:54272
	ds_read_b128 v[184:187], v248 offset:55296
	ds_read_b128 v[188:191], v248 offset:56320
	global_load_lds_dwordx4 v[208:209], off
	s_add_i32 m0, s30, 0x2000
	s_add_u32 s28, s28, 0x80080
	v_lshl_add_u64 v[208:209], v[210:211], 0, s[8:9]
	s_addc_u32 s29, s29, 0
	s_add_i32 s30, s50, s68
	global_load_lds_dwordx4 v[208:209], off
	v_lshl_add_u64 v[208:209], s[28:29], 0, v[194:195]
	s_mov_b32 m0, s30
	s_nop 0
	global_load_lds_dwordx4 v[208:209], off
	v_lshl_add_u64 v[208:209], s[28:29], 0, v[198:199]
	s_add_i32 m0, s30, 0x2000
	s_nop 0
	global_load_lds_dwordx4 v[208:209], off
	v_lshl_add_u64 v[208:209], v[212:213], 0, s[8:9]
	s_mov_b32 m0, s64
	s_nop 0
	global_load_lds_dwordx4 v[208:209], off
	v_lshl_add_u64 v[208:209], v[214:215], 0, s[8:9]
	s_mov_b32 m0, s65
	s_nop 0
	global_load_lds_dwordx4 v[208:209], off
	s_waitcnt vmcnt(8)
	s_waitcnt lgkmcnt(0)
	s_barrier
	s_setprio 1
	s_waitcnt lgkmcnt(0)
	v_mfma_f32_16x16x32_bf16 v[60:63], v[120:123], v[160:163], v[60:63]
	v_mfma_f32_16x16x32_bf16 v[56:59], v[132:135], v[160:163], v[56:59]
	v_mfma_f32_16x16x32_bf16 v[44:47], v[120:123], v[168:171], v[44:47]
	v_mfma_f32_16x16x32_bf16 v[40:43], v[132:135], v[168:171], v[40:43]
	v_mfma_f32_16x16x32_bf16 v[28:31], v[120:123], v[176:179], v[28:31]
	v_mfma_f32_16x16x32_bf16 v[24:27], v[132:135], v[176:179], v[24:27]
	v_mfma_f32_16x16x32_bf16 v[12:15], v[120:123], v[184:187], v[12:15]
	v_mfma_f32_16x16x32_bf16 v[8:11], v[132:135], v[184:187], v[8:11]
	v_mfma_f32_16x16x32_bf16 v[60:63], v[124:127], v[164:167], v[60:63]
	v_mfma_f32_16x16x32_bf16 v[56:59], v[136:139], v[164:167], v[56:59]
	v_mfma_f32_16x16x32_bf16 v[44:47], v[124:127], v[172:175], v[44:47]
	v_mfma_f32_16x16x32_bf16 v[40:43], v[136:139], v[172:175], v[40:43]
	v_mfma_f32_16x16x32_bf16 v[28:31], v[124:127], v[180:183], v[28:31]
	v_mfma_f32_16x16x32_bf16 v[24:27], v[136:139], v[180:183], v[24:27]
	v_mfma_f32_16x16x32_bf16 v[12:15], v[124:127], v[188:191], v[12:15]
	v_mfma_f32_16x16x32_bf16 v[8:11], v[136:139], v[188:191], v[8:11]
	s_setprio 0
	s_setprio 1
	v_mfma_f32_16x16x32_bf16 v[52:55], v[144:147], v[160:163], v[52:55]
	v_mfma_f32_16x16x32_bf16 v[48:51], v[152:155], v[160:163], v[48:51]
	v_mfma_f32_16x16x32_bf16 v[36:39], v[144:147], v[168:171], v[36:39]
	v_mfma_f32_16x16x32_bf16 v[32:35], v[152:155], v[168:171], v[32:35]
	v_mfma_f32_16x16x32_bf16 v[20:23], v[144:147], v[176:179], v[20:23]
	v_mfma_f32_16x16x32_bf16 v[16:19], v[152:155], v[176:179], v[16:19]
	v_mfma_f32_16x16x32_bf16 v[4:7], v[144:147], v[184:187], v[4:7]
	v_mfma_f32_16x16x32_bf16 v[0:3], v[152:155], v[184:187], v[0:3]
	v_mfma_f32_16x16x32_bf16 v[52:55], v[148:151], v[164:167], v[52:55]
	v_mfma_f32_16x16x32_bf16 v[48:51], v[156:159], v[164:167], v[48:51]
	v_mfma_f32_16x16x32_bf16 v[36:39], v[148:151], v[172:175], v[36:39]
	v_mfma_f32_16x16x32_bf16 v[32:35], v[156:159], v[172:175], v[32:35]
	v_mfma_f32_16x16x32_bf16 v[20:23], v[148:151], v[180:183], v[20:23]
	v_mfma_f32_16x16x32_bf16 v[16:19], v[156:159], v[180:183], v[16:19]
	v_mfma_f32_16x16x32_bf16 v[4:7], v[148:151], v[188:191], v[4:7]
	v_mfma_f32_16x16x32_bf16 v[0:3], v[156:159], v[188:191], v[0:3]
	s_setprio 0
	s_barrier
	s_add_i32 s81, s81, 2
	s_add_u32 s79, s79, 0x100
	s_addc_u32 s80, s80, 0
	s_add_u32 s26, s26, 0x100
	s_addc_u32 s27, s27, 0
	s_cmp_gt_u32 s81, 29
	s_cbranch_scc0 .LBB0_401
	s_mov_b32 s32, 1
	s_and_b64 vcc, exec, s[10:11]
	s_cbranch_vccz .LBB0_404
	s_barrier

; #define PG8_STAGE(bufoff, gbase, voff) do { _Pragma("unroll") for (int _i = 0; _i < 2; ++_i) \
;         __builtin_amdgcn_global_load_lds((const unsigned*)((const char*)(gbase) + (voff)[_i]), (LAS unsigned*)(lds + (bufoff) + ldsw + _i * 8192), 16, 0, 0); } while (0)
; #define PG8_WAIT_V(n) asm volatile("s_waitcnt vmcnt(" #n ")" ::: "memory")
; #define PG8_BAR __builtin_amdgcn_s_barrier()
; template <class Epi>
; __device__ __forceinline__ void gemm_phase(LAS unsigned char* lds, const Gemm g, const StaticOrder& S, const Epi& E, const int wid) {
;     ...
;     for (int i = 0; i < 2; ++i) { int R, C; stage_rc(tid * 16 + i * 8192, R, C); const int Rb = Epi::PERM ? ((R & ~31) + perm32(R & 31)) : R;
;         voffA[i] = (unsigned)(R * lda + C) * 2u; voffB[i] = (unsigned)(Rb * K + C) * 2u; }
;     const size_t kstep = (size_t)(BK * 2);
;     const size_t hsA = (size_t)HALF * lda * 2, hsB = (size_t)HALF * K * 2;
;     const size_t tsA = 2 * hsA, tsB = 2 * hsB;
;     const unsigned ldsw = (unsigned)wid * 1024u;
;     const int aoff = lds_byte(wr * 64 + fr, fq * 8), boff = lds_byte(wc * 32 + fr, fq * 8);
;     ...
;     PG8_STAGE(PG8_SB(0, 0), cB, voffB); PG8_STAGE(PG8_SB(0, 1), cB + hsB, voffB); PG8_STAGE(PG8_SA(0, 0), cA, voffA); PG8_STAGE(PG8_SA(0, 1), cA + hsA, voffA);
;     if (wr == 1) PG8_BAR;
;     PG8_WAIT_V(2); PG8_BAR;
;     PG8_STAGE(PG8_SB(1, 0), cB + kstep, voffB); PG8_STAGE(PG8_SA(1, 0), cA + kstep, voffA); PG8_STAGE(PG8_SB(1, 1), cB + hsB + kstep, voffB);
;     PG8_WAIT_V(6); PG8_BAR;
.LBB0_475:
	s_mov_b64 s[8:9], 0x80
	s_add_i32 m0, s35, 0x18000
	v_lshl_add_u64 v[6:7], v[6:7], 0, s[8:9]
	global_load_lds_dwordx4 v[6:7], off
	v_lshl_add_u64 v[4:5], v[4:5], 0, s[8:9]
	s_add_i32 m0, s35, 0x1a000
	s_add_i32 s75, s35, 0x8000
	s_add_i32 s76, s35, 0xa000
	global_load_lds_dwordx4 v[4:5], off
	v_lshl_add_u64 v[0:1], v[0:1], 0, s[8:9]
	s_mov_b32 m0, s75
	s_add_u32 s4, s36, 0x40080
	global_load_lds_dwordx4 v[0:1], off
	v_lshl_add_u64 v[0:1], v[2:3], 0, s[8:9]
	s_mov_b32 m0, s76
	s_addc_u32 s5, s37, 0
	global_load_lds_dwordx4 v[0:1], off
	s_add_i32 m0, s35, 0x1c000
	v_lshl_add_u64 v[0:1], s[4:5], 0, v[130:131]
	global_load_lds_dwordx4 v[0:1], off
	v_lshl_add_u64 v[0:1], s[4:5], 0, v[134:135]
	s_add_i32 m0, s35, 0x1e000
	v_and_b32_e32 v2, 48, v8
	global_load_lds_dwordx4 v[0:1], off
	s_waitcnt vmcnt(8)
	s_barrier
	v_and_b32_e32 v0, 15, v8
	v_ashrrev_i32_e32 v1, 6, v8
	v_readlane_b32 s4, v254, 3
	v_lshl_or_b32 v0, v0, 6, v2
	v_lshlrev_b32_e32 v3, 2, v8
	v_lshl_add_u32 v2, v1, 10, s4
	v_readlane_b32 s4, v254, 5
	v_and_b32_e32 v3, 32, v3
	v_bitop3_b32 v2, v0, v2, v3 bitop3:0xde
	v_add_lshl_u32 v1, v1, s4, 10
	v_bitop3_b32 v144, v0, v1, v3 bitop3:0xde
	v_lshlrev_b32_e32 v0, 14, v12
	v_and_b32_e32 v0, 0xffff8000, v0
	v_lshl_add_u32 v0, v13, 11, v0
	v_and_b32_e32 v1, 1, v12
	v_lshl_or_b32 v0, v1, 6, v0
	v_lshl_add_u32 v136, v14, 1, v0
	v_lshlrev_b32_e32 v0, 14, v9
	v_and_b32_e32 v0, 0xffff8000, v0
	s_waitcnt vmcnt(6)
	s_mov_b32 s32, 0
	s_cmpk_lt_u32 s3, 0x100
	v_lshl_add_u32 v0, v10, 11, v0
	v_and_b32_e32 v1, 1, v9
	s_cselect_b64 s[10:11], -1, 0
	s_lshl_b32 s4, s33, 4
	v_lshl_or_b32 v0, v1, 6, v0
	s_add_i32 s80, 0, 0x10000
	s_add_i32 s81, 0, 0x14000
	s_sext_i32_i8 s89, s6
	s_and_b32 s77, s4, 0x3fffffc0
	s_ashr_i32 s78, s56, 31
	s_mov_b32 s79, s56
	v_mov_b32_e32 v137, v131
	v_lshl_add_u32 v138, v11, 1, v0
	v_mov_b32_e32 v139, v131
	v_mov_b64_e32 v[140:141], 0x800
	v_mov_b64_e32 v[142:143], 0x7ff
	v_add_u32_e32 v145, s80, v144
	v_add_u32_e32 v146, s81, v144
	v_add_u32_e32 v147, 0, v2
	s_mov_b64 s[16:17], 0x100000
	s_mov_b32 s82, 0x100000
	s_mov_b64 s[18:19], 0x120000
	s_mov_b32 s83, 0x120000
	s_mov_b64 s[20:21], 0x140000
	s_mov_b32 s90, 0x140000
	s_mov_b64 s[22:23], 0x160000
	s_mov_b32 s91, 0x160000
	s_barrier
	s_waitcnt vmcnt(0)
	s_branch .LBB0_478

; #define PG8_STAGE(bufoff, gbase, voff) do { _Pragma("unroll") for (int _i = 0; _i < 2; ++_i) \
;         __builtin_amdgcn_global_load_lds((const unsigned*)((const char*)(gbase) + (voff)[_i]), (LAS unsigned*)(lds + (bufoff) + ldsw + _i * 8192), 16, 0, 0); } while (0)
; #define PG8_LDA(dst, b, h) do { _Pragma("unroll") for (int m = 0; m < 4; ++m) _Pragma("unroll") for (int k = 0; k < 2; ++k) dst[m][k] = *(const LAS bf16x8*)(lds + PG8_SA(b, h) + aoff + m * 2048 + k * 1024); } while (0)
; #define PG8_LDB(dst, b, h) do { _Pragma("unroll") for (int n = 0; n < 2; ++n) _Pragma("unroll") for (int k = 0; k < 2; ++k) dst[n][k] = *(const LAS bf16x8*)(lds + PG8_SB(b, h) + boff + n * 2048 + k * 1024); } while (0)
; #define PG8_MMA(ai, bj, At, Bt) do { __builtin_amdgcn_s_setprio(1); _Pragma("unroll") for (int m = 0; m < 4; ++m) _Pragma("unroll") for (int n = 0; n < 2; ++n) _Pragma("unroll") for (int k = 0; k < 2; ++k) \
;         acc[ai][bj][m][n] = __builtin_amdgcn_mfma_f32_16x16x32_bf16(Bt[n][k], At[m][k], acc[ai][bj][m][n], 0, 0, 0); __builtin_amdgcn_s_setprio(0); } while (0)
; #define PG8_WAIT_V(n) asm volatile("s_waitcnt vmcnt(" #n ")" ::: "memory")
; #define PG8_WAIT_L(n) asm volatile("s_waitcnt lgkmcnt(" #n ")" ::: "memory")
; #define PG8_BAR __builtin_amdgcn_s_barrier()
; #define PG8_SCHED __builtin_amdgcn_sched_barrier(0)
; template <class Epi>
; __device__ __forceinline__ void gemm_phase(LAS unsigned char* lds, const Gemm g, const StaticOrder& S, const Epi& E, const int wid) {
;     ...
;             PG8_LDB(B0, 0, 0); PG8_LDB(B1, 0, 1); PG8_SCHED; PG8_LDA(At, 0, 0); PG8_STAGE(PG8_SA(1, 1), a1 + hsA, voffA);
;             PG8_WAIT_V(8); PG8_WAIT_L(0); PG8_BAR; PG8_MMA(0, 0, At, B0); PG8_MMA(0, 1, At, B1); PG8_BAR; PG8_SCHED;
.LBB0_485:
	ds_read_b128 v[148:151], v145
	ds_read_b128 v[152:155], v145 offset:1024
	ds_read_b128 v[156:159], v145 offset:2048
	ds_read_b128 v[160:163], v145 offset:3072
	ds_read_b128 v[164:167], v146
	ds_read_b128 v[168:171], v146 offset:1024
	ds_read_b128 v[172:175], v146 offset:2048
	ds_read_b128 v[176:179], v146 offset:3072
	s_add_u32 s4, s36, 0xfffc0080
	s_addc_u32 s5, s37, -1
	s_cmp_eq_u32 s96, 12
	s_cselect_b32 s61, s27, s5
	s_cselect_b32 s60, s92, s4
	s_cselect_b32 s39, s25, s95
	s_cselect_b32 s38, s93, s94
	v_lshl_add_u64 v[212:213], s[36:37], 0, v[138:139]
	s_add_i32 m0, s35, 0xc000
	ds_read_b128 v[180:183], v147
	ds_read_b128 v[184:187], v147 offset:1024
	ds_read_b128 v[188:191], v147 offset:2048
	ds_read_b128 v[192:195], v147 offset:3072
	ds_read_b128 v[196:199], v147 offset:4096
	ds_read_b128 v[200:203], v147 offset:5120
	ds_read_b128 v[204:207], v147 offset:6144
	ds_read_b128 v[208:211], v147 offset:7168
	global_load_lds_dwordx4 v[212:213], off
	v_lshl_add_u64 v[212:213], s[36:37], 0, v[136:137]
	s_add_i32 m0, s35, 0xe000
	s_nop 0
	global_load_lds_dwordx4 v[212:213], off
	s_cmp_lg_u32 s32, 0
	s_cbranch_scc1 .Lkw3a_b
	s_waitcnt vmcnt(8)
	s_branch .Lkw3a_d

; #define PG8_STAGE(bufoff, gbase, voff) do { _Pragma("unroll") for (int _i = 0; _i < 2; ++_i) \
;         __builtin_amdgcn_global_load_lds((const unsigned*)((const char*)(gbase) + (voff)[_i]), (LAS unsigned*)(lds + (bufoff) + ldsw + _i * 8192), 16, 0, 0); } while (0)
; #define PG8_LDA(dst, b, h) do { _Pragma("unroll") for (int m = 0; m < 4; ++m) _Pragma("unroll") for (int k = 0; k < 2; ++k) dst[m][k] = *(const LAS bf16x8*)(lds + PG8_SA(b, h) + aoff + m * 2048 + k * 1024); } while (0)
; #define PG8_LDB(dst, b, h) do { _Pragma("unroll") for (int n = 0; n < 2; ++n) _Pragma("unroll") for (int k = 0; k < 2; ++k) dst[n][k] = *(const LAS bf16x8*)(lds + PG8_SB(b, h) + boff + n * 2048 + k * 1024); } while (0)
; #define PG8_MMA(ai, bj, At, Bt) do { __builtin_amdgcn_s_setprio(1); _Pragma("unroll") for (int m = 0; m < 4; ++m) _Pragma("unroll") for (int n = 0; n < 2; ++n) _Pragma("unroll") for (int k = 0; k < 2; ++k) \
;         acc[ai][bj][m][n] = __builtin_amdgcn_mfma_f32_16x16x32_bf16(Bt[n][k], At[m][k], acc[ai][bj][m][n], 0, 0, 0); __builtin_amdgcn_s_setprio(0); } while (0)
; #define PG8_WAIT_V(n) asm volatile("s_waitcnt vmcnt(" #n ")" ::: "memory")
; #define PG8_WAIT_L(n) asm volatile("s_waitcnt lgkmcnt(" #n ")" ::: "memory")
; #define PG8_BAR __builtin_amdgcn_s_barrier()
; #define PG8_SCHED __builtin_amdgcn_sched_barrier(0)
; template <class Epi>
; __device__ __forceinline__ void gemm_phase(LAS unsigned char* lds, const Gemm g, const StaticOrder& S, const Epi& E, const int wid) {
;     ...
;             PG8_LDB(B0, 0, 0); PG8_LDB(B1, 0, 1); PG8_SCHED; PG8_LDA(At, 0, 0); PG8_STAGE(PG8_SA(1, 1), a1 + hsA, voffA);
;             PG8_WAIT_V(8); PG8_WAIT_L(0); PG8_BAR; PG8_MMA(0, 0, At, B0); PG8_MMA(0, 1, At, B1); PG8_BAR; PG8_SCHED;
;             PG8_LDA(At, 0, 1); PG8_STAGE(PG8_SB(0, 0), b2, voffB); PG8_STAGE(PG8_SB(0, 1), b2 + hsB, voffB); PG8_STAGE(PG8_SA(0, 0), a2, voffA);
.Lkw3a_d:
	s_waitcnt lgkmcnt(0)
	s_barrier
	s_setprio 1
	s_waitcnt lgkmcnt(0)
	v_mfma_f32_16x16x32_bf16 v[124:127], v[148:151], v[180:183], v[124:127]
	v_mfma_f32_16x16x32_bf16 v[120:123], v[156:159], v[180:183], v[120:123]
	v_mfma_f32_16x16x32_bf16 v[108:111], v[148:151], v[188:191], v[108:111]
	v_mfma_f32_16x16x32_bf16 v[104:107], v[156:159], v[188:191], v[104:107]
	v_mfma_f32_16x16x32_bf16 v[92:95], v[148:151], v[196:199], v[92:95]
	v_mfma_f32_16x16x32_bf16 v[88:91], v[156:159], v[196:199], v[88:91]
	v_mfma_f32_16x16x32_bf16 v[76:79], v[148:151], v[204:207], v[76:79]
	v_mfma_f32_16x16x32_bf16 v[72:75], v[156:159], v[204:207], v[72:75]
	v_mfma_f32_16x16x32_bf16 v[124:127], v[152:155], v[184:187], v[124:127]
	v_mfma_f32_16x16x32_bf16 v[120:123], v[160:163], v[184:187], v[120:123]
	v_mfma_f32_16x16x32_bf16 v[108:111], v[152:155], v[192:195], v[108:111]
	v_mfma_f32_16x16x32_bf16 v[104:107], v[160:163], v[192:195], v[104:107]
	v_mfma_f32_16x16x32_bf16 v[92:95], v[152:155], v[200:203], v[92:95]
	v_mfma_f32_16x16x32_bf16 v[88:91], v[160:163], v[200:203], v[88:91]
	v_mfma_f32_16x16x32_bf16 v[76:79], v[152:155], v[208:211], v[76:79]
	v_mfma_f32_16x16x32_bf16 v[72:75], v[160:163], v[208:211], v[72:75]
	s_setprio 0
	s_setprio 1
	v_mfma_f32_16x16x32_bf16 v[116:119], v[164:167], v[180:183], v[116:119]
	v_mfma_f32_16x16x32_bf16 v[112:115], v[172:175], v[180:183], v[112:115]
	v_mfma_f32_16x16x32_bf16 v[100:103], v[164:167], v[188:191], v[100:103]
	v_mfma_f32_16x16x32_bf16 v[96:99], v[172:175], v[188:191], v[96:99]
	v_mfma_f32_16x16x32_bf16 v[84:87], v[164:167], v[196:199], v[84:87]
	v_mfma_f32_16x16x32_bf16 v[80:83], v[172:175], v[196:199], v[80:83]
	v_mfma_f32_16x16x32_bf16 v[68:71], v[164:167], v[204:207], v[68:71]
	v_mfma_f32_16x16x32_bf16 v[64:67], v[172:175], v[204:207], v[64:67]
	v_mfma_f32_16x16x32_bf16 v[116:119], v[168:171], v[184:187], v[116:119]
	v_mfma_f32_16x16x32_bf16 v[112:115], v[176:179], v[184:187], v[112:115]
	v_mfma_f32_16x16x32_bf16 v[100:103], v[168:171], v[192:195], v[100:103]
	v_mfma_f32_16x16x32_bf16 v[96:99], v[176:179], v[192:195], v[96:99]
	v_mfma_f32_16x16x32_bf16 v[84:87], v[168:171], v[200:203], v[84:87]
	v_mfma_f32_16x16x32_bf16 v[80:83], v[176:179], v[200:203], v[80:83]
	v_mfma_f32_16x16x32_bf16 v[68:71], v[168:171], v[208:211], v[68:71]
	v_mfma_f32_16x16x32_bf16 v[64:67], v[176:179], v[208:211], v[64:67]
	s_setprio 0
	s_barrier
	s_add_i32 s4, s80, s68
	v_lshl_add_u64 v[212:213], s[38:39], 0, v[130:131]
	s_mov_b32 m0, s4
	ds_read_b128 v[180:183], v147 offset:16384
	ds_read_b128 v[184:187], v147 offset:17408
	ds_read_b128 v[188:191], v147 offset:18432
	ds_read_b128 v[192:195], v147 offset:19456
	ds_read_b128 v[196:199], v147 offset:20480
	ds_read_b128 v[200:203], v147 offset:21504
	ds_read_b128 v[204:207], v147 offset:22528
	ds_read_b128 v[208:211], v147 offset:23552
	global_load_lds_dwordx4 v[212:213], off
	s_add_i32 m0, s4, 0x2000
	s_add_u32 s4, s38, 0x40000
	v_lshl_add_u64 v[214:215], s[38:39], 0, v[134:135]
	s_addc_u32 s5, s39, 0
	s_add_i32 s47, s81, s68
	global_load_lds_dwordx4 v[214:215], off
	v_lshl_add_u64 v[216:217], s[4:5], 0, v[130:131]
	s_mov_b32 m0, s47
	v_lshl_add_u64 v[218:219], s[60:61], 0, v[132:133]
	global_load_lds_dwordx4 v[216:217], off
	v_lshl_add_u64 v[216:217], s[4:5], 0, v[134:135]
	s_add_i32 m0, s47, 0x2000
	s_nop 0
	global_load_lds_dwordx4 v[216:217], off
	v_lshl_add_u64 v[216:217], s[60:61], 0, v[128:129]
	s_mov_b32 m0, s35
	s_nop 0
	global_load_lds_dwordx4 v[216:217], off
	s_mov_b32 m0, s65
	s_nop 0
	global_load_lds_dwordx4 v[218:219], off
	s_cmp_lg_u32 s32, 0
	s_cbranch_scc1 .Lkw3b_b
	s_waitcnt vmcnt(8)
	s_branch .Lkw3b_d

; #define PG8_STAGE(bufoff, gbase, voff) do { _Pragma("unroll") for (int _i = 0; _i < 2; ++_i) \
;         __builtin_amdgcn_global_load_lds((const unsigned*)((const char*)(gbase) + (voff)[_i]), (LAS unsigned*)(lds + (bufoff) + ldsw + _i * 8192), 16, 0, 0); } while (0)
; #define PG8_LDA(dst, b, h) do { _Pragma("unroll") for (int m = 0; m < 4; ++m) _Pragma("unroll") for (int k = 0; k < 2; ++k) dst[m][k] = *(const LAS bf16x8*)(lds + PG8_SA(b, h) + aoff + m * 2048 + k * 1024); } while (0)
; #define PG8_LDB(dst, b, h) do { _Pragma("unroll") for (int n = 0; n < 2; ++n) _Pragma("unroll") for (int k = 0; k < 2; ++k) dst[n][k] = *(const LAS bf16x8*)(lds + PG8_SB(b, h) + boff + n * 2048 + k * 1024); } while (0)
; #define PG8_MMA(ai, bj, At, Bt) do { __builtin_amdgcn_s_setprio(1); _Pragma("unroll") for (int m = 0; m < 4; ++m) _Pragma("unroll") for (int n = 0; n < 2; ++n) _Pragma("unroll") for (int k = 0; k < 2; ++k) \
;         acc[ai][bj][m][n] = __builtin_amdgcn_mfma_f32_16x16x32_bf16(Bt[n][k], At[m][k], acc[ai][bj][m][n], 0, 0, 0); __builtin_amdgcn_s_setprio(0); } while (0)
; #define PG8_WAIT_V(n) asm volatile("s_waitcnt vmcnt(" #n ")" ::: "memory")
; #define PG8_WAIT_L(n) asm volatile("s_waitcnt lgkmcnt(" #n ")" ::: "memory")
; #define PG8_BAR __builtin_amdgcn_s_barrier()
; #define PG8_SCHED __builtin_amdgcn_sched_barrier(0)
; template <class Epi>
; __device__ __forceinline__ void gemm_phase(LAS unsigned char* lds, const Gemm g, const StaticOrder& S, const Epi& E, const int wid) {
;     ...
;             PG8_WAIT_V(8); PG8_WAIT_L(0); PG8_BAR; PG8_MMA(1, 0, At, B0); PG8_MMA(1, 1, At, B1); PG8_BAR; PG8_SCHED;
;             PG8_LDB(B0, 1, 0); PG8_LDB(B1, 1, 1); PG8_SCHED; PG8_LDA(At, 1, 0); PG8_STAGE(PG8_SA(0, 1), a2 + hsA, voffA);
;             PG8_WAIT_V(8); PG8_WAIT_L(0); PG8_BAR; PG8_MMA(0, 0, At, B0); PG8_MMA(0, 1, At, B1); PG8_BAR; PG8_SCHED;
.Lkw3b_d:
	s_mov_b32 s32, 0
	s_waitcnt lgkmcnt(0)
	s_barrier
	s_setprio 1
	s_waitcnt lgkmcnt(0)
	v_mfma_f32_16x16x32_bf16 v[60:63], v[148:151], v[180:183], v[60:63]
	v_mfma_f32_16x16x32_bf16 v[56:59], v[156:159], v[180:183], v[56:59]
	v_mfma_f32_16x16x32_bf16 v[44:47], v[148:151], v[188:191], v[44:47]
	v_mfma_f32_16x16x32_bf16 v[40:43], v[156:159], v[188:191], v[40:43]
	v_mfma_f32_16x16x32_bf16 v[28:31], v[148:151], v[196:199], v[28:31]
	v_mfma_f32_16x16x32_bf16 v[24:27], v[156:159], v[196:199], v[24:27]
	v_mfma_f32_16x16x32_bf16 v[12:15], v[148:151], v[204:207], v[12:15]
	v_mfma_f32_16x16x32_bf16 v[8:11], v[156:159], v[204:207], v[8:11]
	v_mfma_f32_16x16x32_bf16 v[60:63], v[152:155], v[184:187], v[60:63]
	v_mfma_f32_16x16x32_bf16 v[56:59], v[160:163], v[184:187], v[56:59]
	v_mfma_f32_16x16x32_bf16 v[44:47], v[152:155], v[192:195], v[44:47]
	v_mfma_f32_16x16x32_bf16 v[40:43], v[160:163], v[192:195], v[40:43]
	v_mfma_f32_16x16x32_bf16 v[28:31], v[152:155], v[200:203], v[28:31]
	v_mfma_f32_16x16x32_bf16 v[24:27], v[160:163], v[200:203], v[24:27]
	v_mfma_f32_16x16x32_bf16 v[12:15], v[152:155], v[208:211], v[12:15]
	v_mfma_f32_16x16x32_bf16 v[8:11], v[160:163], v[208:211], v[8:11]
	s_setprio 0
	s_setprio 1
	v_mfma_f32_16x16x32_bf16 v[52:55], v[164:167], v[180:183], v[52:55]
	v_mfma_f32_16x16x32_bf16 v[48:51], v[172:175], v[180:183], v[48:51]
	v_mfma_f32_16x16x32_bf16 v[36:39], v[164:167], v[188:191], v[36:39]
	v_mfma_f32_16x16x32_bf16 v[32:35], v[172:175], v[188:191], v[32:35]
	v_mfma_f32_16x16x32_bf16 v[20:23], v[164:167], v[196:199], v[20:23]
	v_mfma_f32_16x16x32_bf16 v[16:19], v[172:175], v[196:199], v[16:19]
	v_mfma_f32_16x16x32_bf16 v[4:7], v[164:167], v[204:207], v[4:7]
	v_mfma_f32_16x16x32_bf16 v[0:3], v[172:175], v[204:207], v[0:3]
	v_mfma_f32_16x16x32_bf16 v[52:55], v[168:171], v[184:187], v[52:55]
	v_mfma_f32_16x16x32_bf16 v[48:51], v[176:179], v[184:187], v[48:51]
	v_mfma_f32_16x16x32_bf16 v[36:39], v[168:171], v[192:195], v[36:39]
	v_mfma_f32_16x16x32_bf16 v[32:35], v[176:179], v[192:195], v[32:35]
	v_mfma_f32_16x16x32_bf16 v[20:23], v[168:171], v[200:203], v[20:23]
	v_mfma_f32_16x16x32_bf16 v[16:19], v[176:179], v[200:203], v[16:19]
	v_mfma_f32_16x16x32_bf16 v[4:7], v[168:171], v[208:211], v[4:7]
	v_mfma_f32_16x16x32_bf16 v[0:3], v[176:179], v[208:211], v[0:3]
	s_setprio 0
	s_barrier
	s_add_i32 s47, 0, 0x18000
	s_add_i32 s50, 0, 0x1c000
	v_add_u32_e32 v160, s47, v144
	v_add_u32_e32 v176, s50, v144
	ds_read_b128 v[148:151], v160
	ds_read_b128 v[152:155], v160 offset:1024
	ds_read_b128 v[156:159], v160 offset:2048
	ds_read_b128 v[160:163], v160 offset:3072
	ds_read_b128 v[164:167], v176
	ds_read_b128 v[168:171], v176 offset:1024
	ds_read_b128 v[172:175], v176 offset:2048
	ds_read_b128 v[176:179], v176 offset:3072
	s_add_u32 s4, s60, 0x40000
	s_addc_u32 s5, s61, 0
	s_mov_b32 m0, s66
	v_lshl_add_u64 v[220:221], s[4:5], 0, v[128:129]
	ds_read_b128 v[180:183], v147 offset:32768
	ds_read_b128 v[184:187], v147 offset:33792
	ds_read_b128 v[188:191], v147 offset:34816
	ds_read_b128 v[192:195], v147 offset:35840
	ds_read_b128 v[196:199], v147 offset:36864
	ds_read_b128 v[200:203], v147 offset:37888
	ds_read_b128 v[204:207], v147 offset:38912
	ds_read_b128 v[208:211], v147 offset:39936
	global_load_lds_dwordx4 v[220:221], off
	v_lshl_add_u64 v[220:221], s[4:5], 0, v[132:133]
	s_mov_b32 m0, s67
	s_nop 0
	global_load_lds_dwordx4 v[220:221], off
	s_waitcnt vmcnt(8)
	s_waitcnt lgkmcnt(0)
	s_barrier
	s_setprio 1
	s_waitcnt lgkmcnt(0)
	v_mfma_f32_16x16x32_bf16 v[124:127], v[148:151], v[180:183], v[124:127]
	v_mfma_f32_16x16x32_bf16 v[120:123], v[156:159], v[180:183], v[120:123]
	v_mfma_f32_16x16x32_bf16 v[108:111], v[148:151], v[188:191], v[108:111]
	v_mfma_f32_16x16x32_bf16 v[104:107], v[156:159], v[188:191], v[104:107]
	v_mfma_f32_16x16x32_bf16 v[92:95], v[148:151], v[196:199], v[92:95]
	v_mfma_f32_16x16x32_bf16 v[88:91], v[156:159], v[196:199], v[88:91]
	v_mfma_f32_16x16x32_bf16 v[76:79], v[148:151], v[204:207], v[76:79]
	v_mfma_f32_16x16x32_bf16 v[72:75], v[156:159], v[204:207], v[72:75]
	v_mfma_f32_16x16x32_bf16 v[124:127], v[152:155], v[184:187], v[124:127]
	v_mfma_f32_16x16x32_bf16 v[120:123], v[160:163], v[184:187], v[120:123]
	v_mfma_f32_16x16x32_bf16 v[108:111], v[152:155], v[192:195], v[108:111]
	v_mfma_f32_16x16x32_bf16 v[104:107], v[160:163], v[192:195], v[104:107]
	v_mfma_f32_16x16x32_bf16 v[92:95], v[152:155], v[200:203], v[92:95]
	v_mfma_f32_16x16x32_bf16 v[88:91], v[160:163], v[200:203], v[88:91]
	v_mfma_f32_16x16x32_bf16 v[76:79], v[152:155], v[208:211], v[76:79]
	v_mfma_f32_16x16x32_bf16 v[72:75], v[160:163], v[208:211], v[72:75]
	s_setprio 0
	s_setprio 1
	v_mfma_f32_16x16x32_bf16 v[116:119], v[164:167], v[180:183], v[116:119]
	v_mfma_f32_16x16x32_bf16 v[112:115], v[172:175], v[180:183], v[112:115]
	v_mfma_f32_16x16x32_bf16 v[100:103], v[164:167], v[188:191], v[100:103]
	v_mfma_f32_16x16x32_bf16 v[96:99], v[172:175], v[188:191], v[96:99]
	v_mfma_f32_16x16x32_bf16 v[84:87], v[164:167], v[196:199], v[84:87]
	v_mfma_f32_16x16x32_bf16 v[80:83], v[172:175], v[196:199], v[80:83]
	v_mfma_f32_16x16x32_bf16 v[68:71], v[164:167], v[204:207], v[68:71]
	v_mfma_f32_16x16x32_bf16 v[64:67], v[172:175], v[204:207], v[64:67]
	v_mfma_f32_16x16x32_bf16 v[116:119], v[168:171], v[184:187], v[116:119]
	v_mfma_f32_16x16x32_bf16 v[112:115], v[176:179], v[184:187], v[112:115]
	v_mfma_f32_16x16x32_bf16 v[100:103], v[168:171], v[192:195], v[100:103]
	v_mfma_f32_16x16x32_bf16 v[96:99], v[176:179], v[192:195], v[96:99]
	v_mfma_f32_16x16x32_bf16 v[84:87], v[168:171], v[200:203], v[84:87]
	v_mfma_f32_16x16x32_bf16 v[80:83], v[176:179], v[200:203], v[80:83]
	v_mfma_f32_16x16x32_bf16 v[68:71], v[168:171], v[208:211], v[68:71]
	v_mfma_f32_16x16x32_bf16 v[64:67], v[176:179], v[208:211], v[64:67]
	s_setprio 0
	s_barrier
; #define PG8_STAGE(bufoff, gbase, voff) do { _Pragma("unroll") for (int _i = 0; _i < 2; ++_i) \
;         __builtin_amdgcn_global_load_lds((const unsigned*)((const char*)(gbase) + (voff)[_i]), (LAS unsigned*)(lds + (bufoff) + ldsw + _i * 8192), 16, 0, 0); } while (0)
; #define PG8_LDA(dst, b, h) do { _Pragma("unroll") for (int m = 0; m < 4; ++m) _Pragma("unroll") for (int k = 0; k < 2; ++k) dst[m][k] = *(const LAS bf16x8*)(lds + PG8_SA(b, h) + aoff + m * 2048 + k * 1024); } while (0)
; #define PG8_MMA(ai, bj, At, Bt) do { __builtin_amdgcn_s_setprio(1); _Pragma("unroll") for (int m = 0; m < 4; ++m) _Pragma("unroll") for (int n = 0; n < 2; ++n) _Pragma("unroll") for (int k = 0; k < 2; ++k) \
;         acc[ai][bj][m][n] = __builtin_amdgcn_mfma_f32_16x16x32_bf16(Bt[n][k], At[m][k], acc[ai][bj][m][n], 0, 0, 0); __builtin_amdgcn_s_setprio(0); } while (0)
; #define PG8_WAIT_V(n) asm volatile("s_waitcnt vmcnt(" #n ")" ::: "memory")
; #define PG8_WAIT_L(n) asm volatile("s_waitcnt lgkmcnt(" #n ")" ::: "memory")
; #define PG8_BAR __builtin_amdgcn_s_barrier()
; #define PG8_SCHED __builtin_amdgcn_sched_barrier(0)
; template <class Epi>
; __device__ __forceinline__ void gemm_phase(LAS unsigned char* lds, const Gemm g, const StaticOrder& S, const Epi& E, const int wid) {
;     ...
;             PG8_LDA(At, 1, 1); PG8_STAGE(PG8_SB(1, 0), b3, voffB); PG8_STAGE(PG8_SB(1, 1), b3 + hsB, voffB); PG8_STAGE(PG8_SA(1, 0), a3, voffA);
;             PG8_WAIT_V(8); PG8_WAIT_L(0); PG8_BAR; PG8_MMA(1, 0, At, B0); PG8_MMA(1, 1, At, B1); PG8_BAR; PG8_SCHED;
;         }
;         if (wr == 0) PG8_BAR;
;         E(acc, cur, wid);
;         if (!has_next) break;
	s_add_i32 s4, s47, s68
	v_lshl_add_u64 v[212:213], v[212:213], 0, s[8:9]
	s_mov_b32 m0, s4
	ds_read_b128 v[180:183], v147 offset:49152
	ds_read_b128 v[184:187], v147 offset:50176
	ds_read_b128 v[188:191], v147 offset:51200
	ds_read_b128 v[192:195], v147 offset:52224
	ds_read_b128 v[196:199], v147 offset:53248
	ds_read_b128 v[200:203], v147 offset:54272
	ds_read_b128 v[204:207], v147 offset:55296
	ds_read_b128 v[208:211], v147 offset:56320
	global_load_lds_dwordx4 v[212:213], off
	s_add_i32 m0, s4, 0x2000
	s_add_u32 s4, s38, 0x40080
	v_lshl_add_u64 v[212:213], v[214:215], 0, s[8:9]
	s_addc_u32 s5, s39, 0
	s_add_i32 s38, s50, s68
	global_load_lds_dwordx4 v[212:213], off
	v_lshl_add_u64 v[212:213], s[4:5], 0, v[130:131]
	s_mov_b32 m0, s38
	s_nop 0
	global_load_lds_dwordx4 v[212:213], off
	v_lshl_add_u64 v[212:213], s[4:5], 0, v[134:135]
	s_add_i32 m0, s38, 0x2000
	s_nop 0
	global_load_lds_dwordx4 v[212:213], off
	v_lshl_add_u64 v[212:213], v[216:217], 0, s[8:9]
	s_mov_b32 m0, s75
	s_nop 0
	global_load_lds_dwordx4 v[212:213], off
	v_lshl_add_u64 v[212:213], v[218:219], 0, s[8:9]
	s_mov_b32 m0, s76
	s_nop 0
	global_load_lds_dwordx4 v[212:213], off
	s_waitcnt vmcnt(8)
	s_waitcnt lgkmcnt(0)
	s_barrier
	s_setprio 1
	s_waitcnt lgkmcnt(0)
	v_mfma_f32_16x16x32_bf16 v[60:63], v[148:151], v[180:183], v[60:63]
	v_mfma_f32_16x16x32_bf16 v[56:59], v[156:159], v[180:183], v[56:59]
	v_mfma_f32_16x16x32_bf16 v[44:47], v[148:151], v[188:191], v[44:47]
	v_mfma_f32_16x16x32_bf16 v[40:43], v[156:159], v[188:191], v[40:43]
	v_mfma_f32_16x16x32_bf16 v[28:31], v[148:151], v[196:199], v[28:31]
	v_mfma_f32_16x16x32_bf16 v[24:27], v[156:159], v[196:199], v[24:27]
	v_mfma_f32_16x16x32_bf16 v[12:15], v[148:151], v[204:207], v[12:15]
	v_mfma_f32_16x16x32_bf16 v[8:11], v[156:159], v[204:207], v[8:11]
	v_mfma_f32_16x16x32_bf16 v[60:63], v[152:155], v[184:187], v[60:63]
	v_mfma_f32_16x16x32_bf16 v[56:59], v[160:163], v[184:187], v[56:59]
	v_mfma_f32_16x16x32_bf16 v[44:47], v[152:155], v[192:195], v[44:47]
	v_mfma_f32_16x16x32_bf16 v[40:43], v[160:163], v[192:195], v[40:43]
	v_mfma_f32_16x16x32_bf16 v[28:31], v[152:155], v[200:203], v[28:31]
	v_mfma_f32_16x16x32_bf16 v[24:27], v[160:163], v[200:203], v[24:27]
	v_mfma_f32_16x16x32_bf16 v[12:15], v[152:155], v[208:211], v[12:15]
	v_mfma_f32_16x16x32_bf16 v[8:11], v[160:163], v[208:211], v[8:11]
	s_setprio 0
	s_setprio 1
	v_mfma_f32_16x16x32_bf16 v[52:55], v[164:167], v[180:183], v[52:55]
	v_mfma_f32_16x16x32_bf16 v[48:51], v[172:175], v[180:183], v[48:51]
	v_mfma_f32_16x16x32_bf16 v[36:39], v[164:167], v[188:191], v[36:39]
	v_mfma_f32_16x16x32_bf16 v[32:35], v[172:175], v[188:191], v[32:35]
	v_mfma_f32_16x16x32_bf16 v[20:23], v[164:167], v[196:199], v[20:23]
	v_mfma_f32_16x16x32_bf16 v[16:19], v[172:175], v[196:199], v[16:19]
	v_mfma_f32_16x16x32_bf16 v[4:7], v[164:167], v[204:207], v[4:7]
	v_mfma_f32_16x16x32_bf16 v[0:3], v[172:175], v[204:207], v[0:3]
	v_mfma_f32_16x16x32_bf16 v[52:55], v[168:171], v[184:187], v[52:55]
	v_mfma_f32_16x16x32_bf16 v[48:51], v[176:179], v[184:187], v[48:51]
	v_mfma_f32_16x16x32_bf16 v[36:39], v[168:171], v[192:195], v[36:39]
	v_mfma_f32_16x16x32_bf16 v[32:35], v[176:179], v[192:195], v[32:35]
	v_mfma_f32_16x16x32_bf16 v[20:23], v[168:171], v[200:203], v[20:23]
	v_mfma_f32_16x16x32_bf16 v[16:19], v[176:179], v[200:203], v[16:19]
	v_mfma_f32_16x16x32_bf16 v[4:7], v[168:171], v[208:211], v[4:7]
	v_mfma_f32_16x16x32_bf16 v[0:3], v[176:179], v[208:211], v[0:3]
	s_setprio 0
	s_barrier
	s_add_i32 s96, s96, 2
	s_add_u32 s94, s94, 0x100
	s_addc_u32 s95, s95, 0
	s_add_u32 s36, s36, 0x100
	s_addc_u32 s37, s37, 0
	s_cmp_gt_u32 s96, 13
	s_cbranch_scc0 .LBB0_485
	s_mov_b32 s32, 1
	s_and_b64 vcc, exec, s[10:11]
	s_cbranch_vccz .LBB0_488
	s_barrier

; #define PG8_STAGE(bufoff, gbase, voff) do { _Pragma("unroll") for (int _i = 0; _i < 2; ++_i) \
;         __builtin_amdgcn_global_load_lds((const unsigned*)((const char*)(gbase) + (voff)[_i]), (LAS unsigned*)(lds + (bufoff) + ldsw + _i * 8192), 16, 0, 0); } while (0)
; #define PG8_WAIT_V(n) asm volatile("s_waitcnt vmcnt(" #n ")" ::: "memory")
; #define PG8_BAR __builtin_amdgcn_s_barrier()
; template <class Epi>
; __device__ __forceinline__ void gemm_phase(LAS unsigned char* lds, const Gemm g, const StaticOrder& S, const Epi& E, const int wid) {
;     ...
;     for (int i = 0; i < 2; ++i) { int R, C; stage_rc(tid * 16 + i * 8192, R, C); const int Rb = Epi::PERM ? ((R & ~31) + perm32(R & 31)) : R;
;         voffA[i] = (unsigned)(R * lda + C) * 2u; voffB[i] = (unsigned)(Rb * K + C) * 2u; }
;     const size_t kstep = (size_t)(BK * 2);
;     const size_t hsA = (size_t)HALF * lda * 2, hsB = (size_t)HALF * K * 2;
;     const size_t tsA = 2 * hsA, tsB = 2 * hsB;
;     const unsigned ldsw = (unsigned)wid * 1024u;
;     const int aoff = lds_byte(wr * 64 + fr, fq * 8), boff = lds_byte(wc * 32 + fr, fq * 8);
;     ...
;     PG8_STAGE(PG8_SB(0, 0), cB, voffB); PG8_STAGE(PG8_SB(0, 1), cB + hsB, voffB); PG8_STAGE(PG8_SA(0, 0), cA, voffA); PG8_STAGE(PG8_SA(0, 1), cA + hsA, voffA);
;     if (wr == 1) PG8_BAR;
;     PG8_WAIT_V(2); PG8_BAR;
;     PG8_STAGE(PG8_SB(1, 0), cB + kstep, voffB); PG8_STAGE(PG8_SA(1, 0), cA + kstep, voffA); PG8_STAGE(PG8_SB(1, 1), cB + hsB + kstep, voffB);
;     PG8_WAIT_V(6); PG8_BAR;
.LBB0_545:
	s_mov_b64 s[10:11], 0x80
	s_add_i32 m0, s27, 0x18000
	v_lshl_add_u64 v[6:7], v[6:7], 0, s[10:11]
	global_load_lds_dwordx4 v[6:7], off
	v_lshl_add_u64 v[4:5], v[4:5], 0, s[10:11]
	s_add_i32 m0, s27, 0x1a000
	s_add_i32 s64, s27, 0x8000
	s_add_i32 s65, s27, 0xa000
	global_load_lds_dwordx4 v[4:5], off
	v_lshl_add_u64 v[0:1], v[0:1], 0, s[10:11]
	s_mov_b32 m0, s64
	s_add_u32 s4, s28, 0x100080
	global_load_lds_dwordx4 v[0:1], off
	v_lshl_add_u64 v[0:1], v[2:3], 0, s[10:11]
	s_mov_b32 m0, s65
	s_addc_u32 s5, s29, 0
	global_load_lds_dwordx4 v[0:1], off
	s_add_i32 m0, s27, 0x1c000
	v_lshl_add_u64 v[0:1], s[4:5], 0, v[194:195]
	global_load_lds_dwordx4 v[0:1], off
	v_lshl_add_u64 v[0:1], s[4:5], 0, v[198:199]
	s_add_i32 m0, s27, 0x1e000
	v_and_b32_e32 v2, 48, v8
	global_load_lds_dwordx4 v[0:1], off
	s_waitcnt vmcnt(8)
	s_barrier
	v_and_b32_e32 v0, 15, v8
	v_ashrrev_i32_e32 v1, 6, v8
	v_readlane_b32 s1, v254, 3
	v_lshl_or_b32 v0, v0, 6, v2
	v_lshlrev_b32_e32 v3, 2, v8
	v_lshl_add_u32 v2, v1, 10, s1
	v_readlane_b32 s1, v254, 5
	v_and_b32_e32 v3, 32, v3
	v_bitop3_b32 v2, v0, v2, v3 bitop3:0xde
	v_add_lshl_u32 v1, v1, s1, 10
	v_bitop3_b32 v240, v0, v1, v3 bitop3:0xde
	v_lshlrev_b32_e32 v0, 16, v12
	v_and_b32_e32 v0, 0xfffe0000, v0
	v_lshl_add_u32 v0, v13, 13, v0
	v_and_b32_e32 v1, 1, v12
	v_lshl_or_b32 v0, v1, 6, v0
	v_lshl_add_u32 v200, v14, 1, v0
	v_lshlrev_b32_e32 v0, 16, v9
	v_and_b32_e32 v0, 0xfffe0000, v0
	s_waitcnt vmcnt(6)
	s_mov_b32 s32, 0
	s_cmpk_lt_u32 s3, 0x100
	v_lshl_add_u32 v0, v10, 13, v0
	v_and_b32_e32 v1, 1, v9
	s_cselect_b64 s[16:17], -1, 0
	s_lshl_b32 s1, s33, 4
	v_lshl_or_b32 v0, v1, 6, v0
	s_add_i32 s76, 0, 0x10000
	s_add_i32 s77, 0, 0x14000
	s_and_b32 s66, s1, 0x3fffffc0
	s_ashr_i32 s67, s56, 31
	s_mov_b32 s74, s56
	s_ashr_i32 s75, s2, 31
	v_mov_b32_e32 v201, v195
	v_lshl_add_u32 v202, v11, 1, v0
	v_mov_b32_e32 v203, v195
	v_add_u32_e32 v241, s76, v240
	v_add_u32_e32 v242, s77, v240
	v_add_u32_e32 v243, 0, v2
	v_mov_b32_e32 v245, 0x358637bd
	v_mbcnt_hi_u32_b32 v246, -1, v244
	s_barrier
	s_branch .LBB0_548

; #define PG8_STAGE(bufoff, gbase, voff) do { _Pragma("unroll") for (int _i = 0; _i < 2; ++_i) \
;         __builtin_amdgcn_global_load_lds((const unsigned*)((const char*)(gbase) + (voff)[_i]), (LAS unsigned*)(lds + (bufoff) + ldsw + _i * 8192), 16, 0, 0); } while (0)
; #define PG8_LDA(dst, b, h) do { _Pragma("unroll") for (int m = 0; m < 4; ++m) _Pragma("unroll") for (int k = 0; k < 2; ++k) dst[m][k] = *(const LAS bf16x8*)(lds + PG8_SA(b, h) + aoff + m * 2048 + k * 1024); } while (0)
; #define PG8_LDB(dst, b, h) do { _Pragma("unroll") for (int n = 0; n < 2; ++n) _Pragma("unroll") for (int k = 0; k < 2; ++k) dst[n][k] = *(const LAS bf16x8*)(lds + PG8_SB(b, h) + boff + n * 2048 + k * 1024); } while (0)
; #define PG8_MMA(ai, bj, At, Bt) do { __builtin_amdgcn_s_setprio(1); _Pragma("unroll") for (int m = 0; m < 4; ++m) _Pragma("unroll") for (int n = 0; n < 2; ++n) _Pragma("unroll") for (int k = 0; k < 2; ++k) \
;         acc[ai][bj][m][n] = __builtin_amdgcn_mfma_f32_16x16x32_bf16(Bt[n][k], At[m][k], acc[ai][bj][m][n], 0, 0, 0); __builtin_amdgcn_s_setprio(0); } while (0)
; #define PG8_WAIT_V(n) asm volatile("s_waitcnt vmcnt(" #n ")" ::: "memory")
; #define PG8_WAIT_L(n) asm volatile("s_waitcnt lgkmcnt(" #n ")" ::: "memory")
; #define PG8_BAR __builtin_amdgcn_s_barrier()
; #define PG8_SCHED __builtin_amdgcn_sched_barrier(0)
; template <class Epi>
; __device__ __forceinline__ void gemm_phase(LAS unsigned char* lds, const Gemm g, const StaticOrder& S, const Epi& E, const int wid) {
;     ...
;         for (int t = 0; t < nt; t += 2) {
;             const bool last = (t == nt - 2);
;             const char* a1 = cA + (size_t)(t + 1) * kstep;
;             const char* a2 = last ? nA : cA + (size_t)(t + 2) * kstep; const char* b2 = last ? nB : cB + (size_t)(t + 2) * kstep;
;             const char* a3 = a2 + kstep; const char* b3 = b2 + kstep;
;             PG8_LDB(B0, 0, 0); PG8_LDB(B1, 0, 1); PG8_SCHED; PG8_LDA(At, 0, 0); PG8_STAGE(PG8_SA(1, 1), a1 + hsA, voffA);
;             PG8_WAIT_V(8); PG8_WAIT_L(0); PG8_BAR; PG8_MMA(0, 0, At, B0); PG8_MMA(0, 1, At, B1); PG8_BAR; PG8_SCHED;
.LBB0_555:
	ds_read_b128 v[124:127], v241
	ds_read_b128 v[132:135], v241 offset:1024
	ds_read_b128 v[136:139], v241 offset:2048
	ds_read_b128 v[140:143], v241 offset:3072
	ds_read_b128 v[144:147], v242
	ds_read_b128 v[148:151], v242 offset:1024
	ds_read_b128 v[152:155], v242 offset:2048
	ds_read_b128 v[156:159], v242 offset:3072
	s_add_u32 s4, s28, 0xfff00080
	s_addc_u32 s5, s29, -1
	s_cmp_eq_u32 s81, 60
	s_cselect_b32 s35, s1, s5
	s_cselect_b32 s34, s21, s4
	s_cselect_b32 s31, s19, s80
	s_cselect_b32 s30, s78, s79
	v_lshl_add_u64 v[204:205], s[28:29], 0, v[202:203]
	s_add_i32 m0, s27, 0xc000
	ds_read_b128 v[160:163], v243
	ds_read_b128 v[164:167], v243 offset:1024
	ds_read_b128 v[168:171], v243 offset:2048
	ds_read_b128 v[172:175], v243 offset:3072
	ds_read_b128 v[176:179], v243 offset:4096
	ds_read_b128 v[180:183], v243 offset:5120
	ds_read_b128 v[184:187], v243 offset:6144
	ds_read_b128 v[188:191], v243 offset:7168
	global_load_lds_dwordx4 v[204:205], off
	v_lshl_add_u64 v[204:205], s[28:29], 0, v[200:201]
	s_add_i32 m0, s27, 0xe000
	s_nop 0
	global_load_lds_dwordx4 v[204:205], off
	s_cmp_lg_u32 s32, 0
	s_cbranch_scc1 .Lkw4a_b
	s_waitcnt vmcnt(8)
	s_branch .Lkw4a_d

; #define PG8_STAGE(bufoff, gbase, voff) do { _Pragma("unroll") for (int _i = 0; _i < 2; ++_i) \
;         __builtin_amdgcn_global_load_lds((const unsigned*)((const char*)(gbase) + (voff)[_i]), (LAS unsigned*)(lds + (bufoff) + ldsw + _i * 8192), 16, 0, 0); } while (0)
; #define PG8_LDA(dst, b, h) do { _Pragma("unroll") for (int m = 0; m < 4; ++m) _Pragma("unroll") for (int k = 0; k < 2; ++k) dst[m][k] = *(const LAS bf16x8*)(lds + PG8_SA(b, h) + aoff + m * 2048 + k * 1024); } while (0)
; #define PG8_MMA(ai, bj, At, Bt) do { __builtin_amdgcn_s_setprio(1); _Pragma("unroll") for (int m = 0; m < 4; ++m) _Pragma("unroll") for (int n = 0; n < 2; ++n) _Pragma("unroll") for (int k = 0; k < 2; ++k) \
;         acc[ai][bj][m][n] = __builtin_amdgcn_mfma_f32_16x16x32_bf16(Bt[n][k], At[m][k], acc[ai][bj][m][n], 0, 0, 0); __builtin_amdgcn_s_setprio(0); } while (0)
; #define PG8_WAIT_V(n) asm volatile("s_waitcnt vmcnt(" #n ")" ::: "memory")
; #define PG8_WAIT_L(n) asm volatile("s_waitcnt lgkmcnt(" #n ")" ::: "memory")
; #define PG8_BAR __builtin_amdgcn_s_barrier()
; #define PG8_SCHED __builtin_amdgcn_sched_barrier(0)
; template <class Epi>
; __device__ __forceinline__ void gemm_phase(LAS unsigned char* lds, const Gemm g, const StaticOrder& S, const Epi& E, const int wid) {
;     ...
;             PG8_WAIT_V(8); PG8_WAIT_L(0); PG8_BAR; PG8_MMA(0, 0, At, B0); PG8_MMA(0, 1, At, B1); PG8_BAR; PG8_SCHED;
;             PG8_LDA(At, 0, 1); PG8_STAGE(PG8_SB(0, 0), b2, voffB); PG8_STAGE(PG8_SB(0, 1), b2 + hsB, voffB); PG8_STAGE(PG8_SA(0, 0), a2, voffA);
;             PG8_WAIT_V(8); PG8_WAIT_L(0); PG8_BAR; PG8_MMA(1, 0, At, B0); PG8_MMA(1, 1, At, B1); PG8_BAR; PG8_SCHED;
.Lkw4a_d:
	s_waitcnt lgkmcnt(0)
	s_barrier
	s_setprio 1
	s_waitcnt lgkmcnt(0)
	v_mfma_f32_16x16x32_bf16 v[128:131], v[124:127], v[160:163], v[128:131]
	v_mfma_f32_16x16x32_bf16 v[120:123], v[136:139], v[160:163], v[120:123]
	v_mfma_f32_16x16x32_bf16 v[108:111], v[124:127], v[168:171], v[108:111]
	v_mfma_f32_16x16x32_bf16 v[104:107], v[136:139], v[168:171], v[104:107]
	v_mfma_f32_16x16x32_bf16 v[92:95], v[124:127], v[176:179], v[92:95]
	v_mfma_f32_16x16x32_bf16 v[88:91], v[136:139], v[176:179], v[88:91]
	v_mfma_f32_16x16x32_bf16 v[76:79], v[124:127], v[184:187], v[76:79]
	v_mfma_f32_16x16x32_bf16 v[72:75], v[136:139], v[184:187], v[72:75]
	v_mfma_f32_16x16x32_bf16 v[128:131], v[132:135], v[164:167], v[128:131]
	v_mfma_f32_16x16x32_bf16 v[120:123], v[140:143], v[164:167], v[120:123]
	v_mfma_f32_16x16x32_bf16 v[108:111], v[132:135], v[172:175], v[108:111]
	v_mfma_f32_16x16x32_bf16 v[104:107], v[140:143], v[172:175], v[104:107]
	v_mfma_f32_16x16x32_bf16 v[92:95], v[132:135], v[180:183], v[92:95]
	v_mfma_f32_16x16x32_bf16 v[88:91], v[140:143], v[180:183], v[88:91]
	v_mfma_f32_16x16x32_bf16 v[76:79], v[132:135], v[188:191], v[76:79]
	v_mfma_f32_16x16x32_bf16 v[72:75], v[140:143], v[188:191], v[72:75]
	s_setprio 0
	s_setprio 1
	v_mfma_f32_16x16x32_bf16 v[116:119], v[144:147], v[160:163], v[116:119]
	v_mfma_f32_16x16x32_bf16 v[112:115], v[152:155], v[160:163], v[112:115]
	v_mfma_f32_16x16x32_bf16 v[100:103], v[144:147], v[168:171], v[100:103]
	v_mfma_f32_16x16x32_bf16 v[96:99], v[152:155], v[168:171], v[96:99]
	v_mfma_f32_16x16x32_bf16 v[84:87], v[144:147], v[176:179], v[84:87]
	v_mfma_f32_16x16x32_bf16 v[80:83], v[152:155], v[176:179], v[80:83]
	v_mfma_f32_16x16x32_bf16 v[68:71], v[144:147], v[184:187], v[68:71]
	v_mfma_f32_16x16x32_bf16 v[64:67], v[152:155], v[184:187], v[64:67]
	v_mfma_f32_16x16x32_bf16 v[116:119], v[148:151], v[164:167], v[116:119]
	v_mfma_f32_16x16x32_bf16 v[112:115], v[156:159], v[164:167], v[112:115]
	v_mfma_f32_16x16x32_bf16 v[100:103], v[148:151], v[172:175], v[100:103]
	v_mfma_f32_16x16x32_bf16 v[96:99], v[156:159], v[172:175], v[96:99]
	v_mfma_f32_16x16x32_bf16 v[84:87], v[148:151], v[180:183], v[84:87]
	v_mfma_f32_16x16x32_bf16 v[80:83], v[156:159], v[180:183], v[80:83]
	v_mfma_f32_16x16x32_bf16 v[68:71], v[148:151], v[188:191], v[68:71]
	v_mfma_f32_16x16x32_bf16 v[64:67], v[156:159], v[188:191], v[64:67]
	s_setprio 0
	s_barrier
	s_add_i32 s4, s76, s68
	v_lshl_add_u64 v[204:205], s[30:31], 0, v[194:195]
	s_mov_b32 m0, s4
	ds_read_b128 v[160:163], v243 offset:16384
	ds_read_b128 v[164:167], v243 offset:17408
	ds_read_b128 v[168:171], v243 offset:18432
	ds_read_b128 v[172:175], v243 offset:19456
	ds_read_b128 v[176:179], v243 offset:20480
	ds_read_b128 v[180:183], v243 offset:21504
	ds_read_b128 v[184:187], v243 offset:22528
	ds_read_b128 v[188:191], v243 offset:23552
	global_load_lds_dwordx4 v[204:205], off
	s_add_i32 m0, s4, 0x2000
	s_add_u32 s4, s30, 0x100000
	v_lshl_add_u64 v[206:207], s[30:31], 0, v[198:199]
	s_addc_u32 s5, s31, 0
	s_add_i32 s47, s77, s68
	global_load_lds_dwordx4 v[206:207], off
	v_lshl_add_u64 v[208:209], s[4:5], 0, v[194:195]
	s_mov_b32 m0, s47
	v_lshl_add_u64 v[210:211], s[34:35], 0, v[196:197]
	global_load_lds_dwordx4 v[208:209], off
	v_lshl_add_u64 v[208:209], s[4:5], 0, v[198:199]
	s_add_i32 m0, s47, 0x2000
	s_nop 0
	global_load_lds_dwordx4 v[208:209], off
	v_lshl_add_u64 v[208:209], s[34:35], 0, v[192:193]
	s_mov_b32 m0, s27
	s_nop 0
	global_load_lds_dwordx4 v[208:209], off
	s_mov_b32 m0, s38
	s_nop 0
	global_load_lds_dwordx4 v[210:211], off
	s_cmp_lg_u32 s32, 0
	s_cbranch_scc1 .Lkw4b_b
	s_waitcnt vmcnt(8)
	s_branch .Lkw4b_d

; #define PG8_STAGE(bufoff, gbase, voff) do { _Pragma("unroll") for (int _i = 0; _i < 2; ++_i) \
;         __builtin_amdgcn_global_load_lds((const unsigned*)((const char*)(gbase) + (voff)[_i]), (LAS unsigned*)(lds + (bufoff) + ldsw + _i * 8192), 16, 0, 0); } while (0)
; #define PG8_LDA(dst, b, h) do { _Pragma("unroll") for (int m = 0; m < 4; ++m) _Pragma("unroll") for (int k = 0; k < 2; ++k) dst[m][k] = *(const LAS bf16x8*)(lds + PG8_SA(b, h) + aoff + m * 2048 + k * 1024); } while (0)
; #define PG8_LDB(dst, b, h) do { _Pragma("unroll") for (int n = 0; n < 2; ++n) _Pragma("unroll") for (int k = 0; k < 2; ++k) dst[n][k] = *(const LAS bf16x8*)(lds + PG8_SB(b, h) + boff + n * 2048 + k * 1024); } while (0)
; #define PG8_MMA(ai, bj, At, Bt) do { __builtin_amdgcn_s_setprio(1); _Pragma("unroll") for (int m = 0; m < 4; ++m) _Pragma("unroll") for (int n = 0; n < 2; ++n) _Pragma("unroll") for (int k = 0; k < 2; ++k) \
;         acc[ai][bj][m][n] = __builtin_amdgcn_mfma_f32_16x16x32_bf16(Bt[n][k], At[m][k], acc[ai][bj][m][n], 0, 0, 0); __builtin_amdgcn_s_setprio(0); } while (0)
; #define PG8_WAIT_V(n) asm volatile("s_waitcnt vmcnt(" #n ")" ::: "memory")
; #define PG8_WAIT_L(n) asm volatile("s_waitcnt lgkmcnt(" #n ")" ::: "memory")
; #define PG8_BAR __builtin_amdgcn_s_barrier()
; #define PG8_SCHED __builtin_amdgcn_sched_barrier(0)
; template <class Epi>
; __device__ __forceinline__ void gemm_phase(LAS unsigned char* lds, const Gemm g, const StaticOrder& S, const Epi& E, const int wid) {
;     ...
;             PG8_WAIT_V(8); PG8_WAIT_L(0); PG8_BAR; PG8_MMA(1, 0, At, B0); PG8_MMA(1, 1, At, B1); PG8_BAR; PG8_SCHED;
;             PG8_LDB(B0, 1, 0); PG8_LDB(B1, 1, 1); PG8_SCHED; PG8_LDA(At, 1, 0); PG8_STAGE(PG8_SA(0, 1), a2 + hsA, voffA);
;             PG8_WAIT_V(8); PG8_WAIT_L(0); PG8_BAR; PG8_MMA(0, 0, At, B0); PG8_MMA(0, 1, At, B1); PG8_BAR; PG8_SCHED;
.Lkw4b_d:
	s_mov_b32 s32, 0
	s_waitcnt lgkmcnt(0)
	s_barrier
	s_setprio 1
	s_waitcnt lgkmcnt(0)
	v_mfma_f32_16x16x32_bf16 v[60:63], v[124:127], v[160:163], v[60:63]
	v_mfma_f32_16x16x32_bf16 v[56:59], v[136:139], v[160:163], v[56:59]
	v_mfma_f32_16x16x32_bf16 v[44:47], v[124:127], v[168:171], v[44:47]
	v_mfma_f32_16x16x32_bf16 v[40:43], v[136:139], v[168:171], v[40:43]
	v_mfma_f32_16x16x32_bf16 v[28:31], v[124:127], v[176:179], v[28:31]
	v_mfma_f32_16x16x32_bf16 v[24:27], v[136:139], v[176:179], v[24:27]
	v_mfma_f32_16x16x32_bf16 v[12:15], v[124:127], v[184:187], v[12:15]
	v_mfma_f32_16x16x32_bf16 v[8:11], v[136:139], v[184:187], v[8:11]
	v_mfma_f32_16x16x32_bf16 v[60:63], v[132:135], v[164:167], v[60:63]
	v_mfma_f32_16x16x32_bf16 v[56:59], v[140:143], v[164:167], v[56:59]
	v_mfma_f32_16x16x32_bf16 v[44:47], v[132:135], v[172:175], v[44:47]
	v_mfma_f32_16x16x32_bf16 v[40:43], v[140:143], v[172:175], v[40:43]
	v_mfma_f32_16x16x32_bf16 v[28:31], v[132:135], v[180:183], v[28:31]
	v_mfma_f32_16x16x32_bf16 v[24:27], v[140:143], v[180:183], v[24:27]
	v_mfma_f32_16x16x32_bf16 v[12:15], v[132:135], v[188:191], v[12:15]
	v_mfma_f32_16x16x32_bf16 v[8:11], v[140:143], v[188:191], v[8:11]
	s_setprio 0
	s_setprio 1
	v_mfma_f32_16x16x32_bf16 v[52:55], v[144:147], v[160:163], v[52:55]
	v_mfma_f32_16x16x32_bf16 v[48:51], v[152:155], v[160:163], v[48:51]
	v_mfma_f32_16x16x32_bf16 v[36:39], v[144:147], v[168:171], v[36:39]
	v_mfma_f32_16x16x32_bf16 v[32:35], v[152:155], v[168:171], v[32:35]
	v_mfma_f32_16x16x32_bf16 v[20:23], v[144:147], v[176:179], v[20:23]
	v_mfma_f32_16x16x32_bf16 v[16:19], v[152:155], v[176:179], v[16:19]
	v_mfma_f32_16x16x32_bf16 v[4:7], v[144:147], v[184:187], v[4:7]
	v_mfma_f32_16x16x32_bf16 v[0:3], v[152:155], v[184:187], v[0:3]
	v_mfma_f32_16x16x32_bf16 v[52:55], v[148:151], v[164:167], v[52:55]
	v_mfma_f32_16x16x32_bf16 v[48:51], v[156:159], v[164:167], v[48:51]
	v_mfma_f32_16x16x32_bf16 v[36:39], v[148:151], v[172:175], v[36:39]
	v_mfma_f32_16x16x32_bf16 v[32:35], v[156:159], v[172:175], v[32:35]
	v_mfma_f32_16x16x32_bf16 v[20:23], v[148:151], v[180:183], v[20:23]
	v_mfma_f32_16x16x32_bf16 v[16:19], v[156:159], v[180:183], v[16:19]
	v_mfma_f32_16x16x32_bf16 v[4:7], v[148:151], v[188:191], v[4:7]
	v_mfma_f32_16x16x32_bf16 v[0:3], v[156:159], v[188:191], v[0:3]
	s_setprio 0
	s_barrier
	s_add_i32 s47, 0, 0x18000
	s_add_i32 s50, 0, 0x1c000
	v_add_u32_e32 v140, s47, v240
	v_add_u32_e32 v156, s50, v240
	ds_read_b128 v[124:127], v140
	ds_read_b128 v[132:135], v140 offset:1024
	ds_read_b128 v[136:139], v140 offset:2048
	ds_read_b128 v[140:143], v140 offset:3072
	ds_read_b128 v[144:147], v156
	ds_read_b128 v[148:151], v156 offset:1024
	ds_read_b128 v[152:155], v156 offset:2048
	ds_read_b128 v[156:159], v156 offset:3072
	s_add_u32 s4, s34, 0x100000
	s_addc_u32 s5, s35, 0
	s_mov_b32 m0, s39
	v_lshl_add_u64 v[212:213], s[4:5], 0, v[192:193]
	ds_read_b128 v[160:163], v243 offset:32768
	ds_read_b128 v[164:167], v243 offset:33792
	ds_read_b128 v[168:171], v243 offset:34816
	ds_read_b128 v[172:175], v243 offset:35840
	ds_read_b128 v[176:179], v243 offset:36864
	ds_read_b128 v[180:183], v243 offset:37888
	ds_read_b128 v[184:187], v243 offset:38912
	ds_read_b128 v[188:191], v243 offset:39936
	global_load_lds_dwordx4 v[212:213], off
	v_lshl_add_u64 v[212:213], s[4:5], 0, v[196:197]
	s_mov_b32 m0, s62
	s_nop 0
	global_load_lds_dwordx4 v[212:213], off
	s_waitcnt vmcnt(8)
	s_waitcnt lgkmcnt(0)
	s_barrier
	s_setprio 1
	s_waitcnt lgkmcnt(0)
	v_mfma_f32_16x16x32_bf16 v[128:131], v[124:127], v[160:163], v[128:131]
	v_mfma_f32_16x16x32_bf16 v[120:123], v[136:139], v[160:163], v[120:123]
	v_mfma_f32_16x16x32_bf16 v[108:111], v[124:127], v[168:171], v[108:111]
	v_mfma_f32_16x16x32_bf16 v[104:107], v[136:139], v[168:171], v[104:107]
	v_mfma_f32_16x16x32_bf16 v[92:95], v[124:127], v[176:179], v[92:95]
	v_mfma_f32_16x16x32_bf16 v[88:91], v[136:139], v[176:179], v[88:91]
	v_mfma_f32_16x16x32_bf16 v[76:79], v[124:127], v[184:187], v[76:79]
	v_mfma_f32_16x16x32_bf16 v[72:75], v[136:139], v[184:187], v[72:75]
	v_mfma_f32_16x16x32_bf16 v[128:131], v[132:135], v[164:167], v[128:131]
	v_mfma_f32_16x16x32_bf16 v[120:123], v[140:143], v[164:167], v[120:123]
	v_mfma_f32_16x16x32_bf16 v[108:111], v[132:135], v[172:175], v[108:111]
	v_mfma_f32_16x16x32_bf16 v[104:107], v[140:143], v[172:175], v[104:107]
	v_mfma_f32_16x16x32_bf16 v[92:95], v[132:135], v[180:183], v[92:95]
	v_mfma_f32_16x16x32_bf16 v[88:91], v[140:143], v[180:183], v[88:91]
	v_mfma_f32_16x16x32_bf16 v[76:79], v[132:135], v[188:191], v[76:79]
	v_mfma_f32_16x16x32_bf16 v[72:75], v[140:143], v[188:191], v[72:75]
	s_setprio 0
	s_setprio 1
	v_mfma_f32_16x16x32_bf16 v[116:119], v[144:147], v[160:163], v[116:119]
	v_mfma_f32_16x16x32_bf16 v[112:115], v[152:155], v[160:163], v[112:115]
	v_mfma_f32_16x16x32_bf16 v[100:103], v[144:147], v[168:171], v[100:103]
	v_mfma_f32_16x16x32_bf16 v[96:99], v[152:155], v[168:171], v[96:99]
	v_mfma_f32_16x16x32_bf16 v[84:87], v[144:147], v[176:179], v[84:87]
	v_mfma_f32_16x16x32_bf16 v[80:83], v[152:155], v[176:179], v[80:83]
	v_mfma_f32_16x16x32_bf16 v[68:71], v[144:147], v[184:187], v[68:71]
	v_mfma_f32_16x16x32_bf16 v[64:67], v[152:155], v[184:187], v[64:67]
	v_mfma_f32_16x16x32_bf16 v[116:119], v[148:151], v[164:167], v[116:119]
	v_mfma_f32_16x16x32_bf16 v[112:115], v[156:159], v[164:167], v[112:115]
	v_mfma_f32_16x16x32_bf16 v[100:103], v[148:151], v[172:175], v[100:103]
	v_mfma_f32_16x16x32_bf16 v[96:99], v[156:159], v[172:175], v[96:99]
	v_mfma_f32_16x16x32_bf16 v[84:87], v[148:151], v[180:183], v[84:87]
	v_mfma_f32_16x16x32_bf16 v[80:83], v[156:159], v[180:183], v[80:83]
	v_mfma_f32_16x16x32_bf16 v[68:71], v[148:151], v[188:191], v[68:71]
	v_mfma_f32_16x16x32_bf16 v[64:67], v[156:159], v[188:191], v[64:67]
	s_setprio 0
	s_barrier
; #define PG8_STAGE(bufoff, gbase, voff) do { _Pragma("unroll") for (int _i = 0; _i < 2; ++_i) \
;         __builtin_amdgcn_global_load_lds((const unsigned*)((const char*)(gbase) + (voff)[_i]), (LAS unsigned*)(lds + (bufoff) + ldsw + _i * 8192), 16, 0, 0); } while (0)
; #define PG8_LDA(dst, b, h) do { _Pragma("unroll") for (int m = 0; m < 4; ++m) _Pragma("unroll") for (int k = 0; k < 2; ++k) dst[m][k] = *(const LAS bf16x8*)(lds + PG8_SA(b, h) + aoff + m * 2048 + k * 1024); } while (0)
; #define PG8_MMA(ai, bj, At, Bt) do { __builtin_amdgcn_s_setprio(1); _Pragma("unroll") for (int m = 0; m < 4; ++m) _Pragma("unroll") for (int n = 0; n < 2; ++n) _Pragma("unroll") for (int k = 0; k < 2; ++k) \
;         acc[ai][bj][m][n] = __builtin_amdgcn_mfma_f32_16x16x32_bf16(Bt[n][k], At[m][k], acc[ai][bj][m][n], 0, 0, 0); __builtin_amdgcn_s_setprio(0); } while (0)
; #define PG8_WAIT_V(n) asm volatile("s_waitcnt vmcnt(" #n ")" ::: "memory")
; #define PG8_WAIT_L(n) asm volatile("s_waitcnt lgkmcnt(" #n ")" ::: "memory")
; #define PG8_BAR __builtin_amdgcn_s_barrier()
; #define PG8_SCHED __builtin_amdgcn_sched_barrier(0)
; template <class Epi>
; __device__ __forceinline__ void gemm_phase(LAS unsigned char* lds, const Gemm g, const StaticOrder& S, const Epi& E, const int wid) {
;     ...
;             PG8_LDA(At, 1, 1); PG8_STAGE(PG8_SB(1, 0), b3, voffB); PG8_STAGE(PG8_SB(1, 1), b3 + hsB, voffB); PG8_STAGE(PG8_SA(1, 0), a3, voffA);
;             PG8_WAIT_V(8); PG8_WAIT_L(0); PG8_BAR; PG8_MMA(1, 0, At, B0); PG8_MMA(1, 1, At, B1); PG8_BAR; PG8_SCHED;
;         }
;         if (wr == 0) PG8_BAR;
;         E(acc, cur, wid);
;         if (!has_next) break;
	s_add_i32 s4, s47, s68
	v_lshl_add_u64 v[204:205], v[204:205], 0, s[10:11]
	s_mov_b32 m0, s4
	ds_read_b128 v[160:163], v243 offset:49152
	ds_read_b128 v[164:167], v243 offset:50176
	ds_read_b128 v[168:171], v243 offset:51200
	ds_read_b128 v[172:175], v243 offset:52224
	ds_read_b128 v[176:179], v243 offset:53248
	ds_read_b128 v[180:183], v243 offset:54272
	ds_read_b128 v[184:187], v243 offset:55296
	ds_read_b128 v[188:191], v243 offset:56320
	global_load_lds_dwordx4 v[204:205], off
	s_add_i32 m0, s4, 0x2000
	s_add_u32 s4, s30, 0x100080
	v_lshl_add_u64 v[204:205], v[206:207], 0, s[10:11]
	s_addc_u32 s5, s31, 0
	s_add_i32 s30, s50, s68
	global_load_lds_dwordx4 v[204:205], off
	v_lshl_add_u64 v[204:205], s[4:5], 0, v[194:195]
	s_mov_b32 m0, s30
	s_nop 0
	global_load_lds_dwordx4 v[204:205], off
	v_lshl_add_u64 v[204:205], s[4:5], 0, v[198:199]
	s_add_i32 m0, s30, 0x2000
	s_nop 0
	global_load_lds_dwordx4 v[204:205], off
	v_lshl_add_u64 v[204:205], v[208:209], 0, s[10:11]
	s_mov_b32 m0, s64
	s_nop 0
	global_load_lds_dwordx4 v[204:205], off
	v_lshl_add_u64 v[204:205], v[210:211], 0, s[10:11]
	s_mov_b32 m0, s65
	s_nop 0
	global_load_lds_dwordx4 v[204:205], off
	s_waitcnt vmcnt(8)
	s_waitcnt lgkmcnt(0)
	s_barrier
	s_setprio 1
	s_waitcnt lgkmcnt(0)
	v_mfma_f32_16x16x32_bf16 v[60:63], v[124:127], v[160:163], v[60:63]
	v_mfma_f32_16x16x32_bf16 v[56:59], v[136:139], v[160:163], v[56:59]
	v_mfma_f32_16x16x32_bf16 v[44:47], v[124:127], v[168:171], v[44:47]
	v_mfma_f32_16x16x32_bf16 v[40:43], v[136:139], v[168:171], v[40:43]
	v_mfma_f32_16x16x32_bf16 v[28:31], v[124:127], v[176:179], v[28:31]
	v_mfma_f32_16x16x32_bf16 v[24:27], v[136:139], v[176:179], v[24:27]
	v_mfma_f32_16x16x32_bf16 v[12:15], v[124:127], v[184:187], v[12:15]
	v_mfma_f32_16x16x32_bf16 v[8:11], v[136:139], v[184:187], v[8:11]
	v_mfma_f32_16x16x32_bf16 v[60:63], v[132:135], v[164:167], v[60:63]
	v_mfma_f32_16x16x32_bf16 v[56:59], v[140:143], v[164:167], v[56:59]
	v_mfma_f32_16x16x32_bf16 v[44:47], v[132:135], v[172:175], v[44:47]
	v_mfma_f32_16x16x32_bf16 v[40:43], v[140:143], v[172:175], v[40:43]
	v_mfma_f32_16x16x32_bf16 v[28:31], v[132:135], v[180:183], v[28:31]
	v_mfma_f32_16x16x32_bf16 v[24:27], v[140:143], v[180:183], v[24:27]
	v_mfma_f32_16x16x32_bf16 v[12:15], v[132:135], v[188:191], v[12:15]
	v_mfma_f32_16x16x32_bf16 v[8:11], v[140:143], v[188:191], v[8:11]
	s_setprio 0
	s_setprio 1
	v_mfma_f32_16x16x32_bf16 v[52:55], v[144:147], v[160:163], v[52:55]
	v_mfma_f32_16x16x32_bf16 v[48:51], v[152:155], v[160:163], v[48:51]
	v_mfma_f32_16x16x32_bf16 v[36:39], v[144:147], v[168:171], v[36:39]
	v_mfma_f32_16x16x32_bf16 v[32:35], v[152:155], v[168:171], v[32:35]
	v_mfma_f32_16x16x32_bf16 v[20:23], v[144:147], v[176:179], v[20:23]
	v_mfma_f32_16x16x32_bf16 v[16:19], v[152:155], v[176:179], v[16:19]
	v_mfma_f32_16x16x32_bf16 v[4:7], v[144:147], v[184:187], v[4:7]
	v_mfma_f32_16x16x32_bf16 v[0:3], v[152:155], v[184:187], v[0:3]
	v_mfma_f32_16x16x32_bf16 v[52:55], v[148:151], v[164:167], v[52:55]
	v_mfma_f32_16x16x32_bf16 v[48:51], v[156:159], v[164:167], v[48:51]
	v_mfma_f32_16x16x32_bf16 v[36:39], v[148:151], v[172:175], v[36:39]
	v_mfma_f32_16x16x32_bf16 v[32:35], v[156:159], v[172:175], v[32:35]
	v_mfma_f32_16x16x32_bf16 v[20:23], v[148:151], v[180:183], v[20:23]
	v_mfma_f32_16x16x32_bf16 v[16:19], v[156:159], v[180:183], v[16:19]
	v_mfma_f32_16x16x32_bf16 v[4:7], v[148:151], v[188:191], v[4:7]
	v_mfma_f32_16x16x32_bf16 v[0:3], v[156:159], v[188:191], v[0:3]
	s_setprio 0
	s_barrier
	s_add_i32 s81, s81, 2
	s_add_u32 s79, s79, 0x100
	s_addc_u32 s80, s80, 0
	s_add_u32 s28, s28, 0x100
	s_addc_u32 s29, s29, 0
	s_cmp_gt_u32 s81, 61
	s_cbranch_scc0 .LBB0_555
	s_mov_b32 s32, 1
	s_and_b64 vcc, exec, s[16:17]
	s_cbranch_vccz .LBB0_558
	s_barrier

; __device__ __forceinline__ int lane_id_asm() { int l; asm volatile("v_mbcnt_lo_u32_b32 %0, -1, 0\n\tv_mbcnt_hi_u32_b32 %0, -1, %0" : "=v"(l)); return l; }
; #define PG8_STAGE(bufoff, gbase, voff) do { _Pragma("unroll") for (int _i = 0; _i < 2; ++_i) \
;         __builtin_amdgcn_global_load_lds((const unsigned*)((const char*)(gbase) + (voff)[_i]), (LAS unsigned*)(lds + (bufoff) + ldsw + _i * 8192), 16, 0, 0); } while (0)
; #define PG8_WAIT_V(n) asm volatile("s_waitcnt vmcnt(" #n ")" ::: "memory")
; #define PG8_BAR __builtin_amdgcn_s_barrier()
; template <class Epi>
; __device__ __forceinline__ void gemm_phase(LAS unsigned char* lds, const Gemm g, const StaticOrder& S, const Epi& E, const int wid) {
;     const int lane = lane_id_asm(), tid = wid * 64 + lane, wr = wid >> 2, wc = wid & 3, fr = lane & 15, fq = lane >> 4;
;     const int K = g.K, nt = K / BK, lda = g.lda;
;     unsigned voffA[2], voffB[2];
; #pragma unroll
;     for (int i = 0; i < 2; ++i) { int R, C; stage_rc(tid * 16 + i * 8192, R, C); const int Rb = Epi::PERM ? ((R & ~31) + perm32(R & 31)) : R;
;         voffA[i] = (unsigned)(R * lda + C) * 2u; voffB[i] = (unsigned)(Rb * K + C) * 2u; }
;     const size_t kstep = (size_t)(BK * 2);
;     const size_t hsA = (size_t)HALF * lda * 2, hsB = (size_t)HALF * K * 2;
;     const size_t tsA = 2 * hsA, tsB = 2 * hsB;
;     const unsigned ldsw = (unsigned)wid * 1024u;
;     const int aoff = lds_byte(wr * 64 + fr, fq * 8), boff = lds_byte(wc * 32 + fr, fq * 8);
;     ...
;     PG8_WAIT_V(2); PG8_BAR;
;     PG8_STAGE(PG8_SB(1, 0), cB + kstep, voffB); PG8_STAGE(PG8_SA(1, 0), cA + kstep, voffA); PG8_STAGE(PG8_SB(1, 1), cB + hsB + kstep, voffB);
;     PG8_WAIT_V(6); PG8_BAR;
.LBB0_655:
	s_mov_b64 s[16:17], 0x80
	s_add_i32 m0, s38, 0x18000
	v_lshl_add_u64 v[6:7], v[6:7], 0, s[16:17]
	global_load_lds_dwordx4 v[6:7], off
	v_lshl_add_u64 v[4:5], v[4:5], 0, s[16:17]
	s_add_i32 m0, s38, 0x1a000
	s_add_i32 s65, s38, 0x8000
	s_add_i32 s66, s38, 0xa000
	global_load_lds_dwordx4 v[4:5], off
	v_lshl_add_u64 v[0:1], v[0:1], 0, s[16:17]
	s_mov_b32 m0, s65
	s_add_u32 s4, s28, 0x40080
	global_load_lds_dwordx4 v[0:1], off
	v_lshl_add_u64 v[0:1], v[2:3], 0, s[16:17]
	s_mov_b32 m0, s66
	s_addc_u32 s5, s29, 0
	global_load_lds_dwordx4 v[0:1], off
	s_add_i32 m0, s38, 0x1c000
	v_lshl_add_u64 v[0:1], s[4:5], 0, v[154:155]
	global_load_lds_dwordx4 v[0:1], off
	v_lshl_add_u64 v[0:1], s[4:5], 0, v[158:159]
	s_add_i32 m0, s38, 0x1e000
	v_and_b32_e32 v2, 48, v8
	global_load_lds_dwordx4 v[0:1], off
	s_waitcnt vmcnt(8)
	s_barrier
	v_and_b32_e32 v0, 15, v8
	v_ashrrev_i32_e32 v1, 6, v8
	v_readlane_b32 s4, v254, 3
	v_lshl_or_b32 v0, v0, 6, v2
	v_lshlrev_b32_e32 v3, 2, v8
	v_lshl_add_u32 v2, v1, 10, s4
	v_readlane_b32 s4, v254, 5
	v_and_b32_e32 v3, 32, v3
	v_bitop3_b32 v2, v0, v2, v3 bitop3:0xde
	v_add_lshl_u32 v1, v1, s4, 10
	v_bitop3_b32 v182, v0, v1, v3 bitop3:0xde
	v_lshlrev_b32_e32 v0, 14, v12
	v_and_b32_e32 v0, 0xffff8000, v0
	v_lshl_add_u32 v0, v13, 11, v0
	v_and_b32_e32 v1, 1, v12
	v_lshl_or_b32 v0, v1, 6, v0
	v_lshl_add_u32 v160, v14, 1, v0
	v_lshlrev_b32_e32 v0, 14, v9
	v_and_b32_e32 v0, 0xffff8000, v0
	s_waitcnt vmcnt(6)
	s_mov_b32 s32, 0
	s_cmpk_lt_u32 s3, 0x100
	v_lshl_add_u32 v0, v10, 11, v0
	v_and_b32_e32 v1, 1, v9
	s_cselect_b64 s[18:19], -1, 0
	s_lshl_b32 s4, s33, 4
	v_lshl_or_b32 v0, v1, 6, v0
	s_add_i32 s77, 0, 0x10000
	s_add_i32 s78, 0, 0x14000
	s_and_b32 s67, s4, 0x3fffffc0
	s_ashr_i32 s74, s56, 31
	s_mov_b32 s75, s56
	s_ashr_i32 s76, s2, 31
	v_mov_b32_e32 v161, v155
	v_lshl_add_u32 v162, v11, 1, v0
	v_mov_b32_e32 v163, v155
	v_mov_b64_e32 v[164:165], 0x200
	v_mov_b64_e32 v[166:167], 0x1ff
	v_add_u32_e32 v183, s77, v182
	v_add_u32_e32 v184, s78, v182
	v_add_u32_e32 v185, 0, v2
	v_mov_b32_e32 v186, 0x358637bd
	v_mbcnt_hi_u32_b32 v187, -1, v244
	s_barrier
	s_branch .LBB0_658

; #define PG8_STAGE(bufoff, gbase, voff) do { _Pragma("unroll") for (int _i = 0; _i < 2; ++_i) \
;         __builtin_amdgcn_global_load_lds((const unsigned*)((const char*)(gbase) + (voff)[_i]), (LAS unsigned*)(lds + (bufoff) + ldsw + _i * 8192), 16, 0, 0); } while (0)
; #define PG8_LDA(dst, b, h) do { _Pragma("unroll") for (int m = 0; m < 4; ++m) _Pragma("unroll") for (int k = 0; k < 2; ++k) dst[m][k] = *(const LAS bf16x8*)(lds + PG8_SA(b, h) + aoff + m * 2048 + k * 1024); } while (0)
; #define PG8_LDB(dst, b, h) do { _Pragma("unroll") for (int n = 0; n < 2; ++n) _Pragma("unroll") for (int k = 0; k < 2; ++k) dst[n][k] = *(const LAS bf16x8*)(lds + PG8_SB(b, h) + boff + n * 2048 + k * 1024); } while (0)
; #define PG8_SCHED __builtin_amdgcn_sched_barrier(0)
; template <class Epi>
; __device__ __forceinline__ void gemm_phase(LAS unsigned char* lds, const Gemm g, const StaticOrder& S, const Epi& E, const int wid) {
;     ...
;         for (int t = 0; t < nt; t += 2) {
;             const bool last = (t == nt - 2);
;             const char* a1 = cA + (size_t)(t + 1) * kstep;
;             const char* a2 = last ? nA : cA + (size_t)(t + 2) * kstep; const char* b2 = last ? nB : cB + (size_t)(t + 2) * kstep;
;             const char* a3 = a2 + kstep; const char* b3 = b2 + kstep;
;             PG8_LDB(B0, 0, 0); PG8_LDB(B1, 0, 1); PG8_SCHED; PG8_LDA(At, 0, 0); PG8_STAGE(PG8_SA(1, 1), a1 + hsA, voffA);
.LBB0_665:
	ds_read_b128 v[128:131], v183
	ds_read_b128 v[132:135], v183 offset:1024
	ds_read_b128 v[136:139], v183 offset:2048
	ds_read_b128 v[140:143], v183 offset:3072
	ds_read_b128 v[144:147], v184
	ds_read_b128 v[148:151], v184 offset:1024
	ds_read_b128 v[168:171], v184 offset:2048
	ds_read_b128 v[172:175], v184 offset:3072
	s_add_u32 s4, s28, 0xfffc0080
	s_addc_u32 s5, s29, -1
	s_cmp_eq_u32 s81, 12
	s_cselect_b32 s35, s9, s5
	s_cselect_b32 s34, s11, s4
	s_cselect_b32 s31, s21, s80
	s_cselect_b32 s30, s23, s79
	v_lshl_add_u64 v[180:181], s[28:29], 0, v[162:163]
	s_add_i32 m0, s38, 0xc000
	ds_read_b128 v[176:179], v185
	ds_read_b128 v[188:191], v185 offset:1024
	ds_read_b128 v[192:195], v185 offset:2048
	ds_read_b128 v[196:199], v185 offset:3072
	ds_read_b128 v[200:203], v185 offset:4096
	ds_read_b128 v[204:207], v185 offset:5120
	ds_read_b128 v[208:211], v185 offset:6144
	ds_read_b128 v[212:215], v185 offset:7168
	global_load_lds_dwordx4 v[180:181], off
	v_lshl_add_u64 v[180:181], s[28:29], 0, v[160:161]
	s_add_i32 m0, s38, 0xe000
	s_nop 0
	global_load_lds_dwordx4 v[180:181], off
	s_cmp_lg_u32 s32, 0
	s_cbranch_scc1 .Lkw5a_b
	s_waitcnt vmcnt(8)
	s_branch .Lkw5a_d

; #define PG8_STAGE(bufoff, gbase, voff) do { _Pragma("unroll") for (int _i = 0; _i < 2; ++_i) \
;         __builtin_amdgcn_global_load_lds((const unsigned*)((const char*)(gbase) + (voff)[_i]), (LAS unsigned*)(lds + (bufoff) + ldsw + _i * 8192), 16, 0, 0); } while (0)
; #define PG8_LDA(dst, b, h) do { _Pragma("unroll") for (int m = 0; m < 4; ++m) _Pragma("unroll") for (int k = 0; k < 2; ++k) dst[m][k] = *(const LAS bf16x8*)(lds + PG8_SA(b, h) + aoff + m * 2048 + k * 1024); } while (0)
; #define PG8_MMA(ai, bj, At, Bt) do { __builtin_amdgcn_s_setprio(1); _Pragma("unroll") for (int m = 0; m < 4; ++m) _Pragma("unroll") for (int n = 0; n < 2; ++n) _Pragma("unroll") for (int k = 0; k < 2; ++k) \
;         acc[ai][bj][m][n] = __builtin_amdgcn_mfma_f32_16x16x32_bf16(Bt[n][k], At[m][k], acc[ai][bj][m][n], 0, 0, 0); __builtin_amdgcn_s_setprio(0); } while (0)
; #define PG8_WAIT_V(n) asm volatile("s_waitcnt vmcnt(" #n ")" ::: "memory")
; #define PG8_WAIT_L(n) asm volatile("s_waitcnt lgkmcnt(" #n ")" ::: "memory")
; #define PG8_BAR __builtin_amdgcn_s_barrier()
; #define PG8_SCHED __builtin_amdgcn_sched_barrier(0)
; template <class Epi>
; __device__ __forceinline__ void gemm_phase(LAS unsigned char* lds, const Gemm g, const StaticOrder& S, const Epi& E, const int wid) {
;     ...
;             PG8_WAIT_V(8); PG8_WAIT_L(0); PG8_BAR; PG8_MMA(0, 0, At, B0); PG8_MMA(0, 1, At, B1); PG8_BAR; PG8_SCHED;
;             PG8_LDA(At, 0, 1); PG8_STAGE(PG8_SB(0, 0), b2, voffB); PG8_STAGE(PG8_SB(0, 1), b2 + hsB, voffB); PG8_STAGE(PG8_SA(0, 0), a2, voffA);
;             PG8_WAIT_V(8); PG8_WAIT_L(0); PG8_BAR; PG8_MMA(1, 0, At, B0); PG8_MMA(1, 1, At, B1); PG8_BAR; PG8_SCHED;
.Lkw5a_d:
	s_waitcnt lgkmcnt(0)
	s_barrier
	s_setprio 1
	s_waitcnt lgkmcnt(0)
	v_mfma_f32_16x16x32_bf16 v[124:127], v[128:131], v[176:179], v[124:127]
	v_mfma_f32_16x16x32_bf16 v[120:123], v[136:139], v[176:179], v[120:123]
	v_mfma_f32_16x16x32_bf16 v[108:111], v[128:131], v[192:195], v[108:111]
	v_mfma_f32_16x16x32_bf16 v[104:107], v[136:139], v[192:195], v[104:107]
	v_mfma_f32_16x16x32_bf16 v[92:95], v[128:131], v[200:203], v[92:95]
	v_mfma_f32_16x16x32_bf16 v[88:91], v[136:139], v[200:203], v[88:91]
	v_mfma_f32_16x16x32_bf16 v[76:79], v[128:131], v[208:211], v[76:79]
	v_mfma_f32_16x16x32_bf16 v[72:75], v[136:139], v[208:211], v[72:75]
	v_mfma_f32_16x16x32_bf16 v[124:127], v[132:135], v[188:191], v[124:127]
	v_mfma_f32_16x16x32_bf16 v[120:123], v[140:143], v[188:191], v[120:123]
	v_mfma_f32_16x16x32_bf16 v[108:111], v[132:135], v[196:199], v[108:111]
	v_mfma_f32_16x16x32_bf16 v[104:107], v[140:143], v[196:199], v[104:107]
	v_mfma_f32_16x16x32_bf16 v[92:95], v[132:135], v[204:207], v[92:95]
	v_mfma_f32_16x16x32_bf16 v[88:91], v[140:143], v[204:207], v[88:91]
	v_mfma_f32_16x16x32_bf16 v[76:79], v[132:135], v[212:215], v[76:79]
	v_mfma_f32_16x16x32_bf16 v[72:75], v[140:143], v[212:215], v[72:75]
	s_setprio 0
	s_setprio 1
	v_mfma_f32_16x16x32_bf16 v[116:119], v[144:147], v[176:179], v[116:119]
	v_mfma_f32_16x16x32_bf16 v[112:115], v[168:171], v[176:179], v[112:115]
	v_mfma_f32_16x16x32_bf16 v[100:103], v[144:147], v[192:195], v[100:103]
	v_mfma_f32_16x16x32_bf16 v[96:99], v[168:171], v[192:195], v[96:99]
	v_mfma_f32_16x16x32_bf16 v[84:87], v[144:147], v[200:203], v[84:87]
	v_mfma_f32_16x16x32_bf16 v[80:83], v[168:171], v[200:203], v[80:83]
	v_mfma_f32_16x16x32_bf16 v[68:71], v[144:147], v[208:211], v[68:71]
	v_mfma_f32_16x16x32_bf16 v[64:67], v[168:171], v[208:211], v[64:67]
	v_mfma_f32_16x16x32_bf16 v[116:119], v[148:151], v[188:191], v[116:119]
	v_mfma_f32_16x16x32_bf16 v[112:115], v[172:175], v[188:191], v[112:115]
	v_mfma_f32_16x16x32_bf16 v[100:103], v[148:151], v[196:199], v[100:103]
	v_mfma_f32_16x16x32_bf16 v[96:99], v[172:175], v[196:199], v[96:99]
	v_mfma_f32_16x16x32_bf16 v[84:87], v[148:151], v[204:207], v[84:87]
	v_mfma_f32_16x16x32_bf16 v[80:83], v[172:175], v[204:207], v[80:83]
	v_mfma_f32_16x16x32_bf16 v[68:71], v[148:151], v[212:215], v[68:71]
	v_mfma_f32_16x16x32_bf16 v[64:67], v[172:175], v[212:215], v[64:67]
	s_setprio 0
	s_barrier
	s_add_i32 s4, s77, s68
	v_lshl_add_u64 v[180:181], s[30:31], 0, v[154:155]
	s_mov_b32 m0, s4
	ds_read_b128 v[176:179], v185 offset:16384
	ds_read_b128 v[188:191], v185 offset:17408
	ds_read_b128 v[192:195], v185 offset:18432
	ds_read_b128 v[196:199], v185 offset:19456
	ds_read_b128 v[200:203], v185 offset:20480
	ds_read_b128 v[204:207], v185 offset:21504
	ds_read_b128 v[208:211], v185 offset:22528
	ds_read_b128 v[212:215], v185 offset:23552
	global_load_lds_dwordx4 v[180:181], off
	s_add_i32 m0, s4, 0x2000
	s_add_u32 s4, s30, 0x40000
	v_lshl_add_u64 v[216:217], s[30:31], 0, v[158:159]
	s_addc_u32 s5, s31, 0
	s_add_i32 s47, s78, s68
	global_load_lds_dwordx4 v[216:217], off
	v_lshl_add_u64 v[218:219], s[4:5], 0, v[154:155]
	s_mov_b32 m0, s47
	v_lshl_add_u64 v[220:221], s[34:35], 0, v[156:157]
	global_load_lds_dwordx4 v[218:219], off
	v_lshl_add_u64 v[218:219], s[4:5], 0, v[158:159]
	s_add_i32 m0, s47, 0x2000
	s_nop 0
	global_load_lds_dwordx4 v[218:219], off
	v_lshl_add_u64 v[218:219], s[34:35], 0, v[152:153]
	s_mov_b32 m0, s38
	s_nop 0
	global_load_lds_dwordx4 v[218:219], off
	s_mov_b32 m0, s39
	s_nop 0
	global_load_lds_dwordx4 v[220:221], off
	s_cmp_lg_u32 s32, 0
	s_cbranch_scc1 .Lkw5b_b
	s_waitcnt vmcnt(8)
	s_branch .Lkw5b_d

; #define PG8_STAGE(bufoff, gbase, voff) do { _Pragma("unroll") for (int _i = 0; _i < 2; ++_i) \
;         __builtin_amdgcn_global_load_lds((const unsigned*)((const char*)(gbase) + (voff)[_i]), (LAS unsigned*)(lds + (bufoff) + ldsw + _i * 8192), 16, 0, 0); } while (0)
; #define PG8_LDA(dst, b, h) do { _Pragma("unroll") for (int m = 0; m < 4; ++m) _Pragma("unroll") for (int k = 0; k < 2; ++k) dst[m][k] = *(const LAS bf16x8*)(lds + PG8_SA(b, h) + aoff + m * 2048 + k * 1024); } while (0)
; #define PG8_LDB(dst, b, h) do { _Pragma("unroll") for (int n = 0; n < 2; ++n) _Pragma("unroll") for (int k = 0; k < 2; ++k) dst[n][k] = *(const LAS bf16x8*)(lds + PG8_SB(b, h) + boff + n * 2048 + k * 1024); } while (0)
; #define PG8_MMA(ai, bj, At, Bt) do { __builtin_amdgcn_s_setprio(1); _Pragma("unroll") for (int m = 0; m < 4; ++m) _Pragma("unroll") for (int n = 0; n < 2; ++n) _Pragma("unroll") for (int k = 0; k < 2; ++k) \
;         acc[ai][bj][m][n] = __builtin_amdgcn_mfma_f32_16x16x32_bf16(Bt[n][k], At[m][k], acc[ai][bj][m][n], 0, 0, 0); __builtin_amdgcn_s_setprio(0); } while (0)
; #define PG8_WAIT_V(n) asm volatile("s_waitcnt vmcnt(" #n ")" ::: "memory")
; #define PG8_WAIT_L(n) asm volatile("s_waitcnt lgkmcnt(" #n ")" ::: "memory")
; #define PG8_BAR __builtin_amdgcn_s_barrier()
; #define PG8_SCHED __builtin_amdgcn_sched_barrier(0)
; template <class Epi>
; __device__ __forceinline__ void gemm_phase(LAS unsigned char* lds, const Gemm g, const StaticOrder& S, const Epi& E, const int wid) {
;     ...
;             PG8_WAIT_V(8); PG8_WAIT_L(0); PG8_BAR; PG8_MMA(1, 0, At, B0); PG8_MMA(1, 1, At, B1); PG8_BAR; PG8_SCHED;
;             PG8_LDB(B0, 1, 0); PG8_LDB(B1, 1, 1); PG8_SCHED; PG8_LDA(At, 1, 0); PG8_STAGE(PG8_SA(0, 1), a2 + hsA, voffA);
;             PG8_WAIT_V(8); PG8_WAIT_L(0); PG8_BAR; PG8_MMA(0, 0, At, B0); PG8_MMA(0, 1, At, B1); PG8_BAR; PG8_SCHED;
.Lkw5b_d:
	s_mov_b32 s32, 0
	s_waitcnt lgkmcnt(0)
	s_barrier
	s_setprio 1
	s_waitcnt lgkmcnt(0)
	v_mfma_f32_16x16x32_bf16 v[60:63], v[128:131], v[176:179], v[60:63]
	v_mfma_f32_16x16x32_bf16 v[56:59], v[136:139], v[176:179], v[56:59]
	v_mfma_f32_16x16x32_bf16 v[44:47], v[128:131], v[192:195], v[44:47]
	v_mfma_f32_16x16x32_bf16 v[40:43], v[136:139], v[192:195], v[40:43]
	v_mfma_f32_16x16x32_bf16 v[28:31], v[128:131], v[200:203], v[28:31]
	v_mfma_f32_16x16x32_bf16 v[24:27], v[136:139], v[200:203], v[24:27]
	v_mfma_f32_16x16x32_bf16 v[12:15], v[128:131], v[208:211], v[12:15]
	v_mfma_f32_16x16x32_bf16 v[8:11], v[136:139], v[208:211], v[8:11]
	v_mfma_f32_16x16x32_bf16 v[60:63], v[132:135], v[188:191], v[60:63]
	v_mfma_f32_16x16x32_bf16 v[56:59], v[140:143], v[188:191], v[56:59]
	v_mfma_f32_16x16x32_bf16 v[44:47], v[132:135], v[196:199], v[44:47]
	v_mfma_f32_16x16x32_bf16 v[40:43], v[140:143], v[196:199], v[40:43]
	v_mfma_f32_16x16x32_bf16 v[28:31], v[132:135], v[204:207], v[28:31]
	v_mfma_f32_16x16x32_bf16 v[24:27], v[140:143], v[204:207], v[24:27]
	v_mfma_f32_16x16x32_bf16 v[12:15], v[132:135], v[212:215], v[12:15]
	v_mfma_f32_16x16x32_bf16 v[8:11], v[140:143], v[212:215], v[8:11]
	s_setprio 0
	s_setprio 1
	v_mfma_f32_16x16x32_bf16 v[52:55], v[144:147], v[176:179], v[52:55]
	v_mfma_f32_16x16x32_bf16 v[48:51], v[168:171], v[176:179], v[48:51]
	v_mfma_f32_16x16x32_bf16 v[36:39], v[144:147], v[192:195], v[36:39]
	v_mfma_f32_16x16x32_bf16 v[32:35], v[168:171], v[192:195], v[32:35]
	v_mfma_f32_16x16x32_bf16 v[20:23], v[144:147], v[200:203], v[20:23]
	v_mfma_f32_16x16x32_bf16 v[16:19], v[168:171], v[200:203], v[16:19]
	v_mfma_f32_16x16x32_bf16 v[4:7], v[144:147], v[208:211], v[4:7]
	v_mfma_f32_16x16x32_bf16 v[0:3], v[168:171], v[208:211], v[0:3]
	v_mfma_f32_16x16x32_bf16 v[52:55], v[148:151], v[188:191], v[52:55]
	v_mfma_f32_16x16x32_bf16 v[48:51], v[172:175], v[188:191], v[48:51]
	v_mfma_f32_16x16x32_bf16 v[36:39], v[148:151], v[196:199], v[36:39]
	v_mfma_f32_16x16x32_bf16 v[32:35], v[172:175], v[196:199], v[32:35]
	v_mfma_f32_16x16x32_bf16 v[20:23], v[148:151], v[204:207], v[20:23]
	v_mfma_f32_16x16x32_bf16 v[16:19], v[172:175], v[204:207], v[16:19]
	v_mfma_f32_16x16x32_bf16 v[4:7], v[148:151], v[212:215], v[4:7]
	v_mfma_f32_16x16x32_bf16 v[0:3], v[172:175], v[212:215], v[0:3]
	s_setprio 0
	s_barrier
	s_add_i32 s47, 0, 0x18000
	s_add_i32 s50, 0, 0x1c000
	v_add_u32_e32 v140, s47, v182
	v_add_u32_e32 v172, s50, v182
	ds_read_b128 v[128:131], v140
	ds_read_b128 v[132:135], v140 offset:1024
	ds_read_b128 v[136:139], v140 offset:2048
	ds_read_b128 v[140:143], v140 offset:3072
	ds_read_b128 v[144:147], v172
	ds_read_b128 v[148:151], v172 offset:1024
	ds_read_b128 v[168:171], v172 offset:2048
	ds_read_b128 v[172:175], v172 offset:3072
	s_add_u32 s4, s34, 0x40000
	s_addc_u32 s5, s35, 0
	s_mov_b32 m0, s62
	v_lshl_add_u64 v[222:223], s[4:5], 0, v[152:153]
	ds_read_b128 v[176:179], v185 offset:32768
	ds_read_b128 v[188:191], v185 offset:33792
	ds_read_b128 v[192:195], v185 offset:34816
	ds_read_b128 v[196:199], v185 offset:35840
	ds_read_b128 v[200:203], v185 offset:36864
	ds_read_b128 v[204:207], v185 offset:37888
	ds_read_b128 v[208:211], v185 offset:38912
	ds_read_b128 v[212:215], v185 offset:39936
	global_load_lds_dwordx4 v[222:223], off
	v_lshl_add_u64 v[222:223], s[4:5], 0, v[156:157]
	s_mov_b32 m0, s63
	s_nop 0
	global_load_lds_dwordx4 v[222:223], off
	s_waitcnt vmcnt(8)
	s_waitcnt lgkmcnt(0)
	s_barrier
	s_setprio 1
	s_waitcnt lgkmcnt(0)
	v_mfma_f32_16x16x32_bf16 v[124:127], v[128:131], v[176:179], v[124:127]
	v_mfma_f32_16x16x32_bf16 v[120:123], v[136:139], v[176:179], v[120:123]
	v_mfma_f32_16x16x32_bf16 v[108:111], v[128:131], v[192:195], v[108:111]
	v_mfma_f32_16x16x32_bf16 v[104:107], v[136:139], v[192:195], v[104:107]
	v_mfma_f32_16x16x32_bf16 v[92:95], v[128:131], v[200:203], v[92:95]
	v_mfma_f32_16x16x32_bf16 v[88:91], v[136:139], v[200:203], v[88:91]
	v_mfma_f32_16x16x32_bf16 v[76:79], v[128:131], v[208:211], v[76:79]
	v_mfma_f32_16x16x32_bf16 v[72:75], v[136:139], v[208:211], v[72:75]
	v_mfma_f32_16x16x32_bf16 v[124:127], v[132:135], v[188:191], v[124:127]
	v_mfma_f32_16x16x32_bf16 v[120:123], v[140:143], v[188:191], v[120:123]
	v_mfma_f32_16x16x32_bf16 v[108:111], v[132:135], v[196:199], v[108:111]
	v_mfma_f32_16x16x32_bf16 v[104:107], v[140:143], v[196:199], v[104:107]
	v_mfma_f32_16x16x32_bf16 v[92:95], v[132:135], v[204:207], v[92:95]
	v_mfma_f32_16x16x32_bf16 v[88:91], v[140:143], v[204:207], v[88:91]
	v_mfma_f32_16x16x32_bf16 v[76:79], v[132:135], v[212:215], v[76:79]
	v_mfma_f32_16x16x32_bf16 v[72:75], v[140:143], v[212:215], v[72:75]
	s_setprio 0
	s_setprio 1
	v_mfma_f32_16x16x32_bf16 v[116:119], v[144:147], v[176:179], v[116:119]
	v_mfma_f32_16x16x32_bf16 v[112:115], v[168:171], v[176:179], v[112:115]
	v_mfma_f32_16x16x32_bf16 v[100:103], v[144:147], v[192:195], v[100:103]
	v_mfma_f32_16x16x32_bf16 v[96:99], v[168:171], v[192:195], v[96:99]
	v_mfma_f32_16x16x32_bf16 v[84:87], v[144:147], v[200:203], v[84:87]
	v_mfma_f32_16x16x32_bf16 v[80:83], v[168:171], v[200:203], v[80:83]
	v_mfma_f32_16x16x32_bf16 v[68:71], v[144:147], v[208:211], v[68:71]
	v_mfma_f32_16x16x32_bf16 v[64:67], v[168:171], v[208:211], v[64:67]
	v_mfma_f32_16x16x32_bf16 v[116:119], v[148:151], v[188:191], v[116:119]
	v_mfma_f32_16x16x32_bf16 v[112:115], v[172:175], v[188:191], v[112:115]
	v_mfma_f32_16x16x32_bf16 v[100:103], v[148:151], v[196:199], v[100:103]
	v_mfma_f32_16x16x32_bf16 v[96:99], v[172:175], v[196:199], v[96:99]
	v_mfma_f32_16x16x32_bf16 v[84:87], v[148:151], v[204:207], v[84:87]
	v_mfma_f32_16x16x32_bf16 v[80:83], v[172:175], v[204:207], v[80:83]
	v_mfma_f32_16x16x32_bf16 v[68:71], v[148:151], v[212:215], v[68:71]
	v_mfma_f32_16x16x32_bf16 v[64:67], v[172:175], v[212:215], v[64:67]
	s_setprio 0
	s_barrier
; #define PG8_STAGE(bufoff, gbase, voff) do { _Pragma("unroll") for (int _i = 0; _i < 2; ++_i) \
;         __builtin_amdgcn_global_load_lds((const unsigned*)((const char*)(gbase) + (voff)[_i]), (LAS unsigned*)(lds + (bufoff) + ldsw + _i * 8192), 16, 0, 0); } while (0)
; #define PG8_LDA(dst, b, h) do { _Pragma("unroll") for (int m = 0; m < 4; ++m) _Pragma("unroll") for (int k = 0; k < 2; ++k) dst[m][k] = *(const LAS bf16x8*)(lds + PG8_SA(b, h) + aoff + m * 2048 + k * 1024); } while (0)
; #define PG8_MMA(ai, bj, At, Bt) do { __builtin_amdgcn_s_setprio(1); _Pragma("unroll") for (int m = 0; m < 4; ++m) _Pragma("unroll") for (int n = 0; n < 2; ++n) _Pragma("unroll") for (int k = 0; k < 2; ++k) \
;         acc[ai][bj][m][n] = __builtin_amdgcn_mfma_f32_16x16x32_bf16(Bt[n][k], At[m][k], acc[ai][bj][m][n], 0, 0, 0); __builtin_amdgcn_s_setprio(0); } while (0)
; #define PG8_WAIT_V(n) asm volatile("s_waitcnt vmcnt(" #n ")" ::: "memory")
; #define PG8_WAIT_L(n) asm volatile("s_waitcnt lgkmcnt(" #n ")" ::: "memory")
; #define PG8_BAR __builtin_amdgcn_s_barrier()
; #define PG8_SCHED __builtin_amdgcn_sched_barrier(0)
; template <class Epi>
; __device__ __forceinline__ void gemm_phase(LAS unsigned char* lds, const Gemm g, const StaticOrder& S, const Epi& E, const int wid) {
;     ...
;             PG8_LDA(At, 1, 1); PG8_STAGE(PG8_SB(1, 0), b3, voffB); PG8_STAGE(PG8_SB(1, 1), b3 + hsB, voffB); PG8_STAGE(PG8_SA(1, 0), a3, voffA);
;             PG8_WAIT_V(8); PG8_WAIT_L(0); PG8_BAR; PG8_MMA(1, 0, At, B0); PG8_MMA(1, 1, At, B1); PG8_BAR; PG8_SCHED;
;         }
;         if (wr == 0) PG8_BAR;
;         E(acc, cur, wid);
;         if (!has_next) break;
	s_add_i32 s4, s47, s68
	v_lshl_add_u64 v[180:181], v[180:181], 0, s[16:17]
	s_mov_b32 m0, s4
	ds_read_b128 v[176:179], v185 offset:49152
	ds_read_b128 v[188:191], v185 offset:50176
	ds_read_b128 v[192:195], v185 offset:51200
	ds_read_b128 v[196:199], v185 offset:52224
	ds_read_b128 v[200:203], v185 offset:53248
	ds_read_b128 v[204:207], v185 offset:54272
	ds_read_b128 v[208:211], v185 offset:55296
	ds_read_b128 v[212:215], v185 offset:56320
	global_load_lds_dwordx4 v[180:181], off
	s_add_i32 m0, s4, 0x2000
	s_add_u32 s4, s30, 0x40080
	v_lshl_add_u64 v[180:181], v[216:217], 0, s[16:17]
	s_addc_u32 s5, s31, 0
	s_add_i32 s30, s50, s68
	global_load_lds_dwordx4 v[180:181], off
	v_lshl_add_u64 v[180:181], s[4:5], 0, v[154:155]
	s_mov_b32 m0, s30
	s_nop 0
	global_load_lds_dwordx4 v[180:181], off
	v_lshl_add_u64 v[180:181], s[4:5], 0, v[158:159]
	s_add_i32 m0, s30, 0x2000
	s_nop 0
	global_load_lds_dwordx4 v[180:181], off
	v_lshl_add_u64 v[180:181], v[218:219], 0, s[16:17]
	s_mov_b32 m0, s65
	s_nop 0
	global_load_lds_dwordx4 v[180:181], off
	v_lshl_add_u64 v[180:181], v[220:221], 0, s[16:17]
	s_mov_b32 m0, s66
	s_nop 0
	global_load_lds_dwordx4 v[180:181], off
	s_waitcnt vmcnt(8)
	s_waitcnt lgkmcnt(0)
	s_barrier
	s_setprio 1
	s_waitcnt lgkmcnt(0)
	v_mfma_f32_16x16x32_bf16 v[60:63], v[128:131], v[176:179], v[60:63]
	v_mfma_f32_16x16x32_bf16 v[56:59], v[136:139], v[176:179], v[56:59]
	v_mfma_f32_16x16x32_bf16 v[44:47], v[128:131], v[192:195], v[44:47]
	v_mfma_f32_16x16x32_bf16 v[40:43], v[136:139], v[192:195], v[40:43]
	v_mfma_f32_16x16x32_bf16 v[28:31], v[128:131], v[200:203], v[28:31]
	v_mfma_f32_16x16x32_bf16 v[24:27], v[136:139], v[200:203], v[24:27]
	v_mfma_f32_16x16x32_bf16 v[12:15], v[128:131], v[208:211], v[12:15]
	v_mfma_f32_16x16x32_bf16 v[8:11], v[136:139], v[208:211], v[8:11]
	v_mfma_f32_16x16x32_bf16 v[60:63], v[132:135], v[188:191], v[60:63]
	v_mfma_f32_16x16x32_bf16 v[56:59], v[140:143], v[188:191], v[56:59]
	v_mfma_f32_16x16x32_bf16 v[44:47], v[132:135], v[196:199], v[44:47]
	v_mfma_f32_16x16x32_bf16 v[40:43], v[140:143], v[196:199], v[40:43]
	v_mfma_f32_16x16x32_bf16 v[28:31], v[132:135], v[204:207], v[28:31]
	v_mfma_f32_16x16x32_bf16 v[24:27], v[140:143], v[204:207], v[24:27]
	v_mfma_f32_16x16x32_bf16 v[12:15], v[132:135], v[212:215], v[12:15]
	v_mfma_f32_16x16x32_bf16 v[8:11], v[140:143], v[212:215], v[8:11]
	s_setprio 0
	s_setprio 1
	v_mfma_f32_16x16x32_bf16 v[52:55], v[144:147], v[176:179], v[52:55]
	v_mfma_f32_16x16x32_bf16 v[48:51], v[168:171], v[176:179], v[48:51]
	v_mfma_f32_16x16x32_bf16 v[36:39], v[144:147], v[192:195], v[36:39]
	v_mfma_f32_16x16x32_bf16 v[32:35], v[168:171], v[192:195], v[32:35]
	v_mfma_f32_16x16x32_bf16 v[20:23], v[144:147], v[200:203], v[20:23]
	v_mfma_f32_16x16x32_bf16 v[16:19], v[168:171], v[200:203], v[16:19]
	v_mfma_f32_16x16x32_bf16 v[4:7], v[144:147], v[208:211], v[4:7]
	v_mfma_f32_16x16x32_bf16 v[0:3], v[168:171], v[208:211], v[0:3]
	v_mfma_f32_16x16x32_bf16 v[52:55], v[148:151], v[188:191], v[52:55]
	v_mfma_f32_16x16x32_bf16 v[48:51], v[172:175], v[188:191], v[48:51]
	v_mfma_f32_16x16x32_bf16 v[36:39], v[148:151], v[196:199], v[36:39]
	v_mfma_f32_16x16x32_bf16 v[32:35], v[172:175], v[196:199], v[32:35]
	v_mfma_f32_16x16x32_bf16 v[20:23], v[148:151], v[204:207], v[20:23]
	v_mfma_f32_16x16x32_bf16 v[16:19], v[172:175], v[204:207], v[16:19]
	v_mfma_f32_16x16x32_bf16 v[4:7], v[148:151], v[212:215], v[4:7]
	v_mfma_f32_16x16x32_bf16 v[0:3], v[172:175], v[212:215], v[0:3]
	s_setprio 0
	s_barrier
	s_add_i32 s81, s81, 2
	s_add_u32 s79, s79, 0x100
	s_addc_u32 s80, s80, 0
	s_add_u32 s28, s28, 0x100
	s_addc_u32 s29, s29, 0
	s_cmp_gt_u32 s81, 13
	s_cbranch_scc0 .LBB0_665
	s_mov_b32 s32, 1
	s_and_b64 vcc, exec, s[18:19]
	s_cbranch_vccz .LBB0_668
	s_barrier

; __device__ __forceinline__ int lane_id_asm() { int l; asm volatile("v_mbcnt_lo_u32_b32 %0, -1, 0\n\tv_mbcnt_hi_u32_b32 %0, -1, %0" : "=v"(l)); return l; }
; #define PG8_STAGE(bufoff, gbase, voff) do { _Pragma("unroll") for (int _i = 0; _i < 2; ++_i) \
;         __builtin_amdgcn_global_load_lds((const unsigned*)((const char*)(gbase) + (voff)[_i]), (LAS unsigned*)(lds + (bufoff) + ldsw + _i * 8192), 16, 0, 0); } while (0)
; #define PG8_WAIT_V(n) asm volatile("s_waitcnt vmcnt(" #n ")" ::: "memory")
; #define PG8_BAR __builtin_amdgcn_s_barrier()
; template <class Epi>
; __device__ __forceinline__ void gemm_phase(LAS unsigned char* lds, const Gemm g, const StaticOrder& S, const Epi& E, const int wid) {
;     const int lane = lane_id_asm(), tid = wid * 64 + lane, wr = wid >> 2, wc = wid & 3, fr = lane & 15, fq = lane >> 4;
;     const int K = g.K, nt = K / BK, lda = g.lda;
;     unsigned voffA[2], voffB[2];
; #pragma unroll
;     for (int i = 0; i < 2; ++i) { int R, C; stage_rc(tid * 16 + i * 8192, R, C); const int Rb = Epi::PERM ? ((R & ~31) + perm32(R & 31)) : R;
;         voffA[i] = (unsigned)(R * lda + C) * 2u; voffB[i] = (unsigned)(Rb * K + C) * 2u; }
;     const size_t kstep = (size_t)(BK * 2);
;     const size_t hsA = (size_t)HALF * lda * 2, hsB = (size_t)HALF * K * 2;
;     const size_t tsA = 2 * hsA, tsB = 2 * hsB;
;     const unsigned ldsw = (unsigned)wid * 1024u;
;     const int aoff = lds_byte(wr * 64 + fr, fq * 8), boff = lds_byte(wc * 32 + fr, fq * 8);
;     ...
;     PG8_WAIT_V(2); PG8_BAR;
;     PG8_STAGE(PG8_SB(1, 0), cB + kstep, voffB); PG8_STAGE(PG8_SA(1, 0), cA + kstep, voffA); PG8_STAGE(PG8_SB(1, 1), cB + hsB + kstep, voffB);
;     PG8_WAIT_V(6); PG8_BAR;
.LBB0_769:
	s_add_u32 s66, s54, 0xc0000
	s_mov_b64 s[16:17], 0x80
	s_addc_u32 s67, s55, 0
	s_add_i32 m0, s9, 0x18000
	v_lshl_add_u64 v[6:7], v[6:7], 0, s[16:17]
	global_load_lds_dwordx4 v[6:7], off
	v_lshl_add_u64 v[4:5], v[4:5], 0, s[16:17]
	s_add_i32 m0, s9, 0x1a000
	s_add_i32 s74, s9, 0x8000
	s_add_i32 s75, s9, 0xa000
	global_load_lds_dwordx4 v[4:5], off
	v_lshl_add_u64 v[0:1], v[0:1], 0, s[16:17]
	s_mov_b32 m0, s74
	s_add_u32 s4, s34, 0x40080
	global_load_lds_dwordx4 v[0:1], off
	v_lshl_add_u64 v[0:1], v[2:3], 0, s[16:17]
	s_mov_b32 m0, s75
	s_addc_u32 s5, s35, 0
	global_load_lds_dwordx4 v[0:1], off
	s_add_i32 m0, s9, 0x1c000
	v_lshl_add_u64 v[0:1], s[4:5], 0, v[130:131]
	global_load_lds_dwordx4 v[0:1], off
	v_lshl_add_u64 v[0:1], s[4:5], 0, v[134:135]
	s_add_i32 m0, s9, 0x1e000
	v_and_b32_e32 v2, 48, v8
	global_load_lds_dwordx4 v[0:1], off
	s_waitcnt vmcnt(8)
	s_barrier
	v_and_b32_e32 v0, 15, v8
	v_ashrrev_i32_e32 v1, 6, v8
	v_readlane_b32 s1, v254, 3
	v_lshl_or_b32 v0, v0, 6, v2
	v_lshlrev_b32_e32 v3, 2, v8
	v_lshl_add_u32 v2, v1, 10, s1
	v_readlane_b32 s1, v254, 5
	v_and_b32_e32 v3, 32, v3
	v_bitop3_b32 v2, v0, v2, v3 bitop3:0xde
	v_add_lshl_u32 v1, v1, s1, 10
	v_bitop3_b32 v150, v0, v1, v3 bitop3:0xde
	v_lshlrev_b32_e32 v0, 14, v9
	v_and_b32_e32 v0, 0xffff8000, v0
	v_lshl_add_u32 v0, v10, 11, v0
	v_and_b32_e32 v1, 1, v9
	s_cmpk_lt_u32 s3, 0x100
	v_lshl_or_b32 v0, v1, 6, v0
	s_cselect_b64 s[18:19], -1, 0
	s_lshl_b32 s1, s33, 4
	v_lshl_add_u32 v136, v11, 1, v0
	v_lshlrev_b32_e32 v0, 14, v12
	s_and_b32 s76, s1, 0x3fffffc0
	s_ashr_i32 s77, s56, 31
	s_ashr_i32 s79, s2, 31
	v_and_b32_e32 v0, 0xffff8000, v0
	s_waitcnt vmcnt(6)
	s_mov_b32 s32, 0
	s_cmp_eq_u64 s[58:59], 0
	v_lshl_add_u32 v0, v13, 11, v0
	v_and_b32_e32 v1, 1, v12
	s_cselect_b64 s[20:21], -1, 0
	v_lshl_or_b32 v0, v1, 6, v0
	s_add_i32 s80, 0, 0x10000
	s_add_i32 s81, 0, 0x14000
	s_mov_b32 s78, s56
	v_mov_b32_e32 v137, v131
	v_lshl_add_u32 v138, v14, 1, v0
	v_mov_b32_e32 v139, v131
	v_mov_b64_e32 v[140:141], 0x180
	v_mov_b64_e32 v[142:143], 0x17f
	v_add_u32_e32 v151, s80, v150
	v_add_u32_e32 v152, s81, v150
	v_add_u32_e32 v153, 0, v2
	v_mbcnt_hi_u32_b32 v154, -1, v244
	v_mov_b32_e32 v155, 0x358637bd
	s_movk_i32 s82, 0x600
	s_barrier
	s_branch .LBB0_772

; #define PG8_STAGE(bufoff, gbase, voff) do { _Pragma("unroll") for (int _i = 0; _i < 2; ++_i) \
;         __builtin_amdgcn_global_load_lds((const unsigned*)((const char*)(gbase) + (voff)[_i]), (LAS unsigned*)(lds + (bufoff) + ldsw + _i * 8192), 16, 0, 0); } while (0)
; #define PG8_LDA(dst, b, h) do { _Pragma("unroll") for (int m = 0; m < 4; ++m) _Pragma("unroll") for (int k = 0; k < 2; ++k) dst[m][k] = *(const LAS bf16x8*)(lds + PG8_SA(b, h) + aoff + m * 2048 + k * 1024); } while (0)
; #define PG8_LDB(dst, b, h) do { _Pragma("unroll") for (int n = 0; n < 2; ++n) _Pragma("unroll") for (int k = 0; k < 2; ++k) dst[n][k] = *(const LAS bf16x8*)(lds + PG8_SB(b, h) + boff + n * 2048 + k * 1024); } while (0)
; #define PG8_SCHED __builtin_amdgcn_sched_barrier(0)
; template <class Epi>
; __device__ __forceinline__ void gemm_phase(LAS unsigned char* lds, const Gemm g, const StaticOrder& S, const Epi& E, const int wid) {
;     ...
;         for (int t = 0; t < nt; t += 2) {
;             const bool last = (t == nt - 2);
;             const char* a1 = cA + (size_t)(t + 1) * kstep;
;             const char* a2 = last ? nA : cA + (size_t)(t + 2) * kstep; const char* b2 = last ? nB : cB + (size_t)(t + 2) * kstep;
;             const char* a3 = a2 + kstep; const char* b3 = b2 + kstep;
;             PG8_LDB(B0, 0, 0); PG8_LDB(B1, 0, 1); PG8_SCHED; PG8_LDA(At, 0, 0); PG8_STAGE(PG8_SA(1, 1), a1 + hsA, voffA);
.LBB0_775:
	ds_read_b128 v[144:147], v151
	ds_read_b128 v[156:159], v151 offset:1024
	ds_read_b128 v[160:163], v151 offset:2048
	ds_read_b128 v[164:167], v151 offset:3072
	ds_read_b128 v[168:171], v152
	ds_read_b128 v[172:175], v152 offset:1024
	ds_read_b128 v[176:179], v152 offset:2048
	ds_read_b128 v[180:183], v152 offset:3072
	s_add_u32 s4, s30, 0xfffc0080
	s_addc_u32 s5, s31, -1
	s_cmp_eq_u32 s91, 12
	s_cselect_b32 s37, s1, s5
	s_cselect_b32 s36, s25, s4
	s_cselect_b32 s35, s23, s90
	s_cselect_b32 s34, s83, s89
	v_lshl_add_u64 v[148:149], s[30:31], 0, v[136:137]
	s_add_i32 m0, s9, 0xc000
	ds_read_b128 v[184:187], v153
	ds_read_b128 v[188:191], v153 offset:1024
	ds_read_b128 v[192:195], v153 offset:2048
	ds_read_b128 v[196:199], v153 offset:3072
	ds_read_b128 v[200:203], v153 offset:4096
	ds_read_b128 v[204:207], v153 offset:5120
	ds_read_b128 v[208:211], v153 offset:6144
	ds_read_b128 v[212:215], v153 offset:7168
	global_load_lds_dwordx4 v[148:149], off
	v_lshl_add_u64 v[148:149], s[30:31], 0, v[138:139]
	s_add_i32 m0, s9, 0xe000
	s_nop 0
	global_load_lds_dwordx4 v[148:149], off
	s_cmp_lg_u32 s32, 0
	s_cbranch_scc1 .Lkw6a_b
	s_waitcnt vmcnt(8)
	s_branch .Lkw6a_d

; #define PG8_STAGE(bufoff, gbase, voff) do { _Pragma("unroll") for (int _i = 0; _i < 2; ++_i) \
;         __builtin_amdgcn_global_load_lds((const unsigned*)((const char*)(gbase) + (voff)[_i]), (LAS unsigned*)(lds + (bufoff) + ldsw + _i * 8192), 16, 0, 0); } while (0)
; #define PG8_LDA(dst, b, h) do { _Pragma("unroll") for (int m = 0; m < 4; ++m) _Pragma("unroll") for (int k = 0; k < 2; ++k) dst[m][k] = *(const LAS bf16x8*)(lds + PG8_SA(b, h) + aoff + m * 2048 + k * 1024); } while (0)
; #define PG8_MMA(ai, bj, At, Bt) do { __builtin_amdgcn_s_setprio(1); _Pragma("unroll") for (int m = 0; m < 4; ++m) _Pragma("unroll") for (int n = 0; n < 2; ++n) _Pragma("unroll") for (int k = 0; k < 2; ++k) \
;         acc[ai][bj][m][n] = __builtin_amdgcn_mfma_f32_16x16x32_bf16(Bt[n][k], At[m][k], acc[ai][bj][m][n], 0, 0, 0); __builtin_amdgcn_s_setprio(0); } while (0)
; #define PG8_WAIT_V(n) asm volatile("s_waitcnt vmcnt(" #n ")" ::: "memory")
; #define PG8_WAIT_L(n) asm volatile("s_waitcnt lgkmcnt(" #n ")" ::: "memory")
; #define PG8_BAR __builtin_amdgcn_s_barrier()
; #define PG8_SCHED __builtin_amdgcn_sched_barrier(0)
; template <class Epi>
; __device__ __forceinline__ void gemm_phase(LAS unsigned char* lds, const Gemm g, const StaticOrder& S, const Epi& E, const int wid) {
;     ...
;             PG8_WAIT_V(8); PG8_WAIT_L(0); PG8_BAR; PG8_MMA(0, 0, At, B0); PG8_MMA(0, 1, At, B1); PG8_BAR; PG8_SCHED;
;             PG8_LDA(At, 0, 1); PG8_STAGE(PG8_SB(0, 0), b2, voffB); PG8_STAGE(PG8_SB(0, 1), b2 + hsB, voffB); PG8_STAGE(PG8_SA(0, 0), a2, voffA);
;             PG8_WAIT_V(8); PG8_WAIT_L(0); PG8_BAR; PG8_MMA(1, 0, At, B0); PG8_MMA(1, 1, At, B1); PG8_BAR; PG8_SCHED;
.Lkw6a_d:
	s_waitcnt lgkmcnt(0)
	s_barrier
	s_setprio 1
	s_waitcnt lgkmcnt(0)
	v_mfma_f32_16x16x32_bf16 v[124:127], v[144:147], v[184:187], v[124:127]
	v_mfma_f32_16x16x32_bf16 v[120:123], v[160:163], v[184:187], v[120:123]
	v_mfma_f32_16x16x32_bf16 v[108:111], v[144:147], v[192:195], v[108:111]
	v_mfma_f32_16x16x32_bf16 v[104:107], v[160:163], v[192:195], v[104:107]
	v_mfma_f32_16x16x32_bf16 v[92:95], v[144:147], v[200:203], v[92:95]
	v_mfma_f32_16x16x32_bf16 v[88:91], v[160:163], v[200:203], v[88:91]
	v_mfma_f32_16x16x32_bf16 v[76:79], v[144:147], v[208:211], v[76:79]
	v_mfma_f32_16x16x32_bf16 v[72:75], v[160:163], v[208:211], v[72:75]
	v_mfma_f32_16x16x32_bf16 v[124:127], v[156:159], v[188:191], v[124:127]
	v_mfma_f32_16x16x32_bf16 v[120:123], v[164:167], v[188:191], v[120:123]
	v_mfma_f32_16x16x32_bf16 v[108:111], v[156:159], v[196:199], v[108:111]
	v_mfma_f32_16x16x32_bf16 v[104:107], v[164:167], v[196:199], v[104:107]
	v_mfma_f32_16x16x32_bf16 v[92:95], v[156:159], v[204:207], v[92:95]
	v_mfma_f32_16x16x32_bf16 v[88:91], v[164:167], v[204:207], v[88:91]
	v_mfma_f32_16x16x32_bf16 v[76:79], v[156:159], v[212:215], v[76:79]
	v_mfma_f32_16x16x32_bf16 v[72:75], v[164:167], v[212:215], v[72:75]
	s_setprio 0
	s_setprio 1
	v_mfma_f32_16x16x32_bf16 v[116:119], v[168:171], v[184:187], v[116:119]
	v_mfma_f32_16x16x32_bf16 v[112:115], v[176:179], v[184:187], v[112:115]
	v_mfma_f32_16x16x32_bf16 v[100:103], v[168:171], v[192:195], v[100:103]
	v_mfma_f32_16x16x32_bf16 v[96:99], v[176:179], v[192:195], v[96:99]
	v_mfma_f32_16x16x32_bf16 v[84:87], v[168:171], v[200:203], v[84:87]
	v_mfma_f32_16x16x32_bf16 v[80:83], v[176:179], v[200:203], v[80:83]
	v_mfma_f32_16x16x32_bf16 v[68:71], v[168:171], v[208:211], v[68:71]
	v_mfma_f32_16x16x32_bf16 v[64:67], v[176:179], v[208:211], v[64:67]
	v_mfma_f32_16x16x32_bf16 v[116:119], v[172:175], v[188:191], v[116:119]
	v_mfma_f32_16x16x32_bf16 v[112:115], v[180:183], v[188:191], v[112:115]
	v_mfma_f32_16x16x32_bf16 v[100:103], v[172:175], v[196:199], v[100:103]
	v_mfma_f32_16x16x32_bf16 v[96:99], v[180:183], v[196:199], v[96:99]
	v_mfma_f32_16x16x32_bf16 v[84:87], v[172:175], v[204:207], v[84:87]
	v_mfma_f32_16x16x32_bf16 v[80:83], v[180:183], v[204:207], v[80:83]
	v_mfma_f32_16x16x32_bf16 v[68:71], v[172:175], v[212:215], v[68:71]
	v_mfma_f32_16x16x32_bf16 v[64:67], v[180:183], v[212:215], v[64:67]
	s_setprio 0
	s_barrier
	s_add_i32 s4, s80, s68
	v_lshl_add_u64 v[148:149], s[34:35], 0, v[130:131]
	s_mov_b32 m0, s4
	ds_read_b128 v[184:187], v153 offset:16384
	ds_read_b128 v[188:191], v153 offset:17408
	ds_read_b128 v[192:195], v153 offset:18432
	ds_read_b128 v[196:199], v153 offset:19456
	ds_read_b128 v[200:203], v153 offset:20480
	ds_read_b128 v[204:207], v153 offset:21504
	ds_read_b128 v[208:211], v153 offset:22528
	ds_read_b128 v[212:215], v153 offset:23552
	global_load_lds_dwordx4 v[148:149], off
	s_add_i32 m0, s4, 0x2000
	s_add_u32 s4, s34, 0x40000
	v_lshl_add_u64 v[216:217], s[34:35], 0, v[134:135]
	s_addc_u32 s5, s35, 0
	s_add_i32 s47, s81, s68
	global_load_lds_dwordx4 v[216:217], off
	v_lshl_add_u64 v[218:219], s[4:5], 0, v[130:131]
	s_mov_b32 m0, s47
	v_lshl_add_u64 v[220:221], s[36:37], 0, v[132:133]
	global_load_lds_dwordx4 v[218:219], off
	v_lshl_add_u64 v[218:219], s[4:5], 0, v[134:135]
	s_add_i32 m0, s47, 0x2000
	s_nop 0
	global_load_lds_dwordx4 v[218:219], off
	v_lshl_add_u64 v[218:219], s[36:37], 0, v[128:129]
	s_mov_b32 m0, s9
	s_nop 0
	global_load_lds_dwordx4 v[218:219], off
	s_mov_b32 m0, s62
	s_nop 0
	global_load_lds_dwordx4 v[220:221], off
	s_cmp_lg_u32 s32, 0
	s_cbranch_scc1 .Lkw6b_b
	s_waitcnt vmcnt(8)
	s_branch .Lkw6b_d

; #define PG8_STAGE(bufoff, gbase, voff) do { _Pragma("unroll") for (int _i = 0; _i < 2; ++_i) \
;         __builtin_amdgcn_global_load_lds((const unsigned*)((const char*)(gbase) + (voff)[_i]), (LAS unsigned*)(lds + (bufoff) + ldsw + _i * 8192), 16, 0, 0); } while (0)
; #define PG8_LDA(dst, b, h) do { _Pragma("unroll") for (int m = 0; m < 4; ++m) _Pragma("unroll") for (int k = 0; k < 2; ++k) dst[m][k] = *(const LAS bf16x8*)(lds + PG8_SA(b, h) + aoff + m * 2048 + k * 1024); } while (0)
; #define PG8_LDB(dst, b, h) do { _Pragma("unroll") for (int n = 0; n < 2; ++n) _Pragma("unroll") for (int k = 0; k < 2; ++k) dst[n][k] = *(const LAS bf16x8*)(lds + PG8_SB(b, h) + boff + n * 2048 + k * 1024); } while (0)
; #define PG8_MMA(ai, bj, At, Bt) do { __builtin_amdgcn_s_setprio(1); _Pragma("unroll") for (int m = 0; m < 4; ++m) _Pragma("unroll") for (int n = 0; n < 2; ++n) _Pragma("unroll") for (int k = 0; k < 2; ++k) \
;         acc[ai][bj][m][n] = __builtin_amdgcn_mfma_f32_16x16x32_bf16(Bt[n][k], At[m][k], acc[ai][bj][m][n], 0, 0, 0); __builtin_amdgcn_s_setprio(0); } while (0)
; #define PG8_WAIT_V(n) asm volatile("s_waitcnt vmcnt(" #n ")" ::: "memory")
; #define PG8_WAIT_L(n) asm volatile("s_waitcnt lgkmcnt(" #n ")" ::: "memory")
; #define PG8_BAR __builtin_amdgcn_s_barrier()
; #define PG8_SCHED __builtin_amdgcn_sched_barrier(0)
; template <class Epi>
; __device__ __forceinline__ void gemm_phase(LAS unsigned char* lds, const Gemm g, const StaticOrder& S, const Epi& E, const int wid) {
;     ...
;             PG8_WAIT_V(8); PG8_WAIT_L(0); PG8_BAR; PG8_MMA(1, 0, At, B0); PG8_MMA(1, 1, At, B1); PG8_BAR; PG8_SCHED;
;             PG8_LDB(B0, 1, 0); PG8_LDB(B1, 1, 1); PG8_SCHED; PG8_LDA(At, 1, 0); PG8_STAGE(PG8_SA(0, 1), a2 + hsA, voffA);
;             PG8_WAIT_V(8); PG8_WAIT_L(0); PG8_BAR; PG8_MMA(0, 0, At, B0); PG8_MMA(0, 1, At, B1); PG8_BAR; PG8_SCHED;
.Lkw6b_d:
	s_mov_b32 s32, 0
	s_waitcnt lgkmcnt(0)
	s_barrier
	s_setprio 1
	s_waitcnt lgkmcnt(0)
	v_mfma_f32_16x16x32_bf16 v[60:63], v[144:147], v[184:187], v[60:63]
	v_mfma_f32_16x16x32_bf16 v[56:59], v[160:163], v[184:187], v[56:59]
	v_mfma_f32_16x16x32_bf16 v[44:47], v[144:147], v[192:195], v[44:47]
	v_mfma_f32_16x16x32_bf16 v[40:43], v[160:163], v[192:195], v[40:43]
	v_mfma_f32_16x16x32_bf16 v[28:31], v[144:147], v[200:203], v[28:31]
	v_mfma_f32_16x16x32_bf16 v[24:27], v[160:163], v[200:203], v[24:27]
	v_mfma_f32_16x16x32_bf16 v[12:15], v[144:147], v[208:211], v[12:15]
	v_mfma_f32_16x16x32_bf16 v[8:11], v[160:163], v[208:211], v[8:11]
	v_mfma_f32_16x16x32_bf16 v[60:63], v[156:159], v[188:191], v[60:63]
	v_mfma_f32_16x16x32_bf16 v[56:59], v[164:167], v[188:191], v[56:59]
	v_mfma_f32_16x16x32_bf16 v[44:47], v[156:159], v[196:199], v[44:47]
	v_mfma_f32_16x16x32_bf16 v[40:43], v[164:167], v[196:199], v[40:43]
	v_mfma_f32_16x16x32_bf16 v[28:31], v[156:159], v[204:207], v[28:31]
	v_mfma_f32_16x16x32_bf16 v[24:27], v[164:167], v[204:207], v[24:27]
	v_mfma_f32_16x16x32_bf16 v[12:15], v[156:159], v[212:215], v[12:15]
	v_mfma_f32_16x16x32_bf16 v[8:11], v[164:167], v[212:215], v[8:11]
	s_setprio 0
	s_setprio 1
	v_mfma_f32_16x16x32_bf16 v[52:55], v[168:171], v[184:187], v[52:55]
	v_mfma_f32_16x16x32_bf16 v[48:51], v[176:179], v[184:187], v[48:51]
	v_mfma_f32_16x16x32_bf16 v[36:39], v[168:171], v[192:195], v[36:39]
	v_mfma_f32_16x16x32_bf16 v[32:35], v[176:179], v[192:195], v[32:35]
	v_mfma_f32_16x16x32_bf16 v[20:23], v[168:171], v[200:203], v[20:23]
	v_mfma_f32_16x16x32_bf16 v[16:19], v[176:179], v[200:203], v[16:19]
	v_mfma_f32_16x16x32_bf16 v[4:7], v[168:171], v[208:211], v[4:7]
	v_mfma_f32_16x16x32_bf16 v[0:3], v[176:179], v[208:211], v[0:3]
	v_mfma_f32_16x16x32_bf16 v[52:55], v[172:175], v[188:191], v[52:55]
	v_mfma_f32_16x16x32_bf16 v[48:51], v[180:183], v[188:191], v[48:51]
	v_mfma_f32_16x16x32_bf16 v[36:39], v[172:175], v[196:199], v[36:39]
	v_mfma_f32_16x16x32_bf16 v[32:35], v[180:183], v[196:199], v[32:35]
	v_mfma_f32_16x16x32_bf16 v[20:23], v[172:175], v[204:207], v[20:23]
	v_mfma_f32_16x16x32_bf16 v[16:19], v[180:183], v[204:207], v[16:19]
	v_mfma_f32_16x16x32_bf16 v[4:7], v[172:175], v[212:215], v[4:7]
	v_mfma_f32_16x16x32_bf16 v[0:3], v[180:183], v[212:215], v[0:3]
	s_setprio 0
	s_barrier
	s_add_i32 s47, 0, 0x18000
	s_add_i32 s50, 0, 0x1c000
	v_add_u32_e32 v164, s47, v150
	v_add_u32_e32 v180, s50, v150
	ds_read_b128 v[144:147], v164
	ds_read_b128 v[156:159], v164 offset:1024
	ds_read_b128 v[160:163], v164 offset:2048
	ds_read_b128 v[164:167], v164 offset:3072
	ds_read_b128 v[168:171], v180
	ds_read_b128 v[172:175], v180 offset:1024
	ds_read_b128 v[176:179], v180 offset:2048
	ds_read_b128 v[180:183], v180 offset:3072
	s_add_u32 s4, s36, 0x40000
	s_addc_u32 s5, s37, 0
	s_mov_b32 m0, s63
	v_lshl_add_u64 v[222:223], s[4:5], 0, v[128:129]
	ds_read_b128 v[184:187], v153 offset:32768
	ds_read_b128 v[188:191], v153 offset:33792
	ds_read_b128 v[192:195], v153 offset:34816
	ds_read_b128 v[196:199], v153 offset:35840
	ds_read_b128 v[200:203], v153 offset:36864
	ds_read_b128 v[204:207], v153 offset:37888
	ds_read_b128 v[208:211], v153 offset:38912
	ds_read_b128 v[212:215], v153 offset:39936
	global_load_lds_dwordx4 v[222:223], off
	v_lshl_add_u64 v[222:223], s[4:5], 0, v[132:133]
	s_mov_b32 m0, s64
	s_nop 0
	global_load_lds_dwordx4 v[222:223], off
	s_waitcnt vmcnt(8)
	s_waitcnt lgkmcnt(0)
	s_barrier
	s_setprio 1
	s_waitcnt lgkmcnt(0)
	v_mfma_f32_16x16x32_bf16 v[124:127], v[144:147], v[184:187], v[124:127]
	v_mfma_f32_16x16x32_bf16 v[120:123], v[160:163], v[184:187], v[120:123]
	v_mfma_f32_16x16x32_bf16 v[108:111], v[144:147], v[192:195], v[108:111]
	v_mfma_f32_16x16x32_bf16 v[104:107], v[160:163], v[192:195], v[104:107]
	v_mfma_f32_16x16x32_bf16 v[92:95], v[144:147], v[200:203], v[92:95]
	v_mfma_f32_16x16x32_bf16 v[88:91], v[160:163], v[200:203], v[88:91]
	v_mfma_f32_16x16x32_bf16 v[76:79], v[144:147], v[208:211], v[76:79]
	v_mfma_f32_16x16x32_bf16 v[72:75], v[160:163], v[208:211], v[72:75]
	v_mfma_f32_16x16x32_bf16 v[124:127], v[156:159], v[188:191], v[124:127]
	v_mfma_f32_16x16x32_bf16 v[120:123], v[164:167], v[188:191], v[120:123]
	v_mfma_f32_16x16x32_bf16 v[108:111], v[156:159], v[196:199], v[108:111]
	v_mfma_f32_16x16x32_bf16 v[104:107], v[164:167], v[196:199], v[104:107]
	v_mfma_f32_16x16x32_bf16 v[92:95], v[156:159], v[204:207], v[92:95]
	v_mfma_f32_16x16x32_bf16 v[88:91], v[164:167], v[204:207], v[88:91]
	v_mfma_f32_16x16x32_bf16 v[76:79], v[156:159], v[212:215], v[76:79]
	v_mfma_f32_16x16x32_bf16 v[72:75], v[164:167], v[212:215], v[72:75]
	s_setprio 0
	s_setprio 1
	v_mfma_f32_16x16x32_bf16 v[116:119], v[168:171], v[184:187], v[116:119]
	v_mfma_f32_16x16x32_bf16 v[112:115], v[176:179], v[184:187], v[112:115]
	v_mfma_f32_16x16x32_bf16 v[100:103], v[168:171], v[192:195], v[100:103]
	v_mfma_f32_16x16x32_bf16 v[96:99], v[176:179], v[192:195], v[96:99]
	v_mfma_f32_16x16x32_bf16 v[84:87], v[168:171], v[200:203], v[84:87]
	v_mfma_f32_16x16x32_bf16 v[80:83], v[176:179], v[200:203], v[80:83]
	v_mfma_f32_16x16x32_bf16 v[68:71], v[168:171], v[208:211], v[68:71]
	v_mfma_f32_16x16x32_bf16 v[64:67], v[176:179], v[208:211], v[64:67]
	v_mfma_f32_16x16x32_bf16 v[116:119], v[172:175], v[188:191], v[116:119]
	v_mfma_f32_16x16x32_bf16 v[112:115], v[180:183], v[188:191], v[112:115]
	v_mfma_f32_16x16x32_bf16 v[100:103], v[172:175], v[196:199], v[100:103]
	v_mfma_f32_16x16x32_bf16 v[96:99], v[180:183], v[196:199], v[96:99]
	v_mfma_f32_16x16x32_bf16 v[84:87], v[172:175], v[204:207], v[84:87]
	v_mfma_f32_16x16x32_bf16 v[80:83], v[180:183], v[204:207], v[80:83]
	v_mfma_f32_16x16x32_bf16 v[68:71], v[172:175], v[212:215], v[68:71]
	v_mfma_f32_16x16x32_bf16 v[64:67], v[180:183], v[212:215], v[64:67]
	s_setprio 0
	s_barrier
; #define PG8_STAGE(bufoff, gbase, voff) do { _Pragma("unroll") for (int _i = 0; _i < 2; ++_i) \
;         __builtin_amdgcn_global_load_lds((const unsigned*)((const char*)(gbase) + (voff)[_i]), (LAS unsigned*)(lds + (bufoff) + ldsw + _i * 8192), 16, 0, 0); } while (0)
; #define PG8_LDA(dst, b, h) do { _Pragma("unroll") for (int m = 0; m < 4; ++m) _Pragma("unroll") for (int k = 0; k < 2; ++k) dst[m][k] = *(const LAS bf16x8*)(lds + PG8_SA(b, h) + aoff + m * 2048 + k * 1024); } while (0)
; #define PG8_MMA(ai, bj, At, Bt) do { __builtin_amdgcn_s_setprio(1); _Pragma("unroll") for (int m = 0; m < 4; ++m) _Pragma("unroll") for (int n = 0; n < 2; ++n) _Pragma("unroll") for (int k = 0; k < 2; ++k) \
;         acc[ai][bj][m][n] = __builtin_amdgcn_mfma_f32_16x16x32_bf16(Bt[n][k], At[m][k], acc[ai][bj][m][n], 0, 0, 0); __builtin_amdgcn_s_setprio(0); } while (0)
; #define PG8_WAIT_V(n) asm volatile("s_waitcnt vmcnt(" #n ")" ::: "memory")
; #define PG8_WAIT_L(n) asm volatile("s_waitcnt lgkmcnt(" #n ")" ::: "memory")
; #define PG8_BAR __builtin_amdgcn_s_barrier()
; #define PG8_SCHED __builtin_amdgcn_sched_barrier(0)
; template <class Epi>
; __device__ __forceinline__ void gemm_phase(LAS unsigned char* lds, const Gemm g, const StaticOrder& S, const Epi& E, const int wid) {
;     ...
;             PG8_LDA(At, 1, 1); PG8_STAGE(PG8_SB(1, 0), b3, voffB); PG8_STAGE(PG8_SB(1, 1), b3 + hsB, voffB); PG8_STAGE(PG8_SA(1, 0), a3, voffA);
;             PG8_WAIT_V(8); PG8_WAIT_L(0); PG8_BAR; PG8_MMA(1, 0, At, B0); PG8_MMA(1, 1, At, B1); PG8_BAR; PG8_SCHED;
;         }
;         if (wr == 0) PG8_BAR;
;         E(acc, cur, wid);
;         if (!has_next) break;
	s_add_i32 s4, s47, s68
	v_lshl_add_u64 v[148:149], v[148:149], 0, s[16:17]
	s_mov_b32 m0, s4
	ds_read_b128 v[184:187], v153 offset:49152
	ds_read_b128 v[188:191], v153 offset:50176
	ds_read_b128 v[192:195], v153 offset:51200
	ds_read_b128 v[196:199], v153 offset:52224
	ds_read_b128 v[200:203], v153 offset:53248
	ds_read_b128 v[204:207], v153 offset:54272
	ds_read_b128 v[208:211], v153 offset:55296
	ds_read_b128 v[212:215], v153 offset:56320
	global_load_lds_dwordx4 v[148:149], off
	s_add_i32 m0, s4, 0x2000
	s_add_u32 s4, s34, 0x40080
	v_lshl_add_u64 v[148:149], v[216:217], 0, s[16:17]
	s_addc_u32 s5, s35, 0
	s_add_i32 s34, s50, s68
	global_load_lds_dwordx4 v[148:149], off
	v_lshl_add_u64 v[148:149], s[4:5], 0, v[130:131]
	s_mov_b32 m0, s34
	s_nop 0
	global_load_lds_dwordx4 v[148:149], off
	v_lshl_add_u64 v[148:149], s[4:5], 0, v[134:135]
	s_add_i32 m0, s34, 0x2000
	s_nop 0
	global_load_lds_dwordx4 v[148:149], off
	v_lshl_add_u64 v[148:149], v[218:219], 0, s[16:17]
	s_mov_b32 m0, s74
	s_nop 0
	global_load_lds_dwordx4 v[148:149], off
	v_lshl_add_u64 v[148:149], v[220:221], 0, s[16:17]
	s_mov_b32 m0, s75
	s_nop 0
	global_load_lds_dwordx4 v[148:149], off
	s_waitcnt vmcnt(8)
	s_waitcnt lgkmcnt(0)
	s_barrier
	s_setprio 1
	s_waitcnt lgkmcnt(0)
	v_mfma_f32_16x16x32_bf16 v[60:63], v[144:147], v[184:187], v[60:63]
	v_mfma_f32_16x16x32_bf16 v[56:59], v[160:163], v[184:187], v[56:59]
	v_mfma_f32_16x16x32_bf16 v[44:47], v[144:147], v[192:195], v[44:47]
	v_mfma_f32_16x16x32_bf16 v[40:43], v[160:163], v[192:195], v[40:43]
	v_mfma_f32_16x16x32_bf16 v[28:31], v[144:147], v[200:203], v[28:31]
	v_mfma_f32_16x16x32_bf16 v[24:27], v[160:163], v[200:203], v[24:27]
	v_mfma_f32_16x16x32_bf16 v[12:15], v[144:147], v[208:211], v[12:15]
	v_mfma_f32_16x16x32_bf16 v[8:11], v[160:163], v[208:211], v[8:11]
	v_mfma_f32_16x16x32_bf16 v[60:63], v[156:159], v[188:191], v[60:63]
	v_mfma_f32_16x16x32_bf16 v[56:59], v[164:167], v[188:191], v[56:59]
	v_mfma_f32_16x16x32_bf16 v[44:47], v[156:159], v[196:199], v[44:47]
	v_mfma_f32_16x16x32_bf16 v[40:43], v[164:167], v[196:199], v[40:43]
	v_mfma_f32_16x16x32_bf16 v[28:31], v[156:159], v[204:207], v[28:31]
	v_mfma_f32_16x16x32_bf16 v[24:27], v[164:167], v[204:207], v[24:27]
	v_mfma_f32_16x16x32_bf16 v[12:15], v[156:159], v[212:215], v[12:15]
	v_mfma_f32_16x16x32_bf16 v[8:11], v[164:167], v[212:215], v[8:11]
	s_setprio 0
	s_setprio 1
	v_mfma_f32_16x16x32_bf16 v[52:55], v[168:171], v[184:187], v[52:55]
	v_mfma_f32_16x16x32_bf16 v[48:51], v[176:179], v[184:187], v[48:51]
	v_mfma_f32_16x16x32_bf16 v[36:39], v[168:171], v[192:195], v[36:39]
	v_mfma_f32_16x16x32_bf16 v[32:35], v[176:179], v[192:195], v[32:35]
	v_mfma_f32_16x16x32_bf16 v[20:23], v[168:171], v[200:203], v[20:23]
	v_mfma_f32_16x16x32_bf16 v[16:19], v[176:179], v[200:203], v[16:19]
	v_mfma_f32_16x16x32_bf16 v[4:7], v[168:171], v[208:211], v[4:7]
	v_mfma_f32_16x16x32_bf16 v[0:3], v[176:179], v[208:211], v[0:3]
	v_mfma_f32_16x16x32_bf16 v[52:55], v[172:175], v[188:191], v[52:55]
	v_mfma_f32_16x16x32_bf16 v[48:51], v[180:183], v[188:191], v[48:51]
	v_mfma_f32_16x16x32_bf16 v[36:39], v[172:175], v[196:199], v[36:39]
	v_mfma_f32_16x16x32_bf16 v[32:35], v[180:183], v[196:199], v[32:35]
	v_mfma_f32_16x16x32_bf16 v[20:23], v[172:175], v[204:207], v[20:23]
	v_mfma_f32_16x16x32_bf16 v[16:19], v[180:183], v[204:207], v[16:19]
	v_mfma_f32_16x16x32_bf16 v[4:7], v[172:175], v[212:215], v[4:7]
	v_mfma_f32_16x16x32_bf16 v[0:3], v[180:183], v[212:215], v[0:3]
	s_setprio 0
	s_barrier
	s_add_i32 s91, s91, 2
	s_add_u32 s30, s30, 0x100
	s_addc_u32 s31, s31, 0
	s_add_u32 s89, s89, 0x100
	s_addc_u32 s90, s90, 0
	s_cmp_gt_u32 s91, 13
	s_cbranch_scc0 .LBB0_775
	s_mov_b32 s32, 1
	s_and_b64 vcc, exec, s[18:19]
	s_cbranch_vccz .LBB0_778
	s_barrier

; __device__ __forceinline__ int lane_id_asm() { int l; asm volatile("v_mbcnt_lo_u32_b32 %0, -1, 0\n\tv_mbcnt_hi_u32_b32 %0, -1, %0" : "=v"(l)); return l; }
; #define PG8_STAGE(bufoff, gbase, voff) do { _Pragma("unroll") for (int _i = 0; _i < 2; ++_i) \
;         __builtin_amdgcn_global_load_lds((const unsigned*)((const char*)(gbase) + (voff)[_i]), (LAS unsigned*)(lds + (bufoff) + ldsw + _i * 8192), 16, 0, 0); } while (0)
; #define PG8_WAIT_V(n) asm volatile("s_waitcnt vmcnt(" #n ")" ::: "memory")
; #define PG8_BAR __builtin_amdgcn_s_barrier()
; template <class Epi>
; __device__ __forceinline__ void gemm_phase(LAS unsigned char* lds, const Gemm g, const StaticOrder& S, const Epi& E, const int wid) {
;     const int lane = lane_id_asm(), tid = wid * 64 + lane, wr = wid >> 2, wc = wid & 3, fr = lane & 15, fq = lane >> 4;
;     const int K = g.K, nt = K / BK, lda = g.lda;
;     unsigned voffA[2], voffB[2];
; #pragma unroll
;     for (int i = 0; i < 2; ++i) { int R, C; stage_rc(tid * 16 + i * 8192, R, C); const int Rb = Epi::PERM ? ((R & ~31) + perm32(R & 31)) : R;
;         voffA[i] = (unsigned)(R * lda + C) * 2u; voffB[i] = (unsigned)(Rb * K + C) * 2u; }
;     const size_t kstep = (size_t)(BK * 2);
;     const size_t hsA = (size_t)HALF * lda * 2, hsB = (size_t)HALF * K * 2;
;     const size_t tsA = 2 * hsA, tsB = 2 * hsB;
;     const unsigned ldsw = (unsigned)wid * 1024u;
;     const int aoff = lds_byte(wr * 64 + fr, fq * 8), boff = lds_byte(wc * 32 + fr, fq * 8);
;     ...
;     PG8_WAIT_V(2); PG8_BAR;
;     PG8_STAGE(PG8_SB(1, 0), cB + kstep, voffB); PG8_STAGE(PG8_SA(1, 0), cA + kstep, voffA); PG8_STAGE(PG8_SB(1, 1), cB + hsB + kstep, voffB);
;     PG8_WAIT_V(6); PG8_BAR;
.LBB0_861:
	s_mov_b64 s[10:11], 0x80
	s_add_i32 m0, s34, 0x18000
	v_lshl_add_u64 v[6:7], v[6:7], 0, s[10:11]
	global_load_lds_dwordx4 v[6:7], off
	v_lshl_add_u64 v[4:5], v[4:5], 0, s[10:11]
	s_add_i32 m0, s34, 0x1a000
	s_add_i32 s39, s34, 0x8000
	s_add_i32 s62, s34, 0xa000
	global_load_lds_dwordx4 v[4:5], off
	v_lshl_add_u64 v[0:1], v[0:1], 0, s[10:11]
	s_mov_b32 m0, s39
	s_add_u32 s6, s22, 0x18080
	global_load_lds_dwordx4 v[0:1], off
	v_lshl_add_u64 v[0:1], v[2:3], 0, s[10:11]
	s_mov_b32 m0, s62
	s_addc_u32 s7, s23, 0
	global_load_lds_dwordx4 v[0:1], off
	s_add_i32 m0, s34, 0x1c000
	v_lshl_add_u64 v[0:1], s[6:7], 0, v[132:133]
	global_load_lds_dwordx4 v[0:1], off
	v_lshl_add_u64 v[0:1], s[6:7], 0, v[128:129]
	s_add_i32 m0, s34, 0x1e000
	s_sext_i32_i8 s78, s5
	global_load_lds_dwordx4 v[0:1], off
	s_waitcnt vmcnt(8)
	s_barrier
	v_and_b32_e32 v0, 15, v10
	v_ashrrev_i32_e32 v1, 6, v10
	v_and_b32_e32 v2, 48, v10
	v_readlane_b32 s5, v254, 3
	v_lshl_or_b32 v0, v0, 6, v2
	v_lshlrev_b32_e32 v3, 2, v10
	v_lshl_add_u32 v2, v1, 10, s5
	v_readlane_b32 s5, v254, 5
	s_cmpk_lt_u32 s3, 0x100
	v_and_b32_e32 v3, 32, v3
	v_add_lshl_u32 v1, v1, s5, 10
	s_cselect_b64 s[16:17], -1, 0
	s_lshl_b32 s5, s33, 4
	v_bitop3_b32 v2, v0, v2, v3 bitop3:0xde
	v_bitop3_b32 v144, v0, v1, v3 bitop3:0xde
	s_and_b32 s63, s5, 0x3fffffc0
	v_lshrrev_b32_e32 v1, 1, v8
	v_mul_lo_u32 v0, v9, s4
	s_movk_i32 s5, 0x3000
	v_mad_u64_u32 v[0:1], s[6:7], v1, s5, v[0:1]
	v_or_b32_e32 v0, v0, v11
	v_add_lshl_u32 v0, v0, v12, 1
	v_mov_b32_e32 v1, v133
	s_mov_b64 s[6:7], 0x30080
	v_lshl_add_u64 v[136:137], v[0:1], 0, s[6:7]
	v_lshrrev_b32_e32 v1, 1, v13
	v_mul_lo_u32 v0, v14, s4
	v_mad_u64_u32 v[0:1], s[4:5], v1, s5, v[0:1]
	s_waitcnt vmcnt(6)
	s_mov_b32 s32, 0
	v_or_b32_e32 v0, v0, v15
	v_add_lshl_u32 v0, v0, v16, 1
	v_mov_b32_e32 v1, v133
	s_add_i32 s66, 0, 0x10000
	s_add_i32 s67, 0, 0x14000
	s_ashr_i32 s64, s56, 31
	s_mov_b32 s65, s56
	v_lshl_add_u64 v[138:139], v[0:1], 0, s[6:7]
	v_mov_b64_e32 v[140:141], 0x300
	v_mov_b64_e32 v[142:143], 0x2ff
	v_add_u32_e32 v145, s66, v144
	v_add_u32_e32 v146, s67, v144
	v_add_u32_e32 v147, 0, v2
	s_movk_i32 s74, 0xc00
	s_barrier
	s_branch .LBB0_864

; #define PG8_STAGE(bufoff, gbase, voff) do { _Pragma("unroll") for (int _i = 0; _i < 2; ++_i) \
;         __builtin_amdgcn_global_load_lds((const unsigned*)((const char*)(gbase) + (voff)[_i]), (LAS unsigned*)(lds + (bufoff) + ldsw + _i * 8192), 16, 0, 0); } while (0)
; #define PG8_LDA(dst, b, h) do { _Pragma("unroll") for (int m = 0; m < 4; ++m) _Pragma("unroll") for (int k = 0; k < 2; ++k) dst[m][k] = *(const LAS bf16x8*)(lds + PG8_SA(b, h) + aoff + m * 2048 + k * 1024); } while (0)
; #define PG8_LDB(dst, b, h) do { _Pragma("unroll") for (int n = 0; n < 2; ++n) _Pragma("unroll") for (int k = 0; k < 2; ++k) dst[n][k] = *(const LAS bf16x8*)(lds + PG8_SB(b, h) + boff + n * 2048 + k * 1024); } while (0)
; #define PG8_SCHED __builtin_amdgcn_sched_barrier(0)
; template <class Epi>
; __device__ __forceinline__ void gemm_phase(LAS unsigned char* lds, const Gemm g, const StaticOrder& S, const Epi& E, const int wid) {
;     ...
;         for (int t = 0; t < nt; t += 2) {
;             const bool last = (t == nt - 2);
;             const char* a1 = cA + (size_t)(t + 1) * kstep;
;             const char* a2 = last ? nA : cA + (size_t)(t + 2) * kstep; const char* b2 = last ? nB : cB + (size_t)(t + 2) * kstep;
;             const char* a3 = a2 + kstep; const char* b3 = b2 + kstep;
;             PG8_LDB(B0, 0, 0); PG8_LDB(B1, 0, 1); PG8_SCHED; PG8_LDA(At, 0, 0); PG8_STAGE(PG8_SA(1, 1), a1 + hsA, voffA);
.LBB0_871:
	ds_read_b128 v[148:151], v145
	ds_read_b128 v[152:155], v145 offset:1024
	ds_read_b128 v[156:159], v145 offset:2048
	ds_read_b128 v[160:163], v145 offset:3072
	ds_read_b128 v[164:167], v146
	ds_read_b128 v[168:171], v146 offset:1024
	ds_read_b128 v[172:175], v146 offset:2048
	ds_read_b128 v[176:179], v146 offset:3072
	s_add_u32 s22, s20, 0x100
	s_addc_u32 s23, s21, 0
	s_cmp_eq_u32 s81, 2
	s_cselect_b32 s27, s9, s23
	s_cselect_b32 s26, s8, s22
	s_cselect_b32 s25, s19, s80
	s_cselect_b32 s24, s18, s79
	v_lshl_add_u64 v[212:213], s[20:21], 0, v[138:139]
	s_add_i32 m0, s34, 0xc000
	ds_read_b128 v[180:183], v147
	ds_read_b128 v[184:187], v147 offset:1024
	ds_read_b128 v[188:191], v147 offset:2048
	ds_read_b128 v[192:195], v147 offset:3072
	ds_read_b128 v[196:199], v147 offset:4096
	ds_read_b128 v[200:203], v147 offset:5120
	ds_read_b128 v[204:207], v147 offset:6144
	ds_read_b128 v[208:211], v147 offset:7168
	global_load_lds_dwordx4 v[212:213], off
	v_lshl_add_u64 v[212:213], s[20:21], 0, v[136:137]
	s_add_i32 m0, s34, 0xe000
	s_nop 0
	global_load_lds_dwordx4 v[212:213], off
	s_cmp_lg_u32 s32, 0
	s_cbranch_scc1 .Lkw7a_b
	s_waitcnt vmcnt(8)
	s_branch .Lkw7a_d

; #define PG8_STAGE(bufoff, gbase, voff) do { _Pragma("unroll") for (int _i = 0; _i < 2; ++_i) \
;         __builtin_amdgcn_global_load_lds((const unsigned*)((const char*)(gbase) + (voff)[_i]), (LAS unsigned*)(lds + (bufoff) + ldsw + _i * 8192), 16, 0, 0); } while (0)
; #define PG8_LDA(dst, b, h) do { _Pragma("unroll") for (int m = 0; m < 4; ++m) _Pragma("unroll") for (int k = 0; k < 2; ++k) dst[m][k] = *(const LAS bf16x8*)(lds + PG8_SA(b, h) + aoff + m * 2048 + k * 1024); } while (0)
; #define PG8_MMA(ai, bj, At, Bt) do { __builtin_amdgcn_s_setprio(1); _Pragma("unroll") for (int m = 0; m < 4; ++m) _Pragma("unroll") for (int n = 0; n < 2; ++n) _Pragma("unroll") for (int k = 0; k < 2; ++k) \
;         acc[ai][bj][m][n] = __builtin_amdgcn_mfma_f32_16x16x32_bf16(Bt[n][k], At[m][k], acc[ai][bj][m][n], 0, 0, 0); __builtin_amdgcn_s_setprio(0); } while (0)
; #define PG8_WAIT_V(n) asm volatile("s_waitcnt vmcnt(" #n ")" ::: "memory")
; #define PG8_WAIT_L(n) asm volatile("s_waitcnt lgkmcnt(" #n ")" ::: "memory")
; #define PG8_BAR __builtin_amdgcn_s_barrier()
; #define PG8_SCHED __builtin_amdgcn_sched_barrier(0)
; template <class Epi>
; __device__ __forceinline__ void gemm_phase(LAS unsigned char* lds, const Gemm g, const StaticOrder& S, const Epi& E, const int wid) {
;     ...
;             PG8_WAIT_V(8); PG8_WAIT_L(0); PG8_BAR; PG8_MMA(0, 0, At, B0); PG8_MMA(0, 1, At, B1); PG8_BAR; PG8_SCHED;
;             PG8_LDA(At, 0, 1); PG8_STAGE(PG8_SB(0, 0), b2, voffB); PG8_STAGE(PG8_SB(0, 1), b2 + hsB, voffB); PG8_STAGE(PG8_SA(0, 0), a2, voffA);
;             PG8_WAIT_V(8); PG8_WAIT_L(0); PG8_BAR; PG8_MMA(1, 0, At, B0); PG8_MMA(1, 1, At, B1); PG8_BAR; PG8_SCHED;
.Lkw7a_d:
	s_waitcnt lgkmcnt(0)
	s_barrier
	s_setprio 1
	s_waitcnt lgkmcnt(0)
	v_mfma_f32_16x16x32_bf16 v[124:127], v[148:151], v[180:183], v[124:127]
	v_mfma_f32_16x16x32_bf16 v[120:123], v[156:159], v[180:183], v[120:123]
	v_mfma_f32_16x16x32_bf16 v[116:119], v[148:151], v[188:191], v[116:119]
	v_mfma_f32_16x16x32_bf16 v[112:115], v[156:159], v[188:191], v[112:115]
	v_mfma_f32_16x16x32_bf16 v[100:103], v[148:151], v[196:199], v[100:103]
	v_mfma_f32_16x16x32_bf16 v[96:99], v[156:159], v[196:199], v[96:99]
	v_mfma_f32_16x16x32_bf16 v[84:87], v[148:151], v[204:207], v[84:87]
	v_mfma_f32_16x16x32_bf16 v[80:83], v[156:159], v[204:207], v[80:83]
	v_mfma_f32_16x16x32_bf16 v[124:127], v[152:155], v[184:187], v[124:127]
	v_mfma_f32_16x16x32_bf16 v[120:123], v[160:163], v[184:187], v[120:123]
	v_mfma_f32_16x16x32_bf16 v[116:119], v[152:155], v[192:195], v[116:119]
	v_mfma_f32_16x16x32_bf16 v[112:115], v[160:163], v[192:195], v[112:115]
	v_mfma_f32_16x16x32_bf16 v[100:103], v[152:155], v[200:203], v[100:103]
	v_mfma_f32_16x16x32_bf16 v[96:99], v[160:163], v[200:203], v[96:99]
	v_mfma_f32_16x16x32_bf16 v[84:87], v[152:155], v[208:211], v[84:87]
	v_mfma_f32_16x16x32_bf16 v[80:83], v[160:163], v[208:211], v[80:83]
	s_setprio 0
	s_setprio 1
	v_mfma_f32_16x16x32_bf16 v[108:111], v[164:167], v[180:183], v[108:111]
	v_mfma_f32_16x16x32_bf16 v[104:107], v[172:175], v[180:183], v[104:107]
	v_mfma_f32_16x16x32_bf16 v[92:95], v[164:167], v[188:191], v[92:95]
	v_mfma_f32_16x16x32_bf16 v[88:91], v[172:175], v[188:191], v[88:91]
	v_mfma_f32_16x16x32_bf16 v[76:79], v[164:167], v[196:199], v[76:79]
	v_mfma_f32_16x16x32_bf16 v[72:75], v[172:175], v[196:199], v[72:75]
	v_mfma_f32_16x16x32_bf16 v[68:71], v[164:167], v[204:207], v[68:71]
	v_mfma_f32_16x16x32_bf16 v[64:67], v[172:175], v[204:207], v[64:67]
	v_mfma_f32_16x16x32_bf16 v[108:111], v[168:171], v[184:187], v[108:111]
	v_mfma_f32_16x16x32_bf16 v[104:107], v[176:179], v[184:187], v[104:107]
	v_mfma_f32_16x16x32_bf16 v[92:95], v[168:171], v[192:195], v[92:95]
	v_mfma_f32_16x16x32_bf16 v[88:91], v[176:179], v[192:195], v[88:91]
	v_mfma_f32_16x16x32_bf16 v[76:79], v[168:171], v[200:203], v[76:79]
	v_mfma_f32_16x16x32_bf16 v[72:75], v[176:179], v[200:203], v[72:75]
	v_mfma_f32_16x16x32_bf16 v[68:71], v[168:171], v[208:211], v[68:71]
	v_mfma_f32_16x16x32_bf16 v[64:67], v[176:179], v[208:211], v[64:67]
	s_setprio 0
	s_barrier
	s_add_i32 s4, s66, s68
	v_lshl_add_u64 v[212:213], s[24:25], 0, v[132:133]
	s_mov_b32 m0, s4
	ds_read_b128 v[180:183], v147 offset:16384
	ds_read_b128 v[184:187], v147 offset:17408
	ds_read_b128 v[188:191], v147 offset:18432
	ds_read_b128 v[192:195], v147 offset:19456
	ds_read_b128 v[196:199], v147 offset:20480
	ds_read_b128 v[200:203], v147 offset:21504
	ds_read_b128 v[204:207], v147 offset:22528
	ds_read_b128 v[208:211], v147 offset:23552
	global_load_lds_dwordx4 v[212:213], off
	s_add_i32 m0, s4, 0x2000
	s_add_u32 s4, s24, 0x18000
	v_lshl_add_u64 v[214:215], s[24:25], 0, v[128:129]
	s_addc_u32 s5, s25, 0
	s_add_i32 s20, s67, s68
	global_load_lds_dwordx4 v[214:215], off
	v_lshl_add_u64 v[216:217], s[4:5], 0, v[132:133]
	s_mov_b32 m0, s20
	v_lshl_add_u64 v[218:219], s[26:27], 0, v[130:131]
	global_load_lds_dwordx4 v[216:217], off
	v_lshl_add_u64 v[216:217], s[4:5], 0, v[128:129]
	s_add_i32 m0, s20, 0x2000
	s_nop 0
	global_load_lds_dwordx4 v[216:217], off
	v_lshl_add_u64 v[216:217], s[26:27], 0, v[134:135]
	s_mov_b32 m0, s34
	s_nop 0
	global_load_lds_dwordx4 v[216:217], off
	s_mov_b32 m0, s35
	s_nop 0
	global_load_lds_dwordx4 v[218:219], off
	s_cmp_lg_u32 s32, 0
	s_cbranch_scc1 .Lkw7b_b
	s_waitcnt vmcnt(8)
	s_branch .Lkw7b_d

; #define PG8_STAGE(bufoff, gbase, voff) do { _Pragma("unroll") for (int _i = 0; _i < 2; ++_i) \
;         __builtin_amdgcn_global_load_lds((const unsigned*)((const char*)(gbase) + (voff)[_i]), (LAS unsigned*)(lds + (bufoff) + ldsw + _i * 8192), 16, 0, 0); } while (0)
; #define PG8_LDA(dst, b, h) do { _Pragma("unroll") for (int m = 0; m < 4; ++m) _Pragma("unroll") for (int k = 0; k < 2; ++k) dst[m][k] = *(const LAS bf16x8*)(lds + PG8_SA(b, h) + aoff + m * 2048 + k * 1024); } while (0)
; #define PG8_LDB(dst, b, h) do { _Pragma("unroll") for (int n = 0; n < 2; ++n) _Pragma("unroll") for (int k = 0; k < 2; ++k) dst[n][k] = *(const LAS bf16x8*)(lds + PG8_SB(b, h) + boff + n * 2048 + k * 1024); } while (0)
; #define PG8_MMA(ai, bj, At, Bt) do { __builtin_amdgcn_s_setprio(1); _Pragma("unroll") for (int m = 0; m < 4; ++m) _Pragma("unroll") for (int n = 0; n < 2; ++n) _Pragma("unroll") for (int k = 0; k < 2; ++k) \
;         acc[ai][bj][m][n] = __builtin_amdgcn_mfma_f32_16x16x32_bf16(Bt[n][k], At[m][k], acc[ai][bj][m][n], 0, 0, 0); __builtin_amdgcn_s_setprio(0); } while (0)
; #define PG8_WAIT_V(n) asm volatile("s_waitcnt vmcnt(" #n ")" ::: "memory")
; #define PG8_WAIT_L(n) asm volatile("s_waitcnt lgkmcnt(" #n ")" ::: "memory")
; #define PG8_BAR __builtin_amdgcn_s_barrier()
; #define PG8_SCHED __builtin_amdgcn_sched_barrier(0)
; template <class Epi>
; __device__ __forceinline__ void gemm_phase(LAS unsigned char* lds, const Gemm g, const StaticOrder& S, const Epi& E, const int wid) {
;     ...
;             PG8_WAIT_V(8); PG8_WAIT_L(0); PG8_BAR; PG8_MMA(1, 0, At, B0); PG8_MMA(1, 1, At, B1); PG8_BAR; PG8_SCHED;
;             PG8_LDB(B0, 1, 0); PG8_LDB(B1, 1, 1); PG8_SCHED; PG8_LDA(At, 1, 0); PG8_STAGE(PG8_SA(0, 1), a2 + hsA, voffA);
;             PG8_WAIT_V(8); PG8_WAIT_L(0); PG8_BAR; PG8_MMA(0, 0, At, B0); PG8_MMA(0, 1, At, B1); PG8_BAR; PG8_SCHED;
.Lkw7b_d:
	s_mov_b32 s32, 0
	s_waitcnt lgkmcnt(0)
	s_barrier
	s_setprio 1
	s_waitcnt lgkmcnt(0)
	v_mfma_f32_16x16x32_bf16 v[60:63], v[148:151], v[180:183], v[60:63]
	v_mfma_f32_16x16x32_bf16 v[56:59], v[156:159], v[180:183], v[56:59]
	v_mfma_f32_16x16x32_bf16 v[52:55], v[148:151], v[188:191], v[52:55]
	v_mfma_f32_16x16x32_bf16 v[48:51], v[156:159], v[188:191], v[48:51]
	v_mfma_f32_16x16x32_bf16 v[36:39], v[148:151], v[196:199], v[36:39]
	v_mfma_f32_16x16x32_bf16 v[32:35], v[156:159], v[196:199], v[32:35]
	v_mfma_f32_16x16x32_bf16 v[20:23], v[148:151], v[204:207], v[20:23]
	v_mfma_f32_16x16x32_bf16 v[16:19], v[156:159], v[204:207], v[16:19]
	v_mfma_f32_16x16x32_bf16 v[60:63], v[152:155], v[184:187], v[60:63]
	v_mfma_f32_16x16x32_bf16 v[56:59], v[160:163], v[184:187], v[56:59]
	v_mfma_f32_16x16x32_bf16 v[52:55], v[152:155], v[192:195], v[52:55]
	v_mfma_f32_16x16x32_bf16 v[48:51], v[160:163], v[192:195], v[48:51]
	v_mfma_f32_16x16x32_bf16 v[36:39], v[152:155], v[200:203], v[36:39]
	v_mfma_f32_16x16x32_bf16 v[32:35], v[160:163], v[200:203], v[32:35]
	v_mfma_f32_16x16x32_bf16 v[20:23], v[152:155], v[208:211], v[20:23]
	v_mfma_f32_16x16x32_bf16 v[16:19], v[160:163], v[208:211], v[16:19]
	s_setprio 0
	s_setprio 1
	v_mfma_f32_16x16x32_bf16 v[44:47], v[164:167], v[180:183], v[44:47]
	v_mfma_f32_16x16x32_bf16 v[40:43], v[172:175], v[180:183], v[40:43]
	v_mfma_f32_16x16x32_bf16 v[28:31], v[164:167], v[188:191], v[28:31]
	v_mfma_f32_16x16x32_bf16 v[24:27], v[172:175], v[188:191], v[24:27]
	v_mfma_f32_16x16x32_bf16 v[12:15], v[164:167], v[196:199], v[12:15]
	v_mfma_f32_16x16x32_bf16 v[8:11], v[172:175], v[196:199], v[8:11]
	v_mfma_f32_16x16x32_bf16 v[4:7], v[164:167], v[204:207], v[4:7]
	v_mfma_f32_16x16x32_bf16 v[0:3], v[172:175], v[204:207], v[0:3]
	v_mfma_f32_16x16x32_bf16 v[44:47], v[168:171], v[184:187], v[44:47]
	v_mfma_f32_16x16x32_bf16 v[40:43], v[176:179], v[184:187], v[40:43]
	v_mfma_f32_16x16x32_bf16 v[28:31], v[168:171], v[192:195], v[28:31]
	v_mfma_f32_16x16x32_bf16 v[24:27], v[176:179], v[192:195], v[24:27]
	v_mfma_f32_16x16x32_bf16 v[12:15], v[168:171], v[200:203], v[12:15]
	v_mfma_f32_16x16x32_bf16 v[8:11], v[176:179], v[200:203], v[8:11]
	v_mfma_f32_16x16x32_bf16 v[4:7], v[168:171], v[208:211], v[4:7]
	v_mfma_f32_16x16x32_bf16 v[0:3], v[176:179], v[208:211], v[0:3]
	s_setprio 0
	s_barrier
	s_add_i32 s20, 0, 0x18000
	s_add_i32 s21, 0, 0x1c000
	v_add_u32_e32 v160, s20, v144
	v_add_u32_e32 v176, s21, v144
	ds_read_b128 v[148:151], v160
	ds_read_b128 v[152:155], v160 offset:1024
	ds_read_b128 v[156:159], v160 offset:2048
	ds_read_b128 v[160:163], v160 offset:3072
	ds_read_b128 v[164:167], v176
	ds_read_b128 v[168:171], v176 offset:1024
	ds_read_b128 v[172:175], v176 offset:2048
	ds_read_b128 v[176:179], v176 offset:3072
	s_add_u32 s4, s26, 0x30000
	s_addc_u32 s5, s27, 0
	s_mov_b32 m0, s36
	v_lshl_add_u64 v[220:221], s[4:5], 0, v[134:135]
	ds_read_b128 v[180:183], v147 offset:32768
	ds_read_b128 v[184:187], v147 offset:33792
	ds_read_b128 v[188:191], v147 offset:34816
	ds_read_b128 v[192:195], v147 offset:35840
	ds_read_b128 v[196:199], v147 offset:36864
	ds_read_b128 v[200:203], v147 offset:37888
	ds_read_b128 v[204:207], v147 offset:38912
	ds_read_b128 v[208:211], v147 offset:39936
	global_load_lds_dwordx4 v[220:221], off
	v_lshl_add_u64 v[220:221], s[4:5], 0, v[130:131]
	s_mov_b32 m0, s37
	s_nop 0
	global_load_lds_dwordx4 v[220:221], off
	s_waitcnt vmcnt(8)
	s_waitcnt lgkmcnt(0)
	s_barrier
	s_setprio 1
	s_waitcnt lgkmcnt(0)
	v_mfma_f32_16x16x32_bf16 v[124:127], v[148:151], v[180:183], v[124:127]
	v_mfma_f32_16x16x32_bf16 v[120:123], v[156:159], v[180:183], v[120:123]
	v_mfma_f32_16x16x32_bf16 v[116:119], v[148:151], v[188:191], v[116:119]
	v_mfma_f32_16x16x32_bf16 v[112:115], v[156:159], v[188:191], v[112:115]
	v_mfma_f32_16x16x32_bf16 v[100:103], v[148:151], v[196:199], v[100:103]
	v_mfma_f32_16x16x32_bf16 v[96:99], v[156:159], v[196:199], v[96:99]
	v_mfma_f32_16x16x32_bf16 v[84:87], v[148:151], v[204:207], v[84:87]
	v_mfma_f32_16x16x32_bf16 v[80:83], v[156:159], v[204:207], v[80:83]
	v_mfma_f32_16x16x32_bf16 v[124:127], v[152:155], v[184:187], v[124:127]
	v_mfma_f32_16x16x32_bf16 v[120:123], v[160:163], v[184:187], v[120:123]
	v_mfma_f32_16x16x32_bf16 v[116:119], v[152:155], v[192:195], v[116:119]
	v_mfma_f32_16x16x32_bf16 v[112:115], v[160:163], v[192:195], v[112:115]
	v_mfma_f32_16x16x32_bf16 v[100:103], v[152:155], v[200:203], v[100:103]
	v_mfma_f32_16x16x32_bf16 v[96:99], v[160:163], v[200:203], v[96:99]
	v_mfma_f32_16x16x32_bf16 v[84:87], v[152:155], v[208:211], v[84:87]
	v_mfma_f32_16x16x32_bf16 v[80:83], v[160:163], v[208:211], v[80:83]
	s_setprio 0
	s_setprio 1
	v_mfma_f32_16x16x32_bf16 v[108:111], v[164:167], v[180:183], v[108:111]
	v_mfma_f32_16x16x32_bf16 v[104:107], v[172:175], v[180:183], v[104:107]
	v_mfma_f32_16x16x32_bf16 v[92:95], v[164:167], v[188:191], v[92:95]
	v_mfma_f32_16x16x32_bf16 v[88:91], v[172:175], v[188:191], v[88:91]
	v_mfma_f32_16x16x32_bf16 v[76:79], v[164:167], v[196:199], v[76:79]
	v_mfma_f32_16x16x32_bf16 v[72:75], v[172:175], v[196:199], v[72:75]
	v_mfma_f32_16x16x32_bf16 v[68:71], v[164:167], v[204:207], v[68:71]
	v_mfma_f32_16x16x32_bf16 v[64:67], v[172:175], v[204:207], v[64:67]
	v_mfma_f32_16x16x32_bf16 v[108:111], v[168:171], v[184:187], v[108:111]
	v_mfma_f32_16x16x32_bf16 v[104:107], v[176:179], v[184:187], v[104:107]
	v_mfma_f32_16x16x32_bf16 v[92:95], v[168:171], v[192:195], v[92:95]
	v_mfma_f32_16x16x32_bf16 v[88:91], v[176:179], v[192:195], v[88:91]
	v_mfma_f32_16x16x32_bf16 v[76:79], v[168:171], v[200:203], v[76:79]
	v_mfma_f32_16x16x32_bf16 v[72:75], v[176:179], v[200:203], v[72:75]
	v_mfma_f32_16x16x32_bf16 v[68:71], v[168:171], v[208:211], v[68:71]
	v_mfma_f32_16x16x32_bf16 v[64:67], v[176:179], v[208:211], v[64:67]
	s_setprio 0
	s_barrier
; #define PG8_STAGE(bufoff, gbase, voff) do { _Pragma("unroll") for (int _i = 0; _i < 2; ++_i) \
;         __builtin_amdgcn_global_load_lds((const unsigned*)((const char*)(gbase) + (voff)[_i]), (LAS unsigned*)(lds + (bufoff) + ldsw + _i * 8192), 16, 0, 0); } while (0)
; #define PG8_LDA(dst, b, h) do { _Pragma("unroll") for (int m = 0; m < 4; ++m) _Pragma("unroll") for (int k = 0; k < 2; ++k) dst[m][k] = *(const LAS bf16x8*)(lds + PG8_SA(b, h) + aoff + m * 2048 + k * 1024); } while (0)
; #define PG8_MMA(ai, bj, At, Bt) do { __builtin_amdgcn_s_setprio(1); _Pragma("unroll") for (int m = 0; m < 4; ++m) _Pragma("unroll") for (int n = 0; n < 2; ++n) _Pragma("unroll") for (int k = 0; k < 2; ++k) \
;         acc[ai][bj][m][n] = __builtin_amdgcn_mfma_f32_16x16x32_bf16(Bt[n][k], At[m][k], acc[ai][bj][m][n], 0, 0, 0); __builtin_amdgcn_s_setprio(0); } while (0)
; #define PG8_WAIT_V(n) asm volatile("s_waitcnt vmcnt(" #n ")" ::: "memory")
; #define PG8_WAIT_L(n) asm volatile("s_waitcnt lgkmcnt(" #n ")" ::: "memory")
; #define PG8_BAR __builtin_amdgcn_s_barrier()
; #define PG8_SCHED __builtin_amdgcn_sched_barrier(0)
; template <class Epi>
; __device__ __forceinline__ void gemm_phase(LAS unsigned char* lds, const Gemm g, const StaticOrder& S, const Epi& E, const int wid) {
;     ...
;             PG8_LDA(At, 1, 1); PG8_STAGE(PG8_SB(1, 0), b3, voffB); PG8_STAGE(PG8_SB(1, 1), b3 + hsB, voffB); PG8_STAGE(PG8_SA(1, 0), a3, voffA);
;             PG8_WAIT_V(8); PG8_WAIT_L(0); PG8_BAR; PG8_MMA(1, 0, At, B0); PG8_MMA(1, 1, At, B1); PG8_BAR; PG8_SCHED;
;         }
;         if (wr == 0) PG8_BAR;
;         E(acc, cur, wid);
;         if (!has_next) break;
	s_add_i32 s4, s20, s68
	v_lshl_add_u64 v[212:213], v[212:213], 0, s[10:11]
	s_mov_b32 m0, s4
	ds_read_b128 v[180:183], v147 offset:49152
	ds_read_b128 v[184:187], v147 offset:50176
	ds_read_b128 v[188:191], v147 offset:51200
	ds_read_b128 v[192:195], v147 offset:52224
	ds_read_b128 v[196:199], v147 offset:53248
	ds_read_b128 v[200:203], v147 offset:54272
	ds_read_b128 v[204:207], v147 offset:55296
	ds_read_b128 v[208:211], v147 offset:56320
	global_load_lds_dwordx4 v[212:213], off
	s_add_i32 m0, s4, 0x2000
	s_add_u32 s4, s24, 0x18080
	v_lshl_add_u64 v[212:213], v[214:215], 0, s[10:11]
	s_addc_u32 s5, s25, 0
	s_add_i32 s20, s21, s68
	global_load_lds_dwordx4 v[212:213], off
	v_lshl_add_u64 v[212:213], s[4:5], 0, v[132:133]
	s_mov_b32 m0, s20
	s_nop 0
	global_load_lds_dwordx4 v[212:213], off
	v_lshl_add_u64 v[212:213], s[4:5], 0, v[128:129]
	s_add_i32 m0, s20, 0x2000
	s_nop 0
	global_load_lds_dwordx4 v[212:213], off
	v_lshl_add_u64 v[212:213], v[216:217], 0, s[10:11]
	s_mov_b32 m0, s39
	s_nop 0
	global_load_lds_dwordx4 v[212:213], off
	v_lshl_add_u64 v[212:213], v[218:219], 0, s[10:11]
	s_mov_b32 m0, s62
	s_nop 0
	global_load_lds_dwordx4 v[212:213], off
	s_waitcnt vmcnt(8)
	s_waitcnt lgkmcnt(0)
	s_barrier
	s_setprio 1
	s_waitcnt lgkmcnt(0)
	v_mfma_f32_16x16x32_bf16 v[60:63], v[148:151], v[180:183], v[60:63]
	v_mfma_f32_16x16x32_bf16 v[56:59], v[156:159], v[180:183], v[56:59]
	v_mfma_f32_16x16x32_bf16 v[52:55], v[148:151], v[188:191], v[52:55]
	v_mfma_f32_16x16x32_bf16 v[48:51], v[156:159], v[188:191], v[48:51]
	v_mfma_f32_16x16x32_bf16 v[36:39], v[148:151], v[196:199], v[36:39]
	v_mfma_f32_16x16x32_bf16 v[32:35], v[156:159], v[196:199], v[32:35]
	v_mfma_f32_16x16x32_bf16 v[20:23], v[148:151], v[204:207], v[20:23]
	v_mfma_f32_16x16x32_bf16 v[16:19], v[156:159], v[204:207], v[16:19]
	v_mfma_f32_16x16x32_bf16 v[60:63], v[152:155], v[184:187], v[60:63]
	v_mfma_f32_16x16x32_bf16 v[56:59], v[160:163], v[184:187], v[56:59]
	v_mfma_f32_16x16x32_bf16 v[52:55], v[152:155], v[192:195], v[52:55]
	v_mfma_f32_16x16x32_bf16 v[48:51], v[160:163], v[192:195], v[48:51]
	v_mfma_f32_16x16x32_bf16 v[36:39], v[152:155], v[200:203], v[36:39]
	v_mfma_f32_16x16x32_bf16 v[32:35], v[160:163], v[200:203], v[32:35]
	v_mfma_f32_16x16x32_bf16 v[20:23], v[152:155], v[208:211], v[20:23]
	v_mfma_f32_16x16x32_bf16 v[16:19], v[160:163], v[208:211], v[16:19]
	s_setprio 0
	s_setprio 1
	v_mfma_f32_16x16x32_bf16 v[44:47], v[164:167], v[180:183], v[44:47]
	v_mfma_f32_16x16x32_bf16 v[40:43], v[172:175], v[180:183], v[40:43]
	v_mfma_f32_16x16x32_bf16 v[28:31], v[164:167], v[188:191], v[28:31]
	v_mfma_f32_16x16x32_bf16 v[24:27], v[172:175], v[188:191], v[24:27]
	v_mfma_f32_16x16x32_bf16 v[12:15], v[164:167], v[196:199], v[12:15]
	v_mfma_f32_16x16x32_bf16 v[8:11], v[172:175], v[196:199], v[8:11]
	v_mfma_f32_16x16x32_bf16 v[4:7], v[164:167], v[204:207], v[4:7]
	v_mfma_f32_16x16x32_bf16 v[0:3], v[172:175], v[204:207], v[0:3]
	v_mfma_f32_16x16x32_bf16 v[44:47], v[168:171], v[184:187], v[44:47]
	v_mfma_f32_16x16x32_bf16 v[40:43], v[176:179], v[184:187], v[40:43]
	v_mfma_f32_16x16x32_bf16 v[28:31], v[168:171], v[192:195], v[28:31]
	v_mfma_f32_16x16x32_bf16 v[24:27], v[176:179], v[192:195], v[24:27]
	v_mfma_f32_16x16x32_bf16 v[12:15], v[168:171], v[200:203], v[12:15]
	v_mfma_f32_16x16x32_bf16 v[8:11], v[176:179], v[200:203], v[8:11]
	v_mfma_f32_16x16x32_bf16 v[4:7], v[168:171], v[208:211], v[4:7]
	v_mfma_f32_16x16x32_bf16 v[0:3], v[176:179], v[208:211], v[0:3]
	s_setprio 0
	s_barrier
	s_add_i32 s81, s81, 2
	s_add_u32 s79, s79, 0x100
	s_addc_u32 s80, s80, 0
	s_cmp_gt_u32 s81, 3
	s_mov_b64 s[20:21], s[22:23]
	s_cbranch_scc0 .LBB0_871
	s_mov_b32 s32, 1
	s_and_b64 vcc, exec, s[16:17]
	s_cbranch_vccz .LBB0_874
	s_barrier

; __device__ __forceinline__ int lane_id_asm() { int l; asm volatile("v_mbcnt_lo_u32_b32 %0, -1, 0\n\tv_mbcnt_hi_u32_b32 %0, -1, %0" : "=v"(l)); return l; }
; #define PG8_STAGE(bufoff, gbase, voff) do { _Pragma("unroll") for (int _i = 0; _i < 2; ++_i) \
;         __builtin_amdgcn_global_load_lds((const unsigned*)((const char*)(gbase) + (voff)[_i]), (LAS unsigned*)(lds + (bufoff) + ldsw + _i * 8192), 16, 0, 0); } while (0)
; #define PG8_WAIT_V(n) asm volatile("s_waitcnt vmcnt(" #n ")" ::: "memory")
; #define PG8_BAR __builtin_amdgcn_s_barrier()
; template <class Epi>
; __device__ __forceinline__ void gemm_phase(LAS unsigned char* lds, const Gemm g, const StaticOrder& S, const Epi& E, const int wid) {
;     const int lane = lane_id_asm(), tid = wid * 64 + lane, wr = wid >> 2, wc = wid & 3, fr = lane & 15, fq = lane >> 4;
;     const int K = g.K, nt = K / BK, lda = g.lda;
;     unsigned voffA[2], voffB[2];
; #pragma unroll
;     for (int i = 0; i < 2; ++i) { int R, C; stage_rc(tid * 16 + i * 8192, R, C); const int Rb = Epi::PERM ? ((R & ~31) + perm32(R & 31)) : R;
;         voffA[i] = (unsigned)(R * lda + C) * 2u; voffB[i] = (unsigned)(Rb * K + C) * 2u; }
;     const size_t kstep = (size_t)(BK * 2);
;     const size_t hsA = (size_t)HALF * lda * 2, hsB = (size_t)HALF * K * 2;
;     const size_t tsA = 2 * hsA, tsB = 2 * hsB;
;     const unsigned ldsw = (unsigned)wid * 1024u;
;     const int aoff = lds_byte(wr * 64 + fr, fq * 8), boff = lds_byte(wc * 32 + fr, fq * 8);
;     ...
;     PG8_WAIT_V(2); PG8_BAR;
;     PG8_STAGE(PG8_SB(1, 0), cB + kstep, voffB); PG8_STAGE(PG8_SA(1, 0), cA + kstep, voffA); PG8_STAGE(PG8_SB(1, 1), cB + hsB + kstep, voffB);
;     PG8_WAIT_V(6); PG8_BAR;
.LBB0_1081:
	s_mov_b64 s[10:11], 0x80
	s_add_i32 m0, s27, 0x18000
	v_lshl_add_u64 v[6:7], v[6:7], 0, s[10:11]
	global_load_lds_dwordx4 v[6:7], off
	v_lshl_add_u64 v[4:5], v[4:5], 0, s[10:11]
	s_add_i32 m0, s27, 0x1a000
	s_add_i32 s58, s27, 0x8000
	s_add_i32 s59, s27, 0xa000
	global_load_lds_dwordx4 v[4:5], off
	v_lshl_add_u64 v[0:1], v[0:1], 0, s[10:11]
	s_mov_b32 m0, s58
	s_add_u32 s4, s28, 0x40080
	global_load_lds_dwordx4 v[0:1], off
	v_lshl_add_u64 v[0:1], v[2:3], 0, s[10:11]
	s_mov_b32 m0, s59
	s_addc_u32 s5, s29, 0
	global_load_lds_dwordx4 v[0:1], off
	s_add_i32 m0, s27, 0x1c000
	v_lshl_add_u64 v[0:1], s[4:5], 0, v[194:195]
	global_load_lds_dwordx4 v[0:1], off
	v_lshl_add_u64 v[0:1], s[4:5], 0, v[198:199]
	s_add_i32 m0, s27, 0x1e000
	v_and_b32_e32 v2, 48, v8
	global_load_lds_dwordx4 v[0:1], off
	s_waitcnt vmcnt(8)
	s_barrier
	v_and_b32_e32 v0, 15, v8
	v_ashrrev_i32_e32 v1, 6, v8
	v_readlane_b32 s1, v254, 3
	v_lshl_or_b32 v0, v0, 6, v2
	v_lshlrev_b32_e32 v3, 2, v8
	v_lshl_add_u32 v2, v1, 10, s1
	v_readlane_b32 s1, v254, 5
	v_and_b32_e32 v3, 32, v3
	v_bitop3_b32 v2, v0, v2, v3 bitop3:0xde
	v_add_lshl_u32 v1, v1, s1, 10
	v_bitop3_b32 v245, v0, v1, v3 bitop3:0xde
	v_lshlrev_b32_e32 v0, 14, v12
	v_and_b32_e32 v0, 0xffff8000, v0
	v_lshl_add_u32 v0, v13, 11, v0
	v_and_b32_e32 v1, 1, v12
	v_lshl_or_b32 v0, v1, 6, v0
	v_lshl_add_u32 v200, v14, 1, v0
	v_lshlrev_b32_e32 v0, 14, v9
	v_and_b32_e32 v0, 0xffff8000, v0
	s_waitcnt vmcnt(6)
	s_mov_b32 s32, 0
	s_cmpk_lt_u32 s3, 0x100
	v_lshl_add_u32 v0, v10, 11, v0
	v_and_b32_e32 v1, 1, v9
	s_cselect_b64 s[16:17], -1, 0
	s_lshl_b32 s1, s33, 4
	v_lshl_or_b32 v0, v1, 6, v0
	s_add_i32 s64, 0, 0x10000
	s_add_i32 s65, 0, 0x14000
	s_and_b32 s60, s1, 0x3fffffc0
	s_ashr_i32 s61, s56, 31
	s_mov_b32 s62, s56
	s_ashr_i32 s63, s2, 31
	v_mov_b32_e32 v201, v195
	v_lshl_add_u32 v202, v11, 1, v0
	v_mov_b32_e32 v203, v195
	v_mov_b64_e32 v[204:205], 0x200
	v_mov_b64_e32 v[206:207], 0x1ff
	v_add_u32_e32 v246, s64, v245
	v_add_u32_e32 v247, s65, v245
	v_add_u32_e32 v248, 0, v2
	v_mbcnt_hi_u32_b32 v249, -1, v244
	s_barrier
	s_branch .LBB0_1084

; #define PG8_STAGE(bufoff, gbase, voff) do { _Pragma("unroll") for (int _i = 0; _i < 2; ++_i) \
;         __builtin_amdgcn_global_load_lds((const unsigned*)((const char*)(gbase) + (voff)[_i]), (LAS unsigned*)(lds + (bufoff) + ldsw + _i * 8192), 16, 0, 0); } while (0)
; #define PG8_LDA(dst, b, h) do { _Pragma("unroll") for (int m = 0; m < 4; ++m) _Pragma("unroll") for (int k = 0; k < 2; ++k) dst[m][k] = *(const LAS bf16x8*)(lds + PG8_SA(b, h) + aoff + m * 2048 + k * 1024); } while (0)
; #define PG8_LDB(dst, b, h) do { _Pragma("unroll") for (int n = 0; n < 2; ++n) _Pragma("unroll") for (int k = 0; k < 2; ++k) dst[n][k] = *(const LAS bf16x8*)(lds + PG8_SB(b, h) + boff + n * 2048 + k * 1024); } while (0)
; #define PG8_SCHED __builtin_amdgcn_sched_barrier(0)
; template <class Epi>
; __device__ __forceinline__ void gemm_phase(LAS unsigned char* lds, const Gemm g, const StaticOrder& S, const Epi& E, const int wid) {
;     ...
;         for (int t = 0; t < nt; t += 2) {
;             const bool last = (t == nt - 2);
;             const char* a1 = cA + (size_t)(t + 1) * kstep;
;             const char* a2 = last ? nA : cA + (size_t)(t + 2) * kstep; const char* b2 = last ? nB : cB + (size_t)(t + 2) * kstep;
;             const char* a3 = a2 + kstep; const char* b3 = b2 + kstep;
;             PG8_LDB(B0, 0, 0); PG8_LDB(B1, 0, 1); PG8_SCHED; PG8_LDA(At, 0, 0); PG8_STAGE(PG8_SA(1, 1), a1 + hsA, voffA);
.LBB0_1091:
	ds_read_b128 v[120:123], v246
	ds_read_b128 v[124:127], v246 offset:1024
	ds_read_b128 v[132:135], v246 offset:2048
	ds_read_b128 v[136:139], v246 offset:3072
	ds_read_b128 v[144:147], v247
	ds_read_b128 v[148:151], v247 offset:1024
	ds_read_b128 v[152:155], v247 offset:2048
	ds_read_b128 v[156:159], v247 offset:3072
	s_add_u32 s4, s28, 0xfffc0080
	s_addc_u32 s5, s29, -1
	s_cmp_eq_u32 s74, 12
	s_cselect_b32 s35, s1, s5
	s_cselect_b32 s34, s21, s4
	s_cselect_b32 s31, s19, s73
	s_cselect_b32 s30, s66, s67
	v_lshl_add_u64 v[208:209], s[28:29], 0, v[202:203]
	s_add_i32 m0, s27, 0xc000
	ds_read_b128 v[160:163], v248
	ds_read_b128 v[164:167], v248 offset:1024
	ds_read_b128 v[168:171], v248 offset:2048
	ds_read_b128 v[172:175], v248 offset:3072
	ds_read_b128 v[176:179], v248 offset:4096
	ds_read_b128 v[180:183], v248 offset:5120
	ds_read_b128 v[184:187], v248 offset:6144
	ds_read_b128 v[188:191], v248 offset:7168
	global_load_lds_dwordx4 v[208:209], off
	v_lshl_add_u64 v[208:209], s[28:29], 0, v[200:201]
	s_add_i32 m0, s27, 0xe000
	s_nop 0
	global_load_lds_dwordx4 v[208:209], off
	s_cmp_lg_u32 s32, 0
	s_cbranch_scc1 .Lkw8a_b
	s_waitcnt vmcnt(8)
	s_branch .Lkw8a_d

; #define PG8_STAGE(bufoff, gbase, voff) do { _Pragma("unroll") for (int _i = 0; _i < 2; ++_i) \
;         __builtin_amdgcn_global_load_lds((const unsigned*)((const char*)(gbase) + (voff)[_i]), (LAS unsigned*)(lds + (bufoff) + ldsw + _i * 8192), 16, 0, 0); } while (0)
; #define PG8_LDA(dst, b, h) do { _Pragma("unroll") for (int m = 0; m < 4; ++m) _Pragma("unroll") for (int k = 0; k < 2; ++k) dst[m][k] = *(const LAS bf16x8*)(lds + PG8_SA(b, h) + aoff + m * 2048 + k * 1024); } while (0)
; #define PG8_MMA(ai, bj, At, Bt) do { __builtin_amdgcn_s_setprio(1); _Pragma("unroll") for (int m = 0; m < 4; ++m) _Pragma("unroll") for (int n = 0; n < 2; ++n) _Pragma("unroll") for (int k = 0; k < 2; ++k) \
;         acc[ai][bj][m][n] = __builtin_amdgcn_mfma_f32_16x16x32_bf16(Bt[n][k], At[m][k], acc[ai][bj][m][n], 0, 0, 0); __builtin_amdgcn_s_setprio(0); } while (0)
; #define PG8_WAIT_V(n) asm volatile("s_waitcnt vmcnt(" #n ")" ::: "memory")
; #define PG8_WAIT_L(n) asm volatile("s_waitcnt lgkmcnt(" #n ")" ::: "memory")
; #define PG8_BAR __builtin_amdgcn_s_barrier()
; #define PG8_SCHED __builtin_amdgcn_sched_barrier(0)
; template <class Epi>
; __device__ __forceinline__ void gemm_phase(LAS unsigned char* lds, const Gemm g, const StaticOrder& S, const Epi& E, const int wid) {
;     ...
;             PG8_WAIT_V(8); PG8_WAIT_L(0); PG8_BAR; PG8_MMA(0, 0, At, B0); PG8_MMA(0, 1, At, B1); PG8_BAR; PG8_SCHED;
;             PG8_LDA(At, 0, 1); PG8_STAGE(PG8_SB(0, 0), b2, voffB); PG8_STAGE(PG8_SB(0, 1), b2 + hsB, voffB); PG8_STAGE(PG8_SA(0, 0), a2, voffA);
;             PG8_WAIT_V(8); PG8_WAIT_L(0); PG8_BAR; PG8_MMA(1, 0, At, B0); PG8_MMA(1, 1, At, B1); PG8_BAR; PG8_SCHED;
.Lkw8a_d:
	s_waitcnt lgkmcnt(0)
	s_barrier
	s_setprio 1
	s_waitcnt lgkmcnt(0)
	v_mfma_f32_16x16x32_bf16 v[140:143], v[120:123], v[160:163], v[140:143]
	v_mfma_f32_16x16x32_bf16 v[128:131], v[132:135], v[160:163], v[128:131]
	v_mfma_f32_16x16x32_bf16 v[108:111], v[120:123], v[168:171], v[108:111]
	v_mfma_f32_16x16x32_bf16 v[104:107], v[132:135], v[168:171], v[104:107]
	v_mfma_f32_16x16x32_bf16 v[92:95], v[120:123], v[176:179], v[92:95]
	v_mfma_f32_16x16x32_bf16 v[88:91], v[132:135], v[176:179], v[88:91]
	v_mfma_f32_16x16x32_bf16 v[76:79], v[120:123], v[184:187], v[76:79]
	v_mfma_f32_16x16x32_bf16 v[72:75], v[132:135], v[184:187], v[72:75]
	v_mfma_f32_16x16x32_bf16 v[140:143], v[124:127], v[164:167], v[140:143]
	v_mfma_f32_16x16x32_bf16 v[128:131], v[136:139], v[164:167], v[128:131]
	v_mfma_f32_16x16x32_bf16 v[108:111], v[124:127], v[172:175], v[108:111]
	v_mfma_f32_16x16x32_bf16 v[104:107], v[136:139], v[172:175], v[104:107]
	v_mfma_f32_16x16x32_bf16 v[92:95], v[124:127], v[180:183], v[92:95]
	v_mfma_f32_16x16x32_bf16 v[88:91], v[136:139], v[180:183], v[88:91]
	v_mfma_f32_16x16x32_bf16 v[76:79], v[124:127], v[188:191], v[76:79]
	v_mfma_f32_16x16x32_bf16 v[72:75], v[136:139], v[188:191], v[72:75]
	s_setprio 0
	s_setprio 1
	v_mfma_f32_16x16x32_bf16 v[116:119], v[144:147], v[160:163], v[116:119]
	v_mfma_f32_16x16x32_bf16 v[112:115], v[152:155], v[160:163], v[112:115]
	v_mfma_f32_16x16x32_bf16 v[100:103], v[144:147], v[168:171], v[100:103]
	v_mfma_f32_16x16x32_bf16 v[96:99], v[152:155], v[168:171], v[96:99]
	v_mfma_f32_16x16x32_bf16 v[84:87], v[144:147], v[176:179], v[84:87]
	v_mfma_f32_16x16x32_bf16 v[80:83], v[152:155], v[176:179], v[80:83]
	v_mfma_f32_16x16x32_bf16 v[68:71], v[144:147], v[184:187], v[68:71]
	v_mfma_f32_16x16x32_bf16 v[64:67], v[152:155], v[184:187], v[64:67]
	v_mfma_f32_16x16x32_bf16 v[116:119], v[148:151], v[164:167], v[116:119]
	v_mfma_f32_16x16x32_bf16 v[112:115], v[156:159], v[164:167], v[112:115]
	v_mfma_f32_16x16x32_bf16 v[100:103], v[148:151], v[172:175], v[100:103]
	v_mfma_f32_16x16x32_bf16 v[96:99], v[156:159], v[172:175], v[96:99]
	v_mfma_f32_16x16x32_bf16 v[84:87], v[148:151], v[180:183], v[84:87]
	v_mfma_f32_16x16x32_bf16 v[80:83], v[156:159], v[180:183], v[80:83]
	v_mfma_f32_16x16x32_bf16 v[68:71], v[148:151], v[188:191], v[68:71]
	v_mfma_f32_16x16x32_bf16 v[64:67], v[156:159], v[188:191], v[64:67]
	s_setprio 0
	s_barrier
	s_add_i32 s4, s64, s68
	v_lshl_add_u64 v[208:209], s[30:31], 0, v[194:195]
	s_mov_b32 m0, s4
	ds_read_b128 v[160:163], v248 offset:16384
	ds_read_b128 v[164:167], v248 offset:17408
	ds_read_b128 v[168:171], v248 offset:18432
	ds_read_b128 v[172:175], v248 offset:19456
	ds_read_b128 v[176:179], v248 offset:20480
	ds_read_b128 v[180:183], v248 offset:21504
	ds_read_b128 v[184:187], v248 offset:22528
	ds_read_b128 v[188:191], v248 offset:23552
	global_load_lds_dwordx4 v[208:209], off
	s_add_i32 m0, s4, 0x2000
	s_add_u32 s4, s30, 0x40000
	v_lshl_add_u64 v[210:211], s[30:31], 0, v[198:199]
	s_addc_u32 s5, s31, 0
	s_add_i32 s70, s65, s68
	global_load_lds_dwordx4 v[210:211], off
	v_lshl_add_u64 v[212:213], s[4:5], 0, v[194:195]
	s_mov_b32 m0, s70
	v_lshl_add_u64 v[214:215], s[34:35], 0, v[196:197]
	global_load_lds_dwordx4 v[212:213], off
	v_lshl_add_u64 v[212:213], s[4:5], 0, v[198:199]
	s_add_i32 m0, s70, 0x2000
	s_nop 0
	global_load_lds_dwordx4 v[212:213], off
	v_lshl_add_u64 v[212:213], s[34:35], 0, v[192:193]
	s_mov_b32 m0, s27
	s_nop 0
	global_load_lds_dwordx4 v[212:213], off
	s_mov_b32 m0, s38
	s_nop 0
	global_load_lds_dwordx4 v[214:215], off
	s_cmp_lg_u32 s32, 0
	s_cbranch_scc1 .Lkw8b_b
	s_waitcnt vmcnt(8)
	s_branch .Lkw8b_d

; #define PG8_STAGE(bufoff, gbase, voff) do { _Pragma("unroll") for (int _i = 0; _i < 2; ++_i) \
;         __builtin_amdgcn_global_load_lds((const unsigned*)((const char*)(gbase) + (voff)[_i]), (LAS unsigned*)(lds + (bufoff) + ldsw + _i * 8192), 16, 0, 0); } while (0)
; #define PG8_LDA(dst, b, h) do { _Pragma("unroll") for (int m = 0; m < 4; ++m) _Pragma("unroll") for (int k = 0; k < 2; ++k) dst[m][k] = *(const LAS bf16x8*)(lds + PG8_SA(b, h) + aoff + m * 2048 + k * 1024); } while (0)
; #define PG8_LDB(dst, b, h) do { _Pragma("unroll") for (int n = 0; n < 2; ++n) _Pragma("unroll") for (int k = 0; k < 2; ++k) dst[n][k] = *(const LAS bf16x8*)(lds + PG8_SB(b, h) + boff + n * 2048 + k * 1024); } while (0)
; #define PG8_MMA(ai, bj, At, Bt) do { __builtin_amdgcn_s_setprio(1); _Pragma("unroll") for (int m = 0; m < 4; ++m) _Pragma("unroll") for (int n = 0; n < 2; ++n) _Pragma("unroll") for (int k = 0; k < 2; ++k) \
;         acc[ai][bj][m][n] = __builtin_amdgcn_mfma_f32_16x16x32_bf16(Bt[n][k], At[m][k], acc[ai][bj][m][n], 0, 0, 0); __builtin_amdgcn_s_setprio(0); } while (0)
; #define PG8_WAIT_V(n) asm volatile("s_waitcnt vmcnt(" #n ")" ::: "memory")
; #define PG8_WAIT_L(n) asm volatile("s_waitcnt lgkmcnt(" #n ")" ::: "memory")
; #define PG8_BAR __builtin_amdgcn_s_barrier()
; #define PG8_SCHED __builtin_amdgcn_sched_barrier(0)
; template <class Epi>
; __device__ __forceinline__ void gemm_phase(LAS unsigned char* lds, const Gemm g, const StaticOrder& S, const Epi& E, const int wid) {
;     ...
;             PG8_WAIT_V(8); PG8_WAIT_L(0); PG8_BAR; PG8_MMA(1, 0, At, B0); PG8_MMA(1, 1, At, B1); PG8_BAR; PG8_SCHED;
;             PG8_LDB(B0, 1, 0); PG8_LDB(B1, 1, 1); PG8_SCHED; PG8_LDA(At, 1, 0); PG8_STAGE(PG8_SA(0, 1), a2 + hsA, voffA);
;             PG8_WAIT_V(8); PG8_WAIT_L(0); PG8_BAR; PG8_MMA(0, 0, At, B0); PG8_MMA(0, 1, At, B1); PG8_BAR; PG8_SCHED;
.Lkw8b_d:
	s_mov_b32 s32, 0
	s_waitcnt lgkmcnt(0)
	s_barrier
	s_setprio 1
	s_waitcnt lgkmcnt(0)
	v_mfma_f32_16x16x32_bf16 v[60:63], v[120:123], v[160:163], v[60:63]
	v_mfma_f32_16x16x32_bf16 v[56:59], v[132:135], v[160:163], v[56:59]
	v_mfma_f32_16x16x32_bf16 v[44:47], v[120:123], v[168:171], v[44:47]
	v_mfma_f32_16x16x32_bf16 v[40:43], v[132:135], v[168:171], v[40:43]
	v_mfma_f32_16x16x32_bf16 v[28:31], v[120:123], v[176:179], v[28:31]
	v_mfma_f32_16x16x32_bf16 v[24:27], v[132:135], v[176:179], v[24:27]
	v_mfma_f32_16x16x32_bf16 v[12:15], v[120:123], v[184:187], v[12:15]
	v_mfma_f32_16x16x32_bf16 v[8:11], v[132:135], v[184:187], v[8:11]
	v_mfma_f32_16x16x32_bf16 v[60:63], v[124:127], v[164:167], v[60:63]
	v_mfma_f32_16x16x32_bf16 v[56:59], v[136:139], v[164:167], v[56:59]
	v_mfma_f32_16x16x32_bf16 v[44:47], v[124:127], v[172:175], v[44:47]
	v_mfma_f32_16x16x32_bf16 v[40:43], v[136:139], v[172:175], v[40:43]
	v_mfma_f32_16x16x32_bf16 v[28:31], v[124:127], v[180:183], v[28:31]
	v_mfma_f32_16x16x32_bf16 v[24:27], v[136:139], v[180:183], v[24:27]
	v_mfma_f32_16x16x32_bf16 v[12:15], v[124:127], v[188:191], v[12:15]
	v_mfma_f32_16x16x32_bf16 v[8:11], v[136:139], v[188:191], v[8:11]
	s_setprio 0
	s_setprio 1
	v_mfma_f32_16x16x32_bf16 v[52:55], v[144:147], v[160:163], v[52:55]
	v_mfma_f32_16x16x32_bf16 v[48:51], v[152:155], v[160:163], v[48:51]
	v_mfma_f32_16x16x32_bf16 v[36:39], v[144:147], v[168:171], v[36:39]
	v_mfma_f32_16x16x32_bf16 v[32:35], v[152:155], v[168:171], v[32:35]
	v_mfma_f32_16x16x32_bf16 v[20:23], v[144:147], v[176:179], v[20:23]
	v_mfma_f32_16x16x32_bf16 v[16:19], v[152:155], v[176:179], v[16:19]
	v_mfma_f32_16x16x32_bf16 v[4:7], v[144:147], v[184:187], v[4:7]
	v_mfma_f32_16x16x32_bf16 v[0:3], v[152:155], v[184:187], v[0:3]
	v_mfma_f32_16x16x32_bf16 v[52:55], v[148:151], v[164:167], v[52:55]
	v_mfma_f32_16x16x32_bf16 v[48:51], v[156:159], v[164:167], v[48:51]
	v_mfma_f32_16x16x32_bf16 v[36:39], v[148:151], v[172:175], v[36:39]
	v_mfma_f32_16x16x32_bf16 v[32:35], v[156:159], v[172:175], v[32:35]
	v_mfma_f32_16x16x32_bf16 v[20:23], v[148:151], v[180:183], v[20:23]
	v_mfma_f32_16x16x32_bf16 v[16:19], v[156:159], v[180:183], v[16:19]
	v_mfma_f32_16x16x32_bf16 v[4:7], v[148:151], v[188:191], v[4:7]
	v_mfma_f32_16x16x32_bf16 v[0:3], v[156:159], v[188:191], v[0:3]
	s_setprio 0
	s_barrier
	s_add_i32 s70, 0, 0x18000
	s_add_i32 s71, 0, 0x1c000
	v_add_u32_e32 v136, s70, v245
	v_add_u32_e32 v156, s71, v245
	ds_read_b128 v[120:123], v136
	ds_read_b128 v[124:127], v136 offset:1024
	ds_read_b128 v[132:135], v136 offset:2048
	ds_read_b128 v[136:139], v136 offset:3072
	ds_read_b128 v[144:147], v156
	ds_read_b128 v[148:151], v156 offset:1024
	ds_read_b128 v[152:155], v156 offset:2048
	ds_read_b128 v[156:159], v156 offset:3072
	s_add_u32 s4, s34, 0x40000
	s_addc_u32 s5, s35, 0
	s_mov_b32 m0, s39
	v_lshl_add_u64 v[216:217], s[4:5], 0, v[192:193]
	ds_read_b128 v[160:163], v248 offset:32768
	ds_read_b128 v[164:167], v248 offset:33792
	ds_read_b128 v[168:171], v248 offset:34816
	ds_read_b128 v[172:175], v248 offset:35840
	ds_read_b128 v[176:179], v248 offset:36864
	ds_read_b128 v[180:183], v248 offset:37888
	ds_read_b128 v[184:187], v248 offset:38912
	ds_read_b128 v[188:191], v248 offset:39936
	global_load_lds_dwordx4 v[216:217], off
	v_lshl_add_u64 v[216:217], s[4:5], 0, v[196:197]
	s_mov_b32 m0, s50
	s_nop 0
	global_load_lds_dwordx4 v[216:217], off
	s_waitcnt vmcnt(8)
	s_waitcnt lgkmcnt(0)
	s_barrier
	s_setprio 1
	s_waitcnt lgkmcnt(0)
	v_mfma_f32_16x16x32_bf16 v[140:143], v[120:123], v[160:163], v[140:143]
	v_mfma_f32_16x16x32_bf16 v[128:131], v[132:135], v[160:163], v[128:131]
	v_mfma_f32_16x16x32_bf16 v[108:111], v[120:123], v[168:171], v[108:111]
	v_mfma_f32_16x16x32_bf16 v[104:107], v[132:135], v[168:171], v[104:107]
	v_mfma_f32_16x16x32_bf16 v[92:95], v[120:123], v[176:179], v[92:95]
	v_mfma_f32_16x16x32_bf16 v[88:91], v[132:135], v[176:179], v[88:91]
	v_mfma_f32_16x16x32_bf16 v[76:79], v[120:123], v[184:187], v[76:79]
	v_mfma_f32_16x16x32_bf16 v[72:75], v[132:135], v[184:187], v[72:75]
	v_mfma_f32_16x16x32_bf16 v[140:143], v[124:127], v[164:167], v[140:143]
	v_mfma_f32_16x16x32_bf16 v[128:131], v[136:139], v[164:167], v[128:131]
	v_mfma_f32_16x16x32_bf16 v[108:111], v[124:127], v[172:175], v[108:111]
	v_mfma_f32_16x16x32_bf16 v[104:107], v[136:139], v[172:175], v[104:107]
	v_mfma_f32_16x16x32_bf16 v[92:95], v[124:127], v[180:183], v[92:95]
	v_mfma_f32_16x16x32_bf16 v[88:91], v[136:139], v[180:183], v[88:91]
	v_mfma_f32_16x16x32_bf16 v[76:79], v[124:127], v[188:191], v[76:79]
	v_mfma_f32_16x16x32_bf16 v[72:75], v[136:139], v[188:191], v[72:75]
	s_setprio 0
	s_setprio 1
	v_mfma_f32_16x16x32_bf16 v[116:119], v[144:147], v[160:163], v[116:119]
	v_mfma_f32_16x16x32_bf16 v[112:115], v[152:155], v[160:163], v[112:115]
	v_mfma_f32_16x16x32_bf16 v[100:103], v[144:147], v[168:171], v[100:103]
	v_mfma_f32_16x16x32_bf16 v[96:99], v[152:155], v[168:171], v[96:99]
	v_mfma_f32_16x16x32_bf16 v[84:87], v[144:147], v[176:179], v[84:87]
	v_mfma_f32_16x16x32_bf16 v[80:83], v[152:155], v[176:179], v[80:83]
	v_mfma_f32_16x16x32_bf16 v[68:71], v[144:147], v[184:187], v[68:71]
	v_mfma_f32_16x16x32_bf16 v[64:67], v[152:155], v[184:187], v[64:67]
	v_mfma_f32_16x16x32_bf16 v[116:119], v[148:151], v[164:167], v[116:119]
	v_mfma_f32_16x16x32_bf16 v[112:115], v[156:159], v[164:167], v[112:115]
	v_mfma_f32_16x16x32_bf16 v[100:103], v[148:151], v[172:175], v[100:103]
	v_mfma_f32_16x16x32_bf16 v[96:99], v[156:159], v[172:175], v[96:99]
	v_mfma_f32_16x16x32_bf16 v[84:87], v[148:151], v[180:183], v[84:87]
	v_mfma_f32_16x16x32_bf16 v[80:83], v[156:159], v[180:183], v[80:83]
	v_mfma_f32_16x16x32_bf16 v[68:71], v[148:151], v[188:191], v[68:71]
	v_mfma_f32_16x16x32_bf16 v[64:67], v[156:159], v[188:191], v[64:67]
	s_setprio 0
	s_barrier
; #define PG8_STAGE(bufoff, gbase, voff) do { _Pragma("unroll") for (int _i = 0; _i < 2; ++_i) \
;         __builtin_amdgcn_global_load_lds((const unsigned*)((const char*)(gbase) + (voff)[_i]), (LAS unsigned*)(lds + (bufoff) + ldsw + _i * 8192), 16, 0, 0); } while (0)
; #define PG8_LDA(dst, b, h) do { _Pragma("unroll") for (int m = 0; m < 4; ++m) _Pragma("unroll") for (int k = 0; k < 2; ++k) dst[m][k] = *(const LAS bf16x8*)(lds + PG8_SA(b, h) + aoff + m * 2048 + k * 1024); } while (0)
; #define PG8_MMA(ai, bj, At, Bt) do { __builtin_amdgcn_s_setprio(1); _Pragma("unroll") for (int m = 0; m < 4; ++m) _Pragma("unroll") for (int n = 0; n < 2; ++n) _Pragma("unroll") for (int k = 0; k < 2; ++k) \
;         acc[ai][bj][m][n] = __builtin_amdgcn_mfma_f32_16x16x32_bf16(Bt[n][k], At[m][k], acc[ai][bj][m][n], 0, 0, 0); __builtin_amdgcn_s_setprio(0); } while (0)
; #define PG8_WAIT_V(n) asm volatile("s_waitcnt vmcnt(" #n ")" ::: "memory")
; #define PG8_WAIT_L(n) asm volatile("s_waitcnt lgkmcnt(" #n ")" ::: "memory")
; #define PG8_BAR __builtin_amdgcn_s_barrier()
; #define PG8_SCHED __builtin_amdgcn_sched_barrier(0)
; template <class Epi>
; __device__ __forceinline__ void gemm_phase(LAS unsigned char* lds, const Gemm g, const StaticOrder& S, const Epi& E, const int wid) {
;     ...
;             PG8_LDA(At, 1, 1); PG8_STAGE(PG8_SB(1, 0), b3, voffB); PG8_STAGE(PG8_SB(1, 1), b3 + hsB, voffB); PG8_STAGE(PG8_SA(1, 0), a3, voffA);
;             PG8_WAIT_V(8); PG8_WAIT_L(0); PG8_BAR; PG8_MMA(1, 0, At, B0); PG8_MMA(1, 1, At, B1); PG8_BAR; PG8_SCHED;
;         }
;         if (wr == 0) PG8_BAR;
;         E(acc, cur, wid);
;         if (!has_next) break;
	s_add_i32 s4, s70, s68
	v_lshl_add_u64 v[208:209], v[208:209], 0, s[10:11]
	s_mov_b32 m0, s4
	ds_read_b128 v[160:163], v248 offset:49152
	ds_read_b128 v[164:167], v248 offset:50176
	ds_read_b128 v[168:171], v248 offset:51200
	ds_read_b128 v[172:175], v248 offset:52224
	ds_read_b128 v[176:179], v248 offset:53248
	ds_read_b128 v[180:183], v248 offset:54272
	ds_read_b128 v[184:187], v248 offset:55296
	ds_read_b128 v[188:191], v248 offset:56320
	global_load_lds_dwordx4 v[208:209], off
	s_add_i32 m0, s4, 0x2000
	s_add_u32 s4, s30, 0x40080
	v_lshl_add_u64 v[208:209], v[210:211], 0, s[10:11]
	s_addc_u32 s5, s31, 0
	s_add_i32 s30, s71, s68
	global_load_lds_dwordx4 v[208:209], off
	v_lshl_add_u64 v[208:209], s[4:5], 0, v[194:195]
	s_mov_b32 m0, s30
	s_nop 0
	global_load_lds_dwordx4 v[208:209], off
	v_lshl_add_u64 v[208:209], s[4:5], 0, v[198:199]
	s_add_i32 m0, s30, 0x2000
	s_nop 0
	global_load_lds_dwordx4 v[208:209], off
	v_lshl_add_u64 v[208:209], v[212:213], 0, s[10:11]
	s_mov_b32 m0, s58
	s_nop 0
	global_load_lds_dwordx4 v[208:209], off
	v_lshl_add_u64 v[208:209], v[214:215], 0, s[10:11]
	s_mov_b32 m0, s59
	s_nop 0
	global_load_lds_dwordx4 v[208:209], off
	s_waitcnt vmcnt(8)
	s_waitcnt lgkmcnt(0)
	s_barrier
	s_setprio 1
	s_waitcnt lgkmcnt(0)
	v_mfma_f32_16x16x32_bf16 v[60:63], v[120:123], v[160:163], v[60:63]
	v_mfma_f32_16x16x32_bf16 v[56:59], v[132:135], v[160:163], v[56:59]
	v_mfma_f32_16x16x32_bf16 v[44:47], v[120:123], v[168:171], v[44:47]
	v_mfma_f32_16x16x32_bf16 v[40:43], v[132:135], v[168:171], v[40:43]
	v_mfma_f32_16x16x32_bf16 v[28:31], v[120:123], v[176:179], v[28:31]
	v_mfma_f32_16x16x32_bf16 v[24:27], v[132:135], v[176:179], v[24:27]
	v_mfma_f32_16x16x32_bf16 v[12:15], v[120:123], v[184:187], v[12:15]
	v_mfma_f32_16x16x32_bf16 v[8:11], v[132:135], v[184:187], v[8:11]
	v_mfma_f32_16x16x32_bf16 v[60:63], v[124:127], v[164:167], v[60:63]
	v_mfma_f32_16x16x32_bf16 v[56:59], v[136:139], v[164:167], v[56:59]
	v_mfma_f32_16x16x32_bf16 v[44:47], v[124:127], v[172:175], v[44:47]
	v_mfma_f32_16x16x32_bf16 v[40:43], v[136:139], v[172:175], v[40:43]
	v_mfma_f32_16x16x32_bf16 v[28:31], v[124:127], v[180:183], v[28:31]
	v_mfma_f32_16x16x32_bf16 v[24:27], v[136:139], v[180:183], v[24:27]
	v_mfma_f32_16x16x32_bf16 v[12:15], v[124:127], v[188:191], v[12:15]
	v_mfma_f32_16x16x32_bf16 v[8:11], v[136:139], v[188:191], v[8:11]
	s_setprio 0
	s_setprio 1
	v_mfma_f32_16x16x32_bf16 v[52:55], v[144:147], v[160:163], v[52:55]
	v_mfma_f32_16x16x32_bf16 v[48:51], v[152:155], v[160:163], v[48:51]
	v_mfma_f32_16x16x32_bf16 v[36:39], v[144:147], v[168:171], v[36:39]
	v_mfma_f32_16x16x32_bf16 v[32:35], v[152:155], v[168:171], v[32:35]
	v_mfma_f32_16x16x32_bf16 v[20:23], v[144:147], v[176:179], v[20:23]
	v_mfma_f32_16x16x32_bf16 v[16:19], v[152:155], v[176:179], v[16:19]
	v_mfma_f32_16x16x32_bf16 v[4:7], v[144:147], v[184:187], v[4:7]
	v_mfma_f32_16x16x32_bf16 v[0:3], v[152:155], v[184:187], v[0:3]
	v_mfma_f32_16x16x32_bf16 v[52:55], v[148:151], v[164:167], v[52:55]
	v_mfma_f32_16x16x32_bf16 v[48:51], v[156:159], v[164:167], v[48:51]
	v_mfma_f32_16x16x32_bf16 v[36:39], v[148:151], v[172:175], v[36:39]
	v_mfma_f32_16x16x32_bf16 v[32:35], v[156:159], v[172:175], v[32:35]
	v_mfma_f32_16x16x32_bf16 v[20:23], v[148:151], v[180:183], v[20:23]
	v_mfma_f32_16x16x32_bf16 v[16:19], v[156:159], v[180:183], v[16:19]
	v_mfma_f32_16x16x32_bf16 v[4:7], v[148:151], v[188:191], v[4:7]
	v_mfma_f32_16x16x32_bf16 v[0:3], v[156:159], v[188:191], v[0:3]
	s_setprio 0
	s_barrier
	s_add_i32 s74, s74, 2
	s_add_u32 s67, s67, 0x100
	s_addc_u32 s73, s73, 0
	s_add_u32 s28, s28, 0x100
	s_addc_u32 s29, s29, 0
	s_cmp_gt_u32 s74, 13
	s_cbranch_scc0 .LBB0_1091
	s_mov_b32 s32, 1
	s_and_b64 vcc, exec, s[16:17]
	s_cbranch_vccz .LBB0_1094
	s_barrier

; __device__ __forceinline__ int lane_id_asm() { int l; asm volatile("v_mbcnt_lo_u32_b32 %0, -1, 0\n\tv_mbcnt_hi_u32_b32 %0, -1, %0" : "=v"(l)); return l; }
; #define PG8_STAGE(bufoff, gbase, voff) do { _Pragma("unroll") for (int _i = 0; _i < 2; ++_i) \
;         __builtin_amdgcn_global_load_lds((const unsigned*)((const char*)(gbase) + (voff)[_i]), (LAS unsigned*)(lds + (bufoff) + ldsw + _i * 8192), 16, 0, 0); } while (0)
; #define PG8_WAIT_V(n) asm volatile("s_waitcnt vmcnt(" #n ")" ::: "memory")
; #define PG8_BAR __builtin_amdgcn_s_barrier()
; template <class Epi>
; __device__ __forceinline__ void gemm_phase(LAS unsigned char* lds, const Gemm g, const StaticOrder& S, const Epi& E, const int wid) {
;     const int lane = lane_id_asm(), tid = wid * 64 + lane, wr = wid >> 2, wc = wid & 3, fr = lane & 15, fq = lane >> 4;
;     const int K = g.K, nt = K / BK, lda = g.lda;
;     unsigned voffA[2], voffB[2];
; #pragma unroll
;     for (int i = 0; i < 2; ++i) { int R, C; stage_rc(tid * 16 + i * 8192, R, C); const int Rb = Epi::PERM ? ((R & ~31) + perm32(R & 31)) : R;
;         voffA[i] = (unsigned)(R * lda + C) * 2u; voffB[i] = (unsigned)(Rb * K + C) * 2u; }
;     const size_t kstep = (size_t)(BK * 2);
;     const size_t hsA = (size_t)HALF * lda * 2, hsB = (size_t)HALF * K * 2;
;     const size_t tsA = 2 * hsA, tsB = 2 * hsB;
;     const unsigned ldsw = (unsigned)wid * 1024u;
;     const int aoff = lds_byte(wr * 64 + fr, fq * 8), boff = lds_byte(wc * 32 + fr, fq * 8);
;     ...
;     PG8_WAIT_V(2); PG8_BAR;
;     PG8_STAGE(PG8_SB(1, 0), cB + kstep, voffB); PG8_STAGE(PG8_SA(1, 0), cA + kstep, voffA); PG8_STAGE(PG8_SB(1, 1), cB + hsB + kstep, voffB);
;     PG8_WAIT_V(6); PG8_BAR;
.LBB0_1165:
	s_mov_b64 s[6:7], 0x80
	s_add_i32 m0, s31, 0x18000
	v_lshl_add_u64 v[6:7], v[6:7], 0, s[6:7]
	global_load_lds_dwordx4 v[6:7], off
	v_lshl_add_u64 v[4:5], v[4:5], 0, s[6:7]
	s_add_i32 m0, s31, 0x1a000
	s_add_i32 s63, s31, 0x8000
	s_add_i32 s64, s31, 0xa000
	global_load_lds_dwordx4 v[4:5], off
	v_lshl_add_u64 v[0:1], v[0:1], 0, s[6:7]
	s_mov_b32 m0, s63
	s_add_u32 s8, s34, 0x40080
	global_load_lds_dwordx4 v[0:1], off
	v_lshl_add_u64 v[0:1], v[2:3], 0, s[6:7]
	s_mov_b32 m0, s64
	s_addc_u32 s9, s35, 0
	global_load_lds_dwordx4 v[0:1], off
	s_add_i32 m0, s31, 0x1c000
	v_lshl_add_u64 v[0:1], s[8:9], 0, v[130:131]
	global_load_lds_dwordx4 v[0:1], off
	v_lshl_add_u64 v[0:1], s[8:9], 0, v[134:135]
	s_add_i32 m0, s31, 0x1e000
	s_sext_i32_i8 s79, s4
	global_load_lds_dwordx4 v[0:1], off
	s_waitcnt vmcnt(8)
	s_barrier
	v_and_b32_e32 v0, 15, v8
	v_ashrrev_i32_e32 v1, 6, v8
	v_and_b32_e32 v2, 48, v8
	v_readlane_b32 s4, v254, 3
	v_lshl_or_b32 v0, v0, 6, v2
	v_lshlrev_b32_e32 v3, 2, v8
	v_lshl_add_u32 v2, v1, 10, s4
	v_readlane_b32 s4, v254, 5
	v_and_b32_e32 v3, 32, v3
	v_bitop3_b32 v2, v0, v2, v3 bitop3:0xde
	v_add_lshl_u32 v1, v1, s4, 10
	v_bitop3_b32 v144, v0, v1, v3 bitop3:0xde
	v_lshlrev_b32_e32 v0, 14, v12
	v_and_b32_e32 v0, 0xffff8000, v0
	v_lshl_add_u32 v0, v13, 11, v0
	v_and_b32_e32 v1, 1, v12
	v_lshl_or_b32 v0, v1, 6, v0
	v_lshl_add_u32 v136, v14, 1, v0
	v_lshlrev_b32_e32 v0, 14, v9
	v_and_b32_e32 v0, 0xffff8000, v0
	s_waitcnt vmcnt(6)
	s_mov_b32 s32, 0
	s_cmpk_lt_u32 s3, 0x100
	v_lshl_add_u32 v0, v10, 11, v0
	v_and_b32_e32 v1, 1, v9
	s_cselect_b64 s[8:9], -1, 0
	s_lshl_b32 s4, s33, 4
	v_lshl_or_b32 v0, v1, 6, v0
	s_add_i32 s73, 0, 0x10000
	s_add_i32 s74, 0, 0x14000
	s_and_b32 s65, s4, 0x3fffffc0
	s_ashr_i32 s66, s56, 31
	s_mov_b32 s67, s56
	v_mov_b32_e32 v137, v131
	v_lshl_add_u32 v138, v11, 1, v0
	v_mov_b32_e32 v139, v131
	v_mov_b64_e32 v[140:141], 0x800
	v_mov_b64_e32 v[142:143], 0x7ff
	v_add_u32_e32 v145, s73, v144
	v_add_u32_e32 v146, s74, v144
	v_add_u32_e32 v147, 0, v2
	s_mov_b64 s[10:11], 0x100000
	s_mov_b32 s75, 0x100000
	s_mov_b64 s[16:17], 0x120000
	s_mov_b32 s76, 0x120000
	s_mov_b64 s[18:19], 0x140000
	s_mov_b32 s77, 0x140000
	s_mov_b64 s[20:21], 0x160000
	s_mov_b32 s78, 0x160000
	s_barrier
	s_branch .LBB0_1168

; #define PG8_STAGE(bufoff, gbase, voff) do { _Pragma("unroll") for (int _i = 0; _i < 2; ++_i) \
;         __builtin_amdgcn_global_load_lds((const unsigned*)((const char*)(gbase) + (voff)[_i]), (LAS unsigned*)(lds + (bufoff) + ldsw + _i * 8192), 16, 0, 0); } while (0)
; #define PG8_LDA(dst, b, h) do { _Pragma("unroll") for (int m = 0; m < 4; ++m) _Pragma("unroll") for (int k = 0; k < 2; ++k) dst[m][k] = *(const LAS bf16x8*)(lds + PG8_SA(b, h) + aoff + m * 2048 + k * 1024); } while (0)
; #define PG8_LDB(dst, b, h) do { _Pragma("unroll") for (int n = 0; n < 2; ++n) _Pragma("unroll") for (int k = 0; k < 2; ++k) dst[n][k] = *(const LAS bf16x8*)(lds + PG8_SB(b, h) + boff + n * 2048 + k * 1024); } while (0)
; #define PG8_SCHED __builtin_amdgcn_sched_barrier(0)
; template <class Epi>
; __device__ __forceinline__ void gemm_phase(LAS unsigned char* lds, const Gemm g, const StaticOrder& S, const Epi& E, const int wid) {
;     ...
;         for (int t = 0; t < nt; t += 2) {
;             const bool last = (t == nt - 2);
;             const char* a1 = cA + (size_t)(t + 1) * kstep;
;             const char* a2 = last ? nA : cA + (size_t)(t + 2) * kstep; const char* b2 = last ? nB : cB + (size_t)(t + 2) * kstep;
;             const char* a3 = a2 + kstep; const char* b3 = b2 + kstep;
;             PG8_LDB(B0, 0, 0); PG8_LDB(B1, 0, 1); PG8_SCHED; PG8_LDA(At, 0, 0); PG8_STAGE(PG8_SA(1, 1), a1 + hsA, voffA);
.LBB0_1175:
	ds_read_b128 v[148:151], v145
	ds_read_b128 v[152:155], v145 offset:1024
	ds_read_b128 v[156:159], v145 offset:2048
	ds_read_b128 v[160:163], v145 offset:3072
	ds_read_b128 v[164:167], v146
	ds_read_b128 v[168:171], v146 offset:1024
	ds_read_b128 v[172:175], v146 offset:2048
	ds_read_b128 v[176:179], v146 offset:3072
	s_add_u32 s36, s34, 0xfffc0080
	s_addc_u32 s37, s35, -1
	s_cmp_eq_u32 s87, 12
	s_cselect_b32 s39, s25, s37
	s_cselect_b32 s38, s80, s36
	s_cselect_b32 s37, s23, s83
	s_cselect_b32 s36, s81, s82
	v_lshl_add_u64 v[212:213], s[34:35], 0, v[138:139]
	s_add_i32 m0, s31, 0xc000
	ds_read_b128 v[180:183], v147
	ds_read_b128 v[184:187], v147 offset:1024
	ds_read_b128 v[188:191], v147 offset:2048
	ds_read_b128 v[192:195], v147 offset:3072
	ds_read_b128 v[196:199], v147 offset:4096
	ds_read_b128 v[200:203], v147 offset:5120
	ds_read_b128 v[204:207], v147 offset:6144
	ds_read_b128 v[208:211], v147 offset:7168
	global_load_lds_dwordx4 v[212:213], off
	v_lshl_add_u64 v[212:213], s[34:35], 0, v[136:137]
	s_add_i32 m0, s31, 0xe000
	s_nop 0
	global_load_lds_dwordx4 v[212:213], off
	s_cmp_lg_u32 s32, 0
	s_cbranch_scc1 .Lkw9a_b
	s_waitcnt vmcnt(8)
	s_branch .Lkw9a_d

; #define PG8_STAGE(bufoff, gbase, voff) do { _Pragma("unroll") for (int _i = 0; _i < 2; ++_i) \
;         __builtin_amdgcn_global_load_lds((const unsigned*)((const char*)(gbase) + (voff)[_i]), (LAS unsigned*)(lds + (bufoff) + ldsw + _i * 8192), 16, 0, 0); } while (0)
; #define PG8_LDA(dst, b, h) do { _Pragma("unroll") for (int m = 0; m < 4; ++m) _Pragma("unroll") for (int k = 0; k < 2; ++k) dst[m][k] = *(const LAS bf16x8*)(lds + PG8_SA(b, h) + aoff + m * 2048 + k * 1024); } while (0)
; #define PG8_MMA(ai, bj, At, Bt) do { __builtin_amdgcn_s_setprio(1); _Pragma("unroll") for (int m = 0; m < 4; ++m) _Pragma("unroll") for (int n = 0; n < 2; ++n) _Pragma("unroll") for (int k = 0; k < 2; ++k) \
;         acc[ai][bj][m][n] = __builtin_amdgcn_mfma_f32_16x16x32_bf16(Bt[n][k], At[m][k], acc[ai][bj][m][n], 0, 0, 0); __builtin_amdgcn_s_setprio(0); } while (0)
; #define PG8_WAIT_V(n) asm volatile("s_waitcnt vmcnt(" #n ")" ::: "memory")
; #define PG8_WAIT_L(n) asm volatile("s_waitcnt lgkmcnt(" #n ")" ::: "memory")
; #define PG8_BAR __builtin_amdgcn_s_barrier()
; #define PG8_SCHED __builtin_amdgcn_sched_barrier(0)
; template <class Epi>
; __device__ __forceinline__ void gemm_phase(LAS unsigned char* lds, const Gemm g, const StaticOrder& S, const Epi& E, const int wid) {
;     ...
;             PG8_WAIT_V(8); PG8_WAIT_L(0); PG8_BAR; PG8_MMA(0, 0, At, B0); PG8_MMA(0, 1, At, B1); PG8_BAR; PG8_SCHED;
;             PG8_LDA(At, 0, 1); PG8_STAGE(PG8_SB(0, 0), b2, voffB); PG8_STAGE(PG8_SB(0, 1), b2 + hsB, voffB); PG8_STAGE(PG8_SA(0, 0), a2, voffA);
;             PG8_WAIT_V(8); PG8_WAIT_L(0); PG8_BAR; PG8_MMA(1, 0, At, B0); PG8_MMA(1, 1, At, B1); PG8_BAR; PG8_SCHED;
.Lkw9a_d:
	s_waitcnt lgkmcnt(0)
	s_barrier
	s_setprio 1
	s_waitcnt lgkmcnt(0)
	v_mfma_f32_16x16x32_bf16 v[124:127], v[148:151], v[180:183], v[124:127]
	v_mfma_f32_16x16x32_bf16 v[120:123], v[156:159], v[180:183], v[120:123]
	v_mfma_f32_16x16x32_bf16 v[108:111], v[148:151], v[188:191], v[108:111]
	v_mfma_f32_16x16x32_bf16 v[104:107], v[156:159], v[188:191], v[104:107]
	v_mfma_f32_16x16x32_bf16 v[92:95], v[148:151], v[196:199], v[92:95]
	v_mfma_f32_16x16x32_bf16 v[88:91], v[156:159], v[196:199], v[88:91]
	v_mfma_f32_16x16x32_bf16 v[76:79], v[148:151], v[204:207], v[76:79]
	v_mfma_f32_16x16x32_bf16 v[72:75], v[156:159], v[204:207], v[72:75]
	v_mfma_f32_16x16x32_bf16 v[124:127], v[152:155], v[184:187], v[124:127]
	v_mfma_f32_16x16x32_bf16 v[120:123], v[160:163], v[184:187], v[120:123]
	v_mfma_f32_16x16x32_bf16 v[108:111], v[152:155], v[192:195], v[108:111]
	v_mfma_f32_16x16x32_bf16 v[104:107], v[160:163], v[192:195], v[104:107]
	v_mfma_f32_16x16x32_bf16 v[92:95], v[152:155], v[200:203], v[92:95]
	v_mfma_f32_16x16x32_bf16 v[88:91], v[160:163], v[200:203], v[88:91]
	v_mfma_f32_16x16x32_bf16 v[76:79], v[152:155], v[208:211], v[76:79]
	v_mfma_f32_16x16x32_bf16 v[72:75], v[160:163], v[208:211], v[72:75]
	s_setprio 0
	s_setprio 1
	v_mfma_f32_16x16x32_bf16 v[116:119], v[164:167], v[180:183], v[116:119]
	v_mfma_f32_16x16x32_bf16 v[112:115], v[172:175], v[180:183], v[112:115]
	v_mfma_f32_16x16x32_bf16 v[100:103], v[164:167], v[188:191], v[100:103]
	v_mfma_f32_16x16x32_bf16 v[96:99], v[172:175], v[188:191], v[96:99]
	v_mfma_f32_16x16x32_bf16 v[84:87], v[164:167], v[196:199], v[84:87]
	v_mfma_f32_16x16x32_bf16 v[80:83], v[172:175], v[196:199], v[80:83]
	v_mfma_f32_16x16x32_bf16 v[68:71], v[164:167], v[204:207], v[68:71]
	v_mfma_f32_16x16x32_bf16 v[64:67], v[172:175], v[204:207], v[64:67]
	v_mfma_f32_16x16x32_bf16 v[116:119], v[168:171], v[184:187], v[116:119]
	v_mfma_f32_16x16x32_bf16 v[112:115], v[176:179], v[184:187], v[112:115]
	v_mfma_f32_16x16x32_bf16 v[100:103], v[168:171], v[192:195], v[100:103]
	v_mfma_f32_16x16x32_bf16 v[96:99], v[176:179], v[192:195], v[96:99]
	v_mfma_f32_16x16x32_bf16 v[84:87], v[168:171], v[200:203], v[84:87]
	v_mfma_f32_16x16x32_bf16 v[80:83], v[176:179], v[200:203], v[80:83]
	v_mfma_f32_16x16x32_bf16 v[68:71], v[168:171], v[208:211], v[68:71]
	v_mfma_f32_16x16x32_bf16 v[64:67], v[176:179], v[208:211], v[64:67]
	s_setprio 0
	s_barrier
	s_add_i32 s70, s73, s68
	v_lshl_add_u64 v[212:213], s[36:37], 0, v[130:131]
	s_mov_b32 m0, s70
	ds_read_b128 v[180:183], v147 offset:16384
	ds_read_b128 v[184:187], v147 offset:17408
	ds_read_b128 v[188:191], v147 offset:18432
	ds_read_b128 v[192:195], v147 offset:19456
	ds_read_b128 v[196:199], v147 offset:20480
	ds_read_b128 v[200:203], v147 offset:21504
	ds_read_b128 v[204:207], v147 offset:22528
	ds_read_b128 v[208:211], v147 offset:23552
	global_load_lds_dwordx4 v[212:213], off
	s_add_i32 m0, s70, 0x2000
	s_add_u32 s70, s36, 0x40000
	v_lshl_add_u64 v[214:215], s[36:37], 0, v[134:135]
	s_addc_u32 s71, s37, 0
	s_add_i32 s84, s74, s68
	global_load_lds_dwordx4 v[214:215], off
	v_lshl_add_u64 v[216:217], s[70:71], 0, v[130:131]
	s_mov_b32 m0, s84
	v_lshl_add_u64 v[218:219], s[38:39], 0, v[132:133]
	global_load_lds_dwordx4 v[216:217], off
	v_lshl_add_u64 v[216:217], s[70:71], 0, v[134:135]
	s_add_i32 m0, s84, 0x2000
	s_nop 0
	global_load_lds_dwordx4 v[216:217], off
	v_lshl_add_u64 v[216:217], s[38:39], 0, v[128:129]
	s_mov_b32 m0, s31
	s_nop 0
	global_load_lds_dwordx4 v[216:217], off
	s_mov_b32 m0, s59
	s_nop 0
	global_load_lds_dwordx4 v[218:219], off
	s_cmp_lg_u32 s32, 0
	s_cbranch_scc1 .Lkw9b_b
	s_waitcnt vmcnt(8)
	s_branch .Lkw9b_d

; #define PG8_STAGE(bufoff, gbase, voff) do { _Pragma("unroll") for (int _i = 0; _i < 2; ++_i) \
;         __builtin_amdgcn_global_load_lds((const unsigned*)((const char*)(gbase) + (voff)[_i]), (LAS unsigned*)(lds + (bufoff) + ldsw + _i * 8192), 16, 0, 0); } while (0)
; #define PG8_LDA(dst, b, h) do { _Pragma("unroll") for (int m = 0; m < 4; ++m) _Pragma("unroll") for (int k = 0; k < 2; ++k) dst[m][k] = *(const LAS bf16x8*)(lds + PG8_SA(b, h) + aoff + m * 2048 + k * 1024); } while (0)
; #define PG8_LDB(dst, b, h) do { _Pragma("unroll") for (int n = 0; n < 2; ++n) _Pragma("unroll") for (int k = 0; k < 2; ++k) dst[n][k] = *(const LAS bf16x8*)(lds + PG8_SB(b, h) + boff + n * 2048 + k * 1024); } while (0)
; #define PG8_MMA(ai, bj, At, Bt) do { __builtin_amdgcn_s_setprio(1); _Pragma("unroll") for (int m = 0; m < 4; ++m) _Pragma("unroll") for (int n = 0; n < 2; ++n) _Pragma("unroll") for (int k = 0; k < 2; ++k) \
;         acc[ai][bj][m][n] = __builtin_amdgcn_mfma_f32_16x16x32_bf16(Bt[n][k], At[m][k], acc[ai][bj][m][n], 0, 0, 0); __builtin_amdgcn_s_setprio(0); } while (0)
; #define PG8_WAIT_V(n) asm volatile("s_waitcnt vmcnt(" #n ")" ::: "memory")
; #define PG8_WAIT_L(n) asm volatile("s_waitcnt lgkmcnt(" #n ")" ::: "memory")
; #define PG8_BAR __builtin_amdgcn_s_barrier()
; #define PG8_SCHED __builtin_amdgcn_sched_barrier(0)
; template <class Epi>
; __device__ __forceinline__ void gemm_phase(LAS unsigned char* lds, const Gemm g, const StaticOrder& S, const Epi& E, const int wid) {
;     ...
;             PG8_WAIT_V(8); PG8_WAIT_L(0); PG8_BAR; PG8_MMA(1, 0, At, B0); PG8_MMA(1, 1, At, B1); PG8_BAR; PG8_SCHED;
;             PG8_LDB(B0, 1, 0); PG8_LDB(B1, 1, 1); PG8_SCHED; PG8_LDA(At, 1, 0); PG8_STAGE(PG8_SA(0, 1), a2 + hsA, voffA);
;             PG8_WAIT_V(8); PG8_WAIT_L(0); PG8_BAR; PG8_MMA(0, 0, At, B0); PG8_MMA(0, 1, At, B1); PG8_BAR; PG8_SCHED;
.Lkw9b_d:
	s_mov_b32 s32, 0
	s_waitcnt lgkmcnt(0)
	s_barrier
	s_setprio 1
	s_waitcnt lgkmcnt(0)
	v_mfma_f32_16x16x32_bf16 v[60:63], v[148:151], v[180:183], v[60:63]
	v_mfma_f32_16x16x32_bf16 v[56:59], v[156:159], v[180:183], v[56:59]
	v_mfma_f32_16x16x32_bf16 v[44:47], v[148:151], v[188:191], v[44:47]
	v_mfma_f32_16x16x32_bf16 v[40:43], v[156:159], v[188:191], v[40:43]
	v_mfma_f32_16x16x32_bf16 v[28:31], v[148:151], v[196:199], v[28:31]
	v_mfma_f32_16x16x32_bf16 v[24:27], v[156:159], v[196:199], v[24:27]
	v_mfma_f32_16x16x32_bf16 v[12:15], v[148:151], v[204:207], v[12:15]
	v_mfma_f32_16x16x32_bf16 v[8:11], v[156:159], v[204:207], v[8:11]
	v_mfma_f32_16x16x32_bf16 v[60:63], v[152:155], v[184:187], v[60:63]
	v_mfma_f32_16x16x32_bf16 v[56:59], v[160:163], v[184:187], v[56:59]
	v_mfma_f32_16x16x32_bf16 v[44:47], v[152:155], v[192:195], v[44:47]
	v_mfma_f32_16x16x32_bf16 v[40:43], v[160:163], v[192:195], v[40:43]
	v_mfma_f32_16x16x32_bf16 v[28:31], v[152:155], v[200:203], v[28:31]
	v_mfma_f32_16x16x32_bf16 v[24:27], v[160:163], v[200:203], v[24:27]
	v_mfma_f32_16x16x32_bf16 v[12:15], v[152:155], v[208:211], v[12:15]
	v_mfma_f32_16x16x32_bf16 v[8:11], v[160:163], v[208:211], v[8:11]
	s_setprio 0
	s_setprio 1
	v_mfma_f32_16x16x32_bf16 v[52:55], v[164:167], v[180:183], v[52:55]
	v_mfma_f32_16x16x32_bf16 v[48:51], v[172:175], v[180:183], v[48:51]
	v_mfma_f32_16x16x32_bf16 v[36:39], v[164:167], v[188:191], v[36:39]
	v_mfma_f32_16x16x32_bf16 v[32:35], v[172:175], v[188:191], v[32:35]
	v_mfma_f32_16x16x32_bf16 v[20:23], v[164:167], v[196:199], v[20:23]
	v_mfma_f32_16x16x32_bf16 v[16:19], v[172:175], v[196:199], v[16:19]
	v_mfma_f32_16x16x32_bf16 v[4:7], v[164:167], v[204:207], v[4:7]
	v_mfma_f32_16x16x32_bf16 v[0:3], v[172:175], v[204:207], v[0:3]
	v_mfma_f32_16x16x32_bf16 v[52:55], v[168:171], v[184:187], v[52:55]
	v_mfma_f32_16x16x32_bf16 v[48:51], v[176:179], v[184:187], v[48:51]
	v_mfma_f32_16x16x32_bf16 v[36:39], v[168:171], v[192:195], v[36:39]
	v_mfma_f32_16x16x32_bf16 v[32:35], v[176:179], v[192:195], v[32:35]
	v_mfma_f32_16x16x32_bf16 v[20:23], v[168:171], v[200:203], v[20:23]
	v_mfma_f32_16x16x32_bf16 v[16:19], v[176:179], v[200:203], v[16:19]
	v_mfma_f32_16x16x32_bf16 v[4:7], v[168:171], v[208:211], v[4:7]
	v_mfma_f32_16x16x32_bf16 v[0:3], v[176:179], v[208:211], v[0:3]
	s_setprio 0
	s_barrier
	s_add_i32 s70, 0, 0x18000
	s_add_i32 s71, 0, 0x1c000
	v_add_u32_e32 v160, s70, v144
	v_add_u32_e32 v176, s71, v144
	ds_read_b128 v[148:151], v160
	ds_read_b128 v[152:155], v160 offset:1024
	ds_read_b128 v[156:159], v160 offset:2048
	ds_read_b128 v[160:163], v160 offset:3072
	ds_read_b128 v[164:167], v176
	ds_read_b128 v[168:171], v176 offset:1024
	ds_read_b128 v[172:175], v176 offset:2048
	ds_read_b128 v[176:179], v176 offset:3072
	s_add_u32 s38, s38, 0x40000
	s_addc_u32 s39, s39, 0
	s_mov_b32 m0, s60
	v_lshl_add_u64 v[220:221], s[38:39], 0, v[128:129]
	ds_read_b128 v[180:183], v147 offset:32768
	ds_read_b128 v[184:187], v147 offset:33792
	ds_read_b128 v[188:191], v147 offset:34816
	ds_read_b128 v[192:195], v147 offset:35840
	ds_read_b128 v[196:199], v147 offset:36864
	ds_read_b128 v[200:203], v147 offset:37888
	ds_read_b128 v[204:207], v147 offset:38912
	ds_read_b128 v[208:211], v147 offset:39936
	global_load_lds_dwordx4 v[220:221], off
	v_lshl_add_u64 v[220:221], s[38:39], 0, v[132:133]
	s_mov_b32 m0, s61
	s_nop 0
	global_load_lds_dwordx4 v[220:221], off
	s_waitcnt vmcnt(8)
	s_waitcnt lgkmcnt(0)
	s_barrier
	s_setprio 1
	s_waitcnt lgkmcnt(0)
	v_mfma_f32_16x16x32_bf16 v[124:127], v[148:151], v[180:183], v[124:127]
	v_mfma_f32_16x16x32_bf16 v[120:123], v[156:159], v[180:183], v[120:123]
	v_mfma_f32_16x16x32_bf16 v[108:111], v[148:151], v[188:191], v[108:111]
	v_mfma_f32_16x16x32_bf16 v[104:107], v[156:159], v[188:191], v[104:107]
	v_mfma_f32_16x16x32_bf16 v[92:95], v[148:151], v[196:199], v[92:95]
	v_mfma_f32_16x16x32_bf16 v[88:91], v[156:159], v[196:199], v[88:91]
	v_mfma_f32_16x16x32_bf16 v[76:79], v[148:151], v[204:207], v[76:79]
	v_mfma_f32_16x16x32_bf16 v[72:75], v[156:159], v[204:207], v[72:75]
	v_mfma_f32_16x16x32_bf16 v[124:127], v[152:155], v[184:187], v[124:127]
	v_mfma_f32_16x16x32_bf16 v[120:123], v[160:163], v[184:187], v[120:123]
	v_mfma_f32_16x16x32_bf16 v[108:111], v[152:155], v[192:195], v[108:111]
	v_mfma_f32_16x16x32_bf16 v[104:107], v[160:163], v[192:195], v[104:107]
	v_mfma_f32_16x16x32_bf16 v[92:95], v[152:155], v[200:203], v[92:95]
	v_mfma_f32_16x16x32_bf16 v[88:91], v[160:163], v[200:203], v[88:91]
	v_mfma_f32_16x16x32_bf16 v[76:79], v[152:155], v[208:211], v[76:79]
	v_mfma_f32_16x16x32_bf16 v[72:75], v[160:163], v[208:211], v[72:75]
	s_setprio 0
	s_setprio 1
	v_mfma_f32_16x16x32_bf16 v[116:119], v[164:167], v[180:183], v[116:119]
	v_mfma_f32_16x16x32_bf16 v[112:115], v[172:175], v[180:183], v[112:115]
	v_mfma_f32_16x16x32_bf16 v[100:103], v[164:167], v[188:191], v[100:103]
	v_mfma_f32_16x16x32_bf16 v[96:99], v[172:175], v[188:191], v[96:99]
	v_mfma_f32_16x16x32_bf16 v[84:87], v[164:167], v[196:199], v[84:87]
	v_mfma_f32_16x16x32_bf16 v[80:83], v[172:175], v[196:199], v[80:83]
	v_mfma_f32_16x16x32_bf16 v[68:71], v[164:167], v[204:207], v[68:71]
	v_mfma_f32_16x16x32_bf16 v[64:67], v[172:175], v[204:207], v[64:67]
	v_mfma_f32_16x16x32_bf16 v[116:119], v[168:171], v[184:187], v[116:119]
	v_mfma_f32_16x16x32_bf16 v[112:115], v[176:179], v[184:187], v[112:115]
	v_mfma_f32_16x16x32_bf16 v[100:103], v[168:171], v[192:195], v[100:103]
	v_mfma_f32_16x16x32_bf16 v[96:99], v[176:179], v[192:195], v[96:99]
	v_mfma_f32_16x16x32_bf16 v[84:87], v[168:171], v[200:203], v[84:87]
	v_mfma_f32_16x16x32_bf16 v[80:83], v[176:179], v[200:203], v[80:83]
	v_mfma_f32_16x16x32_bf16 v[68:71], v[168:171], v[208:211], v[68:71]
	v_mfma_f32_16x16x32_bf16 v[64:67], v[176:179], v[208:211], v[64:67]
	s_setprio 0
	s_barrier
; #define PG8_STAGE(bufoff, gbase, voff) do { _Pragma("unroll") for (int _i = 0; _i < 2; ++_i) \
;         __builtin_amdgcn_global_load_lds((const unsigned*)((const char*)(gbase) + (voff)[_i]), (LAS unsigned*)(lds + (bufoff) + ldsw + _i * 8192), 16, 0, 0); } while (0)
; #define PG8_LDA(dst, b, h) do { _Pragma("unroll") for (int m = 0; m < 4; ++m) _Pragma("unroll") for (int k = 0; k < 2; ++k) dst[m][k] = *(const LAS bf16x8*)(lds + PG8_SA(b, h) + aoff + m * 2048 + k * 1024); } while (0)
; #define PG8_MMA(ai, bj, At, Bt) do { __builtin_amdgcn_s_setprio(1); _Pragma("unroll") for (int m = 0; m < 4; ++m) _Pragma("unroll") for (int n = 0; n < 2; ++n) _Pragma("unroll") for (int k = 0; k < 2; ++k) \
;         acc[ai][bj][m][n] = __builtin_amdgcn_mfma_f32_16x16x32_bf16(Bt[n][k], At[m][k], acc[ai][bj][m][n], 0, 0, 0); __builtin_amdgcn_s_setprio(0); } while (0)
; #define PG8_WAIT_V(n) asm volatile("s_waitcnt vmcnt(" #n ")" ::: "memory")
; #define PG8_WAIT_L(n) asm volatile("s_waitcnt lgkmcnt(" #n ")" ::: "memory")
; #define PG8_BAR __builtin_amdgcn_s_barrier()
; #define PG8_SCHED __builtin_amdgcn_sched_barrier(0)
; template <class Epi>
; __device__ __forceinline__ void gemm_phase(LAS unsigned char* lds, const Gemm g, const StaticOrder& S, const Epi& E, const int wid) {
;     ...
;             PG8_LDA(At, 1, 1); PG8_STAGE(PG8_SB(1, 0), b3, voffB); PG8_STAGE(PG8_SB(1, 1), b3 + hsB, voffB); PG8_STAGE(PG8_SA(1, 0), a3, voffA);
;             PG8_WAIT_V(8); PG8_WAIT_L(0); PG8_BAR; PG8_MMA(1, 0, At, B0); PG8_MMA(1, 1, At, B1); PG8_BAR; PG8_SCHED;
;         }
;         if (wr == 0) PG8_BAR;
;         E(acc, cur, wid);
;         if (!has_next) break;
	s_add_i32 s38, s70, s68
	v_lshl_add_u64 v[212:213], v[212:213], 0, s[6:7]
	s_mov_b32 m0, s38
	ds_read_b128 v[180:183], v147 offset:49152
	ds_read_b128 v[184:187], v147 offset:50176
	ds_read_b128 v[188:191], v147 offset:51200
	ds_read_b128 v[192:195], v147 offset:52224
	ds_read_b128 v[196:199], v147 offset:53248
	ds_read_b128 v[200:203], v147 offset:54272
	ds_read_b128 v[204:207], v147 offset:55296
	ds_read_b128 v[208:211], v147 offset:56320
	global_load_lds_dwordx4 v[212:213], off
	s_add_i32 m0, s38, 0x2000
	s_add_u32 s36, s36, 0x40080
	v_lshl_add_u64 v[212:213], v[214:215], 0, s[6:7]
	s_addc_u32 s37, s37, 0
	s_add_i32 s38, s71, s68
	global_load_lds_dwordx4 v[212:213], off
	v_lshl_add_u64 v[212:213], s[36:37], 0, v[130:131]
	s_mov_b32 m0, s38
	s_nop 0
	global_load_lds_dwordx4 v[212:213], off
	v_lshl_add_u64 v[212:213], s[36:37], 0, v[134:135]
	s_add_i32 m0, s38, 0x2000
	s_nop 0
	global_load_lds_dwordx4 v[212:213], off
	v_lshl_add_u64 v[212:213], v[216:217], 0, s[6:7]
	s_mov_b32 m0, s63
	s_nop 0
	global_load_lds_dwordx4 v[212:213], off
	v_lshl_add_u64 v[212:213], v[218:219], 0, s[6:7]
	s_mov_b32 m0, s64
	s_nop 0
	global_load_lds_dwordx4 v[212:213], off
	s_waitcnt vmcnt(8)
	s_waitcnt lgkmcnt(0)
	s_barrier
	s_setprio 1
	s_waitcnt lgkmcnt(0)
	v_mfma_f32_16x16x32_bf16 v[60:63], v[148:151], v[180:183], v[60:63]
	v_mfma_f32_16x16x32_bf16 v[56:59], v[156:159], v[180:183], v[56:59]
	v_mfma_f32_16x16x32_bf16 v[44:47], v[148:151], v[188:191], v[44:47]
	v_mfma_f32_16x16x32_bf16 v[40:43], v[156:159], v[188:191], v[40:43]
	v_mfma_f32_16x16x32_bf16 v[28:31], v[148:151], v[196:199], v[28:31]
	v_mfma_f32_16x16x32_bf16 v[24:27], v[156:159], v[196:199], v[24:27]
	v_mfma_f32_16x16x32_bf16 v[12:15], v[148:151], v[204:207], v[12:15]
	v_mfma_f32_16x16x32_bf16 v[8:11], v[156:159], v[204:207], v[8:11]
	v_mfma_f32_16x16x32_bf16 v[60:63], v[152:155], v[184:187], v[60:63]
	v_mfma_f32_16x16x32_bf16 v[56:59], v[160:163], v[184:187], v[56:59]
	v_mfma_f32_16x16x32_bf16 v[44:47], v[152:155], v[192:195], v[44:47]
	v_mfma_f32_16x16x32_bf16 v[40:43], v[160:163], v[192:195], v[40:43]
	v_mfma_f32_16x16x32_bf16 v[28:31], v[152:155], v[200:203], v[28:31]
	v_mfma_f32_16x16x32_bf16 v[24:27], v[160:163], v[200:203], v[24:27]
	v_mfma_f32_16x16x32_bf16 v[12:15], v[152:155], v[208:211], v[12:15]
	v_mfma_f32_16x16x32_bf16 v[8:11], v[160:163], v[208:211], v[8:11]
	s_setprio 0
	s_setprio 1
	v_mfma_f32_16x16x32_bf16 v[52:55], v[164:167], v[180:183], v[52:55]
	v_mfma_f32_16x16x32_bf16 v[48:51], v[172:175], v[180:183], v[48:51]
	v_mfma_f32_16x16x32_bf16 v[36:39], v[164:167], v[188:191], v[36:39]
	v_mfma_f32_16x16x32_bf16 v[32:35], v[172:175], v[188:191], v[32:35]
	v_mfma_f32_16x16x32_bf16 v[20:23], v[164:167], v[196:199], v[20:23]
	v_mfma_f32_16x16x32_bf16 v[16:19], v[172:175], v[196:199], v[16:19]
	v_mfma_f32_16x16x32_bf16 v[4:7], v[164:167], v[204:207], v[4:7]
	v_mfma_f32_16x16x32_bf16 v[0:3], v[172:175], v[204:207], v[0:3]
	v_mfma_f32_16x16x32_bf16 v[52:55], v[168:171], v[184:187], v[52:55]
	v_mfma_f32_16x16x32_bf16 v[48:51], v[176:179], v[184:187], v[48:51]
	v_mfma_f32_16x16x32_bf16 v[36:39], v[168:171], v[192:195], v[36:39]
	v_mfma_f32_16x16x32_bf16 v[32:35], v[176:179], v[192:195], v[32:35]
	v_mfma_f32_16x16x32_bf16 v[20:23], v[168:171], v[200:203], v[20:23]
	v_mfma_f32_16x16x32_bf16 v[16:19], v[176:179], v[200:203], v[16:19]
	v_mfma_f32_16x16x32_bf16 v[4:7], v[168:171], v[208:211], v[4:7]
	v_mfma_f32_16x16x32_bf16 v[0:3], v[176:179], v[208:211], v[0:3]
	s_setprio 0
	s_barrier
	s_add_i32 s87, s87, 2
	s_add_u32 s82, s82, 0x100
	s_addc_u32 s83, s83, 0
	s_add_u32 s34, s34, 0x100
	s_addc_u32 s35, s35, 0
	s_cmp_gt_u32 s87, 13
	s_cbranch_scc0 .LBB0_1175
	s_mov_b32 s32, 1
	s_and_b64 vcc, exec, s[8:9]
	s_cbranch_vccz .LBB0_1178
	s_barrier

; __device__ __forceinline__ int lane_id_asm() { int l; asm volatile("v_mbcnt_lo_u32_b32 %0, -1, 0\n\tv_mbcnt_hi_u32_b32 %0, -1, %0" : "=v"(l)); return l; }
; #define PG8_STAGE(bufoff, gbase, voff) do { _Pragma("unroll") for (int _i = 0; _i < 2; ++_i) \
;         __builtin_amdgcn_global_load_lds((const unsigned*)((const char*)(gbase) + (voff)[_i]), (LAS unsigned*)(lds + (bufoff) + ldsw + _i * 8192), 16, 0, 0); } while (0)
; #define PG8_WAIT_V(n) asm volatile("s_waitcnt vmcnt(" #n ")" ::: "memory")
; #define PG8_BAR __builtin_amdgcn_s_barrier()
; template <class Epi>
; __device__ __forceinline__ void gemm_phase(LAS unsigned char* lds, const Gemm g, const StaticOrder& S, const Epi& E, const int wid) {
;     const int lane = lane_id_asm(), tid = wid * 64 + lane, wr = wid >> 2, wc = wid & 3, fr = lane & 15, fq = lane >> 4;
;     const int K = g.K, nt = K / BK, lda = g.lda;
;     unsigned voffA[2], voffB[2];
; #pragma unroll
;     for (int i = 0; i < 2; ++i) { int R, C; stage_rc(tid * 16 + i * 8192, R, C); const int Rb = Epi::PERM ? ((R & ~31) + perm32(R & 31)) : R;
;         voffA[i] = (unsigned)(R * lda + C) * 2u; voffB[i] = (unsigned)(Rb * K + C) * 2u; }
;     const size_t kstep = (size_t)(BK * 2);
;     const size_t hsA = (size_t)HALF * lda * 2, hsB = (size_t)HALF * K * 2;
;     const size_t tsA = 2 * hsA, tsB = 2 * hsB;
;     const unsigned ldsw = (unsigned)wid * 1024u;
;     const int aoff = lds_byte(wr * 64 + fr, fq * 8), boff = lds_byte(wc * 32 + fr, fq * 8);
;     ...
;     PG8_WAIT_V(2); PG8_BAR;
;     PG8_STAGE(PG8_SB(1, 0), cB + kstep, voffB); PG8_STAGE(PG8_SA(1, 0), cA + kstep, voffA); PG8_STAGE(PG8_SB(1, 1), cB + hsB + kstep, voffB);
;     PG8_WAIT_V(6); PG8_BAR;
.LBB0_1235:
	s_mov_b64 s[8:9], 0x80
	s_add_i32 m0, s25, 0x18000
	v_lshl_add_u64 v[6:7], v[6:7], 0, s[8:9]
	global_load_lds_dwordx4 v[6:7], off
	v_lshl_add_u64 v[4:5], v[4:5], 0, s[8:9]
	s_add_i32 m0, s25, 0x1a000
	s_add_i32 s58, s25, 0x8000
	s_add_i32 s59, s25, 0xa000
	global_load_lds_dwordx4 v[4:5], off
	v_lshl_add_u64 v[0:1], v[0:1], 0, s[8:9]
	s_mov_b32 m0, s58
	s_add_u32 s4, s26, 0x100080
	global_load_lds_dwordx4 v[0:1], off
	v_lshl_add_u64 v[0:1], v[2:3], 0, s[8:9]
	s_mov_b32 m0, s59
	s_addc_u32 s5, s27, 0
	global_load_lds_dwordx4 v[0:1], off
	s_add_i32 m0, s25, 0x1c000
	v_lshl_add_u64 v[0:1], s[4:5], 0, v[194:195]
	global_load_lds_dwordx4 v[0:1], off
	v_lshl_add_u64 v[0:1], s[4:5], 0, v[198:199]
	s_add_i32 m0, s25, 0x1e000
	v_and_b32_e32 v2, 48, v8
	global_load_lds_dwordx4 v[0:1], off
	s_waitcnt vmcnt(8)
	s_barrier
	v_and_b32_e32 v0, 15, v8
	v_ashrrev_i32_e32 v1, 6, v8
	v_readlane_b32 s1, v254, 3
	v_lshl_or_b32 v0, v0, 6, v2
	v_lshlrev_b32_e32 v3, 2, v8
	v_lshl_add_u32 v2, v1, 10, s1
	v_readlane_b32 s1, v254, 5
	v_and_b32_e32 v3, 32, v3
	v_bitop3_b32 v2, v0, v2, v3 bitop3:0xde
	v_add_lshl_u32 v1, v1, s1, 10
	v_bitop3_b32 v240, v0, v1, v3 bitop3:0xde
	v_lshlrev_b32_e32 v0, 16, v12
	v_and_b32_e32 v0, 0xfffe0000, v0
	v_lshl_add_u32 v0, v13, 13, v0
	v_and_b32_e32 v1, 1, v12
	v_lshl_or_b32 v0, v1, 6, v0
	v_lshl_add_u32 v200, v14, 1, v0
	v_lshlrev_b32_e32 v0, 16, v9
	v_and_b32_e32 v0, 0xfffe0000, v0
	s_waitcnt vmcnt(6)
	s_mov_b32 s32, 0
	s_cmpk_lt_u32 s3, 0x100
	v_lshl_add_u32 v0, v10, 13, v0
	v_and_b32_e32 v1, 1, v9
	s_cselect_b64 s[10:11], -1, 0
	s_lshl_b32 s1, s33, 4
	v_lshl_or_b32 v0, v1, 6, v0
	s_add_i32 s64, 0, 0x10000
	s_add_i32 s65, 0, 0x14000
	s_and_b32 s60, s1, 0x3fffffc0
	s_ashr_i32 s61, s56, 31
	s_mov_b32 s62, s56
	s_ashr_i32 s63, s2, 31
	v_mov_b32_e32 v201, v195
	v_lshl_add_u32 v202, v11, 1, v0
	v_mov_b32_e32 v203, v195
	v_add_u32_e32 v241, s64, v240
	v_add_u32_e32 v242, s65, v240
	v_add_u32_e32 v243, 0, v2
	v_mov_b32_e32 v245, 0x358637bd
	v_mbcnt_hi_u32_b32 v244, -1, v244
	s_barrier
	s_branch .LBB0_1238

; #define PG8_STAGE(bufoff, gbase, voff) do { _Pragma("unroll") for (int _i = 0; _i < 2; ++_i) \
;         __builtin_amdgcn_global_load_lds((const unsigned*)((const char*)(gbase) + (voff)[_i]), (LAS unsigned*)(lds + (bufoff) + ldsw + _i * 8192), 16, 0, 0); } while (0)
; #define PG8_LDA(dst, b, h) do { _Pragma("unroll") for (int m = 0; m < 4; ++m) _Pragma("unroll") for (int k = 0; k < 2; ++k) dst[m][k] = *(const LAS bf16x8*)(lds + PG8_SA(b, h) + aoff + m * 2048 + k * 1024); } while (0)
; #define PG8_LDB(dst, b, h) do { _Pragma("unroll") for (int n = 0; n < 2; ++n) _Pragma("unroll") for (int k = 0; k < 2; ++k) dst[n][k] = *(const LAS bf16x8*)(lds + PG8_SB(b, h) + boff + n * 2048 + k * 1024); } while (0)
; #define PG8_SCHED __builtin_amdgcn_sched_barrier(0)
; template <class Epi>
; __device__ __forceinline__ void gemm_phase(LAS unsigned char* lds, const Gemm g, const StaticOrder& S, const Epi& E, const int wid) {
;     ...
;         for (int t = 0; t < nt; t += 2) {
;             const bool last = (t == nt - 2);
;             const char* a1 = cA + (size_t)(t + 1) * kstep;
;             const char* a2 = last ? nA : cA + (size_t)(t + 2) * kstep; const char* b2 = last ? nB : cB + (size_t)(t + 2) * kstep;
;             const char* a3 = a2 + kstep; const char* b3 = b2 + kstep;
;             PG8_LDB(B0, 0, 0); PG8_LDB(B1, 0, 1); PG8_SCHED; PG8_LDA(At, 0, 0); PG8_STAGE(PG8_SA(1, 1), a1 + hsA, voffA);
.LBB0_1245:
	ds_read_b128 v[124:127], v241
	ds_read_b128 v[132:135], v241 offset:1024
	ds_read_b128 v[136:139], v241 offset:2048
	ds_read_b128 v[140:143], v241 offset:3072
	ds_read_b128 v[144:147], v242
	ds_read_b128 v[148:151], v242 offset:1024
	ds_read_b128 v[152:155], v242 offset:2048
	ds_read_b128 v[156:159], v242 offset:3072
	s_add_u32 s28, s26, 0xfff00080
	s_addc_u32 s29, s27, -1
	s_cmp_eq_u32 s74, 60
	s_cselect_b32 s31, s1, s29
	s_cselect_b32 s30, s19, s28
	s_cselect_b32 s29, s17, s73
	s_cselect_b32 s28, s66, s67
	v_lshl_add_u64 v[204:205], s[26:27], 0, v[202:203]
	s_add_i32 m0, s25, 0xc000
	ds_read_b128 v[160:163], v243
	ds_read_b128 v[164:167], v243 offset:1024
	ds_read_b128 v[168:171], v243 offset:2048
	ds_read_b128 v[172:175], v243 offset:3072
	ds_read_b128 v[176:179], v243 offset:4096
	ds_read_b128 v[180:183], v243 offset:5120
	ds_read_b128 v[184:187], v243 offset:6144
	ds_read_b128 v[188:191], v243 offset:7168
	global_load_lds_dwordx4 v[204:205], off
	v_lshl_add_u64 v[204:205], s[26:27], 0, v[200:201]
	s_add_i32 m0, s25, 0xe000
	s_nop 0
	global_load_lds_dwordx4 v[204:205], off
	s_cmp_lg_u32 s32, 0
	s_cbranch_scc1 .Lkw10a_b
	s_waitcnt vmcnt(8)
	s_branch .Lkw10a_d

; #define PG8_STAGE(bufoff, gbase, voff) do { _Pragma("unroll") for (int _i = 0; _i < 2; ++_i) \
;         __builtin_amdgcn_global_load_lds((const unsigned*)((const char*)(gbase) + (voff)[_i]), (LAS unsigned*)(lds + (bufoff) + ldsw + _i * 8192), 16, 0, 0); } while (0)
; #define PG8_LDA(dst, b, h) do { _Pragma("unroll") for (int m = 0; m < 4; ++m) _Pragma("unroll") for (int k = 0; k < 2; ++k) dst[m][k] = *(const LAS bf16x8*)(lds + PG8_SA(b, h) + aoff + m * 2048 + k * 1024); } while (0)
; #define PG8_MMA(ai, bj, At, Bt) do { __builtin_amdgcn_s_setprio(1); _Pragma("unroll") for (int m = 0; m < 4; ++m) _Pragma("unroll") for (int n = 0; n < 2; ++n) _Pragma("unroll") for (int k = 0; k < 2; ++k) \
;         acc[ai][bj][m][n] = __builtin_amdgcn_mfma_f32_16x16x32_bf16(Bt[n][k], At[m][k], acc[ai][bj][m][n], 0, 0, 0); __builtin_amdgcn_s_setprio(0); } while (0)
; #define PG8_WAIT_V(n) asm volatile("s_waitcnt vmcnt(" #n ")" ::: "memory")
; #define PG8_WAIT_L(n) asm volatile("s_waitcnt lgkmcnt(" #n ")" ::: "memory")
; #define PG8_BAR __builtin_amdgcn_s_barrier()
; #define PG8_SCHED __builtin_amdgcn_sched_barrier(0)
; template <class Epi>
; __device__ __forceinline__ void gemm_phase(LAS unsigned char* lds, const Gemm g, const StaticOrder& S, const Epi& E, const int wid) {
;     ...
;             PG8_WAIT_V(8); PG8_WAIT_L(0); PG8_BAR; PG8_MMA(0, 0, At, B0); PG8_MMA(0, 1, At, B1); PG8_BAR; PG8_SCHED;
;             PG8_LDA(At, 0, 1); PG8_STAGE(PG8_SB(0, 0), b2, voffB); PG8_STAGE(PG8_SB(0, 1), b2 + hsB, voffB); PG8_STAGE(PG8_SA(0, 0), a2, voffA);
;             PG8_WAIT_V(8); PG8_WAIT_L(0); PG8_BAR; PG8_MMA(1, 0, At, B0); PG8_MMA(1, 1, At, B1); PG8_BAR; PG8_SCHED;
.Lkw10a_d:
	s_waitcnt lgkmcnt(0)
	s_barrier
	s_setprio 1
	s_waitcnt lgkmcnt(0)
	v_mfma_f32_16x16x32_bf16 v[128:131], v[124:127], v[160:163], v[128:131]
	v_mfma_f32_16x16x32_bf16 v[120:123], v[136:139], v[160:163], v[120:123]
	v_mfma_f32_16x16x32_bf16 v[108:111], v[124:127], v[168:171], v[108:111]
	v_mfma_f32_16x16x32_bf16 v[104:107], v[136:139], v[168:171], v[104:107]
	v_mfma_f32_16x16x32_bf16 v[92:95], v[124:127], v[176:179], v[92:95]
	v_mfma_f32_16x16x32_bf16 v[88:91], v[136:139], v[176:179], v[88:91]
	v_mfma_f32_16x16x32_bf16 v[76:79], v[124:127], v[184:187], v[76:79]
	v_mfma_f32_16x16x32_bf16 v[72:75], v[136:139], v[184:187], v[72:75]
	v_mfma_f32_16x16x32_bf16 v[128:131], v[132:135], v[164:167], v[128:131]
	v_mfma_f32_16x16x32_bf16 v[120:123], v[140:143], v[164:167], v[120:123]
	v_mfma_f32_16x16x32_bf16 v[108:111], v[132:135], v[172:175], v[108:111]
	v_mfma_f32_16x16x32_bf16 v[104:107], v[140:143], v[172:175], v[104:107]
	v_mfma_f32_16x16x32_bf16 v[92:95], v[132:135], v[180:183], v[92:95]
	v_mfma_f32_16x16x32_bf16 v[88:91], v[140:143], v[180:183], v[88:91]
	v_mfma_f32_16x16x32_bf16 v[76:79], v[132:135], v[188:191], v[76:79]
	v_mfma_f32_16x16x32_bf16 v[72:75], v[140:143], v[188:191], v[72:75]
	s_setprio 0
	s_setprio 1
	v_mfma_f32_16x16x32_bf16 v[116:119], v[144:147], v[160:163], v[116:119]
	v_mfma_f32_16x16x32_bf16 v[112:115], v[152:155], v[160:163], v[112:115]
	v_mfma_f32_16x16x32_bf16 v[100:103], v[144:147], v[168:171], v[100:103]
	v_mfma_f32_16x16x32_bf16 v[96:99], v[152:155], v[168:171], v[96:99]
	v_mfma_f32_16x16x32_bf16 v[84:87], v[144:147], v[176:179], v[84:87]
	v_mfma_f32_16x16x32_bf16 v[80:83], v[152:155], v[176:179], v[80:83]
	v_mfma_f32_16x16x32_bf16 v[68:71], v[144:147], v[184:187], v[68:71]
	v_mfma_f32_16x16x32_bf16 v[64:67], v[152:155], v[184:187], v[64:67]
	v_mfma_f32_16x16x32_bf16 v[116:119], v[148:151], v[164:167], v[116:119]
	v_mfma_f32_16x16x32_bf16 v[112:115], v[156:159], v[164:167], v[112:115]
	v_mfma_f32_16x16x32_bf16 v[100:103], v[148:151], v[172:175], v[100:103]
	v_mfma_f32_16x16x32_bf16 v[96:99], v[156:159], v[172:175], v[96:99]
	v_mfma_f32_16x16x32_bf16 v[84:87], v[148:151], v[180:183], v[84:87]
	v_mfma_f32_16x16x32_bf16 v[80:83], v[156:159], v[180:183], v[80:83]
	v_mfma_f32_16x16x32_bf16 v[68:71], v[148:151], v[188:191], v[68:71]
	v_mfma_f32_16x16x32_bf16 v[64:67], v[156:159], v[188:191], v[64:67]
	s_setprio 0
	s_barrier
	s_add_i32 s70, s64, s68
	v_lshl_add_u64 v[204:205], s[28:29], 0, v[194:195]
	s_mov_b32 m0, s70
	ds_read_b128 v[160:163], v243 offset:16384
	ds_read_b128 v[164:167], v243 offset:17408
	ds_read_b128 v[168:171], v243 offset:18432
	ds_read_b128 v[172:175], v243 offset:19456
	ds_read_b128 v[176:179], v243 offset:20480
	ds_read_b128 v[180:183], v243 offset:21504
	ds_read_b128 v[184:187], v243 offset:22528
	ds_read_b128 v[188:191], v243 offset:23552
	global_load_lds_dwordx4 v[204:205], off
	s_add_i32 m0, s70, 0x2000
	s_add_u32 s70, s28, 0x100000
	v_lshl_add_u64 v[206:207], s[28:29], 0, v[198:199]
	s_addc_u32 s71, s29, 0
	s_add_i32 s75, s65, s68
	global_load_lds_dwordx4 v[206:207], off
	v_lshl_add_u64 v[208:209], s[70:71], 0, v[194:195]
	s_mov_b32 m0, s75
	v_lshl_add_u64 v[210:211], s[30:31], 0, v[196:197]
	global_load_lds_dwordx4 v[208:209], off
	v_lshl_add_u64 v[208:209], s[70:71], 0, v[198:199]
	s_add_i32 m0, s75, 0x2000
	s_nop 0
	global_load_lds_dwordx4 v[208:209], off
	v_lshl_add_u64 v[208:209], s[30:31], 0, v[192:193]
	s_mov_b32 m0, s25
	s_nop 0
	global_load_lds_dwordx4 v[208:209], off
	s_mov_b32 m0, s38
	s_nop 0
	global_load_lds_dwordx4 v[210:211], off
	s_cmp_lg_u32 s32, 0
	s_cbranch_scc1 .Lkw10b_b
	s_waitcnt vmcnt(8)
	s_branch .Lkw10b_d

; #define PG8_STAGE(bufoff, gbase, voff) do { _Pragma("unroll") for (int _i = 0; _i < 2; ++_i) \
;         __builtin_amdgcn_global_load_lds((const unsigned*)((const char*)(gbase) + (voff)[_i]), (LAS unsigned*)(lds + (bufoff) + ldsw + _i * 8192), 16, 0, 0); } while (0)
; #define PG8_LDA(dst, b, h) do { _Pragma("unroll") for (int m = 0; m < 4; ++m) _Pragma("unroll") for (int k = 0; k < 2; ++k) dst[m][k] = *(const LAS bf16x8*)(lds + PG8_SA(b, h) + aoff + m * 2048 + k * 1024); } while (0)
; #define PG8_LDB(dst, b, h) do { _Pragma("unroll") for (int n = 0; n < 2; ++n) _Pragma("unroll") for (int k = 0; k < 2; ++k) dst[n][k] = *(const LAS bf16x8*)(lds + PG8_SB(b, h) + boff + n * 2048 + k * 1024); } while (0)
; #define PG8_MMA(ai, bj, At, Bt) do { __builtin_amdgcn_s_setprio(1); _Pragma("unroll") for (int m = 0; m < 4; ++m) _Pragma("unroll") for (int n = 0; n < 2; ++n) _Pragma("unroll") for (int k = 0; k < 2; ++k) \
;         acc[ai][bj][m][n] = __builtin_amdgcn_mfma_f32_16x16x32_bf16(Bt[n][k], At[m][k], acc[ai][bj][m][n], 0, 0, 0); __builtin_amdgcn_s_setprio(0); } while (0)
; #define PG8_WAIT_V(n) asm volatile("s_waitcnt vmcnt(" #n ")" ::: "memory")
; #define PG8_WAIT_L(n) asm volatile("s_waitcnt lgkmcnt(" #n ")" ::: "memory")
; #define PG8_BAR __builtin_amdgcn_s_barrier()
; #define PG8_SCHED __builtin_amdgcn_sched_barrier(0)
; template <class Epi>
; __device__ __forceinline__ void gemm_phase(LAS unsigned char* lds, const Gemm g, const StaticOrder& S, const Epi& E, const int wid) {
;     ...
;             PG8_WAIT_V(8); PG8_WAIT_L(0); PG8_BAR; PG8_MMA(1, 0, At, B0); PG8_MMA(1, 1, At, B1); PG8_BAR; PG8_SCHED;
;             PG8_LDB(B0, 1, 0); PG8_LDB(B1, 1, 1); PG8_SCHED; PG8_LDA(At, 1, 0); PG8_STAGE(PG8_SA(0, 1), a2 + hsA, voffA);
;             PG8_WAIT_V(8); PG8_WAIT_L(0); PG8_BAR; PG8_MMA(0, 0, At, B0); PG8_MMA(0, 1, At, B1); PG8_BAR; PG8_SCHED;
.Lkw10b_d:
	s_mov_b32 s32, 0
	s_waitcnt lgkmcnt(0)
	s_barrier
	s_setprio 1
	s_waitcnt lgkmcnt(0)
	v_mfma_f32_16x16x32_bf16 v[60:63], v[124:127], v[160:163], v[60:63]
	v_mfma_f32_16x16x32_bf16 v[56:59], v[136:139], v[160:163], v[56:59]
	v_mfma_f32_16x16x32_bf16 v[44:47], v[124:127], v[168:171], v[44:47]
	v_mfma_f32_16x16x32_bf16 v[40:43], v[136:139], v[168:171], v[40:43]
	v_mfma_f32_16x16x32_bf16 v[28:31], v[124:127], v[176:179], v[28:31]
	v_mfma_f32_16x16x32_bf16 v[24:27], v[136:139], v[176:179], v[24:27]
	v_mfma_f32_16x16x32_bf16 v[12:15], v[124:127], v[184:187], v[12:15]
	v_mfma_f32_16x16x32_bf16 v[8:11], v[136:139], v[184:187], v[8:11]
	v_mfma_f32_16x16x32_bf16 v[60:63], v[132:135], v[164:167], v[60:63]
	v_mfma_f32_16x16x32_bf16 v[56:59], v[140:143], v[164:167], v[56:59]
	v_mfma_f32_16x16x32_bf16 v[44:47], v[132:135], v[172:175], v[44:47]
	v_mfma_f32_16x16x32_bf16 v[40:43], v[140:143], v[172:175], v[40:43]
	v_mfma_f32_16x16x32_bf16 v[28:31], v[132:135], v[180:183], v[28:31]
	v_mfma_f32_16x16x32_bf16 v[24:27], v[140:143], v[180:183], v[24:27]
	v_mfma_f32_16x16x32_bf16 v[12:15], v[132:135], v[188:191], v[12:15]
	v_mfma_f32_16x16x32_bf16 v[8:11], v[140:143], v[188:191], v[8:11]
	s_setprio 0
	s_setprio 1
	v_mfma_f32_16x16x32_bf16 v[52:55], v[144:147], v[160:163], v[52:55]
	v_mfma_f32_16x16x32_bf16 v[48:51], v[152:155], v[160:163], v[48:51]
	v_mfma_f32_16x16x32_bf16 v[36:39], v[144:147], v[168:171], v[36:39]
	v_mfma_f32_16x16x32_bf16 v[32:35], v[152:155], v[168:171], v[32:35]
	v_mfma_f32_16x16x32_bf16 v[20:23], v[144:147], v[176:179], v[20:23]
	v_mfma_f32_16x16x32_bf16 v[16:19], v[152:155], v[176:179], v[16:19]
	v_mfma_f32_16x16x32_bf16 v[4:7], v[144:147], v[184:187], v[4:7]
	v_mfma_f32_16x16x32_bf16 v[0:3], v[152:155], v[184:187], v[0:3]
	v_mfma_f32_16x16x32_bf16 v[52:55], v[148:151], v[164:167], v[52:55]
	v_mfma_f32_16x16x32_bf16 v[48:51], v[156:159], v[164:167], v[48:51]
	v_mfma_f32_16x16x32_bf16 v[36:39], v[148:151], v[172:175], v[36:39]
	v_mfma_f32_16x16x32_bf16 v[32:35], v[156:159], v[172:175], v[32:35]
	v_mfma_f32_16x16x32_bf16 v[20:23], v[148:151], v[180:183], v[20:23]
	v_mfma_f32_16x16x32_bf16 v[16:19], v[156:159], v[180:183], v[16:19]
	v_mfma_f32_16x16x32_bf16 v[4:7], v[148:151], v[188:191], v[4:7]
	v_mfma_f32_16x16x32_bf16 v[0:3], v[156:159], v[188:191], v[0:3]
	s_setprio 0
	s_barrier
	s_add_i32 s70, 0, 0x18000
	s_add_i32 s71, 0, 0x1c000
	v_add_u32_e32 v140, s70, v240
	v_add_u32_e32 v156, s71, v240
	ds_read_b128 v[124:127], v140
	ds_read_b128 v[132:135], v140 offset:1024
	ds_read_b128 v[136:139], v140 offset:2048
	ds_read_b128 v[140:143], v140 offset:3072
	ds_read_b128 v[144:147], v156
	ds_read_b128 v[148:151], v156 offset:1024
	ds_read_b128 v[152:155], v156 offset:2048
	ds_read_b128 v[156:159], v156 offset:3072
	s_add_u32 s30, s30, 0x100000
	s_addc_u32 s31, s31, 0
	s_mov_b32 m0, s39
	v_lshl_add_u64 v[212:213], s[30:31], 0, v[192:193]
	ds_read_b128 v[160:163], v243 offset:32768
	ds_read_b128 v[164:167], v243 offset:33792
	ds_read_b128 v[168:171], v243 offset:34816
	ds_read_b128 v[172:175], v243 offset:35840
	ds_read_b128 v[176:179], v243 offset:36864
	ds_read_b128 v[180:183], v243 offset:37888
	ds_read_b128 v[184:187], v243 offset:38912
	ds_read_b128 v[188:191], v243 offset:39936
	global_load_lds_dwordx4 v[212:213], off
	v_lshl_add_u64 v[212:213], s[30:31], 0, v[196:197]
	s_mov_b32 m0, s50
	s_nop 0
	global_load_lds_dwordx4 v[212:213], off
	s_waitcnt vmcnt(8)
	s_waitcnt lgkmcnt(0)
	s_barrier
	s_setprio 1
	s_waitcnt lgkmcnt(0)
	v_mfma_f32_16x16x32_bf16 v[128:131], v[124:127], v[160:163], v[128:131]
	v_mfma_f32_16x16x32_bf16 v[120:123], v[136:139], v[160:163], v[120:123]
	v_mfma_f32_16x16x32_bf16 v[108:111], v[124:127], v[168:171], v[108:111]
	v_mfma_f32_16x16x32_bf16 v[104:107], v[136:139], v[168:171], v[104:107]
	v_mfma_f32_16x16x32_bf16 v[92:95], v[124:127], v[176:179], v[92:95]
	v_mfma_f32_16x16x32_bf16 v[88:91], v[136:139], v[176:179], v[88:91]
	v_mfma_f32_16x16x32_bf16 v[76:79], v[124:127], v[184:187], v[76:79]
	v_mfma_f32_16x16x32_bf16 v[72:75], v[136:139], v[184:187], v[72:75]
	v_mfma_f32_16x16x32_bf16 v[128:131], v[132:135], v[164:167], v[128:131]
	v_mfma_f32_16x16x32_bf16 v[120:123], v[140:143], v[164:167], v[120:123]
	v_mfma_f32_16x16x32_bf16 v[108:111], v[132:135], v[172:175], v[108:111]
	v_mfma_f32_16x16x32_bf16 v[104:107], v[140:143], v[172:175], v[104:107]
	v_mfma_f32_16x16x32_bf16 v[92:95], v[132:135], v[180:183], v[92:95]
	v_mfma_f32_16x16x32_bf16 v[88:91], v[140:143], v[180:183], v[88:91]
	v_mfma_f32_16x16x32_bf16 v[76:79], v[132:135], v[188:191], v[76:79]
	v_mfma_f32_16x16x32_bf16 v[72:75], v[140:143], v[188:191], v[72:75]
	s_setprio 0
	s_setprio 1
	v_mfma_f32_16x16x32_bf16 v[116:119], v[144:147], v[160:163], v[116:119]
	v_mfma_f32_16x16x32_bf16 v[112:115], v[152:155], v[160:163], v[112:115]
	v_mfma_f32_16x16x32_bf16 v[100:103], v[144:147], v[168:171], v[100:103]
	v_mfma_f32_16x16x32_bf16 v[96:99], v[152:155], v[168:171], v[96:99]
	v_mfma_f32_16x16x32_bf16 v[84:87], v[144:147], v[176:179], v[84:87]
	v_mfma_f32_16x16x32_bf16 v[80:83], v[152:155], v[176:179], v[80:83]
	v_mfma_f32_16x16x32_bf16 v[68:71], v[144:147], v[184:187], v[68:71]
	v_mfma_f32_16x16x32_bf16 v[64:67], v[152:155], v[184:187], v[64:67]
	v_mfma_f32_16x16x32_bf16 v[116:119], v[148:151], v[164:167], v[116:119]
	v_mfma_f32_16x16x32_bf16 v[112:115], v[156:159], v[164:167], v[112:115]
	v_mfma_f32_16x16x32_bf16 v[100:103], v[148:151], v[172:175], v[100:103]
	v_mfma_f32_16x16x32_bf16 v[96:99], v[156:159], v[172:175], v[96:99]
	v_mfma_f32_16x16x32_bf16 v[84:87], v[148:151], v[180:183], v[84:87]
	v_mfma_f32_16x16x32_bf16 v[80:83], v[156:159], v[180:183], v[80:83]
	v_mfma_f32_16x16x32_bf16 v[68:71], v[148:151], v[188:191], v[68:71]
	v_mfma_f32_16x16x32_bf16 v[64:67], v[156:159], v[188:191], v[64:67]
	s_setprio 0
	s_barrier
; #define PG8_STAGE(bufoff, gbase, voff) do { _Pragma("unroll") for (int _i = 0; _i < 2; ++_i) \
;         __builtin_amdgcn_global_load_lds((const unsigned*)((const char*)(gbase) + (voff)[_i]), (LAS unsigned*)(lds + (bufoff) + ldsw + _i * 8192), 16, 0, 0); } while (0)
; #define PG8_LDA(dst, b, h) do { _Pragma("unroll") for (int m = 0; m < 4; ++m) _Pragma("unroll") for (int k = 0; k < 2; ++k) dst[m][k] = *(const LAS bf16x8*)(lds + PG8_SA(b, h) + aoff + m * 2048 + k * 1024); } while (0)
; #define PG8_MMA(ai, bj, At, Bt) do { __builtin_amdgcn_s_setprio(1); _Pragma("unroll") for (int m = 0; m < 4; ++m) _Pragma("unroll") for (int n = 0; n < 2; ++n) _Pragma("unroll") for (int k = 0; k < 2; ++k) \
;         acc[ai][bj][m][n] = __builtin_amdgcn_mfma_f32_16x16x32_bf16(Bt[n][k], At[m][k], acc[ai][bj][m][n], 0, 0, 0); __builtin_amdgcn_s_setprio(0); } while (0)
; #define PG8_WAIT_V(n) asm volatile("s_waitcnt vmcnt(" #n ")" ::: "memory")
; #define PG8_WAIT_L(n) asm volatile("s_waitcnt lgkmcnt(" #n ")" ::: "memory")
; #define PG8_BAR __builtin_amdgcn_s_barrier()
; #define PG8_SCHED __builtin_amdgcn_sched_barrier(0)
; template <class Epi>
; __device__ __forceinline__ void gemm_phase(LAS unsigned char* lds, const Gemm g, const StaticOrder& S, const Epi& E, const int wid) {
;     ...
;             PG8_LDA(At, 1, 1); PG8_STAGE(PG8_SB(1, 0), b3, voffB); PG8_STAGE(PG8_SB(1, 1), b3 + hsB, voffB); PG8_STAGE(PG8_SA(1, 0), a3, voffA);
;             PG8_WAIT_V(8); PG8_WAIT_L(0); PG8_BAR; PG8_MMA(1, 0, At, B0); PG8_MMA(1, 1, At, B1); PG8_BAR; PG8_SCHED;
;         }
;         if (wr == 0) PG8_BAR;
;         E(acc, cur, wid);
;         if (!has_next) break;
	s_add_i32 s30, s70, s68
	v_lshl_add_u64 v[204:205], v[204:205], 0, s[8:9]
	s_mov_b32 m0, s30
	ds_read_b128 v[160:163], v243 offset:49152
	ds_read_b128 v[164:167], v243 offset:50176
	ds_read_b128 v[168:171], v243 offset:51200
	ds_read_b128 v[172:175], v243 offset:52224
	ds_read_b128 v[176:179], v243 offset:53248
	ds_read_b128 v[180:183], v243 offset:54272
	ds_read_b128 v[184:187], v243 offset:55296
	ds_read_b128 v[188:191], v243 offset:56320
	global_load_lds_dwordx4 v[204:205], off
	s_add_i32 m0, s30, 0x2000
	s_add_u32 s28, s28, 0x100080
	v_lshl_add_u64 v[204:205], v[206:207], 0, s[8:9]
	s_addc_u32 s29, s29, 0
	s_add_i32 s30, s71, s68
	global_load_lds_dwordx4 v[204:205], off
	v_lshl_add_u64 v[204:205], s[28:29], 0, v[194:195]
	s_mov_b32 m0, s30
	s_nop 0
	global_load_lds_dwordx4 v[204:205], off
	v_lshl_add_u64 v[204:205], s[28:29], 0, v[198:199]
	s_add_i32 m0, s30, 0x2000
	s_nop 0
	global_load_lds_dwordx4 v[204:205], off
	v_lshl_add_u64 v[204:205], v[208:209], 0, s[8:9]
	s_mov_b32 m0, s58
	s_nop 0
	global_load_lds_dwordx4 v[204:205], off
	v_lshl_add_u64 v[204:205], v[210:211], 0, s[8:9]
	s_mov_b32 m0, s59
	s_nop 0
	global_load_lds_dwordx4 v[204:205], off
	s_waitcnt vmcnt(8)
	s_waitcnt lgkmcnt(0)
	s_barrier
	s_setprio 1
	s_waitcnt lgkmcnt(0)
	v_mfma_f32_16x16x32_bf16 v[60:63], v[124:127], v[160:163], v[60:63]
	v_mfma_f32_16x16x32_bf16 v[56:59], v[136:139], v[160:163], v[56:59]
	v_mfma_f32_16x16x32_bf16 v[44:47], v[124:127], v[168:171], v[44:47]
	v_mfma_f32_16x16x32_bf16 v[40:43], v[136:139], v[168:171], v[40:43]
	v_mfma_f32_16x16x32_bf16 v[28:31], v[124:127], v[176:179], v[28:31]
	v_mfma_f32_16x16x32_bf16 v[24:27], v[136:139], v[176:179], v[24:27]
	v_mfma_f32_16x16x32_bf16 v[12:15], v[124:127], v[184:187], v[12:15]
	v_mfma_f32_16x16x32_bf16 v[8:11], v[136:139], v[184:187], v[8:11]
	v_mfma_f32_16x16x32_bf16 v[60:63], v[132:135], v[164:167], v[60:63]
	v_mfma_f32_16x16x32_bf16 v[56:59], v[140:143], v[164:167], v[56:59]
	v_mfma_f32_16x16x32_bf16 v[44:47], v[132:135], v[172:175], v[44:47]
	v_mfma_f32_16x16x32_bf16 v[40:43], v[140:143], v[172:175], v[40:43]
	v_mfma_f32_16x16x32_bf16 v[28:31], v[132:135], v[180:183], v[28:31]
	v_mfma_f32_16x16x32_bf16 v[24:27], v[140:143], v[180:183], v[24:27]
	v_mfma_f32_16x16x32_bf16 v[12:15], v[132:135], v[188:191], v[12:15]
	v_mfma_f32_16x16x32_bf16 v[8:11], v[140:143], v[188:191], v[8:11]
	s_setprio 0
	s_setprio 1
	v_mfma_f32_16x16x32_bf16 v[52:55], v[144:147], v[160:163], v[52:55]
	v_mfma_f32_16x16x32_bf16 v[48:51], v[152:155], v[160:163], v[48:51]
	v_mfma_f32_16x16x32_bf16 v[36:39], v[144:147], v[168:171], v[36:39]
	v_mfma_f32_16x16x32_bf16 v[32:35], v[152:155], v[168:171], v[32:35]
	v_mfma_f32_16x16x32_bf16 v[20:23], v[144:147], v[176:179], v[20:23]
	v_mfma_f32_16x16x32_bf16 v[16:19], v[152:155], v[176:179], v[16:19]
	v_mfma_f32_16x16x32_bf16 v[4:7], v[144:147], v[184:187], v[4:7]
	v_mfma_f32_16x16x32_bf16 v[0:3], v[152:155], v[184:187], v[0:3]
	v_mfma_f32_16x16x32_bf16 v[52:55], v[148:151], v[164:167], v[52:55]
	v_mfma_f32_16x16x32_bf16 v[48:51], v[156:159], v[164:167], v[48:51]
	v_mfma_f32_16x16x32_bf16 v[36:39], v[148:151], v[172:175], v[36:39]
	v_mfma_f32_16x16x32_bf16 v[32:35], v[156:159], v[172:175], v[32:35]
	v_mfma_f32_16x16x32_bf16 v[20:23], v[148:151], v[180:183], v[20:23]
	v_mfma_f32_16x16x32_bf16 v[16:19], v[156:159], v[180:183], v[16:19]
	v_mfma_f32_16x16x32_bf16 v[4:7], v[148:151], v[188:191], v[4:7]
	v_mfma_f32_16x16x32_bf16 v[0:3], v[156:159], v[188:191], v[0:3]
	s_setprio 0
	s_barrier
	s_add_i32 s74, s74, 2
	s_add_u32 s67, s67, 0x100
	s_addc_u32 s73, s73, 0
	s_add_u32 s26, s26, 0x100
	s_addc_u32 s27, s27, 0
	s_cmp_gt_u32 s74, 61
	s_cbranch_scc0 .LBB0_1245
	s_mov_b32 s32, 1
	s_and_b64 vcc, exec, s[10:11]
	s_cbranch_vccz .LBB0_1248
	s_barrier

; __device__ __forceinline__ int lane_id_asm() { int l; asm volatile("v_mbcnt_lo_u32_b32 %0, -1, 0\n\tv_mbcnt_hi_u32_b32 %0, -1, %0" : "=v"(l)); return l; }
; #define PG8_STAGE(bufoff, gbase, voff) do { _Pragma("unroll") for (int _i = 0; _i < 2; ++_i) \
;         __builtin_amdgcn_global_load_lds((const unsigned*)((const char*)(gbase) + (voff)[_i]), (LAS unsigned*)(lds + (bufoff) + ldsw + _i * 8192), 16, 0, 0); } while (0)
; #define PG8_WAIT_V(n) asm volatile("s_waitcnt vmcnt(" #n ")" ::: "memory")
; #define PG8_BAR __builtin_amdgcn_s_barrier()
; template <class Epi>
; __device__ __forceinline__ void gemm_phase(LAS unsigned char* lds, const Gemm g, const StaticOrder& S, const Epi& E, const int wid) {
;     const int lane = lane_id_asm(), tid = wid * 64 + lane, wr = wid >> 2, wc = wid & 3, fr = lane & 15, fq = lane >> 4;
;     const int K = g.K, nt = K / BK, lda = g.lda;
;     unsigned voffA[2], voffB[2];
; #pragma unroll
;     for (int i = 0; i < 2; ++i) { int R, C; stage_rc(tid * 16 + i * 8192, R, C); const int Rb = Epi::PERM ? ((R & ~31) + perm32(R & 31)) : R;
;         voffA[i] = (unsigned)(R * lda + C) * 2u; voffB[i] = (unsigned)(Rb * K + C) * 2u; }
;     const size_t kstep = (size_t)(BK * 2);
;     const size_t hsA = (size_t)HALF * lda * 2, hsB = (size_t)HALF * K * 2;
;     const size_t tsA = 2 * hsA, tsB = 2 * hsB;
;     const unsigned ldsw = (unsigned)wid * 1024u;
;     const int aoff = lds_byte(wr * 64 + fr, fq * 8), boff = lds_byte(wc * 32 + fr, fq * 8);
;     ...
;     PG8_WAIT_V(2); PG8_BAR;
;     PG8_STAGE(PG8_SB(1, 0), cB + kstep, voffB); PG8_STAGE(PG8_SA(1, 0), cA + kstep, voffA); PG8_STAGE(PG8_SB(1, 1), cB + hsB + kstep, voffB);
;     PG8_WAIT_V(6); PG8_BAR;
.LBB0_1343:
	s_mov_b64 s[6:7], 0x80
	s_add_i32 m0, s29, 0x18000
	v_lshl_add_u64 v[6:7], v[6:7], 0, s[6:7]
	global_load_lds_dwordx4 v[6:7], off
	v_lshl_add_u64 v[4:5], v[4:5], 0, s[6:7]
	s_add_i32 m0, s29, 0x1a000
	s_add_i32 s55, s29, 0x8000
	s_add_i32 s57, s29, 0xa000
	global_load_lds_dwordx4 v[4:5], off
	v_lshl_add_u64 v[0:1], v[0:1], 0, s[6:7]
	s_mov_b32 m0, s55
	s_add_u32 s8, s30, 0x40080
	global_load_lds_dwordx4 v[0:1], off
	v_lshl_add_u64 v[0:1], v[2:3], 0, s[6:7]
	s_mov_b32 m0, s57
	s_addc_u32 s9, s31, 0
	global_load_lds_dwordx4 v[0:1], off
	s_add_i32 m0, s29, 0x1c000
	v_lshl_add_u64 v[0:1], s[8:9], 0, v[146:147]
	global_load_lds_dwordx4 v[0:1], off
	v_lshl_add_u64 v[0:1], s[8:9], 0, v[150:151]
	s_add_i32 m0, s29, 0x1e000
	s_sext_i32_i8 s60, s0
	global_load_lds_dwordx4 v[0:1], off
	s_waitcnt vmcnt(8)
	s_barrier
	v_and_b32_e32 v0, 15, v8
	v_ashrrev_i32_e32 v1, 6, v8
	v_and_b32_e32 v2, 48, v8
	v_readlane_b32 s0, v254, 3
	v_lshl_or_b32 v0, v0, 6, v2
	v_lshlrev_b32_e32 v3, 2, v8
	v_lshl_add_u32 v2, v1, 10, s0
	v_readlane_b32 s0, v254, 5
	v_and_b32_e32 v3, 32, v3
	v_bitop3_b32 v2, v0, v2, v3 bitop3:0xde
	v_add_lshl_u32 v1, v1, s0, 10
	v_bitop3_b32 v168, v0, v1, v3 bitop3:0xde
	v_lshlrev_b32_e32 v0, 14, v12
	v_and_b32_e32 v0, 0xffff8000, v0
	v_lshl_add_u32 v0, v13, 11, v0
	v_and_b32_e32 v1, 1, v12
	v_lshl_or_b32 v0, v1, 6, v0
	v_lshl_add_u32 v152, v14, 1, v0
	v_lshlrev_b32_e32 v0, 14, v9
	v_and_b32_e32 v0, 0xffff8000, v0
	s_waitcnt vmcnt(6)
	s_mov_b32 s32, 0
	s_cmpk_lt_u32 s3, 0x100
	v_lshl_add_u32 v0, v10, 11, v0
	v_and_b32_e32 v1, 1, v9
	s_cselect_b64 s[8:9], -1, 0
	s_lshl_b32 s0, s33, 4
	v_lshl_or_b32 v0, v1, 6, v0
	s_add_i32 s58, 0, 0x10000
	s_add_i32 s59, 0, 0x14000
	s_and_b32 s3, s0, 0x3fffffc0
	s_ashr_i32 s33, s56, 31
	v_mov_b32_e32 v153, v147
	v_lshl_add_u32 v154, v11, 1, v0
	v_mov_b32_e32 v155, v147
	v_mov_b64_e32 v[156:157], 0x200
	v_mov_b64_e32 v[158:159], 0x1ff
	s_mov_b64 s[10:11], 0x100
	v_add_u32_e32 v169, s58, v168
	v_add_u32_e32 v170, s59, v168
	v_add_u32_e32 v171, 0, v2
	v_mov_b32_e32 v172, 0x358637bd
	s_mov_b64 s[12:13], 0x24000
	s_mov_b64 s[14:15], 0x20000
	s_mov_b64 s[16:17], 0x2c000
	s_mov_b64 s[18:19], 0x28000
	s_barrier
	s_branch .LBB0_1346

; #define PG8_STAGE(bufoff, gbase, voff) do { _Pragma("unroll") for (int _i = 0; _i < 2; ++_i) \
;         __builtin_amdgcn_global_load_lds((const unsigned*)((const char*)(gbase) + (voff)[_i]), (LAS unsigned*)(lds + (bufoff) + ldsw + _i * 8192), 16, 0, 0); } while (0)
; #define PG8_LDA(dst, b, h) do { _Pragma("unroll") for (int m = 0; m < 4; ++m) _Pragma("unroll") for (int k = 0; k < 2; ++k) dst[m][k] = *(const LAS bf16x8*)(lds + PG8_SA(b, h) + aoff + m * 2048 + k * 1024); } while (0)
; #define PG8_LDB(dst, b, h) do { _Pragma("unroll") for (int n = 0; n < 2; ++n) _Pragma("unroll") for (int k = 0; k < 2; ++k) dst[n][k] = *(const LAS bf16x8*)(lds + PG8_SB(b, h) + boff + n * 2048 + k * 1024); } while (0)
; #define PG8_SCHED __builtin_amdgcn_sched_barrier(0)
; template <class Epi>
; __device__ __forceinline__ void gemm_phase(LAS unsigned char* lds, const Gemm g, const StaticOrder& S, const Epi& E, const int wid) {
;     ...
;         for (int t = 0; t < nt; t += 2) {
;             const bool last = (t == nt - 2);
;             const char* a1 = cA + (size_t)(t + 1) * kstep;
;             const char* a2 = last ? nA : cA + (size_t)(t + 2) * kstep; const char* b2 = last ? nB : cB + (size_t)(t + 2) * kstep;
;             const char* a3 = a2 + kstep; const char* b3 = b2 + kstep;
;             PG8_LDB(B0, 0, 0); PG8_LDB(B1, 0, 1); PG8_SCHED; PG8_LDA(At, 0, 0); PG8_STAGE(PG8_SA(1, 1), a1 + hsA, voffA);
.LBB0_1353:
	ds_read_b128 v[128:131], v169
	ds_read_b128 v[132:135], v169 offset:1024
	ds_read_b128 v[136:139], v169 offset:2048
	ds_read_b128 v[140:143], v169 offset:3072
	ds_read_b128 v[160:163], v170
	ds_read_b128 v[164:167], v170 offset:1024
	ds_read_b128 v[174:177], v170 offset:2048
	ds_read_b128 v[178:181], v170 offset:3072
	s_add_u32 s34, s30, 0xfffc0080
	s_addc_u32 s35, s31, -1
	s_cmp_eq_u32 s65, 12
	s_cselect_b32 s39, s23, s35
	s_cselect_b32 s38, s61, s34
	s_cselect_b32 s35, s21, s64
	s_cselect_b32 s34, s62, s63
	v_lshl_add_u64 v[214:215], s[30:31], 0, v[154:155]
	s_add_i32 m0, s29, 0xc000
	ds_read_b128 v[182:185], v171
	ds_read_b128 v[186:189], v171 offset:1024
	ds_read_b128 v[190:193], v171 offset:2048
	ds_read_b128 v[194:197], v171 offset:3072
	ds_read_b128 v[198:201], v171 offset:4096
	ds_read_b128 v[202:205], v171 offset:5120
	ds_read_b128 v[206:209], v171 offset:6144
	ds_read_b128 v[210:213], v171 offset:7168
	global_load_lds_dwordx4 v[214:215], off
	v_lshl_add_u64 v[214:215], s[30:31], 0, v[152:153]
	s_add_i32 m0, s29, 0xe000
	s_nop 0
	global_load_lds_dwordx4 v[214:215], off
	s_cmp_lg_u32 s32, 0
	s_cbranch_scc1 .Lkw11a_b
	s_waitcnt vmcnt(8)
	s_branch .Lkw11a_d

; #define PG8_STAGE(bufoff, gbase, voff) do { _Pragma("unroll") for (int _i = 0; _i < 2; ++_i) \
;         __builtin_amdgcn_global_load_lds((const unsigned*)((const char*)(gbase) + (voff)[_i]), (LAS unsigned*)(lds + (bufoff) + ldsw + _i * 8192), 16, 0, 0); } while (0)
; #define PG8_LDA(dst, b, h) do { _Pragma("unroll") for (int m = 0; m < 4; ++m) _Pragma("unroll") for (int k = 0; k < 2; ++k) dst[m][k] = *(const LAS bf16x8*)(lds + PG8_SA(b, h) + aoff + m * 2048 + k * 1024); } while (0)
; #define PG8_MMA(ai, bj, At, Bt) do { __builtin_amdgcn_s_setprio(1); _Pragma("unroll") for (int m = 0; m < 4; ++m) _Pragma("unroll") for (int n = 0; n < 2; ++n) _Pragma("unroll") for (int k = 0; k < 2; ++k) \
;         acc[ai][bj][m][n] = __builtin_amdgcn_mfma_f32_16x16x32_bf16(Bt[n][k], At[m][k], acc[ai][bj][m][n], 0, 0, 0); __builtin_amdgcn_s_setprio(0); } while (0)
; #define PG8_WAIT_V(n) asm volatile("s_waitcnt vmcnt(" #n ")" ::: "memory")
; #define PG8_WAIT_L(n) asm volatile("s_waitcnt lgkmcnt(" #n ")" ::: "memory")
; #define PG8_BAR __builtin_amdgcn_s_barrier()
; #define PG8_SCHED __builtin_amdgcn_sched_barrier(0)
; template <class Epi>
; __device__ __forceinline__ void gemm_phase(LAS unsigned char* lds, const Gemm g, const StaticOrder& S, const Epi& E, const int wid) {
;     ...
;             PG8_WAIT_V(8); PG8_WAIT_L(0); PG8_BAR; PG8_MMA(0, 0, At, B0); PG8_MMA(0, 1, At, B1); PG8_BAR; PG8_SCHED;
;             PG8_LDA(At, 0, 1); PG8_STAGE(PG8_SB(0, 0), b2, voffB); PG8_STAGE(PG8_SB(0, 1), b2 + hsB, voffB); PG8_STAGE(PG8_SA(0, 0), a2, voffA);
;             PG8_WAIT_V(8); PG8_WAIT_L(0); PG8_BAR; PG8_MMA(1, 0, At, B0); PG8_MMA(1, 1, At, B1); PG8_BAR; PG8_SCHED;
.Lkw11a_d:
	s_waitcnt lgkmcnt(0)
	s_barrier
	s_setprio 1
	s_waitcnt lgkmcnt(0)
	v_mfma_f32_16x16x32_bf16 v[124:127], v[128:131], v[182:185], v[124:127]
	v_mfma_f32_16x16x32_bf16 v[120:123], v[136:139], v[182:185], v[120:123]
	v_mfma_f32_16x16x32_bf16 v[104:107], v[128:131], v[190:193], v[104:107]
	v_mfma_f32_16x16x32_bf16 v[108:111], v[136:139], v[190:193], v[108:111]
	v_mfma_f32_16x16x32_bf16 v[88:91], v[128:131], v[198:201], v[88:91]
	v_mfma_f32_16x16x32_bf16 v[92:95], v[136:139], v[198:201], v[92:95]
	v_mfma_f32_16x16x32_bf16 v[72:75], v[128:131], v[206:209], v[72:75]
	v_mfma_f32_16x16x32_bf16 v[76:79], v[136:139], v[206:209], v[76:79]
	v_mfma_f32_16x16x32_bf16 v[124:127], v[132:135], v[186:189], v[124:127]
	v_mfma_f32_16x16x32_bf16 v[120:123], v[140:143], v[186:189], v[120:123]
	v_mfma_f32_16x16x32_bf16 v[104:107], v[132:135], v[194:197], v[104:107]
	v_mfma_f32_16x16x32_bf16 v[108:111], v[140:143], v[194:197], v[108:111]
	v_mfma_f32_16x16x32_bf16 v[88:91], v[132:135], v[202:205], v[88:91]
	v_mfma_f32_16x16x32_bf16 v[92:95], v[140:143], v[202:205], v[92:95]
	v_mfma_f32_16x16x32_bf16 v[72:75], v[132:135], v[210:213], v[72:75]
	v_mfma_f32_16x16x32_bf16 v[76:79], v[140:143], v[210:213], v[76:79]
	s_setprio 0
	s_setprio 1
	v_mfma_f32_16x16x32_bf16 v[112:115], v[160:163], v[182:185], v[112:115]
	v_mfma_f32_16x16x32_bf16 v[116:119], v[174:177], v[182:185], v[116:119]
	v_mfma_f32_16x16x32_bf16 v[96:99], v[160:163], v[190:193], v[96:99]
	v_mfma_f32_16x16x32_bf16 v[100:103], v[174:177], v[190:193], v[100:103]
	v_mfma_f32_16x16x32_bf16 v[80:83], v[160:163], v[198:201], v[80:83]
	v_mfma_f32_16x16x32_bf16 v[84:87], v[174:177], v[198:201], v[84:87]
	v_mfma_f32_16x16x32_bf16 v[64:67], v[160:163], v[206:209], v[64:67]
	v_mfma_f32_16x16x32_bf16 v[68:71], v[174:177], v[206:209], v[68:71]
	v_mfma_f32_16x16x32_bf16 v[112:115], v[164:167], v[186:189], v[112:115]
	v_mfma_f32_16x16x32_bf16 v[116:119], v[178:181], v[186:189], v[116:119]
	v_mfma_f32_16x16x32_bf16 v[96:99], v[164:167], v[194:197], v[96:99]
	v_mfma_f32_16x16x32_bf16 v[100:103], v[178:181], v[194:197], v[100:103]
	v_mfma_f32_16x16x32_bf16 v[80:83], v[164:167], v[202:205], v[80:83]
	v_mfma_f32_16x16x32_bf16 v[84:87], v[178:181], v[202:205], v[84:87]
	v_mfma_f32_16x16x32_bf16 v[64:67], v[164:167], v[210:213], v[64:67]
	v_mfma_f32_16x16x32_bf16 v[68:71], v[178:181], v[210:213], v[68:71]
	s_setprio 0
	s_barrier
	s_add_i32 s66, s58, s68
	v_lshl_add_u64 v[214:215], s[34:35], 0, v[146:147]
	s_mov_b32 m0, s66
	ds_read_b128 v[182:185], v171 offset:16384
	ds_read_b128 v[186:189], v171 offset:17408
	ds_read_b128 v[190:193], v171 offset:18432
	ds_read_b128 v[194:197], v171 offset:19456
	ds_read_b128 v[198:201], v171 offset:20480
	ds_read_b128 v[202:205], v171 offset:21504
	ds_read_b128 v[206:209], v171 offset:22528
	ds_read_b128 v[210:213], v171 offset:23552
	global_load_lds_dwordx4 v[214:215], off
	s_add_i32 m0, s66, 0x2000
	s_add_u32 s66, s34, 0x40000
	v_lshl_add_u64 v[216:217], s[34:35], 0, v[150:151]
	s_addc_u32 s67, s35, 0
	s_add_i32 s70, s59, s68
	global_load_lds_dwordx4 v[216:217], off
	v_lshl_add_u64 v[218:219], s[66:67], 0, v[146:147]
	s_mov_b32 m0, s70
	v_lshl_add_u64 v[220:221], s[38:39], 0, v[148:149]
	global_load_lds_dwordx4 v[218:219], off
	v_lshl_add_u64 v[218:219], s[66:67], 0, v[150:151]
	s_add_i32 m0, s70, 0x2000
	s_nop 0
	global_load_lds_dwordx4 v[218:219], off
	v_lshl_add_u64 v[218:219], s[38:39], 0, v[144:145]
	s_mov_b32 m0, s29
	s_nop 0
	global_load_lds_dwordx4 v[218:219], off
	s_mov_b32 m0, s47
	s_nop 0
	global_load_lds_dwordx4 v[220:221], off
	s_cmp_lg_u32 s32, 0
	s_cbranch_scc1 .Lkw11b_b
	s_waitcnt vmcnt(8)
	s_branch .Lkw11b_d

; #define PG8_STAGE(bufoff, gbase, voff) do { _Pragma("unroll") for (int _i = 0; _i < 2; ++_i) \
;         __builtin_amdgcn_global_load_lds((const unsigned*)((const char*)(gbase) + (voff)[_i]), (LAS unsigned*)(lds + (bufoff) + ldsw + _i * 8192), 16, 0, 0); } while (0)
; #define PG8_LDA(dst, b, h) do { _Pragma("unroll") for (int m = 0; m < 4; ++m) _Pragma("unroll") for (int k = 0; k < 2; ++k) dst[m][k] = *(const LAS bf16x8*)(lds + PG8_SA(b, h) + aoff + m * 2048 + k * 1024); } while (0)
; #define PG8_LDB(dst, b, h) do { _Pragma("unroll") for (int n = 0; n < 2; ++n) _Pragma("unroll") for (int k = 0; k < 2; ++k) dst[n][k] = *(const LAS bf16x8*)(lds + PG8_SB(b, h) + boff + n * 2048 + k * 1024); } while (0)
; #define PG8_MMA(ai, bj, At, Bt) do { __builtin_amdgcn_s_setprio(1); _Pragma("unroll") for (int m = 0; m < 4; ++m) _Pragma("unroll") for (int n = 0; n < 2; ++n) _Pragma("unroll") for (int k = 0; k < 2; ++k) \
;         acc[ai][bj][m][n] = __builtin_amdgcn_mfma_f32_16x16x32_bf16(Bt[n][k], At[m][k], acc[ai][bj][m][n], 0, 0, 0); __builtin_amdgcn_s_setprio(0); } while (0)
; #define PG8_WAIT_V(n) asm volatile("s_waitcnt vmcnt(" #n ")" ::: "memory")
; #define PG8_WAIT_L(n) asm volatile("s_waitcnt lgkmcnt(" #n ")" ::: "memory")
; #define PG8_BAR __builtin_amdgcn_s_barrier()
; #define PG8_SCHED __builtin_amdgcn_sched_barrier(0)
; template <class Epi>
; __device__ __forceinline__ void gemm_phase(LAS unsigned char* lds, const Gemm g, const StaticOrder& S, const Epi& E, const int wid) {
;     ...
;             PG8_WAIT_V(8); PG8_WAIT_L(0); PG8_BAR; PG8_MMA(1, 0, At, B0); PG8_MMA(1, 1, At, B1); PG8_BAR; PG8_SCHED;
;             PG8_LDB(B0, 1, 0); PG8_LDB(B1, 1, 1); PG8_SCHED; PG8_LDA(At, 1, 0); PG8_STAGE(PG8_SA(0, 1), a2 + hsA, voffA);
;             PG8_WAIT_V(8); PG8_WAIT_L(0); PG8_BAR; PG8_MMA(0, 0, At, B0); PG8_MMA(0, 1, At, B1); PG8_BAR; PG8_SCHED;
.Lkw11b_d:
	s_mov_b32 s32, 0
	s_waitcnt lgkmcnt(0)
	s_barrier
	s_setprio 1
	s_waitcnt lgkmcnt(0)
	v_mfma_f32_16x16x32_bf16 v[56:59], v[128:131], v[182:185], v[56:59]
	v_mfma_f32_16x16x32_bf16 v[60:63], v[136:139], v[182:185], v[60:63]
	v_mfma_f32_16x16x32_bf16 v[40:43], v[128:131], v[190:193], v[40:43]
	v_mfma_f32_16x16x32_bf16 v[44:47], v[136:139], v[190:193], v[44:47]
	v_mfma_f32_16x16x32_bf16 v[24:27], v[128:131], v[198:201], v[24:27]
	v_mfma_f32_16x16x32_bf16 v[28:31], v[136:139], v[198:201], v[28:31]
	v_mfma_f32_16x16x32_bf16 v[8:11], v[128:131], v[206:209], v[8:11]
	v_mfma_f32_16x16x32_bf16 v[12:15], v[136:139], v[206:209], v[12:15]
	v_mfma_f32_16x16x32_bf16 v[56:59], v[132:135], v[186:189], v[56:59]
	v_mfma_f32_16x16x32_bf16 v[60:63], v[140:143], v[186:189], v[60:63]
	v_mfma_f32_16x16x32_bf16 v[40:43], v[132:135], v[194:197], v[40:43]
	v_mfma_f32_16x16x32_bf16 v[44:47], v[140:143], v[194:197], v[44:47]
	v_mfma_f32_16x16x32_bf16 v[24:27], v[132:135], v[202:205], v[24:27]
	v_mfma_f32_16x16x32_bf16 v[28:31], v[140:143], v[202:205], v[28:31]
	v_mfma_f32_16x16x32_bf16 v[8:11], v[132:135], v[210:213], v[8:11]
	v_mfma_f32_16x16x32_bf16 v[12:15], v[140:143], v[210:213], v[12:15]
	s_setprio 0
	s_setprio 1
	v_mfma_f32_16x16x32_bf16 v[48:51], v[160:163], v[182:185], v[48:51]
	v_mfma_f32_16x16x32_bf16 v[52:55], v[174:177], v[182:185], v[52:55]
	v_mfma_f32_16x16x32_bf16 v[32:35], v[160:163], v[190:193], v[32:35]
	v_mfma_f32_16x16x32_bf16 v[36:39], v[174:177], v[190:193], v[36:39]
	v_mfma_f32_16x16x32_bf16 v[16:19], v[160:163], v[198:201], v[16:19]
	v_mfma_f32_16x16x32_bf16 v[20:23], v[174:177], v[198:201], v[20:23]
	v_mfma_f32_16x16x32_bf16 v[0:3], v[160:163], v[206:209], v[0:3]
	v_mfma_f32_16x16x32_bf16 v[4:7], v[174:177], v[206:209], v[4:7]
	v_mfma_f32_16x16x32_bf16 v[48:51], v[164:167], v[186:189], v[48:51]
	v_mfma_f32_16x16x32_bf16 v[52:55], v[178:181], v[186:189], v[52:55]
	v_mfma_f32_16x16x32_bf16 v[32:35], v[164:167], v[194:197], v[32:35]
	v_mfma_f32_16x16x32_bf16 v[36:39], v[178:181], v[194:197], v[36:39]
	v_mfma_f32_16x16x32_bf16 v[16:19], v[164:167], v[202:205], v[16:19]
	v_mfma_f32_16x16x32_bf16 v[20:23], v[178:181], v[202:205], v[20:23]
	v_mfma_f32_16x16x32_bf16 v[0:3], v[164:167], v[210:213], v[0:3]
	v_mfma_f32_16x16x32_bf16 v[4:7], v[178:181], v[210:213], v[4:7]
	s_setprio 0
	s_barrier
	s_add_i32 s66, 0, 0x18000
	s_add_i32 s67, 0, 0x1c000
	v_add_u32_e32 v140, s66, v168
	v_add_u32_e32 v173, s67, v168
	ds_read_b128 v[128:131], v140
	ds_read_b128 v[132:135], v140 offset:1024
	ds_read_b128 v[136:139], v140 offset:2048
	ds_read_b128 v[140:143], v140 offset:3072
	ds_read_b128 v[160:163], v173
	ds_read_b128 v[164:167], v173 offset:1024
	ds_read_b128 v[174:177], v173 offset:2048
	ds_read_b128 v[178:181], v173 offset:3072
	s_add_u32 s38, s38, 0x40000
	s_addc_u32 s39, s39, 0
	s_mov_b32 m0, s50
	v_lshl_add_u64 v[222:223], s[38:39], 0, v[144:145]
	ds_read_b128 v[182:185], v171 offset:32768
	ds_read_b128 v[186:189], v171 offset:33792
	ds_read_b128 v[190:193], v171 offset:34816
	ds_read_b128 v[194:197], v171 offset:35840
	ds_read_b128 v[198:201], v171 offset:36864
	ds_read_b128 v[202:205], v171 offset:37888
	ds_read_b128 v[206:209], v171 offset:38912
	ds_read_b128 v[210:213], v171 offset:39936
	global_load_lds_dwordx4 v[222:223], off
	v_lshl_add_u64 v[222:223], s[38:39], 0, v[148:149]
	s_mov_b32 m0, s51
	s_nop 0
	global_load_lds_dwordx4 v[222:223], off
	s_waitcnt vmcnt(8)
	s_waitcnt lgkmcnt(0)
	s_barrier
	s_setprio 1
	s_waitcnt lgkmcnt(0)
	v_mfma_f32_16x16x32_bf16 v[124:127], v[128:131], v[182:185], v[124:127]
	v_mfma_f32_16x16x32_bf16 v[120:123], v[136:139], v[182:185], v[120:123]
	v_mfma_f32_16x16x32_bf16 v[104:107], v[128:131], v[190:193], v[104:107]
	v_mfma_f32_16x16x32_bf16 v[108:111], v[136:139], v[190:193], v[108:111]
	v_mfma_f32_16x16x32_bf16 v[88:91], v[128:131], v[198:201], v[88:91]
	v_mfma_f32_16x16x32_bf16 v[92:95], v[136:139], v[198:201], v[92:95]
	v_mfma_f32_16x16x32_bf16 v[72:75], v[128:131], v[206:209], v[72:75]
	v_mfma_f32_16x16x32_bf16 v[76:79], v[136:139], v[206:209], v[76:79]
	v_mfma_f32_16x16x32_bf16 v[124:127], v[132:135], v[186:189], v[124:127]
	v_mfma_f32_16x16x32_bf16 v[120:123], v[140:143], v[186:189], v[120:123]
	v_mfma_f32_16x16x32_bf16 v[104:107], v[132:135], v[194:197], v[104:107]
	v_mfma_f32_16x16x32_bf16 v[108:111], v[140:143], v[194:197], v[108:111]
	v_mfma_f32_16x16x32_bf16 v[88:91], v[132:135], v[202:205], v[88:91]
	v_mfma_f32_16x16x32_bf16 v[92:95], v[140:143], v[202:205], v[92:95]
	v_mfma_f32_16x16x32_bf16 v[72:75], v[132:135], v[210:213], v[72:75]
	v_mfma_f32_16x16x32_bf16 v[76:79], v[140:143], v[210:213], v[76:79]
	s_setprio 0
	s_setprio 1
	v_mfma_f32_16x16x32_bf16 v[112:115], v[160:163], v[182:185], v[112:115]
	v_mfma_f32_16x16x32_bf16 v[116:119], v[174:177], v[182:185], v[116:119]
	v_mfma_f32_16x16x32_bf16 v[96:99], v[160:163], v[190:193], v[96:99]
	v_mfma_f32_16x16x32_bf16 v[100:103], v[174:177], v[190:193], v[100:103]
	v_mfma_f32_16x16x32_bf16 v[80:83], v[160:163], v[198:201], v[80:83]
	v_mfma_f32_16x16x32_bf16 v[84:87], v[174:177], v[198:201], v[84:87]
	v_mfma_f32_16x16x32_bf16 v[64:67], v[160:163], v[206:209], v[64:67]
	v_mfma_f32_16x16x32_bf16 v[68:71], v[174:177], v[206:209], v[68:71]
	v_mfma_f32_16x16x32_bf16 v[112:115], v[164:167], v[186:189], v[112:115]
	v_mfma_f32_16x16x32_bf16 v[116:119], v[178:181], v[186:189], v[116:119]
	v_mfma_f32_16x16x32_bf16 v[96:99], v[164:167], v[194:197], v[96:99]
	v_mfma_f32_16x16x32_bf16 v[100:103], v[178:181], v[194:197], v[100:103]
	v_mfma_f32_16x16x32_bf16 v[80:83], v[164:167], v[202:205], v[80:83]
	v_mfma_f32_16x16x32_bf16 v[84:87], v[178:181], v[202:205], v[84:87]
	v_mfma_f32_16x16x32_bf16 v[64:67], v[164:167], v[210:213], v[64:67]
	v_mfma_f32_16x16x32_bf16 v[68:71], v[178:181], v[210:213], v[68:71]
	s_setprio 0
	s_barrier
; #define PG8_STAGE(bufoff, gbase, voff) do { _Pragma("unroll") for (int _i = 0; _i < 2; ++_i) \
;         __builtin_amdgcn_global_load_lds((const unsigned*)((const char*)(gbase) + (voff)[_i]), (LAS unsigned*)(lds + (bufoff) + ldsw + _i * 8192), 16, 0, 0); } while (0)
; #define PG8_LDA(dst, b, h) do { _Pragma("unroll") for (int m = 0; m < 4; ++m) _Pragma("unroll") for (int k = 0; k < 2; ++k) dst[m][k] = *(const LAS bf16x8*)(lds + PG8_SA(b, h) + aoff + m * 2048 + k * 1024); } while (0)
; #define PG8_MMA(ai, bj, At, Bt) do { __builtin_amdgcn_s_setprio(1); _Pragma("unroll") for (int m = 0; m < 4; ++m) _Pragma("unroll") for (int n = 0; n < 2; ++n) _Pragma("unroll") for (int k = 0; k < 2; ++k) \
;         acc[ai][bj][m][n] = __builtin_amdgcn_mfma_f32_16x16x32_bf16(Bt[n][k], At[m][k], acc[ai][bj][m][n], 0, 0, 0); __builtin_amdgcn_s_setprio(0); } while (0)
; #define PG8_WAIT_V(n) asm volatile("s_waitcnt vmcnt(" #n ")" ::: "memory")
; #define PG8_WAIT_L(n) asm volatile("s_waitcnt lgkmcnt(" #n ")" ::: "memory")
; #define PG8_BAR __builtin_amdgcn_s_barrier()
; #define PG8_SCHED __builtin_amdgcn_sched_barrier(0)
; template <class Epi>
; __device__ __forceinline__ void gemm_phase(LAS unsigned char* lds, const Gemm g, const StaticOrder& S, const Epi& E, const int wid) {
;     ...
;             PG8_LDA(At, 1, 1); PG8_STAGE(PG8_SB(1, 0), b3, voffB); PG8_STAGE(PG8_SB(1, 1), b3 + hsB, voffB); PG8_STAGE(PG8_SA(1, 0), a3, voffA);
;             PG8_WAIT_V(8); PG8_WAIT_L(0); PG8_BAR; PG8_MMA(1, 0, At, B0); PG8_MMA(1, 1, At, B1); PG8_BAR; PG8_SCHED;
;         }
;         if (wr == 0) PG8_BAR;
	s_add_i32 s38, s66, s68
	v_lshl_add_u64 v[214:215], v[214:215], 0, s[6:7]
	s_mov_b32 m0, s38
	ds_read_b128 v[182:185], v171 offset:49152
	ds_read_b128 v[186:189], v171 offset:50176
	ds_read_b128 v[190:193], v171 offset:51200
	ds_read_b128 v[194:197], v171 offset:52224
	ds_read_b128 v[198:201], v171 offset:53248
	ds_read_b128 v[202:205], v171 offset:54272
	ds_read_b128 v[206:209], v171 offset:55296
	ds_read_b128 v[210:213], v171 offset:56320
	global_load_lds_dwordx4 v[214:215], off
	s_add_i32 m0, s38, 0x2000
	s_add_u32 s34, s34, 0x40080
	v_lshl_add_u64 v[214:215], v[216:217], 0, s[6:7]
	s_addc_u32 s35, s35, 0
	s_add_i32 s38, s67, s68
	global_load_lds_dwordx4 v[214:215], off
	v_lshl_add_u64 v[214:215], s[34:35], 0, v[146:147]
	s_mov_b32 m0, s38
	s_nop 0
	global_load_lds_dwordx4 v[214:215], off
	v_lshl_add_u64 v[214:215], s[34:35], 0, v[150:151]
	s_add_i32 m0, s38, 0x2000
	s_nop 0
	global_load_lds_dwordx4 v[214:215], off
	v_lshl_add_u64 v[214:215], v[218:219], 0, s[6:7]
	s_mov_b32 m0, s55
	s_nop 0
	global_load_lds_dwordx4 v[214:215], off
	v_lshl_add_u64 v[214:215], v[220:221], 0, s[6:7]
	s_mov_b32 m0, s57
	s_nop 0
	global_load_lds_dwordx4 v[214:215], off
	s_waitcnt vmcnt(8)
	s_waitcnt lgkmcnt(0)
	s_barrier
	s_setprio 1
	s_waitcnt lgkmcnt(0)
	v_mfma_f32_16x16x32_bf16 v[56:59], v[128:131], v[182:185], v[56:59]
	v_mfma_f32_16x16x32_bf16 v[60:63], v[136:139], v[182:185], v[60:63]
	v_mfma_f32_16x16x32_bf16 v[40:43], v[128:131], v[190:193], v[40:43]
	v_mfma_f32_16x16x32_bf16 v[44:47], v[136:139], v[190:193], v[44:47]
	v_mfma_f32_16x16x32_bf16 v[24:27], v[128:131], v[198:201], v[24:27]
	v_mfma_f32_16x16x32_bf16 v[28:31], v[136:139], v[198:201], v[28:31]
	v_mfma_f32_16x16x32_bf16 v[8:11], v[128:131], v[206:209], v[8:11]
	v_mfma_f32_16x16x32_bf16 v[12:15], v[136:139], v[206:209], v[12:15]
	v_mfma_f32_16x16x32_bf16 v[56:59], v[132:135], v[186:189], v[56:59]
	v_mfma_f32_16x16x32_bf16 v[60:63], v[140:143], v[186:189], v[60:63]
	v_mfma_f32_16x16x32_bf16 v[40:43], v[132:135], v[194:197], v[40:43]
	v_mfma_f32_16x16x32_bf16 v[44:47], v[140:143], v[194:197], v[44:47]
	v_mfma_f32_16x16x32_bf16 v[24:27], v[132:135], v[202:205], v[24:27]
	v_mfma_f32_16x16x32_bf16 v[28:31], v[140:143], v[202:205], v[28:31]
	v_mfma_f32_16x16x32_bf16 v[8:11], v[132:135], v[210:213], v[8:11]
	v_mfma_f32_16x16x32_bf16 v[12:15], v[140:143], v[210:213], v[12:15]
	s_setprio 0
	s_setprio 1
	v_mfma_f32_16x16x32_bf16 v[48:51], v[160:163], v[182:185], v[48:51]
	v_mfma_f32_16x16x32_bf16 v[52:55], v[174:177], v[182:185], v[52:55]
	v_mfma_f32_16x16x32_bf16 v[32:35], v[160:163], v[190:193], v[32:35]
	v_mfma_f32_16x16x32_bf16 v[36:39], v[174:177], v[190:193], v[36:39]
	v_mfma_f32_16x16x32_bf16 v[16:19], v[160:163], v[198:201], v[16:19]
	v_mfma_f32_16x16x32_bf16 v[20:23], v[174:177], v[198:201], v[20:23]
	v_mfma_f32_16x16x32_bf16 v[0:3], v[160:163], v[206:209], v[0:3]
	v_mfma_f32_16x16x32_bf16 v[4:7], v[174:177], v[206:209], v[4:7]
	v_mfma_f32_16x16x32_bf16 v[48:51], v[164:167], v[186:189], v[48:51]
	v_mfma_f32_16x16x32_bf16 v[52:55], v[178:181], v[186:189], v[52:55]
	v_mfma_f32_16x16x32_bf16 v[32:35], v[164:167], v[194:197], v[32:35]
	v_mfma_f32_16x16x32_bf16 v[36:39], v[178:181], v[194:197], v[36:39]
	v_mfma_f32_16x16x32_bf16 v[16:19], v[164:167], v[202:205], v[16:19]
	v_mfma_f32_16x16x32_bf16 v[20:23], v[178:181], v[202:205], v[20:23]
	v_mfma_f32_16x16x32_bf16 v[0:3], v[164:167], v[210:213], v[0:3]
	v_mfma_f32_16x16x32_bf16 v[4:7], v[178:181], v[210:213], v[4:7]
	s_setprio 0
	s_barrier
	s_add_i32 s65, s65, 2
	s_add_u32 s63, s63, 0x100
	s_addc_u32 s64, s64, 0
	s_add_u32 s30, s30, 0x100
	s_addc_u32 s31, s31, 0
	s_cmp_gt_u32 s65, 13
	s_cbranch_scc0 .LBB0_1353
	s_mov_b32 s32, 1
	s_and_b64 vcc, exec, s[8:9]
	s_cbranch_vccz .LBB0_1356
	s_barrier
